# v50 + K-loop handoff trimming: duplicate lgkmcnt(0) after the LOAD barrier dropped, s_setprio 1 issued before that barrier, mid-segment s_setprio 0/1 pair dropped (all 12 loops + 9 peeled copies)
# speedup vs baseline: 1.0124x; 1.0124x over previous
.LBB0_297:
	s_add_u32 s47, s38, s46
	s_addc_u32 s66, s39, 0
	s_add_u32 s64, s47, 0x100
	s_addc_u32 s65, s66, 0
	s_and_b64 s[48:49], s[44:45], exec
	s_cselect_b32 s49, s70, s65
	s_cselect_b32 s48, s71, s64
	s_add_u32 s46, s36, s46
	s_addc_u32 s64, s37, 0
	s_add_u32 s46, s46, 0x100
	s_addc_u32 s64, s64, 0
	s_and_b64 s[44:45], s[44:45], exec
	s_cselect_b32 s65, s72, s64
	s_cselect_b32 s64, s73, s46
	s_add_u32 s68, s47, 0x10080
	ds_read_b128 v[150:153], v146
	ds_read_b128 v[154:157], v146 offset:1024
	ds_read_b128 v[158:161], v146 offset:2048
	ds_read_b128 v[162:165], v146 offset:3072
	ds_read_b128 v[166:169], v147
	ds_read_b128 v[170:173], v147 offset:1024
	ds_read_b128 v[174:177], v147 offset:2048
	ds_read_b128 v[178:181], v147 offset:3072
	s_addc_u32 s69, s66, 0
	s_add_i32 s83, s30, s2
	s_add_i32 m0, s16, 0xc000
	s_add_i32 s84, s16, 0xe000
	s_add_i32 s80, s83, 0x2000
	s_add_u32 s66, s64, 0x40000
	s_addc_u32 s67, s65, 0
	s_add_i32 s82, s31, s2
	s_add_i32 s81, s82, 0x2000
	s_add_i32 s79, 0, 0x18000
	s_add_i32 s78, 0, 0x1c000
	s_add_u32 s46, s48, 0x10000
	s_addc_u32 s47, s49, 0
	s_add_i32 s77, s79, s2
	s_add_i32 s75, s77, 0x2000
	s_add_u32 s44, s64, 0x40080
	s_addc_u32 s45, s65, 0
	s_add_i32 s76, s78, s2
	s_add_i32 s74, s76, 0x2000
	v_lshl_add_u64 v[202:203], s[68:69], 0, v[130:131]
	ds_read_b128 v[182:185], v148
	ds_read_b128 v[186:189], v148 offset:1024
	ds_read_b128 v[190:193], v148 offset:2048
	ds_read_b128 v[194:197], v148 offset:3072
	ds_read_b128 v[198:201], v148 offset:4096
	ds_read_b128 v[206:209], v148 offset:5120
	ds_read_b128 v[210:213], v148 offset:6144
	ds_read_b128 v[214:217], v148 offset:7168
	global_load_lds_dwordx4 v[202:203], off
	v_lshl_add_u64 v[202:203], s[68:69], 0, v[132:133]
	s_mov_b32 m0, s84
	s_nop 0
	global_load_lds_dwordx4 v[202:203], off
	s_waitcnt vmcnt(8)
	s_waitcnt lgkmcnt(0)
	s_setprio 1
	s_barrier
	v_mfma_f32_16x16x32_bf16 v[126:129], v[150:153], v[182:185], v[126:129]
	v_mfma_f32_16x16x32_bf16 v[122:125], v[158:161], v[182:185], v[122:125]
	v_mfma_f32_16x16x32_bf16 v[118:121], v[150:153], v[190:193], v[118:121]
	v_mfma_f32_16x16x32_bf16 v[114:117], v[158:161], v[190:193], v[114:117]
	v_mfma_f32_16x16x32_bf16 v[102:105], v[150:153], v[198:201], v[102:105]
	v_mfma_f32_16x16x32_bf16 v[98:101], v[158:161], v[198:201], v[98:101]
	v_mfma_f32_16x16x32_bf16 v[86:89], v[150:153], v[210:213], v[86:89]
	v_mfma_f32_16x16x32_bf16 v[82:85], v[158:161], v[210:213], v[82:85]
	v_mfma_f32_16x16x32_bf16 v[126:129], v[154:157], v[186:189], v[126:129]
	v_mfma_f32_16x16x32_bf16 v[122:125], v[162:165], v[186:189], v[122:125]
	v_mfma_f32_16x16x32_bf16 v[118:121], v[154:157], v[194:197], v[118:121]
	v_mfma_f32_16x16x32_bf16 v[114:117], v[162:165], v[194:197], v[114:117]
	v_mfma_f32_16x16x32_bf16 v[102:105], v[154:157], v[206:209], v[102:105]
	v_mfma_f32_16x16x32_bf16 v[98:101], v[162:165], v[206:209], v[98:101]
	v_mfma_f32_16x16x32_bf16 v[86:89], v[154:157], v[214:217], v[86:89]
	v_mfma_f32_16x16x32_bf16 v[82:85], v[162:165], v[214:217], v[82:85]
	v_mfma_f32_16x16x32_bf16 v[110:113], v[166:169], v[182:185], v[110:113]
	v_mfma_f32_16x16x32_bf16 v[106:109], v[174:177], v[182:185], v[106:109]
	v_mfma_f32_16x16x32_bf16 v[94:97], v[166:169], v[190:193], v[94:97]
	v_mfma_f32_16x16x32_bf16 v[90:93], v[174:177], v[190:193], v[90:93]
	v_mfma_f32_16x16x32_bf16 v[78:81], v[166:169], v[198:201], v[78:81]
	v_mfma_f32_16x16x32_bf16 v[74:77], v[174:177], v[198:201], v[74:77]
	v_mfma_f32_16x16x32_bf16 v[70:73], v[166:169], v[210:213], v[70:73]
	v_mfma_f32_16x16x32_bf16 v[66:69], v[174:177], v[210:213], v[66:69]
	v_mfma_f32_16x16x32_bf16 v[110:113], v[170:173], v[186:189], v[110:113]
	v_mfma_f32_16x16x32_bf16 v[106:109], v[178:181], v[186:189], v[106:109]
	v_mfma_f32_16x16x32_bf16 v[94:97], v[170:173], v[194:197], v[94:97]
	v_mfma_f32_16x16x32_bf16 v[90:93], v[178:181], v[194:197], v[90:93]
	v_mfma_f32_16x16x32_bf16 v[78:81], v[170:173], v[206:209], v[78:81]
	v_mfma_f32_16x16x32_bf16 v[74:77], v[178:181], v[206:209], v[74:77]
	v_mfma_f32_16x16x32_bf16 v[70:73], v[170:173], v[214:217], v[70:73]
	v_mfma_f32_16x16x32_bf16 v[66:69], v[178:181], v[214:217], v[66:69]
	s_setprio 0
	s_barrier
	s_mov_b32 m0, s83
	v_lshl_add_u64 v[202:203], s[64:65], 0, v[136:137]
	ds_read_b128 v[182:185], v148 offset:16384
	ds_read_b128 v[186:189], v148 offset:17408
	ds_read_b128 v[190:193], v148 offset:18432
	ds_read_b128 v[194:197], v148 offset:19456
	ds_read_b128 v[198:201], v148 offset:20480
	ds_read_b128 v[206:209], v148 offset:21504
	ds_read_b128 v[210:213], v148 offset:22528
	ds_read_b128 v[214:217], v148 offset:23552
	global_load_lds_dwordx4 v[202:203], off
	v_lshl_add_u64 v[218:219], s[64:65], 0, v[134:135]
	s_mov_b32 m0, s80
	v_lshl_add_u64 v[220:221], s[66:67], 0, v[136:137]
	global_load_lds_dwordx4 v[218:219], off
	s_mov_b32 m0, s82
	v_lshl_add_u64 v[222:223], s[48:49], 0, v[132:133]
	global_load_lds_dwordx4 v[220:221], off
	v_lshl_add_u64 v[220:221], s[66:67], 0, v[134:135]
	s_mov_b32 m0, s81
	s_nop 0
	global_load_lds_dwordx4 v[220:221], off
	v_lshl_add_u64 v[220:221], s[48:49], 0, v[130:131]
	s_mov_b32 m0, s16
	s_nop 0
	global_load_lds_dwordx4 v[220:221], off
	s_mov_b32 m0, s17
	s_nop 0
	global_load_lds_dwordx4 v[222:223], off
	s_waitcnt vmcnt(8)
	s_waitcnt lgkmcnt(0)
	s_setprio 1
	s_barrier
	v_mfma_f32_16x16x32_bf16 v[62:65], v[150:153], v[182:185], v[62:65]
	v_mfma_f32_16x16x32_bf16 v[58:61], v[158:161], v[182:185], v[58:61]
	v_mfma_f32_16x16x32_bf16 v[54:57], v[150:153], v[190:193], v[54:57]
	v_mfma_f32_16x16x32_bf16 v[50:53], v[158:161], v[190:193], v[50:53]
	v_mfma_f32_16x16x32_bf16 v[38:41], v[150:153], v[198:201], v[38:41]
	v_mfma_f32_16x16x32_bf16 v[34:37], v[158:161], v[198:201], v[34:37]
	v_mfma_f32_16x16x32_bf16 v[22:25], v[150:153], v[210:213], v[22:25]
	v_mfma_f32_16x16x32_bf16 v[18:21], v[158:161], v[210:213], v[18:21]
	v_mfma_f32_16x16x32_bf16 v[62:65], v[154:157], v[186:189], v[62:65]
	v_mfma_f32_16x16x32_bf16 v[58:61], v[162:165], v[186:189], v[58:61]
	v_mfma_f32_16x16x32_bf16 v[54:57], v[154:157], v[194:197], v[54:57]
	v_mfma_f32_16x16x32_bf16 v[50:53], v[162:165], v[194:197], v[50:53]
	v_mfma_f32_16x16x32_bf16 v[38:41], v[154:157], v[206:209], v[38:41]
	v_mfma_f32_16x16x32_bf16 v[34:37], v[162:165], v[206:209], v[34:37]
	v_mfma_f32_16x16x32_bf16 v[22:25], v[154:157], v[214:217], v[22:25]
	v_mfma_f32_16x16x32_bf16 v[18:21], v[162:165], v[214:217], v[18:21]
	v_mfma_f32_16x16x32_bf16 v[46:49], v[166:169], v[182:185], v[46:49]
	v_mfma_f32_16x16x32_bf16 v[42:45], v[174:177], v[182:185], v[42:45]
	v_mfma_f32_16x16x32_bf16 v[30:33], v[166:169], v[190:193], v[30:33]
	v_mfma_f32_16x16x32_bf16 v[26:29], v[174:177], v[190:193], v[26:29]
	v_mfma_f32_16x16x32_bf16 v[14:17], v[166:169], v[198:201], v[14:17]
	v_mfma_f32_16x16x32_bf16 v[10:13], v[174:177], v[198:201], v[10:13]
	v_mfma_f32_16x16x32_bf16 v[6:9], v[166:169], v[210:213], v[6:9]
	v_mfma_f32_16x16x32_bf16 v[2:5], v[174:177], v[210:213], v[2:5]
	v_mfma_f32_16x16x32_bf16 v[46:49], v[170:173], v[186:189], v[46:49]
	v_mfma_f32_16x16x32_bf16 v[42:45], v[178:181], v[186:189], v[42:45]
	v_mfma_f32_16x16x32_bf16 v[30:33], v[170:173], v[194:197], v[30:33]
	v_mfma_f32_16x16x32_bf16 v[26:29], v[178:181], v[194:197], v[26:29]
	v_mfma_f32_16x16x32_bf16 v[14:17], v[170:173], v[206:209], v[14:17]
	v_mfma_f32_16x16x32_bf16 v[10:13], v[178:181], v[206:209], v[10:13]
	v_mfma_f32_16x16x32_bf16 v[6:9], v[170:173], v[214:217], v[6:9]
	v_mfma_f32_16x16x32_bf16 v[2:5], v[178:181], v[214:217], v[2:5]
	s_setprio 0
	s_barrier
	v_add_u32_e32 v149, s79, v145
	ds_read_b128 v[150:153], v149
	ds_read_b128 v[154:157], v149 offset:1024
	ds_read_b128 v[158:161], v149 offset:2048
	ds_read_b128 v[162:165], v149 offset:3072
	v_add_u32_e32 v149, s78, v145
	ds_read_b128 v[166:169], v149
	ds_read_b128 v[170:173], v149 offset:1024
	ds_read_b128 v[174:177], v149 offset:2048
	ds_read_b128 v[178:181], v149 offset:3072
	s_mov_b32 m0, s18
	v_lshl_add_u64 v[224:225], s[46:47], 0, v[130:131]
	ds_read_b128 v[182:185], v148 offset:32768
	ds_read_b128 v[186:189], v148 offset:33792
	ds_read_b128 v[190:193], v148 offset:34816
	ds_read_b128 v[194:197], v148 offset:35840
	ds_read_b128 v[198:201], v148 offset:36864
	ds_read_b128 v[206:209], v148 offset:37888
	ds_read_b128 v[210:213], v148 offset:38912
	ds_read_b128 v[214:217], v148 offset:39936
	global_load_lds_dwordx4 v[224:225], off
	v_lshl_add_u64 v[224:225], s[46:47], 0, v[132:133]
	s_mov_b32 m0, s19
	s_nop 0
	global_load_lds_dwordx4 v[224:225], off
	s_waitcnt vmcnt(8)
	s_waitcnt lgkmcnt(0)
	s_setprio 1
	s_barrier
	v_mfma_f32_16x16x32_bf16 v[126:129], v[150:153], v[182:185], v[126:129]
	v_mfma_f32_16x16x32_bf16 v[122:125], v[158:161], v[182:185], v[122:125]
	v_mfma_f32_16x16x32_bf16 v[118:121], v[150:153], v[190:193], v[118:121]
	v_mfma_f32_16x16x32_bf16 v[114:117], v[158:161], v[190:193], v[114:117]
	v_mfma_f32_16x16x32_bf16 v[102:105], v[150:153], v[198:201], v[102:105]
	v_mfma_f32_16x16x32_bf16 v[98:101], v[158:161], v[198:201], v[98:101]
	v_mfma_f32_16x16x32_bf16 v[86:89], v[150:153], v[210:213], v[86:89]
	v_mfma_f32_16x16x32_bf16 v[82:85], v[158:161], v[210:213], v[82:85]
	v_mfma_f32_16x16x32_bf16 v[126:129], v[154:157], v[186:189], v[126:129]
	v_mfma_f32_16x16x32_bf16 v[122:125], v[162:165], v[186:189], v[122:125]
	v_mfma_f32_16x16x32_bf16 v[118:121], v[154:157], v[194:197], v[118:121]
	v_mfma_f32_16x16x32_bf16 v[114:117], v[162:165], v[194:197], v[114:117]
	v_mfma_f32_16x16x32_bf16 v[102:105], v[154:157], v[206:209], v[102:105]
	v_mfma_f32_16x16x32_bf16 v[98:101], v[162:165], v[206:209], v[98:101]
	v_mfma_f32_16x16x32_bf16 v[86:89], v[154:157], v[214:217], v[86:89]
	v_mfma_f32_16x16x32_bf16 v[82:85], v[162:165], v[214:217], v[82:85]
	v_mfma_f32_16x16x32_bf16 v[110:113], v[166:169], v[182:185], v[110:113]
	v_mfma_f32_16x16x32_bf16 v[106:109], v[174:177], v[182:185], v[106:109]
	v_mfma_f32_16x16x32_bf16 v[94:97], v[166:169], v[190:193], v[94:97]
	v_mfma_f32_16x16x32_bf16 v[90:93], v[174:177], v[190:193], v[90:93]
	v_mfma_f32_16x16x32_bf16 v[78:81], v[166:169], v[198:201], v[78:81]
	v_mfma_f32_16x16x32_bf16 v[74:77], v[174:177], v[198:201], v[74:77]
	v_mfma_f32_16x16x32_bf16 v[70:73], v[166:169], v[210:213], v[70:73]
	v_mfma_f32_16x16x32_bf16 v[66:69], v[174:177], v[210:213], v[66:69]
	v_mfma_f32_16x16x32_bf16 v[110:113], v[170:173], v[186:189], v[110:113]
	v_mfma_f32_16x16x32_bf16 v[106:109], v[178:181], v[186:189], v[106:109]
	v_mfma_f32_16x16x32_bf16 v[94:97], v[170:173], v[194:197], v[94:97]
	v_mfma_f32_16x16x32_bf16 v[90:93], v[178:181], v[194:197], v[90:93]
	v_mfma_f32_16x16x32_bf16 v[78:81], v[170:173], v[206:209], v[78:81]
	v_mfma_f32_16x16x32_bf16 v[74:77], v[178:181], v[206:209], v[74:77]
	v_mfma_f32_16x16x32_bf16 v[70:73], v[170:173], v[214:217], v[70:73]
	v_mfma_f32_16x16x32_bf16 v[66:69], v[178:181], v[214:217], v[66:69]
	s_setprio 0
	s_barrier
	s_mov_b32 m0, s77
	v_lshl_add_u64 v[202:203], v[202:203], 0, s[8:9]
	ds_read_b128 v[182:185], v148 offset:49152
	ds_read_b128 v[186:189], v148 offset:50176
	ds_read_b128 v[190:193], v148 offset:51200
	ds_read_b128 v[194:197], v148 offset:52224
	ds_read_b128 v[198:201], v148 offset:53248
	ds_read_b128 v[206:209], v148 offset:54272
	ds_read_b128 v[210:213], v148 offset:55296
	ds_read_b128 v[214:217], v148 offset:56320
	global_load_lds_dwordx4 v[202:203], off
	v_lshl_add_u64 v[202:203], v[218:219], 0, s[8:9]
	s_mov_b32 m0, s75
	s_nop 0
	global_load_lds_dwordx4 v[202:203], off
	v_lshl_add_u64 v[202:203], s[44:45], 0, v[136:137]
	s_mov_b32 m0, s76
	s_nop 0
	global_load_lds_dwordx4 v[202:203], off
	v_lshl_add_u64 v[202:203], s[44:45], 0, v[134:135]
	s_mov_b32 m0, s74
	s_nop 0
	global_load_lds_dwordx4 v[202:203], off
	v_lshl_add_u64 v[202:203], v[220:221], 0, s[8:9]
	s_mov_b32 m0, s28
	s_nop 0
	global_load_lds_dwordx4 v[202:203], off
	v_lshl_add_u64 v[202:203], v[222:223], 0, s[8:9]
	s_mov_b32 m0, s29
	s_nop 0
	global_load_lds_dwordx4 v[202:203], off
	s_waitcnt vmcnt(8)
	s_waitcnt lgkmcnt(0)
	s_setprio 1
	s_barrier
	v_mfma_f32_16x16x32_bf16 v[62:65], v[150:153], v[182:185], v[62:65]
	v_mfma_f32_16x16x32_bf16 v[58:61], v[158:161], v[182:185], v[58:61]
	v_mfma_f32_16x16x32_bf16 v[54:57], v[150:153], v[190:193], v[54:57]
	v_mfma_f32_16x16x32_bf16 v[50:53], v[158:161], v[190:193], v[50:53]
	v_mfma_f32_16x16x32_bf16 v[38:41], v[150:153], v[198:201], v[38:41]
	v_mfma_f32_16x16x32_bf16 v[34:37], v[158:161], v[198:201], v[34:37]
	v_mfma_f32_16x16x32_bf16 v[22:25], v[150:153], v[210:213], v[22:25]
	v_mfma_f32_16x16x32_bf16 v[18:21], v[158:161], v[210:213], v[18:21]
	v_mfma_f32_16x16x32_bf16 v[62:65], v[154:157], v[186:189], v[62:65]
	v_mfma_f32_16x16x32_bf16 v[58:61], v[162:165], v[186:189], v[58:61]
	v_mfma_f32_16x16x32_bf16 v[54:57], v[154:157], v[194:197], v[54:57]
	v_mfma_f32_16x16x32_bf16 v[50:53], v[162:165], v[194:197], v[50:53]
	v_mfma_f32_16x16x32_bf16 v[38:41], v[154:157], v[206:209], v[38:41]
	v_mfma_f32_16x16x32_bf16 v[34:37], v[162:165], v[206:209], v[34:37]
	v_mfma_f32_16x16x32_bf16 v[22:25], v[154:157], v[214:217], v[22:25]
	v_mfma_f32_16x16x32_bf16 v[18:21], v[162:165], v[214:217], v[18:21]
	v_mfma_f32_16x16x32_bf16 v[46:49], v[166:169], v[182:185], v[46:49]
	v_mfma_f32_16x16x32_bf16 v[42:45], v[174:177], v[182:185], v[42:45]
	v_mfma_f32_16x16x32_bf16 v[30:33], v[166:169], v[190:193], v[30:33]
	v_mfma_f32_16x16x32_bf16 v[26:29], v[174:177], v[190:193], v[26:29]
	v_mfma_f32_16x16x32_bf16 v[14:17], v[166:169], v[198:201], v[14:17]
	v_mfma_f32_16x16x32_bf16 v[10:13], v[174:177], v[198:201], v[10:13]
	v_mfma_f32_16x16x32_bf16 v[6:9], v[166:169], v[210:213], v[6:9]
	v_mfma_f32_16x16x32_bf16 v[2:5], v[174:177], v[210:213], v[2:5]
	v_mfma_f32_16x16x32_bf16 v[46:49], v[170:173], v[186:189], v[46:49]
	v_mfma_f32_16x16x32_bf16 v[42:45], v[178:181], v[186:189], v[42:45]
	v_mfma_f32_16x16x32_bf16 v[30:33], v[170:173], v[194:197], v[30:33]
	v_mfma_f32_16x16x32_bf16 v[26:29], v[178:181], v[194:197], v[26:29]
	v_mfma_f32_16x16x32_bf16 v[14:17], v[170:173], v[206:209], v[14:17]
	v_mfma_f32_16x16x32_bf16 v[10:13], v[178:181], v[206:209], v[10:13]
	v_mfma_f32_16x16x32_bf16 v[6:9], v[170:173], v[214:217], v[6:9]
	v_mfma_f32_16x16x32_bf16 v[2:5], v[178:181], v[214:217], v[2:5]
	s_setprio 0
	s_barrier
	s_movk_i32 s46, 0x100
	s_andn2_b64 vcc, exec, s[42:43]
	s_mov_b64 s[44:45], -1
	s_mov_b64 s[42:43], 0
	s_cbranch_vccz .LBB0_297
	s_and_b64 vcc, exec, s[10:11]
	s_cbranch_vccz .LBB0_300
	s_barrier

.LBB0_313:
	s_add_u32 s49, s38, s48
	s_addc_u32 s68, s39, 0
	s_add_u32 s66, s49, 0x100
	s_addc_u32 s67, s68, 0
	s_and_b64 s[64:65], s[46:47], exec
	s_cselect_b32 s65, s43, s67
	s_cselect_b32 s64, s75, s66
	s_add_u32 s48, s36, s48
	s_addc_u32 s66, s37, 0
	s_add_u32 s48, s48, 0x100
	s_addc_u32 s66, s66, 0
	s_and_b64 s[46:47], s[46:47], exec
	s_cselect_b32 s67, s76, s66
	s_cselect_b32 s66, s77, s48
	s_add_u32 s70, s49, 0x10080
	ds_read_b128 v[144:147], v140
	ds_read_b128 v[148:151], v140 offset:1024
	ds_read_b128 v[152:155], v140 offset:2048
	ds_read_b128 v[156:159], v140 offset:3072
	ds_read_b128 v[160:163], v141
	ds_read_b128 v[164:167], v141 offset:1024
	ds_read_b128 v[168:171], v141 offset:2048
	ds_read_b128 v[172:175], v141 offset:3072
	s_addc_u32 s71, s68, 0
	s_add_i32 s87, s33, s2
	s_add_i32 m0, s16, 0xc000
	s_add_i32 s88, s16, 0xe000
	s_add_i32 s84, s87, 0x2000
	s_add_u32 s68, s66, 0x1000
	s_addc_u32 s69, s67, 0
	s_add_i32 s86, s34, s2
	s_add_i32 s85, s86, 0x2000
	s_add_i32 s83, 0, 0x18000
	s_add_i32 s82, 0, 0x1c000
	s_add_u32 s48, s64, 0x10000
	s_addc_u32 s49, s65, 0
	s_add_i32 s81, s83, s2
	s_add_i32 s79, s81, 0x2000
	s_add_u32 s46, s66, 0x1080
	s_addc_u32 s47, s67, 0
	s_add_i32 s80, s82, s2
	s_add_i32 s78, s80, 0x2000
	v_lshl_add_u64 v[210:211], s[70:71], 0, v[130:131]
	ds_read_b128 v[176:179], v142
	ds_read_b128 v[180:183], v142 offset:1024
	ds_read_b128 v[184:187], v142 offset:2048
	ds_read_b128 v[188:191], v142 offset:3072
	ds_read_b128 v[192:195], v142 offset:4096
	ds_read_b128 v[196:199], v142 offset:5120
	ds_read_b128 v[200:203], v142 offset:6144
	ds_read_b128 v[206:209], v142 offset:7168
	global_load_lds_dwordx4 v[210:211], off
	v_lshl_add_u64 v[210:211], s[70:71], 0, v[132:133]
	s_mov_b32 m0, s88
	s_nop 0
	global_load_lds_dwordx4 v[210:211], off
	s_waitcnt vmcnt(8)
	s_waitcnt lgkmcnt(0)
	s_setprio 1
	s_barrier
	v_mfma_f32_16x16x32_bf16 v[126:129], v[144:147], v[176:179], v[126:129]
	v_mfma_f32_16x16x32_bf16 v[122:125], v[152:155], v[176:179], v[122:125]
	v_mfma_f32_16x16x32_bf16 v[118:121], v[144:147], v[184:187], v[118:121]
	v_mfma_f32_16x16x32_bf16 v[114:117], v[152:155], v[184:187], v[114:117]
	v_mfma_f32_16x16x32_bf16 v[102:105], v[144:147], v[192:195], v[102:105]
	v_mfma_f32_16x16x32_bf16 v[98:101], v[152:155], v[192:195], v[98:101]
	v_mfma_f32_16x16x32_bf16 v[86:89], v[144:147], v[200:203], v[86:89]
	v_mfma_f32_16x16x32_bf16 v[82:85], v[152:155], v[200:203], v[82:85]
	v_mfma_f32_16x16x32_bf16 v[126:129], v[148:151], v[180:183], v[126:129]
	v_mfma_f32_16x16x32_bf16 v[122:125], v[156:159], v[180:183], v[122:125]
	v_mfma_f32_16x16x32_bf16 v[118:121], v[148:151], v[188:191], v[118:121]
	v_mfma_f32_16x16x32_bf16 v[114:117], v[156:159], v[188:191], v[114:117]
	v_mfma_f32_16x16x32_bf16 v[102:105], v[148:151], v[196:199], v[102:105]
	v_mfma_f32_16x16x32_bf16 v[98:101], v[156:159], v[196:199], v[98:101]
	v_mfma_f32_16x16x32_bf16 v[86:89], v[148:151], v[206:209], v[86:89]
	v_mfma_f32_16x16x32_bf16 v[82:85], v[156:159], v[206:209], v[82:85]
	v_mfma_f32_16x16x32_bf16 v[110:113], v[160:163], v[176:179], v[110:113]
	v_mfma_f32_16x16x32_bf16 v[106:109], v[168:171], v[176:179], v[106:109]
	v_mfma_f32_16x16x32_bf16 v[94:97], v[160:163], v[184:187], v[94:97]
	v_mfma_f32_16x16x32_bf16 v[90:93], v[168:171], v[184:187], v[90:93]
	v_mfma_f32_16x16x32_bf16 v[78:81], v[160:163], v[192:195], v[78:81]
	v_mfma_f32_16x16x32_bf16 v[74:77], v[168:171], v[192:195], v[74:77]
	v_mfma_f32_16x16x32_bf16 v[70:73], v[160:163], v[200:203], v[70:73]
	v_mfma_f32_16x16x32_bf16 v[66:69], v[168:171], v[200:203], v[66:69]
	v_mfma_f32_16x16x32_bf16 v[110:113], v[164:167], v[180:183], v[110:113]
	v_mfma_f32_16x16x32_bf16 v[106:109], v[172:175], v[180:183], v[106:109]
	v_mfma_f32_16x16x32_bf16 v[94:97], v[164:167], v[188:191], v[94:97]
	v_mfma_f32_16x16x32_bf16 v[90:93], v[172:175], v[188:191], v[90:93]
	v_mfma_f32_16x16x32_bf16 v[78:81], v[164:167], v[196:199], v[78:81]
	v_mfma_f32_16x16x32_bf16 v[74:77], v[172:175], v[196:199], v[74:77]
	v_mfma_f32_16x16x32_bf16 v[70:73], v[164:167], v[206:209], v[70:73]
	v_mfma_f32_16x16x32_bf16 v[66:69], v[172:175], v[206:209], v[66:69]
	s_setprio 0
	s_barrier
	s_mov_b32 m0, s87
	v_lshl_add_u64 v[210:211], s[66:67], 0, v[136:137]
	ds_read_b128 v[176:179], v142 offset:16384
	ds_read_b128 v[180:183], v142 offset:17408
	ds_read_b128 v[184:187], v142 offset:18432
	ds_read_b128 v[188:191], v142 offset:19456
	ds_read_b128 v[192:195], v142 offset:20480
	ds_read_b128 v[196:199], v142 offset:21504
	ds_read_b128 v[200:203], v142 offset:22528
	ds_read_b128 v[206:209], v142 offset:23552
	global_load_lds_dwordx4 v[210:211], off
	v_lshl_add_u64 v[212:213], s[66:67], 0, v[134:135]
	s_mov_b32 m0, s84
	v_lshl_add_u64 v[214:215], s[68:69], 0, v[136:137]
	global_load_lds_dwordx4 v[212:213], off
	s_mov_b32 m0, s86
	v_lshl_add_u64 v[216:217], s[64:65], 0, v[132:133]
	global_load_lds_dwordx4 v[214:215], off
	v_lshl_add_u64 v[214:215], s[68:69], 0, v[134:135]
	s_mov_b32 m0, s85
	s_nop 0
	global_load_lds_dwordx4 v[214:215], off
	v_lshl_add_u64 v[214:215], s[64:65], 0, v[130:131]
	s_mov_b32 m0, s16
	s_nop 0
	global_load_lds_dwordx4 v[214:215], off
	s_mov_b32 m0, s17
	s_nop 0
	global_load_lds_dwordx4 v[216:217], off
	s_waitcnt vmcnt(8)
	s_waitcnt lgkmcnt(0)
	s_setprio 1
	s_barrier
	v_mfma_f32_16x16x32_bf16 v[62:65], v[144:147], v[176:179], v[62:65]
	v_mfma_f32_16x16x32_bf16 v[58:61], v[152:155], v[176:179], v[58:61]
	v_mfma_f32_16x16x32_bf16 v[54:57], v[144:147], v[184:187], v[54:57]
	v_mfma_f32_16x16x32_bf16 v[50:53], v[152:155], v[184:187], v[50:53]
	v_mfma_f32_16x16x32_bf16 v[38:41], v[144:147], v[192:195], v[38:41]
	v_mfma_f32_16x16x32_bf16 v[34:37], v[152:155], v[192:195], v[34:37]
	v_mfma_f32_16x16x32_bf16 v[22:25], v[144:147], v[200:203], v[22:25]
	v_mfma_f32_16x16x32_bf16 v[18:21], v[152:155], v[200:203], v[18:21]
	v_mfma_f32_16x16x32_bf16 v[62:65], v[148:151], v[180:183], v[62:65]
	v_mfma_f32_16x16x32_bf16 v[58:61], v[156:159], v[180:183], v[58:61]
	v_mfma_f32_16x16x32_bf16 v[54:57], v[148:151], v[188:191], v[54:57]
	v_mfma_f32_16x16x32_bf16 v[50:53], v[156:159], v[188:191], v[50:53]
	v_mfma_f32_16x16x32_bf16 v[38:41], v[148:151], v[196:199], v[38:41]
	v_mfma_f32_16x16x32_bf16 v[34:37], v[156:159], v[196:199], v[34:37]
	v_mfma_f32_16x16x32_bf16 v[22:25], v[148:151], v[206:209], v[22:25]
	v_mfma_f32_16x16x32_bf16 v[18:21], v[156:159], v[206:209], v[18:21]
	v_mfma_f32_16x16x32_bf16 v[46:49], v[160:163], v[176:179], v[46:49]
	v_mfma_f32_16x16x32_bf16 v[42:45], v[168:171], v[176:179], v[42:45]
	v_mfma_f32_16x16x32_bf16 v[30:33], v[160:163], v[184:187], v[30:33]
	v_mfma_f32_16x16x32_bf16 v[26:29], v[168:171], v[184:187], v[26:29]
	v_mfma_f32_16x16x32_bf16 v[14:17], v[160:163], v[192:195], v[14:17]
	v_mfma_f32_16x16x32_bf16 v[10:13], v[168:171], v[192:195], v[10:13]
	v_mfma_f32_16x16x32_bf16 v[6:9], v[160:163], v[200:203], v[6:9]
	v_mfma_f32_16x16x32_bf16 v[2:5], v[168:171], v[200:203], v[2:5]
	v_mfma_f32_16x16x32_bf16 v[46:49], v[164:167], v[180:183], v[46:49]
	v_mfma_f32_16x16x32_bf16 v[42:45], v[172:175], v[180:183], v[42:45]
	v_mfma_f32_16x16x32_bf16 v[30:33], v[164:167], v[188:191], v[30:33]
	v_mfma_f32_16x16x32_bf16 v[26:29], v[172:175], v[188:191], v[26:29]
	v_mfma_f32_16x16x32_bf16 v[14:17], v[164:167], v[196:199], v[14:17]
	v_mfma_f32_16x16x32_bf16 v[10:13], v[172:175], v[196:199], v[10:13]
	v_mfma_f32_16x16x32_bf16 v[6:9], v[164:167], v[206:209], v[6:9]
	v_mfma_f32_16x16x32_bf16 v[2:5], v[172:175], v[206:209], v[2:5]
	s_setprio 0
	s_barrier
	v_add_u32_e32 v143, s83, v139
	ds_read_b128 v[144:147], v143
	ds_read_b128 v[148:151], v143 offset:1024
	ds_read_b128 v[152:155], v143 offset:2048
	ds_read_b128 v[156:159], v143 offset:3072
	v_add_u32_e32 v143, s82, v139
	ds_read_b128 v[160:163], v143
	ds_read_b128 v[164:167], v143 offset:1024
	ds_read_b128 v[168:171], v143 offset:2048
	ds_read_b128 v[172:175], v143 offset:3072
	s_mov_b32 m0, s18
	v_lshl_add_u64 v[218:219], s[48:49], 0, v[130:131]
	ds_read_b128 v[176:179], v142 offset:32768
	ds_read_b128 v[180:183], v142 offset:33792
	ds_read_b128 v[184:187], v142 offset:34816
	ds_read_b128 v[188:191], v142 offset:35840
	ds_read_b128 v[192:195], v142 offset:36864
	ds_read_b128 v[196:199], v142 offset:37888
	ds_read_b128 v[200:203], v142 offset:38912
	ds_read_b128 v[206:209], v142 offset:39936
	global_load_lds_dwordx4 v[218:219], off
	v_lshl_add_u64 v[218:219], s[48:49], 0, v[132:133]
	s_mov_b32 m0, s19
	s_nop 0
	global_load_lds_dwordx4 v[218:219], off
	s_waitcnt vmcnt(8)
	s_waitcnt lgkmcnt(0)
	s_setprio 1
	s_barrier
	v_mfma_f32_16x16x32_bf16 v[126:129], v[144:147], v[176:179], v[126:129]
	v_mfma_f32_16x16x32_bf16 v[122:125], v[152:155], v[176:179], v[122:125]
	v_mfma_f32_16x16x32_bf16 v[118:121], v[144:147], v[184:187], v[118:121]
	v_mfma_f32_16x16x32_bf16 v[114:117], v[152:155], v[184:187], v[114:117]
	v_mfma_f32_16x16x32_bf16 v[102:105], v[144:147], v[192:195], v[102:105]
	v_mfma_f32_16x16x32_bf16 v[98:101], v[152:155], v[192:195], v[98:101]
	v_mfma_f32_16x16x32_bf16 v[86:89], v[144:147], v[200:203], v[86:89]
	v_mfma_f32_16x16x32_bf16 v[82:85], v[152:155], v[200:203], v[82:85]
	v_mfma_f32_16x16x32_bf16 v[126:129], v[148:151], v[180:183], v[126:129]
	v_mfma_f32_16x16x32_bf16 v[122:125], v[156:159], v[180:183], v[122:125]
	v_mfma_f32_16x16x32_bf16 v[118:121], v[148:151], v[188:191], v[118:121]
	v_mfma_f32_16x16x32_bf16 v[114:117], v[156:159], v[188:191], v[114:117]
	v_mfma_f32_16x16x32_bf16 v[102:105], v[148:151], v[196:199], v[102:105]
	v_mfma_f32_16x16x32_bf16 v[98:101], v[156:159], v[196:199], v[98:101]
	v_mfma_f32_16x16x32_bf16 v[86:89], v[148:151], v[206:209], v[86:89]
	v_mfma_f32_16x16x32_bf16 v[82:85], v[156:159], v[206:209], v[82:85]
	v_mfma_f32_16x16x32_bf16 v[110:113], v[160:163], v[176:179], v[110:113]
	v_mfma_f32_16x16x32_bf16 v[106:109], v[168:171], v[176:179], v[106:109]
	v_mfma_f32_16x16x32_bf16 v[94:97], v[160:163], v[184:187], v[94:97]
	v_mfma_f32_16x16x32_bf16 v[90:93], v[168:171], v[184:187], v[90:93]
	v_mfma_f32_16x16x32_bf16 v[78:81], v[160:163], v[192:195], v[78:81]
	v_mfma_f32_16x16x32_bf16 v[74:77], v[168:171], v[192:195], v[74:77]
	v_mfma_f32_16x16x32_bf16 v[70:73], v[160:163], v[200:203], v[70:73]
	v_mfma_f32_16x16x32_bf16 v[66:69], v[168:171], v[200:203], v[66:69]
	v_mfma_f32_16x16x32_bf16 v[110:113], v[164:167], v[180:183], v[110:113]
	v_mfma_f32_16x16x32_bf16 v[106:109], v[172:175], v[180:183], v[106:109]
	v_mfma_f32_16x16x32_bf16 v[94:97], v[164:167], v[188:191], v[94:97]
	v_mfma_f32_16x16x32_bf16 v[90:93], v[172:175], v[188:191], v[90:93]
	v_mfma_f32_16x16x32_bf16 v[78:81], v[164:167], v[196:199], v[78:81]
	v_mfma_f32_16x16x32_bf16 v[74:77], v[172:175], v[196:199], v[74:77]
	v_mfma_f32_16x16x32_bf16 v[70:73], v[164:167], v[206:209], v[70:73]
	v_mfma_f32_16x16x32_bf16 v[66:69], v[172:175], v[206:209], v[66:69]
	s_setprio 0
	s_barrier
	s_mov_b32 m0, s81
	v_lshl_add_u64 v[210:211], v[210:211], 0, s[8:9]
	ds_read_b128 v[176:179], v142 offset:49152
	ds_read_b128 v[180:183], v142 offset:50176
	ds_read_b128 v[184:187], v142 offset:51200
	ds_read_b128 v[188:191], v142 offset:52224
	ds_read_b128 v[192:195], v142 offset:53248
	ds_read_b128 v[196:199], v142 offset:54272
	ds_read_b128 v[200:203], v142 offset:55296
	ds_read_b128 v[206:209], v142 offset:56320
	global_load_lds_dwordx4 v[210:211], off
	v_lshl_add_u64 v[210:211], v[212:213], 0, s[8:9]
	s_mov_b32 m0, s79
	s_nop 0
	global_load_lds_dwordx4 v[210:211], off
	v_lshl_add_u64 v[210:211], s[46:47], 0, v[136:137]
	s_mov_b32 m0, s80
	s_nop 0
	global_load_lds_dwordx4 v[210:211], off
	v_lshl_add_u64 v[210:211], s[46:47], 0, v[134:135]
	s_mov_b32 m0, s78
	s_nop 0
	global_load_lds_dwordx4 v[210:211], off
	v_lshl_add_u64 v[210:211], v[214:215], 0, s[8:9]
	s_mov_b32 m0, s30
	s_nop 0
	global_load_lds_dwordx4 v[210:211], off
	v_lshl_add_u64 v[210:211], v[216:217], 0, s[8:9]
	s_mov_b32 m0, s31
	s_nop 0
	global_load_lds_dwordx4 v[210:211], off
	s_waitcnt vmcnt(8)
	s_waitcnt lgkmcnt(0)
	s_setprio 1
	s_barrier
	v_mfma_f32_16x16x32_bf16 v[62:65], v[144:147], v[176:179], v[62:65]
	v_mfma_f32_16x16x32_bf16 v[58:61], v[152:155], v[176:179], v[58:61]
	v_mfma_f32_16x16x32_bf16 v[54:57], v[144:147], v[184:187], v[54:57]
	v_mfma_f32_16x16x32_bf16 v[50:53], v[152:155], v[184:187], v[50:53]
	v_mfma_f32_16x16x32_bf16 v[38:41], v[144:147], v[192:195], v[38:41]
	v_mfma_f32_16x16x32_bf16 v[34:37], v[152:155], v[192:195], v[34:37]
	v_mfma_f32_16x16x32_bf16 v[22:25], v[144:147], v[200:203], v[22:25]
	v_mfma_f32_16x16x32_bf16 v[18:21], v[152:155], v[200:203], v[18:21]
	v_mfma_f32_16x16x32_bf16 v[62:65], v[148:151], v[180:183], v[62:65]
	v_mfma_f32_16x16x32_bf16 v[58:61], v[156:159], v[180:183], v[58:61]
	v_mfma_f32_16x16x32_bf16 v[54:57], v[148:151], v[188:191], v[54:57]
	v_mfma_f32_16x16x32_bf16 v[50:53], v[156:159], v[188:191], v[50:53]
	v_mfma_f32_16x16x32_bf16 v[38:41], v[148:151], v[196:199], v[38:41]
	v_mfma_f32_16x16x32_bf16 v[34:37], v[156:159], v[196:199], v[34:37]
	v_mfma_f32_16x16x32_bf16 v[22:25], v[148:151], v[206:209], v[22:25]
	v_mfma_f32_16x16x32_bf16 v[18:21], v[156:159], v[206:209], v[18:21]
	v_mfma_f32_16x16x32_bf16 v[46:49], v[160:163], v[176:179], v[46:49]
	v_mfma_f32_16x16x32_bf16 v[42:45], v[168:171], v[176:179], v[42:45]
	v_mfma_f32_16x16x32_bf16 v[30:33], v[160:163], v[184:187], v[30:33]
	v_mfma_f32_16x16x32_bf16 v[26:29], v[168:171], v[184:187], v[26:29]
	v_mfma_f32_16x16x32_bf16 v[14:17], v[160:163], v[192:195], v[14:17]
	v_mfma_f32_16x16x32_bf16 v[10:13], v[168:171], v[192:195], v[10:13]
	v_mfma_f32_16x16x32_bf16 v[6:9], v[160:163], v[200:203], v[6:9]
	v_mfma_f32_16x16x32_bf16 v[2:5], v[168:171], v[200:203], v[2:5]
	v_mfma_f32_16x16x32_bf16 v[46:49], v[164:167], v[180:183], v[46:49]
	v_mfma_f32_16x16x32_bf16 v[42:45], v[172:175], v[180:183], v[42:45]
	v_mfma_f32_16x16x32_bf16 v[30:33], v[164:167], v[188:191], v[30:33]
	v_mfma_f32_16x16x32_bf16 v[26:29], v[172:175], v[188:191], v[26:29]
	v_mfma_f32_16x16x32_bf16 v[14:17], v[164:167], v[196:199], v[14:17]
	v_mfma_f32_16x16x32_bf16 v[10:13], v[172:175], v[196:199], v[10:13]
	v_mfma_f32_16x16x32_bf16 v[6:9], v[164:167], v[206:209], v[6:9]
	v_mfma_f32_16x16x32_bf16 v[2:5], v[172:175], v[206:209], v[2:5]
	s_setprio 0
	s_barrier
	s_movk_i32 s48, 0x100
	s_andn2_b64 vcc, exec, s[44:45]
	s_mov_b64 s[46:47], -1
	s_mov_b64 s[44:45], 0
	s_cbranch_vccz .LBB0_313
	s_and_b64 vcc, exec, s[10:11]
	s_cbranch_vccz .LBB0_316
	s_barrier

.LBB0_383:
	s_add_u32 s26, s0, s22
	s_addc_u32 s27, s1, s23
	s_and_b64 s[44:45], s[36:37], exec
	s_cselect_b32 s15, s27, s43
	s_cselect_b32 s39, s26, s42
	s_add_u32 s66, s42, 0x100
	s_addc_u32 s67, s43, 0
	s_mov_b32 s68, -2
	s_mov_b64 s[42:43], 0
	ds_read_b128 v[152:155], v146
	ds_read_b128 v[156:159], v146 offset:1024
	ds_read_b128 v[160:163], v146 offset:2048
	ds_read_b128 v[164:167], v146 offset:3072
	ds_read_b128 v[168:171], v147
	ds_read_b128 v[172:175], v147 offset:1024
	ds_read_b128 v[176:179], v147 offset:2048
	ds_read_b128 v[180:183], v147 offset:3072
	s_add_u32 s44, s42, 0x100
	s_addc_u32 s45, s43, 0
	s_add_u32 s46, s66, s42
	s_addc_u32 s47, s67, s43
	s_cmp_eq_u32 s68, 4
	s_cselect_b32 s48, 0, s44
	s_cselect_b32 s49, 0, s45
	s_cselect_b32 s46, s39, s46
	s_cselect_b32 s47, s15, s47
	s_add_u32 s48, s6, s48
	s_addc_u32 s49, s7, s49
	s_mov_b32 m0, s29
	v_lshl_add_u64 v[218:219], v[138:139], 0, s[42:43]
	ds_read_b128 v[184:187], v148
	ds_read_b128 v[188:191], v148 offset:1024
	ds_read_b128 v[192:195], v148 offset:2048
	ds_read_b128 v[196:199], v148 offset:3072
	ds_read_b128 v[200:203], v148 offset:4096
	ds_read_b128 v[206:209], v148 offset:5120
	ds_read_b128 v[210:213], v148 offset:6144
	ds_read_b128 v[214:217], v148 offset:7168
	global_load_lds_dwordx4 v[218:219], off
	v_lshl_add_u64 v[218:219], v[140:141], 0, s[42:43]
	s_mov_b32 m0, s30
	s_nop 0
	global_load_lds_dwordx4 v[218:219], off
	s_waitcnt vmcnt(8)
	s_waitcnt lgkmcnt(0)
	s_setprio 1
	s_barrier
	v_mfma_f32_16x16x32_bf16 v[126:129], v[152:155], v[184:187], 0
	v_mfma_f32_16x16x32_bf16 v[122:125], v[160:163], v[184:187], 0
	v_mfma_f32_16x16x32_bf16 v[118:121], v[152:155], v[192:195], 0
	v_mfma_f32_16x16x32_bf16 v[114:117], v[160:163], v[192:195], 0
	v_mfma_f32_16x16x32_bf16 v[102:105], v[152:155], v[200:203], 0
	v_mfma_f32_16x16x32_bf16 v[98:101], v[160:163], v[200:203], 0
	v_mfma_f32_16x16x32_bf16 v[86:89], v[152:155], v[210:213], 0
	v_mfma_f32_16x16x32_bf16 v[82:85], v[160:163], v[210:213], 0
	v_mfma_f32_16x16x32_bf16 v[126:129], v[156:159], v[188:191], v[126:129]
	v_mfma_f32_16x16x32_bf16 v[122:125], v[164:167], v[188:191], v[122:125]
	v_mfma_f32_16x16x32_bf16 v[118:121], v[156:159], v[196:199], v[118:121]
	v_mfma_f32_16x16x32_bf16 v[114:117], v[164:167], v[196:199], v[114:117]
	v_mfma_f32_16x16x32_bf16 v[102:105], v[156:159], v[206:209], v[102:105]
	v_mfma_f32_16x16x32_bf16 v[98:101], v[164:167], v[206:209], v[98:101]
	v_mfma_f32_16x16x32_bf16 v[86:89], v[156:159], v[214:217], v[86:89]
	v_mfma_f32_16x16x32_bf16 v[82:85], v[164:167], v[214:217], v[82:85]
	v_mfma_f32_16x16x32_bf16 v[110:113], v[168:171], v[184:187], 0
	v_mfma_f32_16x16x32_bf16 v[106:109], v[176:179], v[184:187], 0
	v_mfma_f32_16x16x32_bf16 v[94:97], v[168:171], v[192:195], 0
	v_mfma_f32_16x16x32_bf16 v[90:93], v[176:179], v[192:195], 0
	v_mfma_f32_16x16x32_bf16 v[78:81], v[168:171], v[200:203], 0
	v_mfma_f32_16x16x32_bf16 v[74:77], v[176:179], v[200:203], 0
	v_mfma_f32_16x16x32_bf16 v[70:73], v[168:171], v[210:213], 0
	v_mfma_f32_16x16x32_bf16 v[66:69], v[176:179], v[210:213], 0
	v_mfma_f32_16x16x32_bf16 v[110:113], v[172:175], v[188:191], v[110:113]
	v_mfma_f32_16x16x32_bf16 v[106:109], v[180:183], v[188:191], v[106:109]
	v_mfma_f32_16x16x32_bf16 v[94:97], v[172:175], v[196:199], v[94:97]
	v_mfma_f32_16x16x32_bf16 v[90:93], v[180:183], v[196:199], v[90:93]
	v_mfma_f32_16x16x32_bf16 v[78:81], v[172:175], v[206:209], v[78:81]
	v_mfma_f32_16x16x32_bf16 v[74:77], v[180:183], v[206:209], v[74:77]
	v_mfma_f32_16x16x32_bf16 v[70:73], v[172:175], v[214:217], v[70:73]
	v_mfma_f32_16x16x32_bf16 v[66:69], v[180:183], v[214:217], v[66:69]
	s_setprio 0
	s_barrier
	s_mov_b32 m0, s31
	v_lshl_add_u64 v[218:219], s[46:47], 0, v[134:135]
	s_add_u32 s42, s46, 0x20000
	ds_read_b128 v[184:187], v148 offset:16384
	ds_read_b128 v[188:191], v148 offset:17408
	ds_read_b128 v[192:195], v148 offset:18432
	ds_read_b128 v[196:199], v148 offset:19456
	ds_read_b128 v[200:203], v148 offset:20480
	ds_read_b128 v[206:209], v148 offset:21504
	ds_read_b128 v[210:213], v148 offset:22528
	ds_read_b128 v[214:217], v148 offset:23552
	global_load_lds_dwordx4 v[218:219], off
	v_lshl_add_u64 v[220:221], s[46:47], 0, v[130:131]
	s_mov_b32 m0, s33
	s_addc_u32 s43, s47, 0
	global_load_lds_dwordx4 v[220:221], off
	v_lshl_add_u64 v[222:223], s[42:43], 0, v[134:135]
	s_mov_b32 m0, s34
	v_lshl_add_u64 v[224:225], s[48:49], 0, v[132:133]
	global_load_lds_dwordx4 v[222:223], off
	v_lshl_add_u64 v[222:223], s[42:43], 0, v[130:131]
	s_mov_b32 m0, s35
	s_nop 0
	global_load_lds_dwordx4 v[222:223], off
	v_lshl_add_u64 v[222:223], s[48:49], 0, v[136:137]
	s_mov_b32 m0, s2
	s_nop 0
	global_load_lds_dwordx4 v[222:223], off
	s_mov_b32 m0, s3
	s_nop 0
	global_load_lds_dwordx4 v[224:225], off
	s_waitcnt vmcnt(8)
	s_waitcnt lgkmcnt(0)
	s_setprio 1
	s_barrier
	v_mfma_f32_16x16x32_bf16 v[62:65], v[152:155], v[184:187], 0
	v_mfma_f32_16x16x32_bf16 v[58:61], v[160:163], v[184:187], 0
	v_mfma_f32_16x16x32_bf16 v[54:57], v[152:155], v[192:195], 0
	v_mfma_f32_16x16x32_bf16 v[50:53], v[160:163], v[192:195], 0
	v_mfma_f32_16x16x32_bf16 v[38:41], v[152:155], v[200:203], 0
	v_mfma_f32_16x16x32_bf16 v[34:37], v[160:163], v[200:203], 0
	v_mfma_f32_16x16x32_bf16 v[22:25], v[152:155], v[210:213], 0
	v_mfma_f32_16x16x32_bf16 v[18:21], v[160:163], v[210:213], 0
	v_mfma_f32_16x16x32_bf16 v[62:65], v[156:159], v[188:191], v[62:65]
	v_mfma_f32_16x16x32_bf16 v[58:61], v[164:167], v[188:191], v[58:61]
	v_mfma_f32_16x16x32_bf16 v[54:57], v[156:159], v[196:199], v[54:57]
	v_mfma_f32_16x16x32_bf16 v[50:53], v[164:167], v[196:199], v[50:53]
	v_mfma_f32_16x16x32_bf16 v[38:41], v[156:159], v[206:209], v[38:41]
	v_mfma_f32_16x16x32_bf16 v[34:37], v[164:167], v[206:209], v[34:37]
	v_mfma_f32_16x16x32_bf16 v[22:25], v[156:159], v[214:217], v[22:25]
	v_mfma_f32_16x16x32_bf16 v[18:21], v[164:167], v[214:217], v[18:21]
	v_mfma_f32_16x16x32_bf16 v[46:49], v[168:171], v[184:187], 0
	v_mfma_f32_16x16x32_bf16 v[42:45], v[176:179], v[184:187], 0
	v_mfma_f32_16x16x32_bf16 v[30:33], v[168:171], v[192:195], 0
	v_mfma_f32_16x16x32_bf16 v[26:29], v[176:179], v[192:195], 0
	v_mfma_f32_16x16x32_bf16 v[14:17], v[168:171], v[200:203], 0
	v_mfma_f32_16x16x32_bf16 v[10:13], v[176:179], v[200:203], 0
	v_mfma_f32_16x16x32_bf16 v[6:9], v[168:171], v[210:213], 0
	v_mfma_f32_16x16x32_bf16 v[2:5], v[176:179], v[210:213], 0
	v_mfma_f32_16x16x32_bf16 v[46:49], v[172:175], v[188:191], v[46:49]
	v_mfma_f32_16x16x32_bf16 v[42:45], v[180:183], v[188:191], v[42:45]
	v_mfma_f32_16x16x32_bf16 v[30:33], v[172:175], v[196:199], v[30:33]
	v_mfma_f32_16x16x32_bf16 v[26:29], v[180:183], v[196:199], v[26:29]
	v_mfma_f32_16x16x32_bf16 v[14:17], v[172:175], v[206:209], v[14:17]
	v_mfma_f32_16x16x32_bf16 v[10:13], v[180:183], v[206:209], v[10:13]
	v_mfma_f32_16x16x32_bf16 v[6:9], v[172:175], v[214:217], v[6:9]
	v_mfma_f32_16x16x32_bf16 v[2:5], v[180:183], v[214:217], v[2:5]
	s_setprio 0
	s_barrier
	ds_read_b128 v[152:155], v149
	ds_read_b128 v[156:159], v149 offset:1024
	ds_read_b128 v[160:163], v149 offset:2048
	ds_read_b128 v[164:167], v149 offset:3072
	ds_read_b128 v[168:171], v150
	ds_read_b128 v[172:175], v150 offset:1024
	ds_read_b128 v[176:179], v150 offset:2048
	ds_read_b128 v[180:183], v150 offset:3072
	s_add_u32 s42, s48, 0x20000
	s_addc_u32 s43, s49, 0
	s_mov_b32 m0, s16
	v_lshl_add_u64 v[226:227], s[42:43], 0, v[136:137]
	ds_read_b128 v[184:187], v148 offset:32768
	ds_read_b128 v[188:191], v148 offset:33792
	ds_read_b128 v[192:195], v148 offset:34816
	ds_read_b128 v[196:199], v148 offset:35840
	ds_read_b128 v[200:203], v148 offset:36864
	ds_read_b128 v[206:209], v148 offset:37888
	ds_read_b128 v[210:213], v148 offset:38912
	ds_read_b128 v[214:217], v148 offset:39936
	global_load_lds_dwordx4 v[226:227], off
	v_lshl_add_u64 v[226:227], s[42:43], 0, v[132:133]
	s_mov_b32 m0, s17
	s_nop 0
	global_load_lds_dwordx4 v[226:227], off
	s_waitcnt vmcnt(8)
	s_waitcnt lgkmcnt(0)
	s_setprio 1
	s_barrier
	v_mfma_f32_16x16x32_bf16 v[126:129], v[152:155], v[184:187], v[126:129]
	v_mfma_f32_16x16x32_bf16 v[122:125], v[160:163], v[184:187], v[122:125]
	v_mfma_f32_16x16x32_bf16 v[118:121], v[152:155], v[192:195], v[118:121]
	v_mfma_f32_16x16x32_bf16 v[114:117], v[160:163], v[192:195], v[114:117]
	v_mfma_f32_16x16x32_bf16 v[102:105], v[152:155], v[200:203], v[102:105]
	v_mfma_f32_16x16x32_bf16 v[98:101], v[160:163], v[200:203], v[98:101]
	v_mfma_f32_16x16x32_bf16 v[86:89], v[152:155], v[210:213], v[86:89]
	v_mfma_f32_16x16x32_bf16 v[82:85], v[160:163], v[210:213], v[82:85]
	v_mfma_f32_16x16x32_bf16 v[126:129], v[156:159], v[188:191], v[126:129]
	v_mfma_f32_16x16x32_bf16 v[122:125], v[164:167], v[188:191], v[122:125]
	v_mfma_f32_16x16x32_bf16 v[118:121], v[156:159], v[196:199], v[118:121]
	v_mfma_f32_16x16x32_bf16 v[114:117], v[164:167], v[196:199], v[114:117]
	v_mfma_f32_16x16x32_bf16 v[102:105], v[156:159], v[206:209], v[102:105]
	v_mfma_f32_16x16x32_bf16 v[98:101], v[164:167], v[206:209], v[98:101]
	v_mfma_f32_16x16x32_bf16 v[86:89], v[156:159], v[214:217], v[86:89]
	v_mfma_f32_16x16x32_bf16 v[82:85], v[164:167], v[214:217], v[82:85]
	v_mfma_f32_16x16x32_bf16 v[110:113], v[168:171], v[184:187], v[110:113]
	v_mfma_f32_16x16x32_bf16 v[106:109], v[176:179], v[184:187], v[106:109]
	v_mfma_f32_16x16x32_bf16 v[94:97], v[168:171], v[192:195], v[94:97]
	v_mfma_f32_16x16x32_bf16 v[90:93], v[176:179], v[192:195], v[90:93]
	v_mfma_f32_16x16x32_bf16 v[78:81], v[168:171], v[200:203], v[78:81]
	v_mfma_f32_16x16x32_bf16 v[74:77], v[176:179], v[200:203], v[74:77]
	v_mfma_f32_16x16x32_bf16 v[70:73], v[168:171], v[210:213], v[70:73]
	v_mfma_f32_16x16x32_bf16 v[66:69], v[176:179], v[210:213], v[66:69]
	v_mfma_f32_16x16x32_bf16 v[110:113], v[172:175], v[188:191], v[110:113]
	v_mfma_f32_16x16x32_bf16 v[106:109], v[180:183], v[188:191], v[106:109]
	v_mfma_f32_16x16x32_bf16 v[94:97], v[172:175], v[196:199], v[94:97]
	v_mfma_f32_16x16x32_bf16 v[90:93], v[180:183], v[196:199], v[90:93]
	v_mfma_f32_16x16x32_bf16 v[78:81], v[172:175], v[206:209], v[78:81]
	v_mfma_f32_16x16x32_bf16 v[74:77], v[180:183], v[206:209], v[74:77]
	v_mfma_f32_16x16x32_bf16 v[70:73], v[172:175], v[214:217], v[70:73]
	v_mfma_f32_16x16x32_bf16 v[66:69], v[180:183], v[214:217], v[66:69]
	s_setprio 0
	s_barrier
	s_mov_b32 m0, s62
	v_lshl_add_u64 v[218:219], v[218:219], 0, s[10:11]
	s_add_u32 s42, s46, 0x20080
	ds_read_b128 v[184:187], v148 offset:49152
	ds_read_b128 v[188:191], v148 offset:50176
	ds_read_b128 v[192:195], v148 offset:51200
	ds_read_b128 v[196:199], v148 offset:52224
	ds_read_b128 v[200:203], v148 offset:53248
	ds_read_b128 v[206:209], v148 offset:54272
	ds_read_b128 v[210:213], v148 offset:55296
	ds_read_b128 v[214:217], v148 offset:56320
	global_load_lds_dwordx4 v[218:219], off
	v_lshl_add_u64 v[218:219], v[220:221], 0, s[10:11]
	s_mov_b32 m0, s63
	s_addc_u32 s43, s47, 0
	global_load_lds_dwordx4 v[218:219], off
	v_lshl_add_u64 v[218:219], s[42:43], 0, v[134:135]
	s_mov_b32 m0, s64
	s_nop 0
	global_load_lds_dwordx4 v[218:219], off
	v_lshl_add_u64 v[218:219], s[42:43], 0, v[130:131]
	s_mov_b32 m0, s65
	s_nop 0
	global_load_lds_dwordx4 v[218:219], off
	v_lshl_add_u64 v[218:219], v[222:223], 0, s[10:11]
	s_mov_b32 m0, s25
	s_nop 0
	global_load_lds_dwordx4 v[218:219], off
	v_lshl_add_u64 v[218:219], v[224:225], 0, s[10:11]
	s_mov_b32 m0, s28
	s_nop 0
	global_load_lds_dwordx4 v[218:219], off
	s_waitcnt vmcnt(8)
	s_waitcnt lgkmcnt(0)
	s_setprio 1
	s_barrier
	v_mfma_f32_16x16x32_bf16 v[62:65], v[152:155], v[184:187], v[62:65]
	v_mfma_f32_16x16x32_bf16 v[58:61], v[160:163], v[184:187], v[58:61]
	v_mfma_f32_16x16x32_bf16 v[54:57], v[152:155], v[192:195], v[54:57]
	v_mfma_f32_16x16x32_bf16 v[50:53], v[160:163], v[192:195], v[50:53]
	v_mfma_f32_16x16x32_bf16 v[38:41], v[152:155], v[200:203], v[38:41]
	v_mfma_f32_16x16x32_bf16 v[34:37], v[160:163], v[200:203], v[34:37]
	v_mfma_f32_16x16x32_bf16 v[22:25], v[152:155], v[210:213], v[22:25]
	v_mfma_f32_16x16x32_bf16 v[18:21], v[160:163], v[210:213], v[18:21]
	v_mfma_f32_16x16x32_bf16 v[62:65], v[156:159], v[188:191], v[62:65]
	v_mfma_f32_16x16x32_bf16 v[58:61], v[164:167], v[188:191], v[58:61]
	v_mfma_f32_16x16x32_bf16 v[54:57], v[156:159], v[196:199], v[54:57]
	v_mfma_f32_16x16x32_bf16 v[50:53], v[164:167], v[196:199], v[50:53]
	v_mfma_f32_16x16x32_bf16 v[38:41], v[156:159], v[206:209], v[38:41]
	v_mfma_f32_16x16x32_bf16 v[34:37], v[164:167], v[206:209], v[34:37]
	v_mfma_f32_16x16x32_bf16 v[22:25], v[156:159], v[214:217], v[22:25]
	v_mfma_f32_16x16x32_bf16 v[18:21], v[164:167], v[214:217], v[18:21]
	v_mfma_f32_16x16x32_bf16 v[46:49], v[168:171], v[184:187], v[46:49]
	v_mfma_f32_16x16x32_bf16 v[42:45], v[176:179], v[184:187], v[42:45]
	v_mfma_f32_16x16x32_bf16 v[30:33], v[168:171], v[192:195], v[30:33]
	v_mfma_f32_16x16x32_bf16 v[26:29], v[176:179], v[192:195], v[26:29]
	v_mfma_f32_16x16x32_bf16 v[14:17], v[168:171], v[200:203], v[14:17]
	v_mfma_f32_16x16x32_bf16 v[10:13], v[176:179], v[200:203], v[10:13]
	v_mfma_f32_16x16x32_bf16 v[6:9], v[168:171], v[210:213], v[6:9]
	v_mfma_f32_16x16x32_bf16 v[2:5], v[176:179], v[210:213], v[2:5]
	v_mfma_f32_16x16x32_bf16 v[46:49], v[172:175], v[188:191], v[46:49]
	v_mfma_f32_16x16x32_bf16 v[42:45], v[180:183], v[188:191], v[42:45]
	v_mfma_f32_16x16x32_bf16 v[30:33], v[172:175], v[196:199], v[30:33]
	v_mfma_f32_16x16x32_bf16 v[26:29], v[180:183], v[196:199], v[26:29]
	v_mfma_f32_16x16x32_bf16 v[14:17], v[172:175], v[206:209], v[14:17]
	v_mfma_f32_16x16x32_bf16 v[10:13], v[180:183], v[206:209], v[10:13]
	v_mfma_f32_16x16x32_bf16 v[6:9], v[172:175], v[214:217], v[6:9]
	v_mfma_f32_16x16x32_bf16 v[2:5], v[180:183], v[214:217], v[2:5]
	s_setprio 0
	s_barrier
	s_add_i32 s68, s68, 2
	s_cmp_gt_u32 s68, 5
	s_mov_b64 s[42:43], s[44:45]
.LBB0_384:
	ds_read_b128 v[152:155], v146
	ds_read_b128 v[156:159], v146 offset:1024
	ds_read_b128 v[160:163], v146 offset:2048
	ds_read_b128 v[164:167], v146 offset:3072
	ds_read_b128 v[168:171], v147
	ds_read_b128 v[172:175], v147 offset:1024
	ds_read_b128 v[176:179], v147 offset:2048
	ds_read_b128 v[180:183], v147 offset:3072
	s_add_u32 s44, s42, 0x100
	s_addc_u32 s45, s43, 0
	s_add_u32 s46, s66, s42
	s_addc_u32 s47, s67, s43
	s_cmp_eq_u32 s68, 4
	s_cselect_b32 s48, 0, s44
	s_cselect_b32 s49, 0, s45
	s_cselect_b32 s46, s39, s46
	s_cselect_b32 s47, s15, s47
	s_add_u32 s48, s6, s48
	s_addc_u32 s49, s7, s49
	s_mov_b32 m0, s29
	v_lshl_add_u64 v[218:219], v[138:139], 0, s[42:43]
	ds_read_b128 v[184:187], v148
	ds_read_b128 v[188:191], v148 offset:1024
	ds_read_b128 v[192:195], v148 offset:2048
	ds_read_b128 v[196:199], v148 offset:3072
	ds_read_b128 v[200:203], v148 offset:4096
	ds_read_b128 v[206:209], v148 offset:5120
	ds_read_b128 v[210:213], v148 offset:6144
	ds_read_b128 v[214:217], v148 offset:7168
	global_load_lds_dwordx4 v[218:219], off
	v_lshl_add_u64 v[218:219], v[140:141], 0, s[42:43]
	s_mov_b32 m0, s30
	s_nop 0
	global_load_lds_dwordx4 v[218:219], off
	s_waitcnt vmcnt(8)
	s_waitcnt lgkmcnt(0)
	s_setprio 1
	s_barrier
	v_mfma_f32_16x16x32_bf16 v[126:129], v[152:155], v[184:187], v[126:129]
	v_mfma_f32_16x16x32_bf16 v[122:125], v[160:163], v[184:187], v[122:125]
	v_mfma_f32_16x16x32_bf16 v[118:121], v[152:155], v[192:195], v[118:121]
	v_mfma_f32_16x16x32_bf16 v[114:117], v[160:163], v[192:195], v[114:117]
	v_mfma_f32_16x16x32_bf16 v[102:105], v[152:155], v[200:203], v[102:105]
	v_mfma_f32_16x16x32_bf16 v[98:101], v[160:163], v[200:203], v[98:101]
	v_mfma_f32_16x16x32_bf16 v[86:89], v[152:155], v[210:213], v[86:89]
	v_mfma_f32_16x16x32_bf16 v[82:85], v[160:163], v[210:213], v[82:85]
	v_mfma_f32_16x16x32_bf16 v[126:129], v[156:159], v[188:191], v[126:129]
	v_mfma_f32_16x16x32_bf16 v[122:125], v[164:167], v[188:191], v[122:125]
	v_mfma_f32_16x16x32_bf16 v[118:121], v[156:159], v[196:199], v[118:121]
	v_mfma_f32_16x16x32_bf16 v[114:117], v[164:167], v[196:199], v[114:117]
	v_mfma_f32_16x16x32_bf16 v[102:105], v[156:159], v[206:209], v[102:105]
	v_mfma_f32_16x16x32_bf16 v[98:101], v[164:167], v[206:209], v[98:101]
	v_mfma_f32_16x16x32_bf16 v[86:89], v[156:159], v[214:217], v[86:89]
	v_mfma_f32_16x16x32_bf16 v[82:85], v[164:167], v[214:217], v[82:85]
	v_mfma_f32_16x16x32_bf16 v[110:113], v[168:171], v[184:187], v[110:113]
	v_mfma_f32_16x16x32_bf16 v[106:109], v[176:179], v[184:187], v[106:109]
	v_mfma_f32_16x16x32_bf16 v[94:97], v[168:171], v[192:195], v[94:97]
	v_mfma_f32_16x16x32_bf16 v[90:93], v[176:179], v[192:195], v[90:93]
	v_mfma_f32_16x16x32_bf16 v[78:81], v[168:171], v[200:203], v[78:81]
	v_mfma_f32_16x16x32_bf16 v[74:77], v[176:179], v[200:203], v[74:77]
	v_mfma_f32_16x16x32_bf16 v[70:73], v[168:171], v[210:213], v[70:73]
	v_mfma_f32_16x16x32_bf16 v[66:69], v[176:179], v[210:213], v[66:69]
	v_mfma_f32_16x16x32_bf16 v[110:113], v[172:175], v[188:191], v[110:113]
	v_mfma_f32_16x16x32_bf16 v[106:109], v[180:183], v[188:191], v[106:109]
	v_mfma_f32_16x16x32_bf16 v[94:97], v[172:175], v[196:199], v[94:97]
	v_mfma_f32_16x16x32_bf16 v[90:93], v[180:183], v[196:199], v[90:93]
	v_mfma_f32_16x16x32_bf16 v[78:81], v[172:175], v[206:209], v[78:81]
	v_mfma_f32_16x16x32_bf16 v[74:77], v[180:183], v[206:209], v[74:77]
	v_mfma_f32_16x16x32_bf16 v[70:73], v[172:175], v[214:217], v[70:73]
	v_mfma_f32_16x16x32_bf16 v[66:69], v[180:183], v[214:217], v[66:69]
	s_setprio 0
	s_barrier
	s_mov_b32 m0, s31
	v_lshl_add_u64 v[218:219], s[46:47], 0, v[134:135]
	s_add_u32 s42, s46, 0x20000
	ds_read_b128 v[184:187], v148 offset:16384
	ds_read_b128 v[188:191], v148 offset:17408
	ds_read_b128 v[192:195], v148 offset:18432
	ds_read_b128 v[196:199], v148 offset:19456
	ds_read_b128 v[200:203], v148 offset:20480
	ds_read_b128 v[206:209], v148 offset:21504
	ds_read_b128 v[210:213], v148 offset:22528
	ds_read_b128 v[214:217], v148 offset:23552
	global_load_lds_dwordx4 v[218:219], off
	v_lshl_add_u64 v[220:221], s[46:47], 0, v[130:131]
	s_mov_b32 m0, s33
	s_addc_u32 s43, s47, 0
	global_load_lds_dwordx4 v[220:221], off
	v_lshl_add_u64 v[222:223], s[42:43], 0, v[134:135]
	s_mov_b32 m0, s34
	v_lshl_add_u64 v[224:225], s[48:49], 0, v[132:133]
	global_load_lds_dwordx4 v[222:223], off
	v_lshl_add_u64 v[222:223], s[42:43], 0, v[130:131]
	s_mov_b32 m0, s35
	s_nop 0
	global_load_lds_dwordx4 v[222:223], off
	v_lshl_add_u64 v[222:223], s[48:49], 0, v[136:137]
	s_mov_b32 m0, s2
	s_nop 0
	global_load_lds_dwordx4 v[222:223], off
	s_mov_b32 m0, s3
	s_nop 0
	global_load_lds_dwordx4 v[224:225], off
	s_waitcnt vmcnt(8)
	s_waitcnt lgkmcnt(0)
	s_setprio 1
	s_barrier
	v_mfma_f32_16x16x32_bf16 v[62:65], v[152:155], v[184:187], v[62:65]
	v_mfma_f32_16x16x32_bf16 v[58:61], v[160:163], v[184:187], v[58:61]
	v_mfma_f32_16x16x32_bf16 v[54:57], v[152:155], v[192:195], v[54:57]
	v_mfma_f32_16x16x32_bf16 v[50:53], v[160:163], v[192:195], v[50:53]
	v_mfma_f32_16x16x32_bf16 v[38:41], v[152:155], v[200:203], v[38:41]
	v_mfma_f32_16x16x32_bf16 v[34:37], v[160:163], v[200:203], v[34:37]
	v_mfma_f32_16x16x32_bf16 v[22:25], v[152:155], v[210:213], v[22:25]
	v_mfma_f32_16x16x32_bf16 v[18:21], v[160:163], v[210:213], v[18:21]
	v_mfma_f32_16x16x32_bf16 v[62:65], v[156:159], v[188:191], v[62:65]
	v_mfma_f32_16x16x32_bf16 v[58:61], v[164:167], v[188:191], v[58:61]
	v_mfma_f32_16x16x32_bf16 v[54:57], v[156:159], v[196:199], v[54:57]
	v_mfma_f32_16x16x32_bf16 v[50:53], v[164:167], v[196:199], v[50:53]
	v_mfma_f32_16x16x32_bf16 v[38:41], v[156:159], v[206:209], v[38:41]
	v_mfma_f32_16x16x32_bf16 v[34:37], v[164:167], v[206:209], v[34:37]
	v_mfma_f32_16x16x32_bf16 v[22:25], v[156:159], v[214:217], v[22:25]
	v_mfma_f32_16x16x32_bf16 v[18:21], v[164:167], v[214:217], v[18:21]
	v_mfma_f32_16x16x32_bf16 v[46:49], v[168:171], v[184:187], v[46:49]
	v_mfma_f32_16x16x32_bf16 v[42:45], v[176:179], v[184:187], v[42:45]
	v_mfma_f32_16x16x32_bf16 v[30:33], v[168:171], v[192:195], v[30:33]
	v_mfma_f32_16x16x32_bf16 v[26:29], v[176:179], v[192:195], v[26:29]
	v_mfma_f32_16x16x32_bf16 v[14:17], v[168:171], v[200:203], v[14:17]
	v_mfma_f32_16x16x32_bf16 v[10:13], v[176:179], v[200:203], v[10:13]
	v_mfma_f32_16x16x32_bf16 v[6:9], v[168:171], v[210:213], v[6:9]
	v_mfma_f32_16x16x32_bf16 v[2:5], v[176:179], v[210:213], v[2:5]
	v_mfma_f32_16x16x32_bf16 v[46:49], v[172:175], v[188:191], v[46:49]
	v_mfma_f32_16x16x32_bf16 v[42:45], v[180:183], v[188:191], v[42:45]
	v_mfma_f32_16x16x32_bf16 v[30:33], v[172:175], v[196:199], v[30:33]
	v_mfma_f32_16x16x32_bf16 v[26:29], v[180:183], v[196:199], v[26:29]
	v_mfma_f32_16x16x32_bf16 v[14:17], v[172:175], v[206:209], v[14:17]
	v_mfma_f32_16x16x32_bf16 v[10:13], v[180:183], v[206:209], v[10:13]
	v_mfma_f32_16x16x32_bf16 v[6:9], v[172:175], v[214:217], v[6:9]
	v_mfma_f32_16x16x32_bf16 v[2:5], v[180:183], v[214:217], v[2:5]
	s_setprio 0
	s_barrier
	ds_read_b128 v[152:155], v149
	ds_read_b128 v[156:159], v149 offset:1024
	ds_read_b128 v[160:163], v149 offset:2048
	ds_read_b128 v[164:167], v149 offset:3072
	ds_read_b128 v[168:171], v150
	ds_read_b128 v[172:175], v150 offset:1024
	ds_read_b128 v[176:179], v150 offset:2048
	ds_read_b128 v[180:183], v150 offset:3072
	s_add_u32 s42, s48, 0x20000
	s_addc_u32 s43, s49, 0
	s_mov_b32 m0, s16
	v_lshl_add_u64 v[226:227], s[42:43], 0, v[136:137]
	ds_read_b128 v[184:187], v148 offset:32768
	ds_read_b128 v[188:191], v148 offset:33792
	ds_read_b128 v[192:195], v148 offset:34816
	ds_read_b128 v[196:199], v148 offset:35840
	ds_read_b128 v[200:203], v148 offset:36864
	ds_read_b128 v[206:209], v148 offset:37888
	ds_read_b128 v[210:213], v148 offset:38912
	ds_read_b128 v[214:217], v148 offset:39936
	global_load_lds_dwordx4 v[226:227], off
	v_lshl_add_u64 v[226:227], s[42:43], 0, v[132:133]
	s_mov_b32 m0, s17
	s_nop 0
	global_load_lds_dwordx4 v[226:227], off
	s_waitcnt vmcnt(8)
	s_waitcnt lgkmcnt(0)
	s_setprio 1
	s_barrier
	v_mfma_f32_16x16x32_bf16 v[126:129], v[152:155], v[184:187], v[126:129]
	v_mfma_f32_16x16x32_bf16 v[122:125], v[160:163], v[184:187], v[122:125]
	v_mfma_f32_16x16x32_bf16 v[118:121], v[152:155], v[192:195], v[118:121]
	v_mfma_f32_16x16x32_bf16 v[114:117], v[160:163], v[192:195], v[114:117]
	v_mfma_f32_16x16x32_bf16 v[102:105], v[152:155], v[200:203], v[102:105]
	v_mfma_f32_16x16x32_bf16 v[98:101], v[160:163], v[200:203], v[98:101]
	v_mfma_f32_16x16x32_bf16 v[86:89], v[152:155], v[210:213], v[86:89]
	v_mfma_f32_16x16x32_bf16 v[82:85], v[160:163], v[210:213], v[82:85]
	v_mfma_f32_16x16x32_bf16 v[126:129], v[156:159], v[188:191], v[126:129]
	v_mfma_f32_16x16x32_bf16 v[122:125], v[164:167], v[188:191], v[122:125]
	v_mfma_f32_16x16x32_bf16 v[118:121], v[156:159], v[196:199], v[118:121]
	v_mfma_f32_16x16x32_bf16 v[114:117], v[164:167], v[196:199], v[114:117]
	v_mfma_f32_16x16x32_bf16 v[102:105], v[156:159], v[206:209], v[102:105]
	v_mfma_f32_16x16x32_bf16 v[98:101], v[164:167], v[206:209], v[98:101]
	v_mfma_f32_16x16x32_bf16 v[86:89], v[156:159], v[214:217], v[86:89]
	v_mfma_f32_16x16x32_bf16 v[82:85], v[164:167], v[214:217], v[82:85]
	v_mfma_f32_16x16x32_bf16 v[110:113], v[168:171], v[184:187], v[110:113]
	v_mfma_f32_16x16x32_bf16 v[106:109], v[176:179], v[184:187], v[106:109]
	v_mfma_f32_16x16x32_bf16 v[94:97], v[168:171], v[192:195], v[94:97]
	v_mfma_f32_16x16x32_bf16 v[90:93], v[176:179], v[192:195], v[90:93]
	v_mfma_f32_16x16x32_bf16 v[78:81], v[168:171], v[200:203], v[78:81]
	v_mfma_f32_16x16x32_bf16 v[74:77], v[176:179], v[200:203], v[74:77]
	v_mfma_f32_16x16x32_bf16 v[70:73], v[168:171], v[210:213], v[70:73]
	v_mfma_f32_16x16x32_bf16 v[66:69], v[176:179], v[210:213], v[66:69]
	v_mfma_f32_16x16x32_bf16 v[110:113], v[172:175], v[188:191], v[110:113]
	v_mfma_f32_16x16x32_bf16 v[106:109], v[180:183], v[188:191], v[106:109]
	v_mfma_f32_16x16x32_bf16 v[94:97], v[172:175], v[196:199], v[94:97]
	v_mfma_f32_16x16x32_bf16 v[90:93], v[180:183], v[196:199], v[90:93]
	v_mfma_f32_16x16x32_bf16 v[78:81], v[172:175], v[206:209], v[78:81]
	v_mfma_f32_16x16x32_bf16 v[74:77], v[180:183], v[206:209], v[74:77]
	v_mfma_f32_16x16x32_bf16 v[70:73], v[172:175], v[214:217], v[70:73]
	v_mfma_f32_16x16x32_bf16 v[66:69], v[180:183], v[214:217], v[66:69]
	s_setprio 0
	s_barrier
	s_mov_b32 m0, s62
	v_lshl_add_u64 v[218:219], v[218:219], 0, s[10:11]
	s_add_u32 s42, s46, 0x20080
	ds_read_b128 v[184:187], v148 offset:49152
	ds_read_b128 v[188:191], v148 offset:50176
	ds_read_b128 v[192:195], v148 offset:51200
	ds_read_b128 v[196:199], v148 offset:52224
	ds_read_b128 v[200:203], v148 offset:53248
	ds_read_b128 v[206:209], v148 offset:54272
	ds_read_b128 v[210:213], v148 offset:55296
	ds_read_b128 v[214:217], v148 offset:56320
	global_load_lds_dwordx4 v[218:219], off
	v_lshl_add_u64 v[218:219], v[220:221], 0, s[10:11]
	s_mov_b32 m0, s63
	s_addc_u32 s43, s47, 0
	global_load_lds_dwordx4 v[218:219], off
	v_lshl_add_u64 v[218:219], s[42:43], 0, v[134:135]
	s_mov_b32 m0, s64
	s_nop 0
	global_load_lds_dwordx4 v[218:219], off
	v_lshl_add_u64 v[218:219], s[42:43], 0, v[130:131]
	s_mov_b32 m0, s65
	s_nop 0
	global_load_lds_dwordx4 v[218:219], off
	v_lshl_add_u64 v[218:219], v[222:223], 0, s[10:11]
	s_mov_b32 m0, s25
	s_nop 0
	global_load_lds_dwordx4 v[218:219], off
	v_lshl_add_u64 v[218:219], v[224:225], 0, s[10:11]
	s_mov_b32 m0, s28
	s_nop 0
	global_load_lds_dwordx4 v[218:219], off
	s_waitcnt vmcnt(8)
	s_waitcnt lgkmcnt(0)
	s_setprio 1
	s_barrier
	v_mfma_f32_16x16x32_bf16 v[62:65], v[152:155], v[184:187], v[62:65]
	v_mfma_f32_16x16x32_bf16 v[58:61], v[160:163], v[184:187], v[58:61]
	v_mfma_f32_16x16x32_bf16 v[54:57], v[152:155], v[192:195], v[54:57]
	v_mfma_f32_16x16x32_bf16 v[50:53], v[160:163], v[192:195], v[50:53]
	v_mfma_f32_16x16x32_bf16 v[38:41], v[152:155], v[200:203], v[38:41]
	v_mfma_f32_16x16x32_bf16 v[34:37], v[160:163], v[200:203], v[34:37]
	v_mfma_f32_16x16x32_bf16 v[22:25], v[152:155], v[210:213], v[22:25]
	v_mfma_f32_16x16x32_bf16 v[18:21], v[160:163], v[210:213], v[18:21]
	v_mfma_f32_16x16x32_bf16 v[62:65], v[156:159], v[188:191], v[62:65]
	v_mfma_f32_16x16x32_bf16 v[58:61], v[164:167], v[188:191], v[58:61]
	v_mfma_f32_16x16x32_bf16 v[54:57], v[156:159], v[196:199], v[54:57]
	v_mfma_f32_16x16x32_bf16 v[50:53], v[164:167], v[196:199], v[50:53]
	v_mfma_f32_16x16x32_bf16 v[38:41], v[156:159], v[206:209], v[38:41]
	v_mfma_f32_16x16x32_bf16 v[34:37], v[164:167], v[206:209], v[34:37]
	v_mfma_f32_16x16x32_bf16 v[22:25], v[156:159], v[214:217], v[22:25]
	v_mfma_f32_16x16x32_bf16 v[18:21], v[164:167], v[214:217], v[18:21]
	v_mfma_f32_16x16x32_bf16 v[46:49], v[168:171], v[184:187], v[46:49]
	v_mfma_f32_16x16x32_bf16 v[42:45], v[176:179], v[184:187], v[42:45]
	v_mfma_f32_16x16x32_bf16 v[30:33], v[168:171], v[192:195], v[30:33]
	v_mfma_f32_16x16x32_bf16 v[26:29], v[176:179], v[192:195], v[26:29]
	v_mfma_f32_16x16x32_bf16 v[14:17], v[168:171], v[200:203], v[14:17]
	v_mfma_f32_16x16x32_bf16 v[10:13], v[176:179], v[200:203], v[10:13]
	v_mfma_f32_16x16x32_bf16 v[6:9], v[168:171], v[210:213], v[6:9]
	v_mfma_f32_16x16x32_bf16 v[2:5], v[176:179], v[210:213], v[2:5]
	v_mfma_f32_16x16x32_bf16 v[46:49], v[172:175], v[188:191], v[46:49]
	v_mfma_f32_16x16x32_bf16 v[42:45], v[180:183], v[188:191], v[42:45]
	v_mfma_f32_16x16x32_bf16 v[30:33], v[172:175], v[196:199], v[30:33]
	v_mfma_f32_16x16x32_bf16 v[26:29], v[180:183], v[196:199], v[26:29]
	v_mfma_f32_16x16x32_bf16 v[14:17], v[172:175], v[206:209], v[14:17]
	v_mfma_f32_16x16x32_bf16 v[10:13], v[180:183], v[206:209], v[10:13]
	v_mfma_f32_16x16x32_bf16 v[6:9], v[172:175], v[214:217], v[6:9]
	v_mfma_f32_16x16x32_bf16 v[2:5], v[180:183], v[214:217], v[2:5]
	s_setprio 0
	s_barrier
	s_add_i32 s68, s68, 2
	s_cmp_gt_u32 s68, 5
	s_mov_b64 s[42:43], s[44:45]
	s_cbranch_scc0 .LBB0_384
	s_and_b64 vcc, exec, s[12:13]
	s_cbranch_vccz .LBB0_387
	s_barrier

.LBB0_406:
	s_lshl_b32 s74, s12, 7
	s_add_i32 s12, s12, 2
	v_cndmask_b32_e64 v138, 0, 1, s[66:67]
	s_lshl_b64 s[66:67], s[12:13], 7
	s_and_b64 s[68:69], s[64:65], exec
	s_cselect_b32 s66, 0, s66
	s_cselect_b32 s67, 0, s67
	s_add_u32 s70, s8, s66
	s_addc_u32 s71, s9, s67
	s_lshl_b64 s[66:67], s[12:13], 12
	s_add_u32 s12, s48, s66
	s_addc_u32 s66, s49, s67
	s_and_b64 s[64:65], s[64:65], exec
	s_cselect_b32 s73, s14, s66
	s_cselect_b32 s72, s15, s12
	s_add_u32 s76, s10, s74
	s_addc_u32 s77, s11, 0
	s_add_i32 s91, s62, s16
	s_add_i32 m0, s17, 0xc000
	s_add_i32 s92, s17, 0xe000
	s_add_i32 s88, s91, 0x2000
	s_add_u32 s74, s72, 0x10000
	ds_read_b128 v[146:149], v141
	ds_read_b128 v[150:153], v141 offset:1024
	ds_read_b128 v[154:157], v141 offset:2048
	ds_read_b128 v[158:161], v141 offset:3072
	ds_read_b128 v[162:165], v143
	ds_read_b128 v[166:169], v143 offset:1024
	ds_read_b128 v[170:173], v143 offset:2048
	ds_read_b128 v[174:177], v143 offset:3072
	s_addc_u32 s75, s73, 0
	s_add_i32 s90, s63, s16
	s_add_i32 s89, s90, 0x2000
	s_add_i32 s87, 0, 0x18000
	s_add_i32 s86, 0, 0x1c000
	s_add_u32 s68, s70, 0x10000
	s_addc_u32 s69, s71, 0
	s_add_u32 s64, s72, 0x1000
	s_addc_u32 s65, s73, 0
	s_add_i32 s85, s87, s16
	s_add_i32 s83, s85, 0x2000
	s_add_u32 s66, s72, 0x11000
	s_addc_u32 s67, s73, 0
	s_add_i32 s84, s86, s16
	s_add_i32 s12, s84, 0x2000
	v_cmp_ne_u32_e32 vcc, 1, v138
	v_lshl_add_u64 v[202:203], s[76:77], 0, v[136:137]
	v_lshl_add_u64 v[202:203], v[202:203], 0, s[36:37]
	ds_read_b128 v[178:181], v144
	ds_read_b128 v[182:185], v144 offset:1024
	ds_read_b128 v[186:189], v144 offset:2048
	ds_read_b128 v[190:193], v144 offset:3072
	ds_read_b128 v[194:197], v144 offset:4096
	ds_read_b128 v[198:201], v144 offset:5120
	ds_read_b128 v[206:209], v144 offset:6144
	ds_read_b128 v[210:213], v144 offset:7168
	global_load_lds_dwordx4 v[202:203], off
	v_lshl_add_u64 v[202:203], s[76:77], 0, v[132:133]
	v_lshl_add_u64 v[202:203], v[202:203], 0, s[36:37]
	s_mov_b32 m0, s92
	s_nop 0
	global_load_lds_dwordx4 v[202:203], off
	s_waitcnt vmcnt(8)
	s_waitcnt lgkmcnt(0)
	s_setprio 1
	s_barrier
	v_mfma_f32_16x16x32_bf16 v[126:129], v[146:149], v[178:181], v[126:129]
	v_mfma_f32_16x16x32_bf16 v[122:125], v[154:157], v[178:181], v[122:125]
	v_mfma_f32_16x16x32_bf16 v[118:121], v[146:149], v[186:189], v[118:121]
	v_mfma_f32_16x16x32_bf16 v[110:113], v[154:157], v[186:189], v[110:113]
	v_mfma_f32_16x16x32_bf16 v[102:105], v[146:149], v[194:197], v[102:105]
	v_mfma_f32_16x16x32_bf16 v[98:101], v[154:157], v[194:197], v[98:101]
	v_mfma_f32_16x16x32_bf16 v[86:89], v[146:149], v[206:209], v[86:89]
	v_mfma_f32_16x16x32_bf16 v[82:85], v[154:157], v[206:209], v[82:85]
	v_mfma_f32_16x16x32_bf16 v[126:129], v[150:153], v[182:185], v[126:129]
	v_mfma_f32_16x16x32_bf16 v[122:125], v[158:161], v[182:185], v[122:125]
	v_mfma_f32_16x16x32_bf16 v[118:121], v[150:153], v[190:193], v[118:121]
	v_mfma_f32_16x16x32_bf16 v[110:113], v[158:161], v[190:193], v[110:113]
	v_mfma_f32_16x16x32_bf16 v[102:105], v[150:153], v[198:201], v[102:105]
	v_mfma_f32_16x16x32_bf16 v[98:101], v[158:161], v[198:201], v[98:101]
	v_mfma_f32_16x16x32_bf16 v[86:89], v[150:153], v[210:213], v[86:89]
	v_mfma_f32_16x16x32_bf16 v[82:85], v[158:161], v[210:213], v[82:85]
	v_mfma_f32_16x16x32_bf16 v[114:117], v[162:165], v[178:181], v[114:117]
	v_mfma_f32_16x16x32_bf16 v[106:109], v[170:173], v[178:181], v[106:109]
	v_mfma_f32_16x16x32_bf16 v[94:97], v[162:165], v[186:189], v[94:97]
	v_mfma_f32_16x16x32_bf16 v[90:93], v[170:173], v[186:189], v[90:93]
	v_mfma_f32_16x16x32_bf16 v[78:81], v[162:165], v[194:197], v[78:81]
	v_mfma_f32_16x16x32_bf16 v[74:77], v[170:173], v[194:197], v[74:77]
	v_mfma_f32_16x16x32_bf16 v[70:73], v[162:165], v[206:209], v[70:73]
	v_mfma_f32_16x16x32_bf16 v[66:69], v[170:173], v[206:209], v[66:69]
	v_mfma_f32_16x16x32_bf16 v[114:117], v[166:169], v[182:185], v[114:117]
	v_mfma_f32_16x16x32_bf16 v[106:109], v[174:177], v[182:185], v[106:109]
	v_mfma_f32_16x16x32_bf16 v[94:97], v[166:169], v[190:193], v[94:97]
	v_mfma_f32_16x16x32_bf16 v[90:93], v[174:177], v[190:193], v[90:93]
	v_mfma_f32_16x16x32_bf16 v[78:81], v[166:169], v[198:201], v[78:81]
	v_mfma_f32_16x16x32_bf16 v[74:77], v[174:177], v[198:201], v[74:77]
	v_mfma_f32_16x16x32_bf16 v[70:73], v[166:169], v[210:213], v[70:73]
	v_mfma_f32_16x16x32_bf16 v[66:69], v[174:177], v[210:213], v[66:69]
	s_setprio 0
	s_barrier
	s_mov_b32 m0, s91
	v_lshl_add_u64 v[202:203], s[72:73], 0, v[134:135]
	ds_read_b128 v[178:181], v144 offset:16384
	ds_read_b128 v[182:185], v144 offset:17408
	ds_read_b128 v[186:189], v144 offset:18432
	ds_read_b128 v[190:193], v144 offset:19456
	ds_read_b128 v[194:197], v144 offset:20480
	ds_read_b128 v[198:201], v144 offset:21504
	ds_read_b128 v[206:209], v144 offset:22528
	ds_read_b128 v[210:213], v144 offset:23552
	global_load_lds_dwordx4 v[202:203], off
	v_lshl_add_u64 v[202:203], s[72:73], 0, v[130:131]
	s_mov_b32 m0, s88
	v_lshl_add_u64 v[214:215], s[70:71], 0, v[132:133]
	global_load_lds_dwordx4 v[202:203], off
	v_lshl_add_u64 v[202:203], s[74:75], 0, v[134:135]
	s_mov_b32 m0, s90
	s_nop 0
	global_load_lds_dwordx4 v[202:203], off
	v_lshl_add_u64 v[202:203], s[74:75], 0, v[130:131]
	s_mov_b32 m0, s89
	s_nop 0
	global_load_lds_dwordx4 v[202:203], off
	v_lshl_add_u64 v[202:203], s[70:71], 0, v[136:137]
	s_mov_b32 m0, s17
	s_nop 0
	global_load_lds_dwordx4 v[202:203], off
	s_mov_b32 m0, s18
	s_nop 0
	global_load_lds_dwordx4 v[214:215], off
	s_waitcnt vmcnt(8)
	s_waitcnt lgkmcnt(0)
	s_setprio 1
	s_barrier
	v_mfma_f32_16x16x32_bf16 v[62:65], v[146:149], v[178:181], v[62:65]
	v_mfma_f32_16x16x32_bf16 v[58:61], v[154:157], v[178:181], v[58:61]
	v_mfma_f32_16x16x32_bf16 v[54:57], v[146:149], v[186:189], v[54:57]
	v_mfma_f32_16x16x32_bf16 v[50:53], v[154:157], v[186:189], v[50:53]
	v_mfma_f32_16x16x32_bf16 v[38:41], v[146:149], v[194:197], v[38:41]
	v_mfma_f32_16x16x32_bf16 v[34:37], v[154:157], v[194:197], v[34:37]
	v_mfma_f32_16x16x32_bf16 v[22:25], v[146:149], v[206:209], v[22:25]
	v_mfma_f32_16x16x32_bf16 v[18:21], v[154:157], v[206:209], v[18:21]
	v_mfma_f32_16x16x32_bf16 v[62:65], v[150:153], v[182:185], v[62:65]
	v_mfma_f32_16x16x32_bf16 v[58:61], v[158:161], v[182:185], v[58:61]
	v_mfma_f32_16x16x32_bf16 v[54:57], v[150:153], v[190:193], v[54:57]
	v_mfma_f32_16x16x32_bf16 v[50:53], v[158:161], v[190:193], v[50:53]
	v_mfma_f32_16x16x32_bf16 v[38:41], v[150:153], v[198:201], v[38:41]
	v_mfma_f32_16x16x32_bf16 v[34:37], v[158:161], v[198:201], v[34:37]
	v_mfma_f32_16x16x32_bf16 v[22:25], v[150:153], v[210:213], v[22:25]
	v_mfma_f32_16x16x32_bf16 v[18:21], v[158:161], v[210:213], v[18:21]
	v_mfma_f32_16x16x32_bf16 v[46:49], v[162:165], v[178:181], v[46:49]
	v_mfma_f32_16x16x32_bf16 v[42:45], v[170:173], v[178:181], v[42:45]
	v_mfma_f32_16x16x32_bf16 v[30:33], v[162:165], v[186:189], v[30:33]
	v_mfma_f32_16x16x32_bf16 v[26:29], v[170:173], v[186:189], v[26:29]
	v_mfma_f32_16x16x32_bf16 v[14:17], v[162:165], v[194:197], v[14:17]
	v_mfma_f32_16x16x32_bf16 v[10:13], v[170:173], v[194:197], v[10:13]
	v_mfma_f32_16x16x32_bf16 v[6:9], v[162:165], v[206:209], v[6:9]
	v_mfma_f32_16x16x32_bf16 v[2:5], v[170:173], v[206:209], v[2:5]
	v_mfma_f32_16x16x32_bf16 v[46:49], v[166:169], v[182:185], v[46:49]
	v_mfma_f32_16x16x32_bf16 v[42:45], v[174:177], v[182:185], v[42:45]
	v_mfma_f32_16x16x32_bf16 v[30:33], v[166:169], v[190:193], v[30:33]
	v_mfma_f32_16x16x32_bf16 v[26:29], v[174:177], v[190:193], v[26:29]
	v_mfma_f32_16x16x32_bf16 v[14:17], v[166:169], v[198:201], v[14:17]
	v_mfma_f32_16x16x32_bf16 v[10:13], v[174:177], v[198:201], v[10:13]
	v_mfma_f32_16x16x32_bf16 v[6:9], v[166:169], v[210:213], v[6:9]
	v_mfma_f32_16x16x32_bf16 v[2:5], v[174:177], v[210:213], v[2:5]
	s_setprio 0
	s_barrier
	v_add_u32_e32 v138, s87, v140
	ds_read_b128 v[146:149], v138
	ds_read_b128 v[150:153], v138 offset:1024
	ds_read_b128 v[154:157], v138 offset:2048
	ds_read_b128 v[158:161], v138 offset:3072
	v_add_u32_e32 v138, s86, v140
	ds_read_b128 v[162:165], v138
	ds_read_b128 v[166:169], v138 offset:1024
	ds_read_b128 v[170:173], v138 offset:2048
	ds_read_b128 v[174:177], v138 offset:3072
	s_mov_b32 m0, s19
	v_lshl_add_u64 v[216:217], s[68:69], 0, v[136:137]
	ds_read_b128 v[178:181], v144 offset:32768
	ds_read_b128 v[182:185], v144 offset:33792
	ds_read_b128 v[186:189], v144 offset:34816
	ds_read_b128 v[190:193], v144 offset:35840
	ds_read_b128 v[194:197], v144 offset:36864
	ds_read_b128 v[198:201], v144 offset:37888
	ds_read_b128 v[206:209], v144 offset:38912
	ds_read_b128 v[210:213], v144 offset:39936
	global_load_lds_dwordx4 v[216:217], off
	v_lshl_add_u64 v[216:217], s[68:69], 0, v[132:133]
	s_mov_b32 m0, s24
	s_nop 0
	global_load_lds_dwordx4 v[216:217], off
	s_waitcnt vmcnt(8)
	s_waitcnt lgkmcnt(0)
	s_setprio 1
	s_barrier
	v_mfma_f32_16x16x32_bf16 v[126:129], v[146:149], v[178:181], v[126:129]
	v_mfma_f32_16x16x32_bf16 v[122:125], v[154:157], v[178:181], v[122:125]
	v_mfma_f32_16x16x32_bf16 v[118:121], v[146:149], v[186:189], v[118:121]
	v_mfma_f32_16x16x32_bf16 v[110:113], v[154:157], v[186:189], v[110:113]
	v_mfma_f32_16x16x32_bf16 v[102:105], v[146:149], v[194:197], v[102:105]
	v_mfma_f32_16x16x32_bf16 v[98:101], v[154:157], v[194:197], v[98:101]
	v_mfma_f32_16x16x32_bf16 v[86:89], v[146:149], v[206:209], v[86:89]
	v_mfma_f32_16x16x32_bf16 v[82:85], v[154:157], v[206:209], v[82:85]
	v_mfma_f32_16x16x32_bf16 v[126:129], v[150:153], v[182:185], v[126:129]
	v_mfma_f32_16x16x32_bf16 v[122:125], v[158:161], v[182:185], v[122:125]
	v_mfma_f32_16x16x32_bf16 v[118:121], v[150:153], v[190:193], v[118:121]
	v_mfma_f32_16x16x32_bf16 v[110:113], v[158:161], v[190:193], v[110:113]
	v_mfma_f32_16x16x32_bf16 v[102:105], v[150:153], v[198:201], v[102:105]
	v_mfma_f32_16x16x32_bf16 v[98:101], v[158:161], v[198:201], v[98:101]
	v_mfma_f32_16x16x32_bf16 v[86:89], v[150:153], v[210:213], v[86:89]
	v_mfma_f32_16x16x32_bf16 v[82:85], v[158:161], v[210:213], v[82:85]
	v_mfma_f32_16x16x32_bf16 v[114:117], v[162:165], v[178:181], v[114:117]
	v_mfma_f32_16x16x32_bf16 v[106:109], v[170:173], v[178:181], v[106:109]
	v_mfma_f32_16x16x32_bf16 v[94:97], v[162:165], v[186:189], v[94:97]
	v_mfma_f32_16x16x32_bf16 v[90:93], v[170:173], v[186:189], v[90:93]
	v_mfma_f32_16x16x32_bf16 v[78:81], v[162:165], v[194:197], v[78:81]
	v_mfma_f32_16x16x32_bf16 v[74:77], v[170:173], v[194:197], v[74:77]
	v_mfma_f32_16x16x32_bf16 v[70:73], v[162:165], v[206:209], v[70:73]
	v_mfma_f32_16x16x32_bf16 v[66:69], v[170:173], v[206:209], v[66:69]
	v_mfma_f32_16x16x32_bf16 v[114:117], v[166:169], v[182:185], v[114:117]
	v_mfma_f32_16x16x32_bf16 v[106:109], v[174:177], v[182:185], v[106:109]
	v_mfma_f32_16x16x32_bf16 v[94:97], v[166:169], v[190:193], v[94:97]
	v_mfma_f32_16x16x32_bf16 v[90:93], v[174:177], v[190:193], v[90:93]
	v_mfma_f32_16x16x32_bf16 v[78:81], v[166:169], v[198:201], v[78:81]
	v_mfma_f32_16x16x32_bf16 v[74:77], v[174:177], v[198:201], v[74:77]
	v_mfma_f32_16x16x32_bf16 v[70:73], v[166:169], v[210:213], v[70:73]
	v_mfma_f32_16x16x32_bf16 v[66:69], v[174:177], v[210:213], v[66:69]
	s_setprio 0
	s_barrier
	s_mov_b32 m0, s85
	v_lshl_add_u64 v[216:217], s[64:65], 0, v[134:135]
	ds_read_b128 v[178:181], v144 offset:49152
	ds_read_b128 v[182:185], v144 offset:50176
	ds_read_b128 v[186:189], v144 offset:51200
	ds_read_b128 v[190:193], v144 offset:52224
	ds_read_b128 v[194:197], v144 offset:53248
	ds_read_b128 v[198:201], v144 offset:54272
	ds_read_b128 v[206:209], v144 offset:55296
	ds_read_b128 v[210:213], v144 offset:56320
	global_load_lds_dwordx4 v[216:217], off
	v_lshl_add_u64 v[216:217], s[64:65], 0, v[130:131]
	s_mov_b32 m0, s83
	v_lshl_add_u64 v[202:203], v[202:203], 0, s[36:37]
	global_load_lds_dwordx4 v[216:217], off
	v_lshl_add_u64 v[216:217], s[66:67], 0, v[134:135]
	s_mov_b32 m0, s84
	s_nop 0
	global_load_lds_dwordx4 v[216:217], off
	v_lshl_add_u64 v[216:217], s[66:67], 0, v[130:131]
	s_mov_b32 m0, s12
	s_nop 0
	global_load_lds_dwordx4 v[216:217], off
	s_mov_b32 m0, s31
	s_nop 0
	global_load_lds_dwordx4 v[202:203], off
	v_lshl_add_u64 v[202:203], v[214:215], 0, s[36:37]
	s_mov_b32 m0, s33
	s_nop 0
	global_load_lds_dwordx4 v[202:203], off
	s_waitcnt vmcnt(8)
	s_waitcnt lgkmcnt(0)
	s_setprio 1
	s_barrier
	v_mfma_f32_16x16x32_bf16 v[62:65], v[146:149], v[178:181], v[62:65]
	v_mfma_f32_16x16x32_bf16 v[58:61], v[154:157], v[178:181], v[58:61]
	v_mfma_f32_16x16x32_bf16 v[54:57], v[146:149], v[186:189], v[54:57]
	v_mfma_f32_16x16x32_bf16 v[50:53], v[154:157], v[186:189], v[50:53]
	v_mfma_f32_16x16x32_bf16 v[38:41], v[146:149], v[194:197], v[38:41]
	v_mfma_f32_16x16x32_bf16 v[34:37], v[154:157], v[194:197], v[34:37]
	v_mfma_f32_16x16x32_bf16 v[22:25], v[146:149], v[206:209], v[22:25]
	v_mfma_f32_16x16x32_bf16 v[18:21], v[154:157], v[206:209], v[18:21]
	v_mfma_f32_16x16x32_bf16 v[62:65], v[150:153], v[182:185], v[62:65]
	v_mfma_f32_16x16x32_bf16 v[58:61], v[158:161], v[182:185], v[58:61]
	v_mfma_f32_16x16x32_bf16 v[54:57], v[150:153], v[190:193], v[54:57]
	v_mfma_f32_16x16x32_bf16 v[50:53], v[158:161], v[190:193], v[50:53]
	v_mfma_f32_16x16x32_bf16 v[38:41], v[150:153], v[198:201], v[38:41]
	v_mfma_f32_16x16x32_bf16 v[34:37], v[158:161], v[198:201], v[34:37]
	v_mfma_f32_16x16x32_bf16 v[22:25], v[150:153], v[210:213], v[22:25]
	v_mfma_f32_16x16x32_bf16 v[18:21], v[158:161], v[210:213], v[18:21]
	v_mfma_f32_16x16x32_bf16 v[46:49], v[162:165], v[178:181], v[46:49]
	v_mfma_f32_16x16x32_bf16 v[42:45], v[170:173], v[178:181], v[42:45]
	v_mfma_f32_16x16x32_bf16 v[30:33], v[162:165], v[186:189], v[30:33]
	v_mfma_f32_16x16x32_bf16 v[26:29], v[170:173], v[186:189], v[26:29]
	v_mfma_f32_16x16x32_bf16 v[14:17], v[162:165], v[194:197], v[14:17]
	v_mfma_f32_16x16x32_bf16 v[10:13], v[170:173], v[194:197], v[10:13]
	v_mfma_f32_16x16x32_bf16 v[6:9], v[162:165], v[206:209], v[6:9]
	v_mfma_f32_16x16x32_bf16 v[2:5], v[170:173], v[206:209], v[2:5]
	v_mfma_f32_16x16x32_bf16 v[46:49], v[166:169], v[182:185], v[46:49]
	v_mfma_f32_16x16x32_bf16 v[42:45], v[174:177], v[182:185], v[42:45]
	v_mfma_f32_16x16x32_bf16 v[30:33], v[166:169], v[190:193], v[30:33]
	v_mfma_f32_16x16x32_bf16 v[26:29], v[174:177], v[190:193], v[26:29]
	v_mfma_f32_16x16x32_bf16 v[14:17], v[166:169], v[198:201], v[14:17]
	v_mfma_f32_16x16x32_bf16 v[10:13], v[174:177], v[198:201], v[10:13]
	v_mfma_f32_16x16x32_bf16 v[6:9], v[166:169], v[210:213], v[6:9]
	v_mfma_f32_16x16x32_bf16 v[2:5], v[174:177], v[210:213], v[2:5]
	s_setprio 0
	s_barrier
	s_mov_b64 s[66:67], 0
	s_mov_b64 s[64:65], -1
	s_mov_b32 s12, 2
	s_cbranch_vccz .LBB0_406
	s_and_b64 vcc, exec, s[22:23]
	s_cbranch_vccz .LBB0_409
	s_barrier

.LBB0_476:
	s_add_u32 s22, s2, s49
	s_addc_u32 s23, s3, s29
	s_and_b64 s[26:27], s[20:21], exec
	s_cselect_b32 s63, s23, s37
	s_cselect_b32 s64, s22, s36
	s_add_u32 s26, s16, s12
	s_addc_u32 s27, s17, s13
	s_and_b64 s[42:43], s[20:21], exec
	s_cselect_b32 s65, s27, s39
	s_cselect_b32 s66, s26, s38
	s_add_u32 s36, s36, 0x20080
	s_addc_u32 s37, s37, 0
	s_add_u32 s67, s38, 0x100
	s_addc_u32 s68, s39, 0
	s_mov_b32 s69, -2
	ds_read_b128 v[148:151], v144
	ds_read_b128 v[152:155], v144 offset:1024
	ds_read_b128 v[156:159], v144 offset:2048
	ds_read_b128 v[160:163], v144 offset:3072
	ds_read_b128 v[164:167], v145
	ds_read_b128 v[168:171], v145 offset:1024
	ds_read_b128 v[172:175], v145 offset:2048
	ds_read_b128 v[176:179], v145 offset:3072
	s_add_u32 s38, s36, 0xfffe0080
	s_addc_u32 s39, s37, -1
	s_cmp_eq_u32 s69, 4
	s_cselect_b32 s43, s63, s39
	s_cselect_b32 s42, s64, s38
	s_cselect_b32 s39, s65, s68
	s_cselect_b32 s38, s66, s67
	v_lshl_add_u64 v[214:215], s[36:37], 0, v[138:139]
	s_add_i32 m0, s19, 0xc000
	ds_read_b128 v[180:183], v146
	ds_read_b128 v[184:187], v146 offset:1024
	ds_read_b128 v[188:191], v146 offset:2048
	ds_read_b128 v[192:195], v146 offset:3072
	ds_read_b128 v[196:199], v146 offset:4096
	ds_read_b128 v[200:203], v146 offset:5120
	ds_read_b128 v[206:209], v146 offset:6144
	ds_read_b128 v[210:213], v146 offset:7168
	global_load_lds_dwordx4 v[214:215], off
	v_lshl_add_u64 v[214:215], s[36:37], 0, v[140:141]
	s_add_i32 m0, s19, 0xe000
	s_nop 0
	global_load_lds_dwordx4 v[214:215], off
	s_waitcnt vmcnt(8)
	s_waitcnt lgkmcnt(0)
	s_setprio 1
	s_barrier
	v_mfma_f32_16x16x32_bf16 v[126:129], v[148:151], v[180:183], 0
	v_mfma_f32_16x16x32_bf16 v[122:125], v[156:159], v[180:183], 0
	v_mfma_f32_16x16x32_bf16 v[118:121], v[148:151], v[188:191], 0
	v_mfma_f32_16x16x32_bf16 v[114:117], v[156:159], v[188:191], 0
	v_mfma_f32_16x16x32_bf16 v[102:105], v[148:151], v[196:199], 0
	v_mfma_f32_16x16x32_bf16 v[98:101], v[156:159], v[196:199], 0
	v_mfma_f32_16x16x32_bf16 v[86:89], v[148:151], v[206:209], 0
	v_mfma_f32_16x16x32_bf16 v[82:85], v[156:159], v[206:209], 0
	v_mfma_f32_16x16x32_bf16 v[126:129], v[152:155], v[184:187], v[126:129]
	v_mfma_f32_16x16x32_bf16 v[122:125], v[160:163], v[184:187], v[122:125]
	v_mfma_f32_16x16x32_bf16 v[118:121], v[152:155], v[192:195], v[118:121]
	v_mfma_f32_16x16x32_bf16 v[114:117], v[160:163], v[192:195], v[114:117]
	v_mfma_f32_16x16x32_bf16 v[102:105], v[152:155], v[200:203], v[102:105]
	v_mfma_f32_16x16x32_bf16 v[98:101], v[160:163], v[200:203], v[98:101]
	v_mfma_f32_16x16x32_bf16 v[86:89], v[152:155], v[210:213], v[86:89]
	v_mfma_f32_16x16x32_bf16 v[82:85], v[160:163], v[210:213], v[82:85]
	v_mfma_f32_16x16x32_bf16 v[110:113], v[164:167], v[180:183], 0
	v_mfma_f32_16x16x32_bf16 v[106:109], v[172:175], v[180:183], 0
	v_mfma_f32_16x16x32_bf16 v[94:97], v[164:167], v[188:191], 0
	v_mfma_f32_16x16x32_bf16 v[90:93], v[172:175], v[188:191], 0
	v_mfma_f32_16x16x32_bf16 v[78:81], v[164:167], v[196:199], 0
	v_mfma_f32_16x16x32_bf16 v[74:77], v[172:175], v[196:199], 0
	v_mfma_f32_16x16x32_bf16 v[70:73], v[164:167], v[206:209], 0
	v_mfma_f32_16x16x32_bf16 v[66:69], v[172:175], v[206:209], 0
	v_mfma_f32_16x16x32_bf16 v[110:113], v[168:171], v[184:187], v[110:113]
	v_mfma_f32_16x16x32_bf16 v[106:109], v[176:179], v[184:187], v[106:109]
	v_mfma_f32_16x16x32_bf16 v[94:97], v[168:171], v[192:195], v[94:97]
	v_mfma_f32_16x16x32_bf16 v[90:93], v[176:179], v[192:195], v[90:93]
	v_mfma_f32_16x16x32_bf16 v[78:81], v[168:171], v[200:203], v[78:81]
	v_mfma_f32_16x16x32_bf16 v[74:77], v[176:179], v[200:203], v[74:77]
	v_mfma_f32_16x16x32_bf16 v[70:73], v[168:171], v[210:213], v[70:73]
	v_mfma_f32_16x16x32_bf16 v[66:69], v[176:179], v[210:213], v[66:69]
	s_setprio 0
	s_barrier
	s_add_i32 s70, s35, s18
	v_lshl_add_u64 v[214:215], s[38:39], 0, v[134:135]
	s_mov_b32 m0, s70
	ds_read_b128 v[180:183], v146 offset:16384
	ds_read_b128 v[184:187], v146 offset:17408
	ds_read_b128 v[188:191], v146 offset:18432
	ds_read_b128 v[192:195], v146 offset:19456
	ds_read_b128 v[196:199], v146 offset:20480
	ds_read_b128 v[200:203], v146 offset:21504
	ds_read_b128 v[206:209], v146 offset:22528
	ds_read_b128 v[210:213], v146 offset:23552
	global_load_lds_dwordx4 v[214:215], off
	s_add_i32 m0, s70, 0x2000
	s_add_u32 s70, s38, 0x200000
	v_lshl_add_u64 v[216:217], s[38:39], 0, v[130:131]
	s_addc_u32 s71, s39, 0
	s_add_i32 s72, s44, s18
	global_load_lds_dwordx4 v[216:217], off
	v_lshl_add_u64 v[218:219], s[70:71], 0, v[134:135]
	s_mov_b32 m0, s72
	v_lshl_add_u64 v[220:221], s[42:43], 0, v[132:133]
	global_load_lds_dwordx4 v[218:219], off
	v_lshl_add_u64 v[218:219], s[70:71], 0, v[130:131]
	s_add_i32 m0, s72, 0x2000
	s_nop 0
	global_load_lds_dwordx4 v[218:219], off
	v_lshl_add_u64 v[218:219], s[42:43], 0, v[136:137]
	s_mov_b32 m0, s19
	s_nop 0
	global_load_lds_dwordx4 v[218:219], off
	s_mov_b32 m0, s24
	s_nop 0
	global_load_lds_dwordx4 v[220:221], off
	s_waitcnt vmcnt(8)
	s_waitcnt lgkmcnt(0)
	s_setprio 1
	s_barrier
	v_mfma_f32_16x16x32_bf16 v[62:65], v[148:151], v[180:183], 0
	v_mfma_f32_16x16x32_bf16 v[58:61], v[156:159], v[180:183], 0
	v_mfma_f32_16x16x32_bf16 v[54:57], v[148:151], v[188:191], 0
	v_mfma_f32_16x16x32_bf16 v[50:53], v[156:159], v[188:191], 0
	v_mfma_f32_16x16x32_bf16 v[38:41], v[148:151], v[196:199], 0
	v_mfma_f32_16x16x32_bf16 v[34:37], v[156:159], v[196:199], 0
	v_mfma_f32_16x16x32_bf16 v[22:25], v[148:151], v[206:209], 0
	v_mfma_f32_16x16x32_bf16 v[18:21], v[156:159], v[206:209], 0
	v_mfma_f32_16x16x32_bf16 v[62:65], v[152:155], v[184:187], v[62:65]
	v_mfma_f32_16x16x32_bf16 v[58:61], v[160:163], v[184:187], v[58:61]
	v_mfma_f32_16x16x32_bf16 v[54:57], v[152:155], v[192:195], v[54:57]
	v_mfma_f32_16x16x32_bf16 v[50:53], v[160:163], v[192:195], v[50:53]
	v_mfma_f32_16x16x32_bf16 v[38:41], v[152:155], v[200:203], v[38:41]
	v_mfma_f32_16x16x32_bf16 v[34:37], v[160:163], v[200:203], v[34:37]
	v_mfma_f32_16x16x32_bf16 v[22:25], v[152:155], v[210:213], v[22:25]
	v_mfma_f32_16x16x32_bf16 v[18:21], v[160:163], v[210:213], v[18:21]
	v_mfma_f32_16x16x32_bf16 v[46:49], v[164:167], v[180:183], 0
	v_mfma_f32_16x16x32_bf16 v[42:45], v[172:175], v[180:183], 0
	v_mfma_f32_16x16x32_bf16 v[30:33], v[164:167], v[188:191], 0
	v_mfma_f32_16x16x32_bf16 v[26:29], v[172:175], v[188:191], 0
	v_mfma_f32_16x16x32_bf16 v[14:17], v[164:167], v[196:199], 0
	v_mfma_f32_16x16x32_bf16 v[10:13], v[172:175], v[196:199], 0
	v_mfma_f32_16x16x32_bf16 v[6:9], v[164:167], v[206:209], 0
	v_mfma_f32_16x16x32_bf16 v[2:5], v[172:175], v[206:209], 0
	v_mfma_f32_16x16x32_bf16 v[46:49], v[168:171], v[184:187], v[46:49]
	v_mfma_f32_16x16x32_bf16 v[42:45], v[176:179], v[184:187], v[42:45]
	v_mfma_f32_16x16x32_bf16 v[30:33], v[168:171], v[192:195], v[30:33]
	v_mfma_f32_16x16x32_bf16 v[26:29], v[176:179], v[192:195], v[26:29]
	v_mfma_f32_16x16x32_bf16 v[14:17], v[168:171], v[200:203], v[14:17]
	v_mfma_f32_16x16x32_bf16 v[10:13], v[176:179], v[200:203], v[10:13]
	v_mfma_f32_16x16x32_bf16 v[6:9], v[168:171], v[210:213], v[6:9]
	v_mfma_f32_16x16x32_bf16 v[2:5], v[176:179], v[210:213], v[2:5]
	s_setprio 0
	s_barrier
	s_add_i32 s70, 0, 0x18000
	v_add_u32_e32 v147, s70, v143
	s_add_i32 s71, 0, 0x1c000
	ds_read_b128 v[148:151], v147
	ds_read_b128 v[152:155], v147 offset:1024
	ds_read_b128 v[156:159], v147 offset:2048
	ds_read_b128 v[160:163], v147 offset:3072
	v_add_u32_e32 v147, s71, v143
	ds_read_b128 v[164:167], v147
	ds_read_b128 v[168:171], v147 offset:1024
	ds_read_b128 v[172:175], v147 offset:2048
	ds_read_b128 v[176:179], v147 offset:3072
	s_add_u32 s42, s42, 0x20000
	s_addc_u32 s43, s43, 0
	s_mov_b32 m0, s25
	v_lshl_add_u64 v[222:223], s[42:43], 0, v[136:137]
	ds_read_b128 v[180:183], v146 offset:32768
	ds_read_b128 v[184:187], v146 offset:33792
	ds_read_b128 v[188:191], v146 offset:34816
	ds_read_b128 v[192:195], v146 offset:35840
	ds_read_b128 v[196:199], v146 offset:36864
	ds_read_b128 v[200:203], v146 offset:37888
	ds_read_b128 v[206:209], v146 offset:38912
	ds_read_b128 v[210:213], v146 offset:39936
	global_load_lds_dwordx4 v[222:223], off
	v_lshl_add_u64 v[222:223], s[42:43], 0, v[132:133]
	s_mov_b32 m0, s28
	s_nop 0
	global_load_lds_dwordx4 v[222:223], off
	s_waitcnt vmcnt(8)
	s_waitcnt lgkmcnt(0)
	s_setprio 1
	s_barrier
	v_mfma_f32_16x16x32_bf16 v[126:129], v[148:151], v[180:183], v[126:129]
	v_mfma_f32_16x16x32_bf16 v[122:125], v[156:159], v[180:183], v[122:125]
	v_mfma_f32_16x16x32_bf16 v[118:121], v[148:151], v[188:191], v[118:121]
	v_mfma_f32_16x16x32_bf16 v[114:117], v[156:159], v[188:191], v[114:117]
	v_mfma_f32_16x16x32_bf16 v[102:105], v[148:151], v[196:199], v[102:105]
	v_mfma_f32_16x16x32_bf16 v[98:101], v[156:159], v[196:199], v[98:101]
	v_mfma_f32_16x16x32_bf16 v[86:89], v[148:151], v[206:209], v[86:89]
	v_mfma_f32_16x16x32_bf16 v[82:85], v[156:159], v[206:209], v[82:85]
	v_mfma_f32_16x16x32_bf16 v[126:129], v[152:155], v[184:187], v[126:129]
	v_mfma_f32_16x16x32_bf16 v[122:125], v[160:163], v[184:187], v[122:125]
	v_mfma_f32_16x16x32_bf16 v[118:121], v[152:155], v[192:195], v[118:121]
	v_mfma_f32_16x16x32_bf16 v[114:117], v[160:163], v[192:195], v[114:117]
	v_mfma_f32_16x16x32_bf16 v[102:105], v[152:155], v[200:203], v[102:105]
	v_mfma_f32_16x16x32_bf16 v[98:101], v[160:163], v[200:203], v[98:101]
	v_mfma_f32_16x16x32_bf16 v[86:89], v[152:155], v[210:213], v[86:89]
	v_mfma_f32_16x16x32_bf16 v[82:85], v[160:163], v[210:213], v[82:85]
	v_mfma_f32_16x16x32_bf16 v[110:113], v[164:167], v[180:183], v[110:113]
	v_mfma_f32_16x16x32_bf16 v[106:109], v[172:175], v[180:183], v[106:109]
	v_mfma_f32_16x16x32_bf16 v[94:97], v[164:167], v[188:191], v[94:97]
	v_mfma_f32_16x16x32_bf16 v[90:93], v[172:175], v[188:191], v[90:93]
	v_mfma_f32_16x16x32_bf16 v[78:81], v[164:167], v[196:199], v[78:81]
	v_mfma_f32_16x16x32_bf16 v[74:77], v[172:175], v[196:199], v[74:77]
	v_mfma_f32_16x16x32_bf16 v[70:73], v[164:167], v[206:209], v[70:73]
	v_mfma_f32_16x16x32_bf16 v[66:69], v[172:175], v[206:209], v[66:69]
	v_mfma_f32_16x16x32_bf16 v[110:113], v[168:171], v[184:187], v[110:113]
	v_mfma_f32_16x16x32_bf16 v[106:109], v[176:179], v[184:187], v[106:109]
	v_mfma_f32_16x16x32_bf16 v[94:97], v[168:171], v[192:195], v[94:97]
	v_mfma_f32_16x16x32_bf16 v[90:93], v[176:179], v[192:195], v[90:93]
	v_mfma_f32_16x16x32_bf16 v[78:81], v[168:171], v[200:203], v[78:81]
	v_mfma_f32_16x16x32_bf16 v[74:77], v[176:179], v[200:203], v[74:77]
	v_mfma_f32_16x16x32_bf16 v[70:73], v[168:171], v[210:213], v[70:73]
	v_mfma_f32_16x16x32_bf16 v[66:69], v[176:179], v[210:213], v[66:69]
	s_setprio 0
	s_barrier
	s_add_i32 s42, s70, s18
	v_lshl_add_u64 v[214:215], v[214:215], 0, s[8:9]
	s_mov_b32 m0, s42
	ds_read_b128 v[180:183], v146 offset:49152
	ds_read_b128 v[184:187], v146 offset:50176
	ds_read_b128 v[188:191], v146 offset:51200
	ds_read_b128 v[192:195], v146 offset:52224
	ds_read_b128 v[196:199], v146 offset:53248
	ds_read_b128 v[200:203], v146 offset:54272
	ds_read_b128 v[206:209], v146 offset:55296
	ds_read_b128 v[210:213], v146 offset:56320
	global_load_lds_dwordx4 v[214:215], off
	s_add_i32 m0, s42, 0x2000
	s_add_u32 s38, s38, 0x200080
	v_lshl_add_u64 v[214:215], v[216:217], 0, s[8:9]
	s_addc_u32 s39, s39, 0
	s_add_i32 s42, s71, s18
	global_load_lds_dwordx4 v[214:215], off
	v_lshl_add_u64 v[214:215], s[38:39], 0, v[134:135]
	s_mov_b32 m0, s42
	s_nop 0
	global_load_lds_dwordx4 v[214:215], off
	v_lshl_add_u64 v[214:215], s[38:39], 0, v[130:131]
	s_add_i32 m0, s42, 0x2000
	s_nop 0
	global_load_lds_dwordx4 v[214:215], off
	v_lshl_add_u64 v[214:215], v[218:219], 0, s[8:9]
	s_mov_b32 m0, s33
	s_nop 0
	global_load_lds_dwordx4 v[214:215], off
	v_lshl_add_u64 v[214:215], v[220:221], 0, s[8:9]
	s_mov_b32 m0, s34
	s_nop 0
	global_load_lds_dwordx4 v[214:215], off
	s_waitcnt vmcnt(8)
	s_waitcnt lgkmcnt(0)
	s_setprio 1
	s_barrier
	v_mfma_f32_16x16x32_bf16 v[62:65], v[148:151], v[180:183], v[62:65]
	v_mfma_f32_16x16x32_bf16 v[58:61], v[156:159], v[180:183], v[58:61]
	v_mfma_f32_16x16x32_bf16 v[54:57], v[148:151], v[188:191], v[54:57]
	v_mfma_f32_16x16x32_bf16 v[50:53], v[156:159], v[188:191], v[50:53]
	v_mfma_f32_16x16x32_bf16 v[38:41], v[148:151], v[196:199], v[38:41]
	v_mfma_f32_16x16x32_bf16 v[34:37], v[156:159], v[196:199], v[34:37]
	v_mfma_f32_16x16x32_bf16 v[22:25], v[148:151], v[206:209], v[22:25]
	v_mfma_f32_16x16x32_bf16 v[18:21], v[156:159], v[206:209], v[18:21]
	v_mfma_f32_16x16x32_bf16 v[62:65], v[152:155], v[184:187], v[62:65]
	v_mfma_f32_16x16x32_bf16 v[58:61], v[160:163], v[184:187], v[58:61]
	v_mfma_f32_16x16x32_bf16 v[54:57], v[152:155], v[192:195], v[54:57]
	v_mfma_f32_16x16x32_bf16 v[50:53], v[160:163], v[192:195], v[50:53]
	v_mfma_f32_16x16x32_bf16 v[38:41], v[152:155], v[200:203], v[38:41]
	v_mfma_f32_16x16x32_bf16 v[34:37], v[160:163], v[200:203], v[34:37]
	v_mfma_f32_16x16x32_bf16 v[22:25], v[152:155], v[210:213], v[22:25]
	v_mfma_f32_16x16x32_bf16 v[18:21], v[160:163], v[210:213], v[18:21]
	v_mfma_f32_16x16x32_bf16 v[46:49], v[164:167], v[180:183], v[46:49]
	v_mfma_f32_16x16x32_bf16 v[42:45], v[172:175], v[180:183], v[42:45]
	v_mfma_f32_16x16x32_bf16 v[30:33], v[164:167], v[188:191], v[30:33]
	v_mfma_f32_16x16x32_bf16 v[26:29], v[172:175], v[188:191], v[26:29]
	v_mfma_f32_16x16x32_bf16 v[14:17], v[164:167], v[196:199], v[14:17]
	v_mfma_f32_16x16x32_bf16 v[10:13], v[172:175], v[196:199], v[10:13]
	v_mfma_f32_16x16x32_bf16 v[6:9], v[164:167], v[206:209], v[6:9]
	v_mfma_f32_16x16x32_bf16 v[2:5], v[172:175], v[206:209], v[2:5]
	v_mfma_f32_16x16x32_bf16 v[46:49], v[168:171], v[184:187], v[46:49]
	v_mfma_f32_16x16x32_bf16 v[42:45], v[176:179], v[184:187], v[42:45]
	v_mfma_f32_16x16x32_bf16 v[30:33], v[168:171], v[192:195], v[30:33]
	v_mfma_f32_16x16x32_bf16 v[26:29], v[176:179], v[192:195], v[26:29]
	v_mfma_f32_16x16x32_bf16 v[14:17], v[168:171], v[200:203], v[14:17]
	v_mfma_f32_16x16x32_bf16 v[10:13], v[176:179], v[200:203], v[10:13]
	v_mfma_f32_16x16x32_bf16 v[6:9], v[168:171], v[210:213], v[6:9]
	v_mfma_f32_16x16x32_bf16 v[2:5], v[176:179], v[210:213], v[2:5]
	s_setprio 0
	s_barrier
	s_add_i32 s69, s69, 2
	s_add_u32 s36, s36, 0x100
	s_addc_u32 s37, s37, 0
	s_add_u32 s67, s67, 0x100
	s_addc_u32 s68, s68, 0
	s_cmp_gt_u32 s69, 5
.LBB0_477:
	ds_read_b128 v[148:151], v144
	ds_read_b128 v[152:155], v144 offset:1024
	ds_read_b128 v[156:159], v144 offset:2048
	ds_read_b128 v[160:163], v144 offset:3072
	ds_read_b128 v[164:167], v145
	ds_read_b128 v[168:171], v145 offset:1024
	ds_read_b128 v[172:175], v145 offset:2048
	ds_read_b128 v[176:179], v145 offset:3072
	s_add_u32 s38, s36, 0xfffe0080
	s_addc_u32 s39, s37, -1
	s_cmp_eq_u32 s69, 4
	s_cselect_b32 s43, s63, s39
	s_cselect_b32 s42, s64, s38
	s_cselect_b32 s39, s65, s68
	s_cselect_b32 s38, s66, s67
	v_lshl_add_u64 v[214:215], s[36:37], 0, v[138:139]
	s_add_i32 m0, s19, 0xc000
	ds_read_b128 v[180:183], v146
	ds_read_b128 v[184:187], v146 offset:1024
	ds_read_b128 v[188:191], v146 offset:2048
	ds_read_b128 v[192:195], v146 offset:3072
	ds_read_b128 v[196:199], v146 offset:4096
	ds_read_b128 v[200:203], v146 offset:5120
	ds_read_b128 v[206:209], v146 offset:6144
	ds_read_b128 v[210:213], v146 offset:7168
	global_load_lds_dwordx4 v[214:215], off
	v_lshl_add_u64 v[214:215], s[36:37], 0, v[140:141]
	s_add_i32 m0, s19, 0xe000
	s_nop 0
	global_load_lds_dwordx4 v[214:215], off
	s_waitcnt vmcnt(8)
	s_waitcnt lgkmcnt(0)
	s_setprio 1
	s_barrier
	v_mfma_f32_16x16x32_bf16 v[126:129], v[148:151], v[180:183], v[126:129]
	v_mfma_f32_16x16x32_bf16 v[122:125], v[156:159], v[180:183], v[122:125]
	v_mfma_f32_16x16x32_bf16 v[118:121], v[148:151], v[188:191], v[118:121]
	v_mfma_f32_16x16x32_bf16 v[114:117], v[156:159], v[188:191], v[114:117]
	v_mfma_f32_16x16x32_bf16 v[102:105], v[148:151], v[196:199], v[102:105]
	v_mfma_f32_16x16x32_bf16 v[98:101], v[156:159], v[196:199], v[98:101]
	v_mfma_f32_16x16x32_bf16 v[86:89], v[148:151], v[206:209], v[86:89]
	v_mfma_f32_16x16x32_bf16 v[82:85], v[156:159], v[206:209], v[82:85]
	v_mfma_f32_16x16x32_bf16 v[126:129], v[152:155], v[184:187], v[126:129]
	v_mfma_f32_16x16x32_bf16 v[122:125], v[160:163], v[184:187], v[122:125]
	v_mfma_f32_16x16x32_bf16 v[118:121], v[152:155], v[192:195], v[118:121]
	v_mfma_f32_16x16x32_bf16 v[114:117], v[160:163], v[192:195], v[114:117]
	v_mfma_f32_16x16x32_bf16 v[102:105], v[152:155], v[200:203], v[102:105]
	v_mfma_f32_16x16x32_bf16 v[98:101], v[160:163], v[200:203], v[98:101]
	v_mfma_f32_16x16x32_bf16 v[86:89], v[152:155], v[210:213], v[86:89]
	v_mfma_f32_16x16x32_bf16 v[82:85], v[160:163], v[210:213], v[82:85]
	v_mfma_f32_16x16x32_bf16 v[110:113], v[164:167], v[180:183], v[110:113]
	v_mfma_f32_16x16x32_bf16 v[106:109], v[172:175], v[180:183], v[106:109]
	v_mfma_f32_16x16x32_bf16 v[94:97], v[164:167], v[188:191], v[94:97]
	v_mfma_f32_16x16x32_bf16 v[90:93], v[172:175], v[188:191], v[90:93]
	v_mfma_f32_16x16x32_bf16 v[78:81], v[164:167], v[196:199], v[78:81]
	v_mfma_f32_16x16x32_bf16 v[74:77], v[172:175], v[196:199], v[74:77]
	v_mfma_f32_16x16x32_bf16 v[70:73], v[164:167], v[206:209], v[70:73]
	v_mfma_f32_16x16x32_bf16 v[66:69], v[172:175], v[206:209], v[66:69]
	v_mfma_f32_16x16x32_bf16 v[110:113], v[168:171], v[184:187], v[110:113]
	v_mfma_f32_16x16x32_bf16 v[106:109], v[176:179], v[184:187], v[106:109]
	v_mfma_f32_16x16x32_bf16 v[94:97], v[168:171], v[192:195], v[94:97]
	v_mfma_f32_16x16x32_bf16 v[90:93], v[176:179], v[192:195], v[90:93]
	v_mfma_f32_16x16x32_bf16 v[78:81], v[168:171], v[200:203], v[78:81]
	v_mfma_f32_16x16x32_bf16 v[74:77], v[176:179], v[200:203], v[74:77]
	v_mfma_f32_16x16x32_bf16 v[70:73], v[168:171], v[210:213], v[70:73]
	v_mfma_f32_16x16x32_bf16 v[66:69], v[176:179], v[210:213], v[66:69]
	s_setprio 0
	s_barrier
	s_add_i32 s70, s35, s18
	v_lshl_add_u64 v[214:215], s[38:39], 0, v[134:135]
	s_mov_b32 m0, s70
	ds_read_b128 v[180:183], v146 offset:16384
	ds_read_b128 v[184:187], v146 offset:17408
	ds_read_b128 v[188:191], v146 offset:18432
	ds_read_b128 v[192:195], v146 offset:19456
	ds_read_b128 v[196:199], v146 offset:20480
	ds_read_b128 v[200:203], v146 offset:21504
	ds_read_b128 v[206:209], v146 offset:22528
	ds_read_b128 v[210:213], v146 offset:23552
	global_load_lds_dwordx4 v[214:215], off
	s_add_i32 m0, s70, 0x2000
	s_add_u32 s70, s38, 0x200000
	v_lshl_add_u64 v[216:217], s[38:39], 0, v[130:131]
	s_addc_u32 s71, s39, 0
	s_add_i32 s72, s44, s18
	global_load_lds_dwordx4 v[216:217], off
	v_lshl_add_u64 v[218:219], s[70:71], 0, v[134:135]
	s_mov_b32 m0, s72
	v_lshl_add_u64 v[220:221], s[42:43], 0, v[132:133]
	global_load_lds_dwordx4 v[218:219], off
	v_lshl_add_u64 v[218:219], s[70:71], 0, v[130:131]
	s_add_i32 m0, s72, 0x2000
	s_nop 0
	global_load_lds_dwordx4 v[218:219], off
	v_lshl_add_u64 v[218:219], s[42:43], 0, v[136:137]
	s_mov_b32 m0, s19
	s_nop 0
	global_load_lds_dwordx4 v[218:219], off
	s_mov_b32 m0, s24
	s_nop 0
	global_load_lds_dwordx4 v[220:221], off
	s_waitcnt vmcnt(8)
	s_waitcnt lgkmcnt(0)
	s_setprio 1
	s_barrier
	v_mfma_f32_16x16x32_bf16 v[62:65], v[148:151], v[180:183], v[62:65]
	v_mfma_f32_16x16x32_bf16 v[58:61], v[156:159], v[180:183], v[58:61]
	v_mfma_f32_16x16x32_bf16 v[54:57], v[148:151], v[188:191], v[54:57]
	v_mfma_f32_16x16x32_bf16 v[50:53], v[156:159], v[188:191], v[50:53]
	v_mfma_f32_16x16x32_bf16 v[38:41], v[148:151], v[196:199], v[38:41]
	v_mfma_f32_16x16x32_bf16 v[34:37], v[156:159], v[196:199], v[34:37]
	v_mfma_f32_16x16x32_bf16 v[22:25], v[148:151], v[206:209], v[22:25]
	v_mfma_f32_16x16x32_bf16 v[18:21], v[156:159], v[206:209], v[18:21]
	v_mfma_f32_16x16x32_bf16 v[62:65], v[152:155], v[184:187], v[62:65]
	v_mfma_f32_16x16x32_bf16 v[58:61], v[160:163], v[184:187], v[58:61]
	v_mfma_f32_16x16x32_bf16 v[54:57], v[152:155], v[192:195], v[54:57]
	v_mfma_f32_16x16x32_bf16 v[50:53], v[160:163], v[192:195], v[50:53]
	v_mfma_f32_16x16x32_bf16 v[38:41], v[152:155], v[200:203], v[38:41]
	v_mfma_f32_16x16x32_bf16 v[34:37], v[160:163], v[200:203], v[34:37]
	v_mfma_f32_16x16x32_bf16 v[22:25], v[152:155], v[210:213], v[22:25]
	v_mfma_f32_16x16x32_bf16 v[18:21], v[160:163], v[210:213], v[18:21]
	v_mfma_f32_16x16x32_bf16 v[46:49], v[164:167], v[180:183], v[46:49]
	v_mfma_f32_16x16x32_bf16 v[42:45], v[172:175], v[180:183], v[42:45]
	v_mfma_f32_16x16x32_bf16 v[30:33], v[164:167], v[188:191], v[30:33]
	v_mfma_f32_16x16x32_bf16 v[26:29], v[172:175], v[188:191], v[26:29]
	v_mfma_f32_16x16x32_bf16 v[14:17], v[164:167], v[196:199], v[14:17]
	v_mfma_f32_16x16x32_bf16 v[10:13], v[172:175], v[196:199], v[10:13]
	v_mfma_f32_16x16x32_bf16 v[6:9], v[164:167], v[206:209], v[6:9]
	v_mfma_f32_16x16x32_bf16 v[2:5], v[172:175], v[206:209], v[2:5]
	v_mfma_f32_16x16x32_bf16 v[46:49], v[168:171], v[184:187], v[46:49]
	v_mfma_f32_16x16x32_bf16 v[42:45], v[176:179], v[184:187], v[42:45]
	v_mfma_f32_16x16x32_bf16 v[30:33], v[168:171], v[192:195], v[30:33]
	v_mfma_f32_16x16x32_bf16 v[26:29], v[176:179], v[192:195], v[26:29]
	v_mfma_f32_16x16x32_bf16 v[14:17], v[168:171], v[200:203], v[14:17]
	v_mfma_f32_16x16x32_bf16 v[10:13], v[176:179], v[200:203], v[10:13]
	v_mfma_f32_16x16x32_bf16 v[6:9], v[168:171], v[210:213], v[6:9]
	v_mfma_f32_16x16x32_bf16 v[2:5], v[176:179], v[210:213], v[2:5]
	s_setprio 0
	s_barrier
	s_add_i32 s70, 0, 0x18000
	v_add_u32_e32 v147, s70, v143
	s_add_i32 s71, 0, 0x1c000
	ds_read_b128 v[148:151], v147
	ds_read_b128 v[152:155], v147 offset:1024
	ds_read_b128 v[156:159], v147 offset:2048
	ds_read_b128 v[160:163], v147 offset:3072
	v_add_u32_e32 v147, s71, v143
	ds_read_b128 v[164:167], v147
	ds_read_b128 v[168:171], v147 offset:1024
	ds_read_b128 v[172:175], v147 offset:2048
	ds_read_b128 v[176:179], v147 offset:3072
	s_add_u32 s42, s42, 0x20000
	s_addc_u32 s43, s43, 0
	s_mov_b32 m0, s25
	v_lshl_add_u64 v[222:223], s[42:43], 0, v[136:137]
	ds_read_b128 v[180:183], v146 offset:32768
	ds_read_b128 v[184:187], v146 offset:33792
	ds_read_b128 v[188:191], v146 offset:34816
	ds_read_b128 v[192:195], v146 offset:35840
	ds_read_b128 v[196:199], v146 offset:36864
	ds_read_b128 v[200:203], v146 offset:37888
	ds_read_b128 v[206:209], v146 offset:38912
	ds_read_b128 v[210:213], v146 offset:39936
	global_load_lds_dwordx4 v[222:223], off
	v_lshl_add_u64 v[222:223], s[42:43], 0, v[132:133]
	s_mov_b32 m0, s28
	s_nop 0
	global_load_lds_dwordx4 v[222:223], off
	s_waitcnt vmcnt(8)
	s_waitcnt lgkmcnt(0)
	s_setprio 1
	s_barrier
	v_mfma_f32_16x16x32_bf16 v[126:129], v[148:151], v[180:183], v[126:129]
	v_mfma_f32_16x16x32_bf16 v[122:125], v[156:159], v[180:183], v[122:125]
	v_mfma_f32_16x16x32_bf16 v[118:121], v[148:151], v[188:191], v[118:121]
	v_mfma_f32_16x16x32_bf16 v[114:117], v[156:159], v[188:191], v[114:117]
	v_mfma_f32_16x16x32_bf16 v[102:105], v[148:151], v[196:199], v[102:105]
	v_mfma_f32_16x16x32_bf16 v[98:101], v[156:159], v[196:199], v[98:101]
	v_mfma_f32_16x16x32_bf16 v[86:89], v[148:151], v[206:209], v[86:89]
	v_mfma_f32_16x16x32_bf16 v[82:85], v[156:159], v[206:209], v[82:85]
	v_mfma_f32_16x16x32_bf16 v[126:129], v[152:155], v[184:187], v[126:129]
	v_mfma_f32_16x16x32_bf16 v[122:125], v[160:163], v[184:187], v[122:125]
	v_mfma_f32_16x16x32_bf16 v[118:121], v[152:155], v[192:195], v[118:121]
	v_mfma_f32_16x16x32_bf16 v[114:117], v[160:163], v[192:195], v[114:117]
	v_mfma_f32_16x16x32_bf16 v[102:105], v[152:155], v[200:203], v[102:105]
	v_mfma_f32_16x16x32_bf16 v[98:101], v[160:163], v[200:203], v[98:101]
	v_mfma_f32_16x16x32_bf16 v[86:89], v[152:155], v[210:213], v[86:89]
	v_mfma_f32_16x16x32_bf16 v[82:85], v[160:163], v[210:213], v[82:85]
	v_mfma_f32_16x16x32_bf16 v[110:113], v[164:167], v[180:183], v[110:113]
	v_mfma_f32_16x16x32_bf16 v[106:109], v[172:175], v[180:183], v[106:109]
	v_mfma_f32_16x16x32_bf16 v[94:97], v[164:167], v[188:191], v[94:97]
	v_mfma_f32_16x16x32_bf16 v[90:93], v[172:175], v[188:191], v[90:93]
	v_mfma_f32_16x16x32_bf16 v[78:81], v[164:167], v[196:199], v[78:81]
	v_mfma_f32_16x16x32_bf16 v[74:77], v[172:175], v[196:199], v[74:77]
	v_mfma_f32_16x16x32_bf16 v[70:73], v[164:167], v[206:209], v[70:73]
	v_mfma_f32_16x16x32_bf16 v[66:69], v[172:175], v[206:209], v[66:69]
	v_mfma_f32_16x16x32_bf16 v[110:113], v[168:171], v[184:187], v[110:113]
	v_mfma_f32_16x16x32_bf16 v[106:109], v[176:179], v[184:187], v[106:109]
	v_mfma_f32_16x16x32_bf16 v[94:97], v[168:171], v[192:195], v[94:97]
	v_mfma_f32_16x16x32_bf16 v[90:93], v[176:179], v[192:195], v[90:93]
	v_mfma_f32_16x16x32_bf16 v[78:81], v[168:171], v[200:203], v[78:81]
	v_mfma_f32_16x16x32_bf16 v[74:77], v[176:179], v[200:203], v[74:77]
	v_mfma_f32_16x16x32_bf16 v[70:73], v[168:171], v[210:213], v[70:73]
	v_mfma_f32_16x16x32_bf16 v[66:69], v[176:179], v[210:213], v[66:69]
	s_setprio 0
	s_barrier
	s_add_i32 s42, s70, s18
	v_lshl_add_u64 v[214:215], v[214:215], 0, s[8:9]
	s_mov_b32 m0, s42
	ds_read_b128 v[180:183], v146 offset:49152
	ds_read_b128 v[184:187], v146 offset:50176
	ds_read_b128 v[188:191], v146 offset:51200
	ds_read_b128 v[192:195], v146 offset:52224
	ds_read_b128 v[196:199], v146 offset:53248
	ds_read_b128 v[200:203], v146 offset:54272
	ds_read_b128 v[206:209], v146 offset:55296
	ds_read_b128 v[210:213], v146 offset:56320
	global_load_lds_dwordx4 v[214:215], off
	s_add_i32 m0, s42, 0x2000
	s_add_u32 s38, s38, 0x200080
	v_lshl_add_u64 v[214:215], v[216:217], 0, s[8:9]
	s_addc_u32 s39, s39, 0
	s_add_i32 s42, s71, s18
	global_load_lds_dwordx4 v[214:215], off
	v_lshl_add_u64 v[214:215], s[38:39], 0, v[134:135]
	s_mov_b32 m0, s42
	s_nop 0
	global_load_lds_dwordx4 v[214:215], off
	v_lshl_add_u64 v[214:215], s[38:39], 0, v[130:131]
	s_add_i32 m0, s42, 0x2000
	s_nop 0
	global_load_lds_dwordx4 v[214:215], off
	v_lshl_add_u64 v[214:215], v[218:219], 0, s[8:9]
	s_mov_b32 m0, s33
	s_nop 0
	global_load_lds_dwordx4 v[214:215], off
	v_lshl_add_u64 v[214:215], v[220:221], 0, s[8:9]
	s_mov_b32 m0, s34
	s_nop 0
	global_load_lds_dwordx4 v[214:215], off
	s_waitcnt vmcnt(8)
	s_waitcnt lgkmcnt(0)
	s_setprio 1
	s_barrier
	v_mfma_f32_16x16x32_bf16 v[62:65], v[148:151], v[180:183], v[62:65]
	v_mfma_f32_16x16x32_bf16 v[58:61], v[156:159], v[180:183], v[58:61]
	v_mfma_f32_16x16x32_bf16 v[54:57], v[148:151], v[188:191], v[54:57]
	v_mfma_f32_16x16x32_bf16 v[50:53], v[156:159], v[188:191], v[50:53]
	v_mfma_f32_16x16x32_bf16 v[38:41], v[148:151], v[196:199], v[38:41]
	v_mfma_f32_16x16x32_bf16 v[34:37], v[156:159], v[196:199], v[34:37]
	v_mfma_f32_16x16x32_bf16 v[22:25], v[148:151], v[206:209], v[22:25]
	v_mfma_f32_16x16x32_bf16 v[18:21], v[156:159], v[206:209], v[18:21]
	v_mfma_f32_16x16x32_bf16 v[62:65], v[152:155], v[184:187], v[62:65]
	v_mfma_f32_16x16x32_bf16 v[58:61], v[160:163], v[184:187], v[58:61]
	v_mfma_f32_16x16x32_bf16 v[54:57], v[152:155], v[192:195], v[54:57]
	v_mfma_f32_16x16x32_bf16 v[50:53], v[160:163], v[192:195], v[50:53]
	v_mfma_f32_16x16x32_bf16 v[38:41], v[152:155], v[200:203], v[38:41]
	v_mfma_f32_16x16x32_bf16 v[34:37], v[160:163], v[200:203], v[34:37]
	v_mfma_f32_16x16x32_bf16 v[22:25], v[152:155], v[210:213], v[22:25]
	v_mfma_f32_16x16x32_bf16 v[18:21], v[160:163], v[210:213], v[18:21]
	v_mfma_f32_16x16x32_bf16 v[46:49], v[164:167], v[180:183], v[46:49]
	v_mfma_f32_16x16x32_bf16 v[42:45], v[172:175], v[180:183], v[42:45]
	v_mfma_f32_16x16x32_bf16 v[30:33], v[164:167], v[188:191], v[30:33]
	v_mfma_f32_16x16x32_bf16 v[26:29], v[172:175], v[188:191], v[26:29]
	v_mfma_f32_16x16x32_bf16 v[14:17], v[164:167], v[196:199], v[14:17]
	v_mfma_f32_16x16x32_bf16 v[10:13], v[172:175], v[196:199], v[10:13]
	v_mfma_f32_16x16x32_bf16 v[6:9], v[164:167], v[206:209], v[6:9]
	v_mfma_f32_16x16x32_bf16 v[2:5], v[172:175], v[206:209], v[2:5]
	v_mfma_f32_16x16x32_bf16 v[46:49], v[168:171], v[184:187], v[46:49]
	v_mfma_f32_16x16x32_bf16 v[42:45], v[176:179], v[184:187], v[42:45]
	v_mfma_f32_16x16x32_bf16 v[30:33], v[168:171], v[192:195], v[30:33]
	v_mfma_f32_16x16x32_bf16 v[26:29], v[176:179], v[192:195], v[26:29]
	v_mfma_f32_16x16x32_bf16 v[14:17], v[168:171], v[200:203], v[14:17]
	v_mfma_f32_16x16x32_bf16 v[10:13], v[176:179], v[200:203], v[10:13]
	v_mfma_f32_16x16x32_bf16 v[6:9], v[168:171], v[210:213], v[6:9]
	v_mfma_f32_16x16x32_bf16 v[2:5], v[176:179], v[210:213], v[2:5]
	s_setprio 0
	s_barrier
	s_add_i32 s69, s69, 2
	s_add_u32 s36, s36, 0x100
	s_addc_u32 s37, s37, 0
	s_add_u32 s67, s67, 0x100
	s_addc_u32 s68, s68, 0
	s_cmp_gt_u32 s69, 5
	s_cbranch_scc0 .LBB0_477
	s_and_b64 vcc, exec, s[10:11]
	s_cbranch_vccz .LBB0_480
	s_barrier

.LBB0_565:
	v_readlane_b32 s62, v249, 27
	v_readlane_b32 s63, v249, 28
	s_add_u32 s72, s62, s68
	s_addc_u32 s73, s63, s69
	s_and_b64 s[62:63], s[70:71], exec
	s_cselect_b32 s31, s73, s77
	s_cselect_b32 s33, s72, s76
	s_add_u32 s74, s35, s66
	s_addc_u32 s75, s85, s67
	s_and_b64 s[62:63], s[70:71], exec
	s_cselect_b32 s34, s75, s79
	s_cselect_b32 s39, s74, s78
	s_add_i32 s45, s7, -2
	s_add_u32 s76, s76, 0x40080
	s_addc_u32 s77, s77, 0
	s_add_u32 s47, s78, 0x100
	s_addc_u32 s62, s79, 0
	s_mov_b32 s63, 0
	s_waitcnt vmcnt(0)
	ds_read_b128 v[114:117], v190
	ds_read_b128 v[118:121], v190 offset:1024
	ds_read_b128 v[122:125], v190 offset:2048
	ds_read_b128 v[126:129], v190 offset:3072
	ds_read_b128 v[146:149], v191
	ds_read_b128 v[150:153], v191 offset:1024
	ds_read_b128 v[154:157], v191 offset:2048
	ds_read_b128 v[158:161], v191 offset:3072
	s_add_i32 s82, s63, 2
	s_add_u32 s78, s76, 0xfffc0080
	s_addc_u32 s79, s77, -1
	s_cmp_eq_u32 s45, s63
	s_cselect_b32 s81, s31, s79
	s_cselect_b32 s80, s33, s78
	s_cselect_b32 s79, s34, s62
	s_cselect_b32 s78, s39, s47
	v_lshl_add_u64 v[186:187], s[76:77], 0, v[180:181]
	s_add_i32 m0, s87, 0xc000
	ds_read_b128 v[162:165], v192
	ds_read_b128 v[166:169], v192 offset:1024
	ds_read_b128 v[194:197], v192 offset:2048
	ds_read_b128 v[198:201], v192 offset:3072
	ds_read_b128 v[206:209], v192 offset:4096
	ds_read_b128 v[210:213], v192 offset:5120
	ds_read_b128 v[214:217], v192 offset:6144
	ds_read_b128 v[218:221], v192 offset:7168
	global_load_lds_dwordx4 v[186:187], off
	v_lshl_add_u64 v[186:187], s[76:77], 0, v[182:183]
	s_add_i32 m0, s87, 0xe000
	s_nop 0
	global_load_lds_dwordx4 v[186:187], off
	s_waitcnt vmcnt(8)
	s_waitcnt lgkmcnt(0)
	s_setprio 1
	s_barrier
	v_mfma_f32_16x16x32_bf16 v[142:145], v[114:117], v[162:165], 0
	v_mfma_f32_16x16x32_bf16 v[138:141], v[122:125], v[162:165], 0
	v_mfma_f32_16x16x32_bf16 v[110:113], v[114:117], v[194:197], 0
	v_mfma_f32_16x16x32_bf16 v[106:109], v[122:125], v[194:197], 0
	v_mfma_f32_16x16x32_bf16 v[98:101], v[114:117], v[206:209], 0
	v_mfma_f32_16x16x32_bf16 v[90:93], v[122:125], v[206:209], 0
	v_mfma_f32_16x16x32_bf16 v[82:85], v[114:117], v[214:217], 0
	v_mfma_f32_16x16x32_bf16 v[74:77], v[122:125], v[214:217], 0
	v_mfma_f32_16x16x32_bf16 v[142:145], v[118:121], v[166:169], v[142:145]
	v_mfma_f32_16x16x32_bf16 v[138:141], v[126:129], v[166:169], v[138:141]
	v_mfma_f32_16x16x32_bf16 v[110:113], v[118:121], v[198:201], v[110:113]
	v_mfma_f32_16x16x32_bf16 v[106:109], v[126:129], v[198:201], v[106:109]
	v_mfma_f32_16x16x32_bf16 v[98:101], v[118:121], v[210:213], v[98:101]
	v_mfma_f32_16x16x32_bf16 v[90:93], v[126:129], v[210:213], v[90:93]
	v_mfma_f32_16x16x32_bf16 v[82:85], v[118:121], v[218:221], v[82:85]
	v_mfma_f32_16x16x32_bf16 v[74:77], v[126:129], v[218:221], v[74:77]
	v_mfma_f32_16x16x32_bf16 v[134:137], v[146:149], v[162:165], 0
	v_mfma_f32_16x16x32_bf16 v[130:133], v[154:157], v[162:165], 0
	v_mfma_f32_16x16x32_bf16 v[102:105], v[146:149], v[194:197], 0
	v_mfma_f32_16x16x32_bf16 v[94:97], v[154:157], v[194:197], 0
	v_mfma_f32_16x16x32_bf16 v[86:89], v[146:149], v[206:209], 0
	v_mfma_f32_16x16x32_bf16 v[78:81], v[154:157], v[206:209], 0
	v_mfma_f32_16x16x32_bf16 v[70:73], v[146:149], v[214:217], 0
	v_mfma_f32_16x16x32_bf16 v[66:69], v[154:157], v[214:217], 0
	v_mfma_f32_16x16x32_bf16 v[134:137], v[150:153], v[166:169], v[134:137]
	v_mfma_f32_16x16x32_bf16 v[130:133], v[158:161], v[166:169], v[130:133]
	v_mfma_f32_16x16x32_bf16 v[102:105], v[150:153], v[198:201], v[102:105]
	v_mfma_f32_16x16x32_bf16 v[94:97], v[158:161], v[198:201], v[94:97]
	v_mfma_f32_16x16x32_bf16 v[86:89], v[150:153], v[210:213], v[86:89]
	v_mfma_f32_16x16x32_bf16 v[78:81], v[158:161], v[210:213], v[78:81]
	v_mfma_f32_16x16x32_bf16 v[70:73], v[150:153], v[218:221], v[70:73]
	v_mfma_f32_16x16x32_bf16 v[66:69], v[158:161], v[218:221], v[66:69]
	s_setprio 0
	s_barrier
	s_add_i32 s63, s24, s86
	v_lshl_add_u64 v[186:187], s[78:79], 0, v[172:173]
	s_mov_b32 m0, s63
	ds_read_b128 v[162:165], v192 offset:16384
	ds_read_b128 v[166:169], v192 offset:17408
	ds_read_b128 v[194:197], v192 offset:18432
	ds_read_b128 v[198:201], v192 offset:19456
	ds_read_b128 v[206:209], v192 offset:20480
	ds_read_b128 v[210:213], v192 offset:21504
	ds_read_b128 v[214:217], v192 offset:22528
	ds_read_b128 v[218:221], v192 offset:23552
	global_load_lds_dwordx4 v[186:187], off
	s_add_i32 m0, s63, 0x2000
	s_add_u32 vcc_lo, s78, 0x40000
	v_lshl_add_u64 v[202:203], s[78:79], 0, v[176:177]
	s_addc_u32 vcc_hi, s79, 0
	s_add_i32 s63, s25, s86
	global_load_lds_dwordx4 v[202:203], off
	v_lshl_add_u64 v[222:223], vcc, 0, v[172:173]
	s_mov_b32 m0, s63
	v_lshl_add_u64 v[224:225], s[80:81], 0, v[174:175]
	global_load_lds_dwordx4 v[222:223], off
	v_lshl_add_u64 v[222:223], vcc, 0, v[176:177]
	s_add_i32 m0, s63, 0x2000
	s_nop 0
	global_load_lds_dwordx4 v[222:223], off
	v_lshl_add_u64 v[222:223], s[80:81], 0, v[170:171]
	s_mov_b32 m0, s87
	s_nop 0
	global_load_lds_dwordx4 v[222:223], off
	s_mov_b32 m0, s88
	s_nop 0
	global_load_lds_dwordx4 v[224:225], off
	s_waitcnt vmcnt(8)
	s_waitcnt lgkmcnt(0)
	s_setprio 1
	s_barrier
	v_mfma_f32_16x16x32_bf16 v[62:65], v[114:117], v[162:165], 0
	v_mfma_f32_16x16x32_bf16 v[58:61], v[122:125], v[162:165], 0
	v_mfma_f32_16x16x32_bf16 v[50:53], v[114:117], v[194:197], 0
	v_mfma_f32_16x16x32_bf16 v[42:45], v[122:125], v[194:197], 0
	v_mfma_f32_16x16x32_bf16 v[34:37], v[114:117], v[206:209], 0
	v_mfma_f32_16x16x32_bf16 v[26:29], v[122:125], v[206:209], 0
	v_mfma_f32_16x16x32_bf16 v[18:21], v[114:117], v[214:217], 0
	v_mfma_f32_16x16x32_bf16 v[10:13], v[122:125], v[214:217], 0
	v_mfma_f32_16x16x32_bf16 v[62:65], v[118:121], v[166:169], v[62:65]
	v_mfma_f32_16x16x32_bf16 v[58:61], v[126:129], v[166:169], v[58:61]
	v_mfma_f32_16x16x32_bf16 v[50:53], v[118:121], v[198:201], v[50:53]
	v_mfma_f32_16x16x32_bf16 v[42:45], v[126:129], v[198:201], v[42:45]
	v_mfma_f32_16x16x32_bf16 v[34:37], v[118:121], v[210:213], v[34:37]
	v_mfma_f32_16x16x32_bf16 v[26:29], v[126:129], v[210:213], v[26:29]
	v_mfma_f32_16x16x32_bf16 v[18:21], v[118:121], v[218:221], v[18:21]
	v_mfma_f32_16x16x32_bf16 v[10:13], v[126:129], v[218:221], v[10:13]
	v_mfma_f32_16x16x32_bf16 v[54:57], v[146:149], v[162:165], 0
	v_mfma_f32_16x16x32_bf16 v[46:49], v[154:157], v[162:165], 0
	v_mfma_f32_16x16x32_bf16 v[38:41], v[146:149], v[194:197], 0
	v_mfma_f32_16x16x32_bf16 v[30:33], v[154:157], v[194:197], 0
	v_mfma_f32_16x16x32_bf16 v[22:25], v[146:149], v[206:209], 0
	v_mfma_f32_16x16x32_bf16 v[14:17], v[154:157], v[206:209], 0
	v_mfma_f32_16x16x32_bf16 v[6:9], v[146:149], v[214:217], 0
	v_mfma_f32_16x16x32_bf16 v[2:5], v[154:157], v[214:217], 0
	v_mfma_f32_16x16x32_bf16 v[54:57], v[150:153], v[166:169], v[54:57]
	v_mfma_f32_16x16x32_bf16 v[46:49], v[158:161], v[166:169], v[46:49]
	v_mfma_f32_16x16x32_bf16 v[38:41], v[150:153], v[198:201], v[38:41]
	v_mfma_f32_16x16x32_bf16 v[30:33], v[158:161], v[198:201], v[30:33]
	v_mfma_f32_16x16x32_bf16 v[22:25], v[150:153], v[210:213], v[22:25]
	v_mfma_f32_16x16x32_bf16 v[14:17], v[158:161], v[210:213], v[14:17]
	v_mfma_f32_16x16x32_bf16 v[6:9], v[150:153], v[218:221], v[6:9]
	v_mfma_f32_16x16x32_bf16 v[2:5], v[158:161], v[218:221], v[2:5]
	s_setprio 0
	s_barrier
	s_add_i32 s63, 0, 0x18000
	s_add_i32 s83, 0, 0x1c000
	v_add_u32_e32 v126, s63, v189
	v_add_u32_e32 v158, s83, v189
	ds_read_b128 v[114:117], v126
	ds_read_b128 v[118:121], v126 offset:1024
	ds_read_b128 v[122:125], v126 offset:2048
	ds_read_b128 v[126:129], v126 offset:3072
	ds_read_b128 v[146:149], v158
	ds_read_b128 v[150:153], v158 offset:1024
	ds_read_b128 v[154:157], v158 offset:2048
	ds_read_b128 v[158:161], v158 offset:3072
	s_add_u32 s80, s80, 0x40000
	s_addc_u32 s81, s81, 0
	s_mov_b32 m0, s89
	v_lshl_add_u64 v[226:227], s[80:81], 0, v[170:171]
	ds_read_b128 v[162:165], v192 offset:32768
	ds_read_b128 v[166:169], v192 offset:33792
	ds_read_b128 v[194:197], v192 offset:34816
	ds_read_b128 v[198:201], v192 offset:35840
	ds_read_b128 v[206:209], v192 offset:36864
	ds_read_b128 v[210:213], v192 offset:37888
	ds_read_b128 v[214:217], v192 offset:38912
	ds_read_b128 v[218:221], v192 offset:39936
	global_load_lds_dwordx4 v[226:227], off
	v_lshl_add_u64 v[226:227], s[80:81], 0, v[174:175]
	s_mov_b32 m0, s90
	s_nop 0
	global_load_lds_dwordx4 v[226:227], off
	s_waitcnt vmcnt(8)
	s_waitcnt lgkmcnt(0)
	s_setprio 1
	s_barrier
	v_mfma_f32_16x16x32_bf16 v[142:145], v[114:117], v[162:165], v[142:145]
	v_mfma_f32_16x16x32_bf16 v[138:141], v[122:125], v[162:165], v[138:141]
	v_mfma_f32_16x16x32_bf16 v[110:113], v[114:117], v[194:197], v[110:113]
	v_mfma_f32_16x16x32_bf16 v[106:109], v[122:125], v[194:197], v[106:109]
	v_mfma_f32_16x16x32_bf16 v[98:101], v[114:117], v[206:209], v[98:101]
	v_mfma_f32_16x16x32_bf16 v[90:93], v[122:125], v[206:209], v[90:93]
	v_mfma_f32_16x16x32_bf16 v[82:85], v[114:117], v[214:217], v[82:85]
	v_mfma_f32_16x16x32_bf16 v[74:77], v[122:125], v[214:217], v[74:77]
	v_mfma_f32_16x16x32_bf16 v[142:145], v[118:121], v[166:169], v[142:145]
	v_mfma_f32_16x16x32_bf16 v[138:141], v[126:129], v[166:169], v[138:141]
	v_mfma_f32_16x16x32_bf16 v[110:113], v[118:121], v[198:201], v[110:113]
	v_mfma_f32_16x16x32_bf16 v[106:109], v[126:129], v[198:201], v[106:109]
	v_mfma_f32_16x16x32_bf16 v[98:101], v[118:121], v[210:213], v[98:101]
	v_mfma_f32_16x16x32_bf16 v[90:93], v[126:129], v[210:213], v[90:93]
	v_mfma_f32_16x16x32_bf16 v[82:85], v[118:121], v[218:221], v[82:85]
	v_mfma_f32_16x16x32_bf16 v[74:77], v[126:129], v[218:221], v[74:77]
	v_mfma_f32_16x16x32_bf16 v[134:137], v[146:149], v[162:165], v[134:137]
	v_mfma_f32_16x16x32_bf16 v[130:133], v[154:157], v[162:165], v[130:133]
	v_mfma_f32_16x16x32_bf16 v[102:105], v[146:149], v[194:197], v[102:105]
	v_mfma_f32_16x16x32_bf16 v[94:97], v[154:157], v[194:197], v[94:97]
	v_mfma_f32_16x16x32_bf16 v[86:89], v[146:149], v[206:209], v[86:89]
	v_mfma_f32_16x16x32_bf16 v[78:81], v[154:157], v[206:209], v[78:81]
	v_mfma_f32_16x16x32_bf16 v[70:73], v[146:149], v[214:217], v[70:73]
	v_mfma_f32_16x16x32_bf16 v[66:69], v[154:157], v[214:217], v[66:69]
	v_mfma_f32_16x16x32_bf16 v[134:137], v[150:153], v[166:169], v[134:137]
	v_mfma_f32_16x16x32_bf16 v[130:133], v[158:161], v[166:169], v[130:133]
	v_mfma_f32_16x16x32_bf16 v[102:105], v[150:153], v[198:201], v[102:105]
	v_mfma_f32_16x16x32_bf16 v[94:97], v[158:161], v[198:201], v[94:97]
	v_mfma_f32_16x16x32_bf16 v[86:89], v[150:153], v[210:213], v[86:89]
	v_mfma_f32_16x16x32_bf16 v[78:81], v[158:161], v[210:213], v[78:81]
	v_mfma_f32_16x16x32_bf16 v[70:73], v[150:153], v[218:221], v[70:73]
	v_mfma_f32_16x16x32_bf16 v[66:69], v[158:161], v[218:221], v[66:69]
	s_setprio 0
	s_barrier
	s_add_i32 s63, s63, s86
	v_lshl_add_u64 v[186:187], v[186:187], 0, s[22:23]
	s_mov_b32 m0, s63
	ds_read_b128 v[162:165], v192 offset:49152
	ds_read_b128 v[166:169], v192 offset:50176
	ds_read_b128 v[194:197], v192 offset:51200
	ds_read_b128 v[198:201], v192 offset:52224
	ds_read_b128 v[206:209], v192 offset:53248
	ds_read_b128 v[210:213], v192 offset:54272
	ds_read_b128 v[214:217], v192 offset:55296
	ds_read_b128 v[218:221], v192 offset:56320
	global_load_lds_dwordx4 v[186:187], off
	s_add_i32 m0, s63, 0x2000
	s_add_u32 s78, s78, 0x40080
	v_lshl_add_u64 v[186:187], v[202:203], 0, s[22:23]
	s_addc_u32 s79, s79, 0
	s_add_i32 s63, s83, s86
	global_load_lds_dwordx4 v[186:187], off
	v_lshl_add_u64 v[186:187], s[78:79], 0, v[172:173]
	s_mov_b32 m0, s63
	s_nop 0
	global_load_lds_dwordx4 v[186:187], off
	v_lshl_add_u64 v[186:187], s[78:79], 0, v[176:177]
	s_add_i32 m0, s63, 0x2000
	s_nop 0
	global_load_lds_dwordx4 v[186:187], off
	v_lshl_add_u64 v[186:187], v[222:223], 0, s[22:23]
	s_mov_b32 m0, s95
	s_nop 0
	global_load_lds_dwordx4 v[186:187], off
	v_lshl_add_u64 v[186:187], v[224:225], 0, s[22:23]
	s_mov_b32 m0, s96
	s_nop 0
	global_load_lds_dwordx4 v[186:187], off
	s_waitcnt vmcnt(8)
	s_waitcnt lgkmcnt(0)
	s_setprio 1
	s_barrier
	v_mfma_f32_16x16x32_bf16 v[62:65], v[114:117], v[162:165], v[62:65]
	v_mfma_f32_16x16x32_bf16 v[58:61], v[122:125], v[162:165], v[58:61]
	v_mfma_f32_16x16x32_bf16 v[50:53], v[114:117], v[194:197], v[50:53]
	v_mfma_f32_16x16x32_bf16 v[42:45], v[122:125], v[194:197], v[42:45]
	v_mfma_f32_16x16x32_bf16 v[34:37], v[114:117], v[206:209], v[34:37]
	v_mfma_f32_16x16x32_bf16 v[26:29], v[122:125], v[206:209], v[26:29]
	v_mfma_f32_16x16x32_bf16 v[18:21], v[114:117], v[214:217], v[18:21]
	v_mfma_f32_16x16x32_bf16 v[10:13], v[122:125], v[214:217], v[10:13]
	v_mfma_f32_16x16x32_bf16 v[62:65], v[118:121], v[166:169], v[62:65]
	v_mfma_f32_16x16x32_bf16 v[58:61], v[126:129], v[166:169], v[58:61]
	v_mfma_f32_16x16x32_bf16 v[50:53], v[118:121], v[198:201], v[50:53]
	v_mfma_f32_16x16x32_bf16 v[42:45], v[126:129], v[198:201], v[42:45]
	v_mfma_f32_16x16x32_bf16 v[34:37], v[118:121], v[210:213], v[34:37]
	v_mfma_f32_16x16x32_bf16 v[26:29], v[126:129], v[210:213], v[26:29]
	v_mfma_f32_16x16x32_bf16 v[18:21], v[118:121], v[218:221], v[18:21]
	v_mfma_f32_16x16x32_bf16 v[10:13], v[126:129], v[218:221], v[10:13]
	v_mfma_f32_16x16x32_bf16 v[54:57], v[146:149], v[162:165], v[54:57]
	v_mfma_f32_16x16x32_bf16 v[46:49], v[154:157], v[162:165], v[46:49]
	v_mfma_f32_16x16x32_bf16 v[38:41], v[146:149], v[194:197], v[38:41]
	v_mfma_f32_16x16x32_bf16 v[30:33], v[154:157], v[194:197], v[30:33]
	v_mfma_f32_16x16x32_bf16 v[22:25], v[146:149], v[206:209], v[22:25]
	v_mfma_f32_16x16x32_bf16 v[14:17], v[154:157], v[206:209], v[14:17]
	v_mfma_f32_16x16x32_bf16 v[6:9], v[146:149], v[214:217], v[6:9]
	v_mfma_f32_16x16x32_bf16 v[2:5], v[154:157], v[214:217], v[2:5]
	v_mfma_f32_16x16x32_bf16 v[54:57], v[150:153], v[166:169], v[54:57]
	v_mfma_f32_16x16x32_bf16 v[46:49], v[158:161], v[166:169], v[46:49]
	v_mfma_f32_16x16x32_bf16 v[38:41], v[150:153], v[198:201], v[38:41]
	v_mfma_f32_16x16x32_bf16 v[30:33], v[158:161], v[198:201], v[30:33]
	v_mfma_f32_16x16x32_bf16 v[22:25], v[150:153], v[210:213], v[22:25]
	v_mfma_f32_16x16x32_bf16 v[14:17], v[158:161], v[210:213], v[14:17]
	v_mfma_f32_16x16x32_bf16 v[6:9], v[150:153], v[218:221], v[6:9]
	v_mfma_f32_16x16x32_bf16 v[2:5], v[158:161], v[218:221], v[2:5]
	s_setprio 0
	s_barrier
	s_add_u32 s76, s76, 0x100
	s_addc_u32 s77, s77, 0
	s_add_u32 s47, s47, 0x100
	s_addc_u32 s62, s62, 0
	s_cmp_ge_i32 s82, s7
	s_mov_b32 s63, s82
.LBB0_566:
	s_waitcnt vmcnt(0)
	ds_read_b128 v[114:117], v190
	ds_read_b128 v[118:121], v190 offset:1024
	ds_read_b128 v[122:125], v190 offset:2048
	ds_read_b128 v[126:129], v190 offset:3072
	ds_read_b128 v[146:149], v191
	ds_read_b128 v[150:153], v191 offset:1024
	ds_read_b128 v[154:157], v191 offset:2048
	ds_read_b128 v[158:161], v191 offset:3072
	s_add_i32 s82, s63, 2
	s_add_u32 s78, s76, 0xfffc0080
	s_addc_u32 s79, s77, -1
	s_cmp_eq_u32 s45, s63
	s_cselect_b32 s81, s31, s79
	s_cselect_b32 s80, s33, s78
	s_cselect_b32 s79, s34, s62
	s_cselect_b32 s78, s39, s47
	v_lshl_add_u64 v[186:187], s[76:77], 0, v[180:181]
	s_add_i32 m0, s87, 0xc000
	ds_read_b128 v[162:165], v192
	ds_read_b128 v[166:169], v192 offset:1024
	ds_read_b128 v[194:197], v192 offset:2048
	ds_read_b128 v[198:201], v192 offset:3072
	ds_read_b128 v[206:209], v192 offset:4096
	ds_read_b128 v[210:213], v192 offset:5120
	ds_read_b128 v[214:217], v192 offset:6144
	ds_read_b128 v[218:221], v192 offset:7168
	global_load_lds_dwordx4 v[186:187], off
	v_lshl_add_u64 v[186:187], s[76:77], 0, v[182:183]
	s_add_i32 m0, s87, 0xe000
	s_nop 0
	global_load_lds_dwordx4 v[186:187], off
	s_waitcnt vmcnt(8)
	s_waitcnt lgkmcnt(0)
	s_setprio 1
	s_barrier
	v_mfma_f32_16x16x32_bf16 v[142:145], v[114:117], v[162:165], v[142:145]
	v_mfma_f32_16x16x32_bf16 v[138:141], v[122:125], v[162:165], v[138:141]
	v_mfma_f32_16x16x32_bf16 v[110:113], v[114:117], v[194:197], v[110:113]
	v_mfma_f32_16x16x32_bf16 v[106:109], v[122:125], v[194:197], v[106:109]
	v_mfma_f32_16x16x32_bf16 v[98:101], v[114:117], v[206:209], v[98:101]
	v_mfma_f32_16x16x32_bf16 v[90:93], v[122:125], v[206:209], v[90:93]
	v_mfma_f32_16x16x32_bf16 v[82:85], v[114:117], v[214:217], v[82:85]
	v_mfma_f32_16x16x32_bf16 v[74:77], v[122:125], v[214:217], v[74:77]
	v_mfma_f32_16x16x32_bf16 v[142:145], v[118:121], v[166:169], v[142:145]
	v_mfma_f32_16x16x32_bf16 v[138:141], v[126:129], v[166:169], v[138:141]
	v_mfma_f32_16x16x32_bf16 v[110:113], v[118:121], v[198:201], v[110:113]
	v_mfma_f32_16x16x32_bf16 v[106:109], v[126:129], v[198:201], v[106:109]
	v_mfma_f32_16x16x32_bf16 v[98:101], v[118:121], v[210:213], v[98:101]
	v_mfma_f32_16x16x32_bf16 v[90:93], v[126:129], v[210:213], v[90:93]
	v_mfma_f32_16x16x32_bf16 v[82:85], v[118:121], v[218:221], v[82:85]
	v_mfma_f32_16x16x32_bf16 v[74:77], v[126:129], v[218:221], v[74:77]
	v_mfma_f32_16x16x32_bf16 v[134:137], v[146:149], v[162:165], v[134:137]
	v_mfma_f32_16x16x32_bf16 v[130:133], v[154:157], v[162:165], v[130:133]
	v_mfma_f32_16x16x32_bf16 v[102:105], v[146:149], v[194:197], v[102:105]
	v_mfma_f32_16x16x32_bf16 v[94:97], v[154:157], v[194:197], v[94:97]
	v_mfma_f32_16x16x32_bf16 v[86:89], v[146:149], v[206:209], v[86:89]
	v_mfma_f32_16x16x32_bf16 v[78:81], v[154:157], v[206:209], v[78:81]
	v_mfma_f32_16x16x32_bf16 v[70:73], v[146:149], v[214:217], v[70:73]
	v_mfma_f32_16x16x32_bf16 v[66:69], v[154:157], v[214:217], v[66:69]
	v_mfma_f32_16x16x32_bf16 v[134:137], v[150:153], v[166:169], v[134:137]
	v_mfma_f32_16x16x32_bf16 v[130:133], v[158:161], v[166:169], v[130:133]
	v_mfma_f32_16x16x32_bf16 v[102:105], v[150:153], v[198:201], v[102:105]
	v_mfma_f32_16x16x32_bf16 v[94:97], v[158:161], v[198:201], v[94:97]
	v_mfma_f32_16x16x32_bf16 v[86:89], v[150:153], v[210:213], v[86:89]
	v_mfma_f32_16x16x32_bf16 v[78:81], v[158:161], v[210:213], v[78:81]
	v_mfma_f32_16x16x32_bf16 v[70:73], v[150:153], v[218:221], v[70:73]
	v_mfma_f32_16x16x32_bf16 v[66:69], v[158:161], v[218:221], v[66:69]
	s_setprio 0
	s_barrier
	s_add_i32 s63, s24, s86
	v_lshl_add_u64 v[186:187], s[78:79], 0, v[172:173]
	s_mov_b32 m0, s63
	ds_read_b128 v[162:165], v192 offset:16384
	ds_read_b128 v[166:169], v192 offset:17408
	ds_read_b128 v[194:197], v192 offset:18432
	ds_read_b128 v[198:201], v192 offset:19456
	ds_read_b128 v[206:209], v192 offset:20480
	ds_read_b128 v[210:213], v192 offset:21504
	ds_read_b128 v[214:217], v192 offset:22528
	ds_read_b128 v[218:221], v192 offset:23552
	global_load_lds_dwordx4 v[186:187], off
	s_add_i32 m0, s63, 0x2000
	s_add_u32 vcc_lo, s78, 0x40000
	v_lshl_add_u64 v[202:203], s[78:79], 0, v[176:177]
	s_addc_u32 vcc_hi, s79, 0
	s_add_i32 s63, s25, s86
	global_load_lds_dwordx4 v[202:203], off
	v_lshl_add_u64 v[222:223], vcc, 0, v[172:173]
	s_mov_b32 m0, s63
	v_lshl_add_u64 v[224:225], s[80:81], 0, v[174:175]
	global_load_lds_dwordx4 v[222:223], off
	v_lshl_add_u64 v[222:223], vcc, 0, v[176:177]
	s_add_i32 m0, s63, 0x2000
	s_nop 0
	global_load_lds_dwordx4 v[222:223], off
	v_lshl_add_u64 v[222:223], s[80:81], 0, v[170:171]
	s_mov_b32 m0, s87
	s_nop 0
	global_load_lds_dwordx4 v[222:223], off
	s_mov_b32 m0, s88
	s_nop 0
	global_load_lds_dwordx4 v[224:225], off
	s_waitcnt vmcnt(8)
	s_waitcnt lgkmcnt(0)
	s_setprio 1
	s_barrier
	v_mfma_f32_16x16x32_bf16 v[62:65], v[114:117], v[162:165], v[62:65]
	v_mfma_f32_16x16x32_bf16 v[58:61], v[122:125], v[162:165], v[58:61]
	v_mfma_f32_16x16x32_bf16 v[50:53], v[114:117], v[194:197], v[50:53]
	v_mfma_f32_16x16x32_bf16 v[42:45], v[122:125], v[194:197], v[42:45]
	v_mfma_f32_16x16x32_bf16 v[34:37], v[114:117], v[206:209], v[34:37]
	v_mfma_f32_16x16x32_bf16 v[26:29], v[122:125], v[206:209], v[26:29]
	v_mfma_f32_16x16x32_bf16 v[18:21], v[114:117], v[214:217], v[18:21]
	v_mfma_f32_16x16x32_bf16 v[10:13], v[122:125], v[214:217], v[10:13]
	v_mfma_f32_16x16x32_bf16 v[62:65], v[118:121], v[166:169], v[62:65]
	v_mfma_f32_16x16x32_bf16 v[58:61], v[126:129], v[166:169], v[58:61]
	v_mfma_f32_16x16x32_bf16 v[50:53], v[118:121], v[198:201], v[50:53]
	v_mfma_f32_16x16x32_bf16 v[42:45], v[126:129], v[198:201], v[42:45]
	v_mfma_f32_16x16x32_bf16 v[34:37], v[118:121], v[210:213], v[34:37]
	v_mfma_f32_16x16x32_bf16 v[26:29], v[126:129], v[210:213], v[26:29]
	v_mfma_f32_16x16x32_bf16 v[18:21], v[118:121], v[218:221], v[18:21]
	v_mfma_f32_16x16x32_bf16 v[10:13], v[126:129], v[218:221], v[10:13]
	v_mfma_f32_16x16x32_bf16 v[54:57], v[146:149], v[162:165], v[54:57]
	v_mfma_f32_16x16x32_bf16 v[46:49], v[154:157], v[162:165], v[46:49]
	v_mfma_f32_16x16x32_bf16 v[38:41], v[146:149], v[194:197], v[38:41]
	v_mfma_f32_16x16x32_bf16 v[30:33], v[154:157], v[194:197], v[30:33]
	v_mfma_f32_16x16x32_bf16 v[22:25], v[146:149], v[206:209], v[22:25]
	v_mfma_f32_16x16x32_bf16 v[14:17], v[154:157], v[206:209], v[14:17]
	v_mfma_f32_16x16x32_bf16 v[6:9], v[146:149], v[214:217], v[6:9]
	v_mfma_f32_16x16x32_bf16 v[2:5], v[154:157], v[214:217], v[2:5]
	v_mfma_f32_16x16x32_bf16 v[54:57], v[150:153], v[166:169], v[54:57]
	v_mfma_f32_16x16x32_bf16 v[46:49], v[158:161], v[166:169], v[46:49]
	v_mfma_f32_16x16x32_bf16 v[38:41], v[150:153], v[198:201], v[38:41]
	v_mfma_f32_16x16x32_bf16 v[30:33], v[158:161], v[198:201], v[30:33]
	v_mfma_f32_16x16x32_bf16 v[22:25], v[150:153], v[210:213], v[22:25]
	v_mfma_f32_16x16x32_bf16 v[14:17], v[158:161], v[210:213], v[14:17]
	v_mfma_f32_16x16x32_bf16 v[6:9], v[150:153], v[218:221], v[6:9]
	v_mfma_f32_16x16x32_bf16 v[2:5], v[158:161], v[218:221], v[2:5]
	s_setprio 0
	s_barrier
	s_add_i32 s63, 0, 0x18000
	s_add_i32 s83, 0, 0x1c000
	v_add_u32_e32 v126, s63, v189
	v_add_u32_e32 v158, s83, v189
	ds_read_b128 v[114:117], v126
	ds_read_b128 v[118:121], v126 offset:1024
	ds_read_b128 v[122:125], v126 offset:2048
	ds_read_b128 v[126:129], v126 offset:3072
	ds_read_b128 v[146:149], v158
	ds_read_b128 v[150:153], v158 offset:1024
	ds_read_b128 v[154:157], v158 offset:2048
	ds_read_b128 v[158:161], v158 offset:3072
	s_add_u32 s80, s80, 0x40000
	s_addc_u32 s81, s81, 0
	s_mov_b32 m0, s89
	v_lshl_add_u64 v[226:227], s[80:81], 0, v[170:171]
	ds_read_b128 v[162:165], v192 offset:32768
	ds_read_b128 v[166:169], v192 offset:33792
	ds_read_b128 v[194:197], v192 offset:34816
	ds_read_b128 v[198:201], v192 offset:35840
	ds_read_b128 v[206:209], v192 offset:36864
	ds_read_b128 v[210:213], v192 offset:37888
	ds_read_b128 v[214:217], v192 offset:38912
	ds_read_b128 v[218:221], v192 offset:39936
	global_load_lds_dwordx4 v[226:227], off
	v_lshl_add_u64 v[226:227], s[80:81], 0, v[174:175]
	s_mov_b32 m0, s90
	s_nop 0
	global_load_lds_dwordx4 v[226:227], off
	s_waitcnt vmcnt(8)
	s_waitcnt lgkmcnt(0)
	s_setprio 1
	s_barrier
	v_mfma_f32_16x16x32_bf16 v[142:145], v[114:117], v[162:165], v[142:145]
	v_mfma_f32_16x16x32_bf16 v[138:141], v[122:125], v[162:165], v[138:141]
	v_mfma_f32_16x16x32_bf16 v[110:113], v[114:117], v[194:197], v[110:113]
	v_mfma_f32_16x16x32_bf16 v[106:109], v[122:125], v[194:197], v[106:109]
	v_mfma_f32_16x16x32_bf16 v[98:101], v[114:117], v[206:209], v[98:101]
	v_mfma_f32_16x16x32_bf16 v[90:93], v[122:125], v[206:209], v[90:93]
	v_mfma_f32_16x16x32_bf16 v[82:85], v[114:117], v[214:217], v[82:85]
	v_mfma_f32_16x16x32_bf16 v[74:77], v[122:125], v[214:217], v[74:77]
	v_mfma_f32_16x16x32_bf16 v[142:145], v[118:121], v[166:169], v[142:145]
	v_mfma_f32_16x16x32_bf16 v[138:141], v[126:129], v[166:169], v[138:141]
	v_mfma_f32_16x16x32_bf16 v[110:113], v[118:121], v[198:201], v[110:113]
	v_mfma_f32_16x16x32_bf16 v[106:109], v[126:129], v[198:201], v[106:109]
	v_mfma_f32_16x16x32_bf16 v[98:101], v[118:121], v[210:213], v[98:101]
	v_mfma_f32_16x16x32_bf16 v[90:93], v[126:129], v[210:213], v[90:93]
	v_mfma_f32_16x16x32_bf16 v[82:85], v[118:121], v[218:221], v[82:85]
	v_mfma_f32_16x16x32_bf16 v[74:77], v[126:129], v[218:221], v[74:77]
	v_mfma_f32_16x16x32_bf16 v[134:137], v[146:149], v[162:165], v[134:137]
	v_mfma_f32_16x16x32_bf16 v[130:133], v[154:157], v[162:165], v[130:133]
	v_mfma_f32_16x16x32_bf16 v[102:105], v[146:149], v[194:197], v[102:105]
	v_mfma_f32_16x16x32_bf16 v[94:97], v[154:157], v[194:197], v[94:97]
	v_mfma_f32_16x16x32_bf16 v[86:89], v[146:149], v[206:209], v[86:89]
	v_mfma_f32_16x16x32_bf16 v[78:81], v[154:157], v[206:209], v[78:81]
	v_mfma_f32_16x16x32_bf16 v[70:73], v[146:149], v[214:217], v[70:73]
	v_mfma_f32_16x16x32_bf16 v[66:69], v[154:157], v[214:217], v[66:69]
	v_mfma_f32_16x16x32_bf16 v[134:137], v[150:153], v[166:169], v[134:137]
	v_mfma_f32_16x16x32_bf16 v[130:133], v[158:161], v[166:169], v[130:133]
	v_mfma_f32_16x16x32_bf16 v[102:105], v[150:153], v[198:201], v[102:105]
	v_mfma_f32_16x16x32_bf16 v[94:97], v[158:161], v[198:201], v[94:97]
	v_mfma_f32_16x16x32_bf16 v[86:89], v[150:153], v[210:213], v[86:89]
	v_mfma_f32_16x16x32_bf16 v[78:81], v[158:161], v[210:213], v[78:81]
	v_mfma_f32_16x16x32_bf16 v[70:73], v[150:153], v[218:221], v[70:73]
	v_mfma_f32_16x16x32_bf16 v[66:69], v[158:161], v[218:221], v[66:69]
	s_setprio 0
	s_barrier
	s_add_i32 s63, s63, s86
	v_lshl_add_u64 v[186:187], v[186:187], 0, s[22:23]
	s_mov_b32 m0, s63
	ds_read_b128 v[162:165], v192 offset:49152
	ds_read_b128 v[166:169], v192 offset:50176
	ds_read_b128 v[194:197], v192 offset:51200
	ds_read_b128 v[198:201], v192 offset:52224
	ds_read_b128 v[206:209], v192 offset:53248
	ds_read_b128 v[210:213], v192 offset:54272
	ds_read_b128 v[214:217], v192 offset:55296
	ds_read_b128 v[218:221], v192 offset:56320
	global_load_lds_dwordx4 v[186:187], off
	s_add_i32 m0, s63, 0x2000
	s_add_u32 s78, s78, 0x40080
	v_lshl_add_u64 v[186:187], v[202:203], 0, s[22:23]
	s_addc_u32 s79, s79, 0
	s_add_i32 s63, s83, s86
	global_load_lds_dwordx4 v[186:187], off
	v_lshl_add_u64 v[186:187], s[78:79], 0, v[172:173]
	s_mov_b32 m0, s63
	s_nop 0
	global_load_lds_dwordx4 v[186:187], off
	v_lshl_add_u64 v[186:187], s[78:79], 0, v[176:177]
	s_add_i32 m0, s63, 0x2000
	s_nop 0
	global_load_lds_dwordx4 v[186:187], off
	v_lshl_add_u64 v[186:187], v[222:223], 0, s[22:23]
	s_mov_b32 m0, s95
	s_nop 0
	global_load_lds_dwordx4 v[186:187], off
	v_lshl_add_u64 v[186:187], v[224:225], 0, s[22:23]
	s_mov_b32 m0, s96
	s_nop 0
	global_load_lds_dwordx4 v[186:187], off
	s_waitcnt vmcnt(8)
	s_waitcnt lgkmcnt(0)
	s_setprio 1
	s_barrier
	v_mfma_f32_16x16x32_bf16 v[62:65], v[114:117], v[162:165], v[62:65]
	v_mfma_f32_16x16x32_bf16 v[58:61], v[122:125], v[162:165], v[58:61]
	v_mfma_f32_16x16x32_bf16 v[50:53], v[114:117], v[194:197], v[50:53]
	v_mfma_f32_16x16x32_bf16 v[42:45], v[122:125], v[194:197], v[42:45]
	v_mfma_f32_16x16x32_bf16 v[34:37], v[114:117], v[206:209], v[34:37]
	v_mfma_f32_16x16x32_bf16 v[26:29], v[122:125], v[206:209], v[26:29]
	v_mfma_f32_16x16x32_bf16 v[18:21], v[114:117], v[214:217], v[18:21]
	v_mfma_f32_16x16x32_bf16 v[10:13], v[122:125], v[214:217], v[10:13]
	v_mfma_f32_16x16x32_bf16 v[62:65], v[118:121], v[166:169], v[62:65]
	v_mfma_f32_16x16x32_bf16 v[58:61], v[126:129], v[166:169], v[58:61]
	v_mfma_f32_16x16x32_bf16 v[50:53], v[118:121], v[198:201], v[50:53]
	v_mfma_f32_16x16x32_bf16 v[42:45], v[126:129], v[198:201], v[42:45]
	v_mfma_f32_16x16x32_bf16 v[34:37], v[118:121], v[210:213], v[34:37]
	v_mfma_f32_16x16x32_bf16 v[26:29], v[126:129], v[210:213], v[26:29]
	v_mfma_f32_16x16x32_bf16 v[18:21], v[118:121], v[218:221], v[18:21]
	v_mfma_f32_16x16x32_bf16 v[10:13], v[126:129], v[218:221], v[10:13]
	v_mfma_f32_16x16x32_bf16 v[54:57], v[146:149], v[162:165], v[54:57]
	v_mfma_f32_16x16x32_bf16 v[46:49], v[154:157], v[162:165], v[46:49]
	v_mfma_f32_16x16x32_bf16 v[38:41], v[146:149], v[194:197], v[38:41]
	v_mfma_f32_16x16x32_bf16 v[30:33], v[154:157], v[194:197], v[30:33]
	v_mfma_f32_16x16x32_bf16 v[22:25], v[146:149], v[206:209], v[22:25]
	v_mfma_f32_16x16x32_bf16 v[14:17], v[154:157], v[206:209], v[14:17]
	v_mfma_f32_16x16x32_bf16 v[6:9], v[146:149], v[214:217], v[6:9]
	v_mfma_f32_16x16x32_bf16 v[2:5], v[154:157], v[214:217], v[2:5]
	v_mfma_f32_16x16x32_bf16 v[54:57], v[150:153], v[166:169], v[54:57]
	v_mfma_f32_16x16x32_bf16 v[46:49], v[158:161], v[166:169], v[46:49]
	v_mfma_f32_16x16x32_bf16 v[38:41], v[150:153], v[198:201], v[38:41]
	v_mfma_f32_16x16x32_bf16 v[30:33], v[158:161], v[198:201], v[30:33]
	v_mfma_f32_16x16x32_bf16 v[22:25], v[150:153], v[210:213], v[22:25]
	v_mfma_f32_16x16x32_bf16 v[14:17], v[158:161], v[210:213], v[14:17]
	v_mfma_f32_16x16x32_bf16 v[6:9], v[150:153], v[218:221], v[6:9]
	v_mfma_f32_16x16x32_bf16 v[2:5], v[158:161], v[218:221], v[2:5]
	s_setprio 0
	s_barrier
	s_add_u32 s76, s76, 0x100
	s_addc_u32 s77, s77, 0
	s_add_u32 s47, s47, 0x100
	s_addc_u32 s62, s62, 0
	s_cmp_ge_i32 s82, s7
	s_mov_b32 s63, s82
	s_cbranch_scc0 .LBB0_566
	s_and_b64 vcc, exec, s[26:27]
	s_cbranch_vccz .LBB0_569
	s_barrier

.LBB0_744:
	s_add_u32 s36, s96, s22
	s_addc_u32 s37, s97, s23
	s_and_b64 s[14:15], s[4:5], exec
	s_cselect_b32 s14, s37, s43
	s_cselect_b32 s15, s36, s42
	s_add_u32 s38, s2, s26
	s_addc_u32 s39, s3, s27
	s_and_b64 s[46:47], s[4:5], exec
	s_cselect_b32 s21, s39, s45
	s_cselect_b32 s65, s38, s44
	s_add_u32 s42, s42, 0x40080
	s_addc_u32 s43, s43, 0
	s_add_u32 s66, s44, 0x100
	s_addc_u32 s67, s45, 0
	s_mov_b32 s68, -2
	ds_read_b128 v[154:157], v150
	ds_read_b128 v[158:161], v150 offset:1024
	ds_read_b128 v[162:165], v150 offset:2048
	ds_read_b128 v[166:169], v150 offset:3072
	ds_read_b128 v[170:173], v151
	ds_read_b128 v[174:177], v151 offset:1024
	ds_read_b128 v[178:181], v151 offset:2048
	ds_read_b128 v[182:185], v151 offset:3072
	s_add_u32 s44, s42, 0xfffc0080
	s_addc_u32 s45, s43, -1
	s_cmp_eq_u32 s68, 12
	s_cselect_b32 s47, s14, s45
	s_cselect_b32 s46, s15, s44
	s_cselect_b32 s45, s21, s67
	s_cselect_b32 s44, s65, s66
	v_lshl_add_u64 v[146:147], s[42:43], 0, v[138:139]
	s_add_i32 m0, s19, 0xc000
	ds_read_b128 v[186:189], v152
	ds_read_b128 v[190:193], v152 offset:1024
	ds_read_b128 v[194:197], v152 offset:2048
	ds_read_b128 v[198:201], v152 offset:3072
	ds_read_b128 v[206:209], v152 offset:4096
	ds_read_b128 v[210:213], v152 offset:5120
	ds_read_b128 v[214:217], v152 offset:6144
	ds_read_b128 v[218:221], v152 offset:7168
	global_load_lds_dwordx4 v[146:147], off
	v_lshl_add_u64 v[146:147], s[42:43], 0, v[140:141]
	s_add_i32 m0, s19, 0xe000
	s_nop 0
	global_load_lds_dwordx4 v[146:147], off
	s_waitcnt vmcnt(8)
	s_waitcnt lgkmcnt(0)
	s_setprio 1
	s_barrier
	v_mfma_f32_16x16x32_bf16 v[126:129], v[154:157], v[186:189], 0
	v_mfma_f32_16x16x32_bf16 v[122:125], v[162:165], v[186:189], 0
	v_mfma_f32_16x16x32_bf16 v[110:113], v[154:157], v[194:197], 0
	v_mfma_f32_16x16x32_bf16 v[106:109], v[162:165], v[194:197], 0
	v_mfma_f32_16x16x32_bf16 v[94:97], v[154:157], v[206:209], 0
	v_mfma_f32_16x16x32_bf16 v[90:93], v[162:165], v[206:209], 0
	v_mfma_f32_16x16x32_bf16 v[78:81], v[154:157], v[214:217], 0
	v_mfma_f32_16x16x32_bf16 v[74:77], v[162:165], v[214:217], 0
	v_mfma_f32_16x16x32_bf16 v[126:129], v[158:161], v[190:193], v[126:129]
	v_mfma_f32_16x16x32_bf16 v[122:125], v[166:169], v[190:193], v[122:125]
	v_mfma_f32_16x16x32_bf16 v[110:113], v[158:161], v[198:201], v[110:113]
	v_mfma_f32_16x16x32_bf16 v[106:109], v[166:169], v[198:201], v[106:109]
	v_mfma_f32_16x16x32_bf16 v[94:97], v[158:161], v[210:213], v[94:97]
	v_mfma_f32_16x16x32_bf16 v[90:93], v[166:169], v[210:213], v[90:93]
	v_mfma_f32_16x16x32_bf16 v[78:81], v[158:161], v[218:221], v[78:81]
	v_mfma_f32_16x16x32_bf16 v[74:77], v[166:169], v[218:221], v[74:77]
	v_mfma_f32_16x16x32_bf16 v[118:121], v[170:173], v[186:189], 0
	v_mfma_f32_16x16x32_bf16 v[114:117], v[178:181], v[186:189], 0
	v_mfma_f32_16x16x32_bf16 v[102:105], v[170:173], v[194:197], 0
	v_mfma_f32_16x16x32_bf16 v[98:101], v[178:181], v[194:197], 0
	v_mfma_f32_16x16x32_bf16 v[86:89], v[170:173], v[206:209], 0
	v_mfma_f32_16x16x32_bf16 v[82:85], v[178:181], v[206:209], 0
	v_mfma_f32_16x16x32_bf16 v[70:73], v[170:173], v[214:217], 0
	v_mfma_f32_16x16x32_bf16 v[66:69], v[178:181], v[214:217], 0
	v_mfma_f32_16x16x32_bf16 v[118:121], v[174:177], v[190:193], v[118:121]
	v_mfma_f32_16x16x32_bf16 v[114:117], v[182:185], v[190:193], v[114:117]
	v_mfma_f32_16x16x32_bf16 v[102:105], v[174:177], v[198:201], v[102:105]
	v_mfma_f32_16x16x32_bf16 v[98:101], v[182:185], v[198:201], v[98:101]
	v_mfma_f32_16x16x32_bf16 v[86:89], v[174:177], v[210:213], v[86:89]
	v_mfma_f32_16x16x32_bf16 v[82:85], v[182:185], v[210:213], v[82:85]
	v_mfma_f32_16x16x32_bf16 v[70:73], v[174:177], v[218:221], v[70:73]
	v_mfma_f32_16x16x32_bf16 v[66:69], v[182:185], v[218:221], v[66:69]
	s_setprio 0
	s_barrier
	s_add_i32 s69, s49, s16
	v_lshl_add_u64 v[146:147], s[44:45], 0, v[134:135]
	s_mov_b32 m0, s69
	ds_read_b128 v[186:189], v152 offset:16384
	ds_read_b128 v[190:193], v152 offset:17408
	ds_read_b128 v[194:197], v152 offset:18432
	ds_read_b128 v[198:201], v152 offset:19456
	ds_read_b128 v[206:209], v152 offset:20480
	ds_read_b128 v[210:213], v152 offset:21504
	ds_read_b128 v[214:217], v152 offset:22528
	ds_read_b128 v[218:221], v152 offset:23552
	global_load_lds_dwordx4 v[146:147], off
	s_add_i32 m0, s69, 0x2000
	s_add_u32 s70, s44, 0x40000
	v_lshl_add_u64 v[202:203], s[44:45], 0, v[130:131]
	s_addc_u32 s71, s45, 0
	s_add_i32 s69, s62, s16
	global_load_lds_dwordx4 v[202:203], off
	v_lshl_add_u64 v[222:223], s[70:71], 0, v[134:135]
	s_mov_b32 m0, s69
	v_lshl_add_u64 v[224:225], s[46:47], 0, v[132:133]
	global_load_lds_dwordx4 v[222:223], off
	v_lshl_add_u64 v[222:223], s[70:71], 0, v[130:131]
	s_add_i32 m0, s69, 0x2000
	s_nop 0
	global_load_lds_dwordx4 v[222:223], off
	v_lshl_add_u64 v[222:223], s[46:47], 0, v[136:137]
	s_mov_b32 m0, s19
	s_nop 0
	global_load_lds_dwordx4 v[222:223], off
	s_mov_b32 m0, s24
	s_nop 0
	global_load_lds_dwordx4 v[224:225], off
	s_waitcnt vmcnt(8)
	s_waitcnt lgkmcnt(0)
	s_setprio 1
	s_barrier
	v_mfma_f32_16x16x32_bf16 v[62:65], v[154:157], v[186:189], 0
	v_mfma_f32_16x16x32_bf16 v[58:61], v[162:165], v[186:189], 0
	v_mfma_f32_16x16x32_bf16 v[46:49], v[154:157], v[194:197], 0
	v_mfma_f32_16x16x32_bf16 v[42:45], v[162:165], v[194:197], 0
	v_mfma_f32_16x16x32_bf16 v[30:33], v[154:157], v[206:209], 0
	v_mfma_f32_16x16x32_bf16 v[26:29], v[162:165], v[206:209], 0
	v_mfma_f32_16x16x32_bf16 v[14:17], v[154:157], v[214:217], 0
	v_mfma_f32_16x16x32_bf16 v[10:13], v[162:165], v[214:217], 0
	v_mfma_f32_16x16x32_bf16 v[62:65], v[158:161], v[190:193], v[62:65]
	v_mfma_f32_16x16x32_bf16 v[58:61], v[166:169], v[190:193], v[58:61]
	v_mfma_f32_16x16x32_bf16 v[46:49], v[158:161], v[198:201], v[46:49]
	v_mfma_f32_16x16x32_bf16 v[42:45], v[166:169], v[198:201], v[42:45]
	v_mfma_f32_16x16x32_bf16 v[30:33], v[158:161], v[210:213], v[30:33]
	v_mfma_f32_16x16x32_bf16 v[26:29], v[166:169], v[210:213], v[26:29]
	v_mfma_f32_16x16x32_bf16 v[14:17], v[158:161], v[218:221], v[14:17]
	v_mfma_f32_16x16x32_bf16 v[10:13], v[166:169], v[218:221], v[10:13]
	v_mfma_f32_16x16x32_bf16 v[54:57], v[170:173], v[186:189], 0
	v_mfma_f32_16x16x32_bf16 v[50:53], v[178:181], v[186:189], 0
	v_mfma_f32_16x16x32_bf16 v[38:41], v[170:173], v[194:197], 0
	v_mfma_f32_16x16x32_bf16 v[34:37], v[178:181], v[194:197], 0
	v_mfma_f32_16x16x32_bf16 v[22:25], v[170:173], v[206:209], 0
	v_mfma_f32_16x16x32_bf16 v[18:21], v[178:181], v[206:209], 0
	v_mfma_f32_16x16x32_bf16 v[6:9], v[170:173], v[214:217], 0
	v_mfma_f32_16x16x32_bf16 v[2:5], v[178:181], v[214:217], 0
	v_mfma_f32_16x16x32_bf16 v[54:57], v[174:177], v[190:193], v[54:57]
	v_mfma_f32_16x16x32_bf16 v[50:53], v[182:185], v[190:193], v[50:53]
	v_mfma_f32_16x16x32_bf16 v[38:41], v[174:177], v[198:201], v[38:41]
	v_mfma_f32_16x16x32_bf16 v[34:37], v[182:185], v[198:201], v[34:37]
	v_mfma_f32_16x16x32_bf16 v[22:25], v[174:177], v[210:213], v[22:25]
	v_mfma_f32_16x16x32_bf16 v[18:21], v[182:185], v[210:213], v[18:21]
	v_mfma_f32_16x16x32_bf16 v[6:9], v[174:177], v[218:221], v[6:9]
	v_mfma_f32_16x16x32_bf16 v[2:5], v[182:185], v[218:221], v[2:5]
	s_setprio 0
	s_barrier
	s_add_i32 s69, 0, 0x18000
	v_add_u32_e32 v153, s69, v149
	s_add_i32 s70, 0, 0x1c000
	ds_read_b128 v[154:157], v153
	ds_read_b128 v[158:161], v153 offset:1024
	ds_read_b128 v[162:165], v153 offset:2048
	ds_read_b128 v[166:169], v153 offset:3072
	v_add_u32_e32 v153, s70, v149
	ds_read_b128 v[170:173], v153
	ds_read_b128 v[174:177], v153 offset:1024
	ds_read_b128 v[178:181], v153 offset:2048
	ds_read_b128 v[182:185], v153 offset:3072
	s_add_u32 s46, s46, 0x40000
	s_addc_u32 s47, s47, 0
	s_mov_b32 m0, s25
	v_lshl_add_u64 v[226:227], s[46:47], 0, v[136:137]
	ds_read_b128 v[186:189], v152 offset:32768
	ds_read_b128 v[190:193], v152 offset:33792
	ds_read_b128 v[194:197], v152 offset:34816
	ds_read_b128 v[198:201], v152 offset:35840
	ds_read_b128 v[206:209], v152 offset:36864
	ds_read_b128 v[210:213], v152 offset:37888
	ds_read_b128 v[214:217], v152 offset:38912
	ds_read_b128 v[218:221], v152 offset:39936
	global_load_lds_dwordx4 v[226:227], off
	v_lshl_add_u64 v[226:227], s[46:47], 0, v[132:133]
	s_mov_b32 m0, s28
	s_nop 0
	global_load_lds_dwordx4 v[226:227], off
	s_waitcnt vmcnt(8)
	s_waitcnt lgkmcnt(0)
	s_setprio 1
	s_barrier
	v_mfma_f32_16x16x32_bf16 v[126:129], v[154:157], v[186:189], v[126:129]
	v_mfma_f32_16x16x32_bf16 v[122:125], v[162:165], v[186:189], v[122:125]
	v_mfma_f32_16x16x32_bf16 v[110:113], v[154:157], v[194:197], v[110:113]
	v_mfma_f32_16x16x32_bf16 v[106:109], v[162:165], v[194:197], v[106:109]
	v_mfma_f32_16x16x32_bf16 v[94:97], v[154:157], v[206:209], v[94:97]
	v_mfma_f32_16x16x32_bf16 v[90:93], v[162:165], v[206:209], v[90:93]
	v_mfma_f32_16x16x32_bf16 v[78:81], v[154:157], v[214:217], v[78:81]
	v_mfma_f32_16x16x32_bf16 v[74:77], v[162:165], v[214:217], v[74:77]
	v_mfma_f32_16x16x32_bf16 v[126:129], v[158:161], v[190:193], v[126:129]
	v_mfma_f32_16x16x32_bf16 v[122:125], v[166:169], v[190:193], v[122:125]
	v_mfma_f32_16x16x32_bf16 v[110:113], v[158:161], v[198:201], v[110:113]
	v_mfma_f32_16x16x32_bf16 v[106:109], v[166:169], v[198:201], v[106:109]
	v_mfma_f32_16x16x32_bf16 v[94:97], v[158:161], v[210:213], v[94:97]
	v_mfma_f32_16x16x32_bf16 v[90:93], v[166:169], v[210:213], v[90:93]
	v_mfma_f32_16x16x32_bf16 v[78:81], v[158:161], v[218:221], v[78:81]
	v_mfma_f32_16x16x32_bf16 v[74:77], v[166:169], v[218:221], v[74:77]
	v_mfma_f32_16x16x32_bf16 v[118:121], v[170:173], v[186:189], v[118:121]
	v_mfma_f32_16x16x32_bf16 v[114:117], v[178:181], v[186:189], v[114:117]
	v_mfma_f32_16x16x32_bf16 v[102:105], v[170:173], v[194:197], v[102:105]
	v_mfma_f32_16x16x32_bf16 v[98:101], v[178:181], v[194:197], v[98:101]
	v_mfma_f32_16x16x32_bf16 v[86:89], v[170:173], v[206:209], v[86:89]
	v_mfma_f32_16x16x32_bf16 v[82:85], v[178:181], v[206:209], v[82:85]
	v_mfma_f32_16x16x32_bf16 v[70:73], v[170:173], v[214:217], v[70:73]
	v_mfma_f32_16x16x32_bf16 v[66:69], v[178:181], v[214:217], v[66:69]
	v_mfma_f32_16x16x32_bf16 v[118:121], v[174:177], v[190:193], v[118:121]
	v_mfma_f32_16x16x32_bf16 v[114:117], v[182:185], v[190:193], v[114:117]
	v_mfma_f32_16x16x32_bf16 v[102:105], v[174:177], v[198:201], v[102:105]
	v_mfma_f32_16x16x32_bf16 v[98:101], v[182:185], v[198:201], v[98:101]
	v_mfma_f32_16x16x32_bf16 v[86:89], v[174:177], v[210:213], v[86:89]
	v_mfma_f32_16x16x32_bf16 v[82:85], v[182:185], v[210:213], v[82:85]
	v_mfma_f32_16x16x32_bf16 v[70:73], v[174:177], v[218:221], v[70:73]
	v_mfma_f32_16x16x32_bf16 v[66:69], v[182:185], v[218:221], v[66:69]
	s_setprio 0
	s_barrier
	s_add_i32 s46, s69, s16
	v_lshl_add_u64 v[146:147], v[146:147], 0, s[10:11]
	s_mov_b32 m0, s46
	ds_read_b128 v[186:189], v152 offset:49152
	ds_read_b128 v[190:193], v152 offset:50176
	ds_read_b128 v[194:197], v152 offset:51200
	ds_read_b128 v[198:201], v152 offset:52224
	ds_read_b128 v[206:209], v152 offset:53248
	ds_read_b128 v[210:213], v152 offset:54272
	ds_read_b128 v[214:217], v152 offset:55296
	ds_read_b128 v[218:221], v152 offset:56320
	global_load_lds_dwordx4 v[146:147], off
	s_add_i32 m0, s46, 0x2000
	s_add_u32 s44, s44, 0x40080
	v_lshl_add_u64 v[146:147], v[202:203], 0, s[10:11]
	s_addc_u32 s45, s45, 0
	s_add_i32 s46, s70, s16
	global_load_lds_dwordx4 v[146:147], off
	v_lshl_add_u64 v[146:147], s[44:45], 0, v[134:135]
	s_mov_b32 m0, s46
	s_nop 0
	global_load_lds_dwordx4 v[146:147], off
	v_lshl_add_u64 v[146:147], s[44:45], 0, v[130:131]
	s_add_i32 m0, s46, 0x2000
	s_nop 0
	global_load_lds_dwordx4 v[146:147], off
	v_lshl_add_u64 v[146:147], v[222:223], 0, s[10:11]
	s_mov_b32 m0, s33
	s_nop 0
	global_load_lds_dwordx4 v[146:147], off
	v_lshl_add_u64 v[146:147], v[224:225], 0, s[10:11]
	s_mov_b32 m0, s35
	s_nop 0
	global_load_lds_dwordx4 v[146:147], off
	s_waitcnt vmcnt(8)
	s_waitcnt lgkmcnt(0)
	s_setprio 1
	s_barrier
	v_mfma_f32_16x16x32_bf16 v[62:65], v[154:157], v[186:189], v[62:65]
	v_mfma_f32_16x16x32_bf16 v[58:61], v[162:165], v[186:189], v[58:61]
	v_mfma_f32_16x16x32_bf16 v[46:49], v[154:157], v[194:197], v[46:49]
	v_mfma_f32_16x16x32_bf16 v[42:45], v[162:165], v[194:197], v[42:45]
	v_mfma_f32_16x16x32_bf16 v[30:33], v[154:157], v[206:209], v[30:33]
	v_mfma_f32_16x16x32_bf16 v[26:29], v[162:165], v[206:209], v[26:29]
	v_mfma_f32_16x16x32_bf16 v[14:17], v[154:157], v[214:217], v[14:17]
	v_mfma_f32_16x16x32_bf16 v[10:13], v[162:165], v[214:217], v[10:13]
	v_mfma_f32_16x16x32_bf16 v[62:65], v[158:161], v[190:193], v[62:65]
	v_mfma_f32_16x16x32_bf16 v[58:61], v[166:169], v[190:193], v[58:61]
	v_mfma_f32_16x16x32_bf16 v[46:49], v[158:161], v[198:201], v[46:49]
	v_mfma_f32_16x16x32_bf16 v[42:45], v[166:169], v[198:201], v[42:45]
	v_mfma_f32_16x16x32_bf16 v[30:33], v[158:161], v[210:213], v[30:33]
	v_mfma_f32_16x16x32_bf16 v[26:29], v[166:169], v[210:213], v[26:29]
	v_mfma_f32_16x16x32_bf16 v[14:17], v[158:161], v[218:221], v[14:17]
	v_mfma_f32_16x16x32_bf16 v[10:13], v[166:169], v[218:221], v[10:13]
	v_mfma_f32_16x16x32_bf16 v[54:57], v[170:173], v[186:189], v[54:57]
	v_mfma_f32_16x16x32_bf16 v[50:53], v[178:181], v[186:189], v[50:53]
	v_mfma_f32_16x16x32_bf16 v[38:41], v[170:173], v[194:197], v[38:41]
	v_mfma_f32_16x16x32_bf16 v[34:37], v[178:181], v[194:197], v[34:37]
	v_mfma_f32_16x16x32_bf16 v[22:25], v[170:173], v[206:209], v[22:25]
	v_mfma_f32_16x16x32_bf16 v[18:21], v[178:181], v[206:209], v[18:21]
	v_mfma_f32_16x16x32_bf16 v[6:9], v[170:173], v[214:217], v[6:9]
	v_mfma_f32_16x16x32_bf16 v[2:5], v[178:181], v[214:217], v[2:5]
	v_mfma_f32_16x16x32_bf16 v[54:57], v[174:177], v[190:193], v[54:57]
	v_mfma_f32_16x16x32_bf16 v[50:53], v[182:185], v[190:193], v[50:53]
	v_mfma_f32_16x16x32_bf16 v[38:41], v[174:177], v[198:201], v[38:41]
	v_mfma_f32_16x16x32_bf16 v[34:37], v[182:185], v[198:201], v[34:37]
	v_mfma_f32_16x16x32_bf16 v[22:25], v[174:177], v[210:213], v[22:25]
	v_mfma_f32_16x16x32_bf16 v[18:21], v[182:185], v[210:213], v[18:21]
	v_mfma_f32_16x16x32_bf16 v[6:9], v[174:177], v[218:221], v[6:9]
	v_mfma_f32_16x16x32_bf16 v[2:5], v[182:185], v[218:221], v[2:5]
	s_setprio 0
	s_barrier
	s_add_i32 s68, s68, 2
	s_add_u32 s42, s42, 0x100
	s_addc_u32 s43, s43, 0
	s_add_u32 s66, s66, 0x100
	s_addc_u32 s67, s67, 0
	s_cmp_gt_u32 s68, 13
.LBB0_745:
	ds_read_b128 v[154:157], v150
	ds_read_b128 v[158:161], v150 offset:1024
	ds_read_b128 v[162:165], v150 offset:2048
	ds_read_b128 v[166:169], v150 offset:3072
	ds_read_b128 v[170:173], v151
	ds_read_b128 v[174:177], v151 offset:1024
	ds_read_b128 v[178:181], v151 offset:2048
	ds_read_b128 v[182:185], v151 offset:3072
	s_add_u32 s44, s42, 0xfffc0080
	s_addc_u32 s45, s43, -1
	s_cmp_eq_u32 s68, 12
	s_cselect_b32 s47, s14, s45
	s_cselect_b32 s46, s15, s44
	s_cselect_b32 s45, s21, s67
	s_cselect_b32 s44, s65, s66
	v_lshl_add_u64 v[146:147], s[42:43], 0, v[138:139]
	s_add_i32 m0, s19, 0xc000
	ds_read_b128 v[186:189], v152
	ds_read_b128 v[190:193], v152 offset:1024
	ds_read_b128 v[194:197], v152 offset:2048
	ds_read_b128 v[198:201], v152 offset:3072
	ds_read_b128 v[206:209], v152 offset:4096
	ds_read_b128 v[210:213], v152 offset:5120
	ds_read_b128 v[214:217], v152 offset:6144
	ds_read_b128 v[218:221], v152 offset:7168
	global_load_lds_dwordx4 v[146:147], off
	v_lshl_add_u64 v[146:147], s[42:43], 0, v[140:141]
	s_add_i32 m0, s19, 0xe000
	s_nop 0
	global_load_lds_dwordx4 v[146:147], off
	s_waitcnt vmcnt(8)
	s_waitcnt lgkmcnt(0)
	s_setprio 1
	s_barrier
	v_mfma_f32_16x16x32_bf16 v[126:129], v[154:157], v[186:189], v[126:129]
	v_mfma_f32_16x16x32_bf16 v[122:125], v[162:165], v[186:189], v[122:125]
	v_mfma_f32_16x16x32_bf16 v[110:113], v[154:157], v[194:197], v[110:113]
	v_mfma_f32_16x16x32_bf16 v[106:109], v[162:165], v[194:197], v[106:109]
	v_mfma_f32_16x16x32_bf16 v[94:97], v[154:157], v[206:209], v[94:97]
	v_mfma_f32_16x16x32_bf16 v[90:93], v[162:165], v[206:209], v[90:93]
	v_mfma_f32_16x16x32_bf16 v[78:81], v[154:157], v[214:217], v[78:81]
	v_mfma_f32_16x16x32_bf16 v[74:77], v[162:165], v[214:217], v[74:77]
	v_mfma_f32_16x16x32_bf16 v[126:129], v[158:161], v[190:193], v[126:129]
	v_mfma_f32_16x16x32_bf16 v[122:125], v[166:169], v[190:193], v[122:125]
	v_mfma_f32_16x16x32_bf16 v[110:113], v[158:161], v[198:201], v[110:113]
	v_mfma_f32_16x16x32_bf16 v[106:109], v[166:169], v[198:201], v[106:109]
	v_mfma_f32_16x16x32_bf16 v[94:97], v[158:161], v[210:213], v[94:97]
	v_mfma_f32_16x16x32_bf16 v[90:93], v[166:169], v[210:213], v[90:93]
	v_mfma_f32_16x16x32_bf16 v[78:81], v[158:161], v[218:221], v[78:81]
	v_mfma_f32_16x16x32_bf16 v[74:77], v[166:169], v[218:221], v[74:77]
	v_mfma_f32_16x16x32_bf16 v[118:121], v[170:173], v[186:189], v[118:121]
	v_mfma_f32_16x16x32_bf16 v[114:117], v[178:181], v[186:189], v[114:117]
	v_mfma_f32_16x16x32_bf16 v[102:105], v[170:173], v[194:197], v[102:105]
	v_mfma_f32_16x16x32_bf16 v[98:101], v[178:181], v[194:197], v[98:101]
	v_mfma_f32_16x16x32_bf16 v[86:89], v[170:173], v[206:209], v[86:89]
	v_mfma_f32_16x16x32_bf16 v[82:85], v[178:181], v[206:209], v[82:85]
	v_mfma_f32_16x16x32_bf16 v[70:73], v[170:173], v[214:217], v[70:73]
	v_mfma_f32_16x16x32_bf16 v[66:69], v[178:181], v[214:217], v[66:69]
	v_mfma_f32_16x16x32_bf16 v[118:121], v[174:177], v[190:193], v[118:121]
	v_mfma_f32_16x16x32_bf16 v[114:117], v[182:185], v[190:193], v[114:117]
	v_mfma_f32_16x16x32_bf16 v[102:105], v[174:177], v[198:201], v[102:105]
	v_mfma_f32_16x16x32_bf16 v[98:101], v[182:185], v[198:201], v[98:101]
	v_mfma_f32_16x16x32_bf16 v[86:89], v[174:177], v[210:213], v[86:89]
	v_mfma_f32_16x16x32_bf16 v[82:85], v[182:185], v[210:213], v[82:85]
	v_mfma_f32_16x16x32_bf16 v[70:73], v[174:177], v[218:221], v[70:73]
	v_mfma_f32_16x16x32_bf16 v[66:69], v[182:185], v[218:221], v[66:69]
	s_setprio 0
	s_barrier
	s_add_i32 s69, s49, s16
	v_lshl_add_u64 v[146:147], s[44:45], 0, v[134:135]
	s_mov_b32 m0, s69
	ds_read_b128 v[186:189], v152 offset:16384
	ds_read_b128 v[190:193], v152 offset:17408
	ds_read_b128 v[194:197], v152 offset:18432
	ds_read_b128 v[198:201], v152 offset:19456
	ds_read_b128 v[206:209], v152 offset:20480
	ds_read_b128 v[210:213], v152 offset:21504
	ds_read_b128 v[214:217], v152 offset:22528
	ds_read_b128 v[218:221], v152 offset:23552
	global_load_lds_dwordx4 v[146:147], off
	s_add_i32 m0, s69, 0x2000
	s_add_u32 s70, s44, 0x40000
	v_lshl_add_u64 v[202:203], s[44:45], 0, v[130:131]
	s_addc_u32 s71, s45, 0
	s_add_i32 s69, s62, s16
	global_load_lds_dwordx4 v[202:203], off
	v_lshl_add_u64 v[222:223], s[70:71], 0, v[134:135]
	s_mov_b32 m0, s69
	v_lshl_add_u64 v[224:225], s[46:47], 0, v[132:133]
	global_load_lds_dwordx4 v[222:223], off
	v_lshl_add_u64 v[222:223], s[70:71], 0, v[130:131]
	s_add_i32 m0, s69, 0x2000
	s_nop 0
	global_load_lds_dwordx4 v[222:223], off
	v_lshl_add_u64 v[222:223], s[46:47], 0, v[136:137]
	s_mov_b32 m0, s19
	s_nop 0
	global_load_lds_dwordx4 v[222:223], off
	s_mov_b32 m0, s24
	s_nop 0
	global_load_lds_dwordx4 v[224:225], off
	s_waitcnt vmcnt(8)
	s_waitcnt lgkmcnt(0)
	s_setprio 1
	s_barrier
	v_mfma_f32_16x16x32_bf16 v[62:65], v[154:157], v[186:189], v[62:65]
	v_mfma_f32_16x16x32_bf16 v[58:61], v[162:165], v[186:189], v[58:61]
	v_mfma_f32_16x16x32_bf16 v[46:49], v[154:157], v[194:197], v[46:49]
	v_mfma_f32_16x16x32_bf16 v[42:45], v[162:165], v[194:197], v[42:45]
	v_mfma_f32_16x16x32_bf16 v[30:33], v[154:157], v[206:209], v[30:33]
	v_mfma_f32_16x16x32_bf16 v[26:29], v[162:165], v[206:209], v[26:29]
	v_mfma_f32_16x16x32_bf16 v[14:17], v[154:157], v[214:217], v[14:17]
	v_mfma_f32_16x16x32_bf16 v[10:13], v[162:165], v[214:217], v[10:13]
	v_mfma_f32_16x16x32_bf16 v[62:65], v[158:161], v[190:193], v[62:65]
	v_mfma_f32_16x16x32_bf16 v[58:61], v[166:169], v[190:193], v[58:61]
	v_mfma_f32_16x16x32_bf16 v[46:49], v[158:161], v[198:201], v[46:49]
	v_mfma_f32_16x16x32_bf16 v[42:45], v[166:169], v[198:201], v[42:45]
	v_mfma_f32_16x16x32_bf16 v[30:33], v[158:161], v[210:213], v[30:33]
	v_mfma_f32_16x16x32_bf16 v[26:29], v[166:169], v[210:213], v[26:29]
	v_mfma_f32_16x16x32_bf16 v[14:17], v[158:161], v[218:221], v[14:17]
	v_mfma_f32_16x16x32_bf16 v[10:13], v[166:169], v[218:221], v[10:13]
	v_mfma_f32_16x16x32_bf16 v[54:57], v[170:173], v[186:189], v[54:57]
	v_mfma_f32_16x16x32_bf16 v[50:53], v[178:181], v[186:189], v[50:53]
	v_mfma_f32_16x16x32_bf16 v[38:41], v[170:173], v[194:197], v[38:41]
	v_mfma_f32_16x16x32_bf16 v[34:37], v[178:181], v[194:197], v[34:37]
	v_mfma_f32_16x16x32_bf16 v[22:25], v[170:173], v[206:209], v[22:25]
	v_mfma_f32_16x16x32_bf16 v[18:21], v[178:181], v[206:209], v[18:21]
	v_mfma_f32_16x16x32_bf16 v[6:9], v[170:173], v[214:217], v[6:9]
	v_mfma_f32_16x16x32_bf16 v[2:5], v[178:181], v[214:217], v[2:5]
	v_mfma_f32_16x16x32_bf16 v[54:57], v[174:177], v[190:193], v[54:57]
	v_mfma_f32_16x16x32_bf16 v[50:53], v[182:185], v[190:193], v[50:53]
	v_mfma_f32_16x16x32_bf16 v[38:41], v[174:177], v[198:201], v[38:41]
	v_mfma_f32_16x16x32_bf16 v[34:37], v[182:185], v[198:201], v[34:37]
	v_mfma_f32_16x16x32_bf16 v[22:25], v[174:177], v[210:213], v[22:25]
	v_mfma_f32_16x16x32_bf16 v[18:21], v[182:185], v[210:213], v[18:21]
	v_mfma_f32_16x16x32_bf16 v[6:9], v[174:177], v[218:221], v[6:9]
	v_mfma_f32_16x16x32_bf16 v[2:5], v[182:185], v[218:221], v[2:5]
	s_setprio 0
	s_barrier
	s_add_i32 s69, 0, 0x18000
	v_add_u32_e32 v153, s69, v149
	s_add_i32 s70, 0, 0x1c000
	ds_read_b128 v[154:157], v153
	ds_read_b128 v[158:161], v153 offset:1024
	ds_read_b128 v[162:165], v153 offset:2048
	ds_read_b128 v[166:169], v153 offset:3072
	v_add_u32_e32 v153, s70, v149
	ds_read_b128 v[170:173], v153
	ds_read_b128 v[174:177], v153 offset:1024
	ds_read_b128 v[178:181], v153 offset:2048
	ds_read_b128 v[182:185], v153 offset:3072
	s_add_u32 s46, s46, 0x40000
	s_addc_u32 s47, s47, 0
	s_mov_b32 m0, s25
	v_lshl_add_u64 v[226:227], s[46:47], 0, v[136:137]
	ds_read_b128 v[186:189], v152 offset:32768
	ds_read_b128 v[190:193], v152 offset:33792
	ds_read_b128 v[194:197], v152 offset:34816
	ds_read_b128 v[198:201], v152 offset:35840
	ds_read_b128 v[206:209], v152 offset:36864
	ds_read_b128 v[210:213], v152 offset:37888
	ds_read_b128 v[214:217], v152 offset:38912
	ds_read_b128 v[218:221], v152 offset:39936
	global_load_lds_dwordx4 v[226:227], off
	v_lshl_add_u64 v[226:227], s[46:47], 0, v[132:133]
	s_mov_b32 m0, s28
	s_nop 0
	global_load_lds_dwordx4 v[226:227], off
	s_waitcnt vmcnt(8)
	s_waitcnt lgkmcnt(0)
	s_setprio 1
	s_barrier
	v_mfma_f32_16x16x32_bf16 v[126:129], v[154:157], v[186:189], v[126:129]
	v_mfma_f32_16x16x32_bf16 v[122:125], v[162:165], v[186:189], v[122:125]
	v_mfma_f32_16x16x32_bf16 v[110:113], v[154:157], v[194:197], v[110:113]
	v_mfma_f32_16x16x32_bf16 v[106:109], v[162:165], v[194:197], v[106:109]
	v_mfma_f32_16x16x32_bf16 v[94:97], v[154:157], v[206:209], v[94:97]
	v_mfma_f32_16x16x32_bf16 v[90:93], v[162:165], v[206:209], v[90:93]
	v_mfma_f32_16x16x32_bf16 v[78:81], v[154:157], v[214:217], v[78:81]
	v_mfma_f32_16x16x32_bf16 v[74:77], v[162:165], v[214:217], v[74:77]
	v_mfma_f32_16x16x32_bf16 v[126:129], v[158:161], v[190:193], v[126:129]
	v_mfma_f32_16x16x32_bf16 v[122:125], v[166:169], v[190:193], v[122:125]
	v_mfma_f32_16x16x32_bf16 v[110:113], v[158:161], v[198:201], v[110:113]
	v_mfma_f32_16x16x32_bf16 v[106:109], v[166:169], v[198:201], v[106:109]
	v_mfma_f32_16x16x32_bf16 v[94:97], v[158:161], v[210:213], v[94:97]
	v_mfma_f32_16x16x32_bf16 v[90:93], v[166:169], v[210:213], v[90:93]
	v_mfma_f32_16x16x32_bf16 v[78:81], v[158:161], v[218:221], v[78:81]
	v_mfma_f32_16x16x32_bf16 v[74:77], v[166:169], v[218:221], v[74:77]
	v_mfma_f32_16x16x32_bf16 v[118:121], v[170:173], v[186:189], v[118:121]
	v_mfma_f32_16x16x32_bf16 v[114:117], v[178:181], v[186:189], v[114:117]
	v_mfma_f32_16x16x32_bf16 v[102:105], v[170:173], v[194:197], v[102:105]
	v_mfma_f32_16x16x32_bf16 v[98:101], v[178:181], v[194:197], v[98:101]
	v_mfma_f32_16x16x32_bf16 v[86:89], v[170:173], v[206:209], v[86:89]
	v_mfma_f32_16x16x32_bf16 v[82:85], v[178:181], v[206:209], v[82:85]
	v_mfma_f32_16x16x32_bf16 v[70:73], v[170:173], v[214:217], v[70:73]
	v_mfma_f32_16x16x32_bf16 v[66:69], v[178:181], v[214:217], v[66:69]
	v_mfma_f32_16x16x32_bf16 v[118:121], v[174:177], v[190:193], v[118:121]
	v_mfma_f32_16x16x32_bf16 v[114:117], v[182:185], v[190:193], v[114:117]
	v_mfma_f32_16x16x32_bf16 v[102:105], v[174:177], v[198:201], v[102:105]
	v_mfma_f32_16x16x32_bf16 v[98:101], v[182:185], v[198:201], v[98:101]
	v_mfma_f32_16x16x32_bf16 v[86:89], v[174:177], v[210:213], v[86:89]
	v_mfma_f32_16x16x32_bf16 v[82:85], v[182:185], v[210:213], v[82:85]
	v_mfma_f32_16x16x32_bf16 v[70:73], v[174:177], v[218:221], v[70:73]
	v_mfma_f32_16x16x32_bf16 v[66:69], v[182:185], v[218:221], v[66:69]
	s_setprio 0
	s_barrier
	s_add_i32 s46, s69, s16
	v_lshl_add_u64 v[146:147], v[146:147], 0, s[10:11]
	s_mov_b32 m0, s46
	ds_read_b128 v[186:189], v152 offset:49152
	ds_read_b128 v[190:193], v152 offset:50176
	ds_read_b128 v[194:197], v152 offset:51200
	ds_read_b128 v[198:201], v152 offset:52224
	ds_read_b128 v[206:209], v152 offset:53248
	ds_read_b128 v[210:213], v152 offset:54272
	ds_read_b128 v[214:217], v152 offset:55296
	ds_read_b128 v[218:221], v152 offset:56320
	global_load_lds_dwordx4 v[146:147], off
	s_add_i32 m0, s46, 0x2000
	s_add_u32 s44, s44, 0x40080
	v_lshl_add_u64 v[146:147], v[202:203], 0, s[10:11]
	s_addc_u32 s45, s45, 0
	s_add_i32 s46, s70, s16
	global_load_lds_dwordx4 v[146:147], off
	v_lshl_add_u64 v[146:147], s[44:45], 0, v[134:135]
	s_mov_b32 m0, s46
	s_nop 0
	global_load_lds_dwordx4 v[146:147], off
	v_lshl_add_u64 v[146:147], s[44:45], 0, v[130:131]
	s_add_i32 m0, s46, 0x2000
	s_nop 0
	global_load_lds_dwordx4 v[146:147], off
	v_lshl_add_u64 v[146:147], v[222:223], 0, s[10:11]
	s_mov_b32 m0, s33
	s_nop 0
	global_load_lds_dwordx4 v[146:147], off
	v_lshl_add_u64 v[146:147], v[224:225], 0, s[10:11]
	s_mov_b32 m0, s35
	s_nop 0
	global_load_lds_dwordx4 v[146:147], off
	s_waitcnt vmcnt(8)
	s_waitcnt lgkmcnt(0)
	s_setprio 1
	s_barrier
	v_mfma_f32_16x16x32_bf16 v[62:65], v[154:157], v[186:189], v[62:65]
	v_mfma_f32_16x16x32_bf16 v[58:61], v[162:165], v[186:189], v[58:61]
	v_mfma_f32_16x16x32_bf16 v[46:49], v[154:157], v[194:197], v[46:49]
	v_mfma_f32_16x16x32_bf16 v[42:45], v[162:165], v[194:197], v[42:45]
	v_mfma_f32_16x16x32_bf16 v[30:33], v[154:157], v[206:209], v[30:33]
	v_mfma_f32_16x16x32_bf16 v[26:29], v[162:165], v[206:209], v[26:29]
	v_mfma_f32_16x16x32_bf16 v[14:17], v[154:157], v[214:217], v[14:17]
	v_mfma_f32_16x16x32_bf16 v[10:13], v[162:165], v[214:217], v[10:13]
	v_mfma_f32_16x16x32_bf16 v[62:65], v[158:161], v[190:193], v[62:65]
	v_mfma_f32_16x16x32_bf16 v[58:61], v[166:169], v[190:193], v[58:61]
	v_mfma_f32_16x16x32_bf16 v[46:49], v[158:161], v[198:201], v[46:49]
	v_mfma_f32_16x16x32_bf16 v[42:45], v[166:169], v[198:201], v[42:45]
	v_mfma_f32_16x16x32_bf16 v[30:33], v[158:161], v[210:213], v[30:33]
	v_mfma_f32_16x16x32_bf16 v[26:29], v[166:169], v[210:213], v[26:29]
	v_mfma_f32_16x16x32_bf16 v[14:17], v[158:161], v[218:221], v[14:17]
	v_mfma_f32_16x16x32_bf16 v[10:13], v[166:169], v[218:221], v[10:13]
	v_mfma_f32_16x16x32_bf16 v[54:57], v[170:173], v[186:189], v[54:57]
	v_mfma_f32_16x16x32_bf16 v[50:53], v[178:181], v[186:189], v[50:53]
	v_mfma_f32_16x16x32_bf16 v[38:41], v[170:173], v[194:197], v[38:41]
	v_mfma_f32_16x16x32_bf16 v[34:37], v[178:181], v[194:197], v[34:37]
	v_mfma_f32_16x16x32_bf16 v[22:25], v[170:173], v[206:209], v[22:25]
	v_mfma_f32_16x16x32_bf16 v[18:21], v[178:181], v[206:209], v[18:21]
	v_mfma_f32_16x16x32_bf16 v[6:9], v[170:173], v[214:217], v[6:9]
	v_mfma_f32_16x16x32_bf16 v[2:5], v[178:181], v[214:217], v[2:5]
	v_mfma_f32_16x16x32_bf16 v[54:57], v[174:177], v[190:193], v[54:57]
	v_mfma_f32_16x16x32_bf16 v[50:53], v[182:185], v[190:193], v[50:53]
	v_mfma_f32_16x16x32_bf16 v[38:41], v[174:177], v[198:201], v[38:41]
	v_mfma_f32_16x16x32_bf16 v[34:37], v[182:185], v[198:201], v[34:37]
	v_mfma_f32_16x16x32_bf16 v[22:25], v[174:177], v[210:213], v[22:25]
	v_mfma_f32_16x16x32_bf16 v[18:21], v[182:185], v[210:213], v[18:21]
	v_mfma_f32_16x16x32_bf16 v[6:9], v[174:177], v[218:221], v[6:9]
	v_mfma_f32_16x16x32_bf16 v[2:5], v[182:185], v[218:221], v[2:5]
	s_setprio 0
	s_barrier
	s_add_i32 s68, s68, 2
	s_add_u32 s42, s42, 0x100
	s_addc_u32 s43, s43, 0
	s_add_u32 s66, s66, 0x100
	s_addc_u32 s67, s67, 0
	s_cmp_gt_u32 s68, 13
	s_cbranch_scc0 .LBB0_745
	s_and_b64 vcc, exec, s[12:13]
	s_cbranch_vccz .LBB0_748
	s_barrier

.LBB0_833:
	s_add_u32 s72, s0, s68
	s_addc_u32 s73, s1, s69
	s_and_b64 s[62:63], s[70:71], exec
	s_cselect_b32 s15, s73, s77
	s_cselect_b32 s33, s72, s76
	s_add_u32 s74, s35, s66
	s_addc_u32 s75, s85, s67
	s_and_b64 s[62:63], s[70:71], exec
	s_cselect_b32 s34, s75, s79
	s_cselect_b32 s39, s74, s78
	s_add_i32 s45, s7, -2
	s_add_u32 s76, s76, 0x100080
	s_addc_u32 s77, s77, 0
	s_add_u32 s47, s78, 0x100
	s_addc_u32 s62, s79, 0
	s_mov_b32 s63, 0
	s_waitcnt vmcnt(0)
	ds_read_b128 v[114:117], v190
	ds_read_b128 v[118:121], v190 offset:1024
	ds_read_b128 v[122:125], v190 offset:2048
	ds_read_b128 v[126:129], v190 offset:3072
	ds_read_b128 v[146:149], v191
	ds_read_b128 v[150:153], v191 offset:1024
	ds_read_b128 v[154:157], v191 offset:2048
	ds_read_b128 v[158:161], v191 offset:3072
	s_add_i32 s82, s63, 2
	s_add_u32 s78, s76, 0xfff00080
	s_addc_u32 s79, s77, -1
	s_cmp_eq_u32 s45, s63
	s_cselect_b32 s81, s15, s79
	s_cselect_b32 s80, s33, s78
	s_cselect_b32 s79, s34, s62
	s_cselect_b32 s78, s39, s47
	v_lshl_add_u64 v[186:187], s[76:77], 0, v[180:181]
	s_add_i32 m0, s87, 0xc000
	ds_read_b128 v[162:165], v192
	ds_read_b128 v[166:169], v192 offset:1024
	ds_read_b128 v[194:197], v192 offset:2048
	ds_read_b128 v[198:201], v192 offset:3072
	ds_read_b128 v[206:209], v192 offset:4096
	ds_read_b128 v[210:213], v192 offset:5120
	ds_read_b128 v[214:217], v192 offset:6144
	ds_read_b128 v[218:221], v192 offset:7168
	global_load_lds_dwordx4 v[186:187], off
	v_lshl_add_u64 v[186:187], s[76:77], 0, v[182:183]
	s_add_i32 m0, s87, 0xe000
	s_nop 0
	global_load_lds_dwordx4 v[186:187], off
	s_waitcnt vmcnt(8)
	s_waitcnt lgkmcnt(0)
	s_setprio 1
	s_barrier
	v_mfma_f32_16x16x32_bf16 v[142:145], v[114:117], v[162:165], 0
	v_mfma_f32_16x16x32_bf16 v[138:141], v[122:125], v[162:165], 0
	v_mfma_f32_16x16x32_bf16 v[110:113], v[114:117], v[194:197], 0
	v_mfma_f32_16x16x32_bf16 v[106:109], v[122:125], v[194:197], 0
	v_mfma_f32_16x16x32_bf16 v[98:101], v[114:117], v[206:209], 0
	v_mfma_f32_16x16x32_bf16 v[90:93], v[122:125], v[206:209], 0
	v_mfma_f32_16x16x32_bf16 v[82:85], v[114:117], v[214:217], 0
	v_mfma_f32_16x16x32_bf16 v[74:77], v[122:125], v[214:217], 0
	v_mfma_f32_16x16x32_bf16 v[142:145], v[118:121], v[166:169], v[142:145]
	v_mfma_f32_16x16x32_bf16 v[138:141], v[126:129], v[166:169], v[138:141]
	v_mfma_f32_16x16x32_bf16 v[110:113], v[118:121], v[198:201], v[110:113]
	v_mfma_f32_16x16x32_bf16 v[106:109], v[126:129], v[198:201], v[106:109]
	v_mfma_f32_16x16x32_bf16 v[98:101], v[118:121], v[210:213], v[98:101]
	v_mfma_f32_16x16x32_bf16 v[90:93], v[126:129], v[210:213], v[90:93]
	v_mfma_f32_16x16x32_bf16 v[82:85], v[118:121], v[218:221], v[82:85]
	v_mfma_f32_16x16x32_bf16 v[74:77], v[126:129], v[218:221], v[74:77]
	v_mfma_f32_16x16x32_bf16 v[134:137], v[146:149], v[162:165], 0
	v_mfma_f32_16x16x32_bf16 v[130:133], v[154:157], v[162:165], 0
	v_mfma_f32_16x16x32_bf16 v[102:105], v[146:149], v[194:197], 0
	v_mfma_f32_16x16x32_bf16 v[94:97], v[154:157], v[194:197], 0
	v_mfma_f32_16x16x32_bf16 v[86:89], v[146:149], v[206:209], 0
	v_mfma_f32_16x16x32_bf16 v[78:81], v[154:157], v[206:209], 0
	v_mfma_f32_16x16x32_bf16 v[70:73], v[146:149], v[214:217], 0
	v_mfma_f32_16x16x32_bf16 v[66:69], v[154:157], v[214:217], 0
	v_mfma_f32_16x16x32_bf16 v[134:137], v[150:153], v[166:169], v[134:137]
	v_mfma_f32_16x16x32_bf16 v[130:133], v[158:161], v[166:169], v[130:133]
	v_mfma_f32_16x16x32_bf16 v[102:105], v[150:153], v[198:201], v[102:105]
	v_mfma_f32_16x16x32_bf16 v[94:97], v[158:161], v[198:201], v[94:97]
	v_mfma_f32_16x16x32_bf16 v[86:89], v[150:153], v[210:213], v[86:89]
	v_mfma_f32_16x16x32_bf16 v[78:81], v[158:161], v[210:213], v[78:81]
	v_mfma_f32_16x16x32_bf16 v[70:73], v[150:153], v[218:221], v[70:73]
	v_mfma_f32_16x16x32_bf16 v[66:69], v[158:161], v[218:221], v[66:69]
	s_setprio 0
	s_barrier
	s_add_i32 s63, s24, s86
	v_lshl_add_u64 v[186:187], s[78:79], 0, v[172:173]
	s_mov_b32 m0, s63
	ds_read_b128 v[162:165], v192 offset:16384
	ds_read_b128 v[166:169], v192 offset:17408
	ds_read_b128 v[194:197], v192 offset:18432
	ds_read_b128 v[198:201], v192 offset:19456
	ds_read_b128 v[206:209], v192 offset:20480
	ds_read_b128 v[210:213], v192 offset:21504
	ds_read_b128 v[214:217], v192 offset:22528
	ds_read_b128 v[218:221], v192 offset:23552
	global_load_lds_dwordx4 v[186:187], off
	s_add_i32 m0, s63, 0x2000
	s_add_u32 vcc_lo, s78, 0x100000
	v_lshl_add_u64 v[202:203], s[78:79], 0, v[176:177]
	s_addc_u32 vcc_hi, s79, 0
	s_add_i32 s63, s25, s86
	global_load_lds_dwordx4 v[202:203], off
	v_lshl_add_u64 v[222:223], vcc, 0, v[172:173]
	s_mov_b32 m0, s63
	v_lshl_add_u64 v[224:225], s[80:81], 0, v[174:175]
	global_load_lds_dwordx4 v[222:223], off
	v_lshl_add_u64 v[222:223], vcc, 0, v[176:177]
	s_add_i32 m0, s63, 0x2000
	s_nop 0
	global_load_lds_dwordx4 v[222:223], off
	v_lshl_add_u64 v[222:223], s[80:81], 0, v[170:171]
	s_mov_b32 m0, s87
	s_nop 0
	global_load_lds_dwordx4 v[222:223], off
	s_mov_b32 m0, s88
	s_nop 0
	global_load_lds_dwordx4 v[224:225], off
	s_waitcnt vmcnt(8)
	s_waitcnt lgkmcnt(0)
	s_setprio 1
	s_barrier
	v_mfma_f32_16x16x32_bf16 v[62:65], v[114:117], v[162:165], 0
	v_mfma_f32_16x16x32_bf16 v[58:61], v[122:125], v[162:165], 0
	v_mfma_f32_16x16x32_bf16 v[50:53], v[114:117], v[194:197], 0
	v_mfma_f32_16x16x32_bf16 v[42:45], v[122:125], v[194:197], 0
	v_mfma_f32_16x16x32_bf16 v[34:37], v[114:117], v[206:209], 0
	v_mfma_f32_16x16x32_bf16 v[26:29], v[122:125], v[206:209], 0
	v_mfma_f32_16x16x32_bf16 v[18:21], v[114:117], v[214:217], 0
	v_mfma_f32_16x16x32_bf16 v[10:13], v[122:125], v[214:217], 0
	v_mfma_f32_16x16x32_bf16 v[62:65], v[118:121], v[166:169], v[62:65]
	v_mfma_f32_16x16x32_bf16 v[58:61], v[126:129], v[166:169], v[58:61]
	v_mfma_f32_16x16x32_bf16 v[50:53], v[118:121], v[198:201], v[50:53]
	v_mfma_f32_16x16x32_bf16 v[42:45], v[126:129], v[198:201], v[42:45]
	v_mfma_f32_16x16x32_bf16 v[34:37], v[118:121], v[210:213], v[34:37]
	v_mfma_f32_16x16x32_bf16 v[26:29], v[126:129], v[210:213], v[26:29]
	v_mfma_f32_16x16x32_bf16 v[18:21], v[118:121], v[218:221], v[18:21]
	v_mfma_f32_16x16x32_bf16 v[10:13], v[126:129], v[218:221], v[10:13]
	v_mfma_f32_16x16x32_bf16 v[54:57], v[146:149], v[162:165], 0
	v_mfma_f32_16x16x32_bf16 v[46:49], v[154:157], v[162:165], 0
	v_mfma_f32_16x16x32_bf16 v[38:41], v[146:149], v[194:197], 0
	v_mfma_f32_16x16x32_bf16 v[30:33], v[154:157], v[194:197], 0
	v_mfma_f32_16x16x32_bf16 v[22:25], v[146:149], v[206:209], 0
	v_mfma_f32_16x16x32_bf16 v[14:17], v[154:157], v[206:209], 0
	v_mfma_f32_16x16x32_bf16 v[6:9], v[146:149], v[214:217], 0
	v_mfma_f32_16x16x32_bf16 v[2:5], v[154:157], v[214:217], 0
	v_mfma_f32_16x16x32_bf16 v[54:57], v[150:153], v[166:169], v[54:57]
	v_mfma_f32_16x16x32_bf16 v[46:49], v[158:161], v[166:169], v[46:49]
	v_mfma_f32_16x16x32_bf16 v[38:41], v[150:153], v[198:201], v[38:41]
	v_mfma_f32_16x16x32_bf16 v[30:33], v[158:161], v[198:201], v[30:33]
	v_mfma_f32_16x16x32_bf16 v[22:25], v[150:153], v[210:213], v[22:25]
	v_mfma_f32_16x16x32_bf16 v[14:17], v[158:161], v[210:213], v[14:17]
	v_mfma_f32_16x16x32_bf16 v[6:9], v[150:153], v[218:221], v[6:9]
	v_mfma_f32_16x16x32_bf16 v[2:5], v[158:161], v[218:221], v[2:5]
	s_setprio 0
	s_barrier
	s_add_i32 s63, 0, 0x18000
	s_add_i32 s83, 0, 0x1c000
	v_add_u32_e32 v126, s63, v189
	v_add_u32_e32 v158, s83, v189
	ds_read_b128 v[114:117], v126
	ds_read_b128 v[118:121], v126 offset:1024
	ds_read_b128 v[122:125], v126 offset:2048
	ds_read_b128 v[126:129], v126 offset:3072
	ds_read_b128 v[146:149], v158
	ds_read_b128 v[150:153], v158 offset:1024
	ds_read_b128 v[154:157], v158 offset:2048
	ds_read_b128 v[158:161], v158 offset:3072
	s_add_u32 s80, s80, 0x100000
	s_addc_u32 s81, s81, 0
	s_mov_b32 m0, s89
	v_lshl_add_u64 v[226:227], s[80:81], 0, v[170:171]
	ds_read_b128 v[162:165], v192 offset:32768
	ds_read_b128 v[166:169], v192 offset:33792
	ds_read_b128 v[194:197], v192 offset:34816
	ds_read_b128 v[198:201], v192 offset:35840
	ds_read_b128 v[206:209], v192 offset:36864
	ds_read_b128 v[210:213], v192 offset:37888
	ds_read_b128 v[214:217], v192 offset:38912
	ds_read_b128 v[218:221], v192 offset:39936
	global_load_lds_dwordx4 v[226:227], off
	v_lshl_add_u64 v[226:227], s[80:81], 0, v[174:175]
	s_mov_b32 m0, s90
	s_nop 0
	global_load_lds_dwordx4 v[226:227], off
	s_waitcnt vmcnt(8)
	s_waitcnt lgkmcnt(0)
	s_setprio 1
	s_barrier
	v_mfma_f32_16x16x32_bf16 v[142:145], v[114:117], v[162:165], v[142:145]
	v_mfma_f32_16x16x32_bf16 v[138:141], v[122:125], v[162:165], v[138:141]
	v_mfma_f32_16x16x32_bf16 v[110:113], v[114:117], v[194:197], v[110:113]
	v_mfma_f32_16x16x32_bf16 v[106:109], v[122:125], v[194:197], v[106:109]
	v_mfma_f32_16x16x32_bf16 v[98:101], v[114:117], v[206:209], v[98:101]
	v_mfma_f32_16x16x32_bf16 v[90:93], v[122:125], v[206:209], v[90:93]
	v_mfma_f32_16x16x32_bf16 v[82:85], v[114:117], v[214:217], v[82:85]
	v_mfma_f32_16x16x32_bf16 v[74:77], v[122:125], v[214:217], v[74:77]
	v_mfma_f32_16x16x32_bf16 v[142:145], v[118:121], v[166:169], v[142:145]
	v_mfma_f32_16x16x32_bf16 v[138:141], v[126:129], v[166:169], v[138:141]
	v_mfma_f32_16x16x32_bf16 v[110:113], v[118:121], v[198:201], v[110:113]
	v_mfma_f32_16x16x32_bf16 v[106:109], v[126:129], v[198:201], v[106:109]
	v_mfma_f32_16x16x32_bf16 v[98:101], v[118:121], v[210:213], v[98:101]
	v_mfma_f32_16x16x32_bf16 v[90:93], v[126:129], v[210:213], v[90:93]
	v_mfma_f32_16x16x32_bf16 v[82:85], v[118:121], v[218:221], v[82:85]
	v_mfma_f32_16x16x32_bf16 v[74:77], v[126:129], v[218:221], v[74:77]
	v_mfma_f32_16x16x32_bf16 v[134:137], v[146:149], v[162:165], v[134:137]
	v_mfma_f32_16x16x32_bf16 v[130:133], v[154:157], v[162:165], v[130:133]
	v_mfma_f32_16x16x32_bf16 v[102:105], v[146:149], v[194:197], v[102:105]
	v_mfma_f32_16x16x32_bf16 v[94:97], v[154:157], v[194:197], v[94:97]
	v_mfma_f32_16x16x32_bf16 v[86:89], v[146:149], v[206:209], v[86:89]
	v_mfma_f32_16x16x32_bf16 v[78:81], v[154:157], v[206:209], v[78:81]
	v_mfma_f32_16x16x32_bf16 v[70:73], v[146:149], v[214:217], v[70:73]
	v_mfma_f32_16x16x32_bf16 v[66:69], v[154:157], v[214:217], v[66:69]
	v_mfma_f32_16x16x32_bf16 v[134:137], v[150:153], v[166:169], v[134:137]
	v_mfma_f32_16x16x32_bf16 v[130:133], v[158:161], v[166:169], v[130:133]
	v_mfma_f32_16x16x32_bf16 v[102:105], v[150:153], v[198:201], v[102:105]
	v_mfma_f32_16x16x32_bf16 v[94:97], v[158:161], v[198:201], v[94:97]
	v_mfma_f32_16x16x32_bf16 v[86:89], v[150:153], v[210:213], v[86:89]
	v_mfma_f32_16x16x32_bf16 v[78:81], v[158:161], v[210:213], v[78:81]
	v_mfma_f32_16x16x32_bf16 v[70:73], v[150:153], v[218:221], v[70:73]
	v_mfma_f32_16x16x32_bf16 v[66:69], v[158:161], v[218:221], v[66:69]
	s_setprio 0
	s_barrier
	s_add_i32 s63, s63, s86
	v_lshl_add_u64 v[186:187], v[186:187], 0, s[22:23]
	s_mov_b32 m0, s63
	ds_read_b128 v[162:165], v192 offset:49152
	ds_read_b128 v[166:169], v192 offset:50176
	ds_read_b128 v[194:197], v192 offset:51200
	ds_read_b128 v[198:201], v192 offset:52224
	ds_read_b128 v[206:209], v192 offset:53248
	ds_read_b128 v[210:213], v192 offset:54272
	ds_read_b128 v[214:217], v192 offset:55296
	ds_read_b128 v[218:221], v192 offset:56320
	global_load_lds_dwordx4 v[186:187], off
	s_add_i32 m0, s63, 0x2000
	s_add_u32 s78, s78, 0x100080
	v_lshl_add_u64 v[186:187], v[202:203], 0, s[22:23]
	s_addc_u32 s79, s79, 0
	s_add_i32 s63, s83, s86
	global_load_lds_dwordx4 v[186:187], off
	v_lshl_add_u64 v[186:187], s[78:79], 0, v[172:173]
	s_mov_b32 m0, s63
	s_nop 0
	global_load_lds_dwordx4 v[186:187], off
	v_lshl_add_u64 v[186:187], s[78:79], 0, v[176:177]
	s_add_i32 m0, s63, 0x2000
	s_nop 0
	global_load_lds_dwordx4 v[186:187], off
	v_lshl_add_u64 v[186:187], v[222:223], 0, s[22:23]
	s_mov_b32 m0, s95
	s_nop 0
	global_load_lds_dwordx4 v[186:187], off
	v_lshl_add_u64 v[186:187], v[224:225], 0, s[22:23]
	s_mov_b32 m0, s96
	s_nop 0
	global_load_lds_dwordx4 v[186:187], off
	s_waitcnt vmcnt(8)
	s_waitcnt lgkmcnt(0)
	s_setprio 1
	s_barrier
	v_mfma_f32_16x16x32_bf16 v[62:65], v[114:117], v[162:165], v[62:65]
	v_mfma_f32_16x16x32_bf16 v[58:61], v[122:125], v[162:165], v[58:61]
	v_mfma_f32_16x16x32_bf16 v[50:53], v[114:117], v[194:197], v[50:53]
	v_mfma_f32_16x16x32_bf16 v[42:45], v[122:125], v[194:197], v[42:45]
	v_mfma_f32_16x16x32_bf16 v[34:37], v[114:117], v[206:209], v[34:37]
	v_mfma_f32_16x16x32_bf16 v[26:29], v[122:125], v[206:209], v[26:29]
	v_mfma_f32_16x16x32_bf16 v[18:21], v[114:117], v[214:217], v[18:21]
	v_mfma_f32_16x16x32_bf16 v[10:13], v[122:125], v[214:217], v[10:13]
	v_mfma_f32_16x16x32_bf16 v[62:65], v[118:121], v[166:169], v[62:65]
	v_mfma_f32_16x16x32_bf16 v[58:61], v[126:129], v[166:169], v[58:61]
	v_mfma_f32_16x16x32_bf16 v[50:53], v[118:121], v[198:201], v[50:53]
	v_mfma_f32_16x16x32_bf16 v[42:45], v[126:129], v[198:201], v[42:45]
	v_mfma_f32_16x16x32_bf16 v[34:37], v[118:121], v[210:213], v[34:37]
	v_mfma_f32_16x16x32_bf16 v[26:29], v[126:129], v[210:213], v[26:29]
	v_mfma_f32_16x16x32_bf16 v[18:21], v[118:121], v[218:221], v[18:21]
	v_mfma_f32_16x16x32_bf16 v[10:13], v[126:129], v[218:221], v[10:13]
	v_mfma_f32_16x16x32_bf16 v[54:57], v[146:149], v[162:165], v[54:57]
	v_mfma_f32_16x16x32_bf16 v[46:49], v[154:157], v[162:165], v[46:49]
	v_mfma_f32_16x16x32_bf16 v[38:41], v[146:149], v[194:197], v[38:41]
	v_mfma_f32_16x16x32_bf16 v[30:33], v[154:157], v[194:197], v[30:33]
	v_mfma_f32_16x16x32_bf16 v[22:25], v[146:149], v[206:209], v[22:25]
	v_mfma_f32_16x16x32_bf16 v[14:17], v[154:157], v[206:209], v[14:17]
	v_mfma_f32_16x16x32_bf16 v[6:9], v[146:149], v[214:217], v[6:9]
	v_mfma_f32_16x16x32_bf16 v[2:5], v[154:157], v[214:217], v[2:5]
	v_mfma_f32_16x16x32_bf16 v[54:57], v[150:153], v[166:169], v[54:57]
	v_mfma_f32_16x16x32_bf16 v[46:49], v[158:161], v[166:169], v[46:49]
	v_mfma_f32_16x16x32_bf16 v[38:41], v[150:153], v[198:201], v[38:41]
	v_mfma_f32_16x16x32_bf16 v[30:33], v[158:161], v[198:201], v[30:33]
	v_mfma_f32_16x16x32_bf16 v[22:25], v[150:153], v[210:213], v[22:25]
	v_mfma_f32_16x16x32_bf16 v[14:17], v[158:161], v[210:213], v[14:17]
	v_mfma_f32_16x16x32_bf16 v[6:9], v[150:153], v[218:221], v[6:9]
	v_mfma_f32_16x16x32_bf16 v[2:5], v[158:161], v[218:221], v[2:5]
	s_setprio 0
	s_barrier
	s_add_u32 s76, s76, 0x100
	s_addc_u32 s77, s77, 0
	s_add_u32 s47, s47, 0x100
	s_addc_u32 s62, s62, 0
	s_cmp_ge_i32 s82, s7
	s_mov_b32 s63, s82
.LBB0_834:
	ds_read_b128 v[114:117], v190
	ds_read_b128 v[118:121], v190 offset:1024
	ds_read_b128 v[122:125], v190 offset:2048
	ds_read_b128 v[126:129], v190 offset:3072
	ds_read_b128 v[146:149], v191
	ds_read_b128 v[150:153], v191 offset:1024
	ds_read_b128 v[154:157], v191 offset:2048
	ds_read_b128 v[158:161], v191 offset:3072
	s_add_i32 s82, s63, 2
	s_add_u32 s78, s76, 0xfff00080
	s_addc_u32 s79, s77, -1
	s_cmp_eq_u32 s45, s63
	s_cselect_b32 s81, s15, s79
	s_cselect_b32 s80, s33, s78
	s_cselect_b32 s79, s34, s62
	s_cselect_b32 s78, s39, s47
	v_lshl_add_u64 v[186:187], s[76:77], 0, v[180:181]
	s_add_i32 m0, s87, 0xc000
	ds_read_b128 v[162:165], v192
	ds_read_b128 v[166:169], v192 offset:1024
	ds_read_b128 v[194:197], v192 offset:2048
	ds_read_b128 v[198:201], v192 offset:3072
	ds_read_b128 v[206:209], v192 offset:4096
	ds_read_b128 v[210:213], v192 offset:5120
	ds_read_b128 v[214:217], v192 offset:6144
	ds_read_b128 v[218:221], v192 offset:7168
	global_load_lds_dwordx4 v[186:187], off
	v_lshl_add_u64 v[186:187], s[76:77], 0, v[182:183]
	s_add_i32 m0, s87, 0xe000
	s_nop 0
	global_load_lds_dwordx4 v[186:187], off
	s_waitcnt vmcnt(8)
	s_waitcnt lgkmcnt(0)
	s_setprio 1
	s_barrier
	v_mfma_f32_16x16x32_bf16 v[142:145], v[114:117], v[162:165], v[142:145]
	v_mfma_f32_16x16x32_bf16 v[138:141], v[122:125], v[162:165], v[138:141]
	v_mfma_f32_16x16x32_bf16 v[110:113], v[114:117], v[194:197], v[110:113]
	v_mfma_f32_16x16x32_bf16 v[106:109], v[122:125], v[194:197], v[106:109]
	v_mfma_f32_16x16x32_bf16 v[98:101], v[114:117], v[206:209], v[98:101]
	v_mfma_f32_16x16x32_bf16 v[90:93], v[122:125], v[206:209], v[90:93]
	v_mfma_f32_16x16x32_bf16 v[82:85], v[114:117], v[214:217], v[82:85]
	v_mfma_f32_16x16x32_bf16 v[74:77], v[122:125], v[214:217], v[74:77]
	v_mfma_f32_16x16x32_bf16 v[142:145], v[118:121], v[166:169], v[142:145]
	v_mfma_f32_16x16x32_bf16 v[138:141], v[126:129], v[166:169], v[138:141]
	v_mfma_f32_16x16x32_bf16 v[110:113], v[118:121], v[198:201], v[110:113]
	v_mfma_f32_16x16x32_bf16 v[106:109], v[126:129], v[198:201], v[106:109]
	v_mfma_f32_16x16x32_bf16 v[98:101], v[118:121], v[210:213], v[98:101]
	v_mfma_f32_16x16x32_bf16 v[90:93], v[126:129], v[210:213], v[90:93]
	v_mfma_f32_16x16x32_bf16 v[82:85], v[118:121], v[218:221], v[82:85]
	v_mfma_f32_16x16x32_bf16 v[74:77], v[126:129], v[218:221], v[74:77]
	v_mfma_f32_16x16x32_bf16 v[134:137], v[146:149], v[162:165], v[134:137]
	v_mfma_f32_16x16x32_bf16 v[130:133], v[154:157], v[162:165], v[130:133]
	v_mfma_f32_16x16x32_bf16 v[102:105], v[146:149], v[194:197], v[102:105]
	v_mfma_f32_16x16x32_bf16 v[94:97], v[154:157], v[194:197], v[94:97]
	v_mfma_f32_16x16x32_bf16 v[86:89], v[146:149], v[206:209], v[86:89]
	v_mfma_f32_16x16x32_bf16 v[78:81], v[154:157], v[206:209], v[78:81]
	v_mfma_f32_16x16x32_bf16 v[70:73], v[146:149], v[214:217], v[70:73]
	v_mfma_f32_16x16x32_bf16 v[66:69], v[154:157], v[214:217], v[66:69]
	v_mfma_f32_16x16x32_bf16 v[134:137], v[150:153], v[166:169], v[134:137]
	v_mfma_f32_16x16x32_bf16 v[130:133], v[158:161], v[166:169], v[130:133]
	v_mfma_f32_16x16x32_bf16 v[102:105], v[150:153], v[198:201], v[102:105]
	v_mfma_f32_16x16x32_bf16 v[94:97], v[158:161], v[198:201], v[94:97]
	v_mfma_f32_16x16x32_bf16 v[86:89], v[150:153], v[210:213], v[86:89]
	v_mfma_f32_16x16x32_bf16 v[78:81], v[158:161], v[210:213], v[78:81]
	v_mfma_f32_16x16x32_bf16 v[70:73], v[150:153], v[218:221], v[70:73]
	v_mfma_f32_16x16x32_bf16 v[66:69], v[158:161], v[218:221], v[66:69]
	s_setprio 0
	s_barrier
	s_add_i32 s63, s24, s86
	v_lshl_add_u64 v[186:187], s[78:79], 0, v[172:173]
	s_mov_b32 m0, s63
	ds_read_b128 v[162:165], v192 offset:16384
	ds_read_b128 v[166:169], v192 offset:17408
	ds_read_b128 v[194:197], v192 offset:18432
	ds_read_b128 v[198:201], v192 offset:19456
	ds_read_b128 v[206:209], v192 offset:20480
	ds_read_b128 v[210:213], v192 offset:21504
	ds_read_b128 v[214:217], v192 offset:22528
	ds_read_b128 v[218:221], v192 offset:23552
	global_load_lds_dwordx4 v[186:187], off
	s_add_i32 m0, s63, 0x2000
	s_add_u32 vcc_lo, s78, 0x100000
	v_lshl_add_u64 v[202:203], s[78:79], 0, v[176:177]
	s_addc_u32 vcc_hi, s79, 0
	s_add_i32 s63, s25, s86
	global_load_lds_dwordx4 v[202:203], off
	v_lshl_add_u64 v[222:223], vcc, 0, v[172:173]
	s_mov_b32 m0, s63
	v_lshl_add_u64 v[224:225], s[80:81], 0, v[174:175]
	global_load_lds_dwordx4 v[222:223], off
	v_lshl_add_u64 v[222:223], vcc, 0, v[176:177]
	s_add_i32 m0, s63, 0x2000
	s_nop 0
	global_load_lds_dwordx4 v[222:223], off
	v_lshl_add_u64 v[222:223], s[80:81], 0, v[170:171]
	s_mov_b32 m0, s87
	s_nop 0
	global_load_lds_dwordx4 v[222:223], off
	s_mov_b32 m0, s88
	s_nop 0
	global_load_lds_dwordx4 v[224:225], off
	s_waitcnt vmcnt(8)
	s_waitcnt lgkmcnt(0)
	s_setprio 1
	s_barrier
	v_mfma_f32_16x16x32_bf16 v[62:65], v[114:117], v[162:165], v[62:65]
	v_mfma_f32_16x16x32_bf16 v[58:61], v[122:125], v[162:165], v[58:61]
	v_mfma_f32_16x16x32_bf16 v[50:53], v[114:117], v[194:197], v[50:53]
	v_mfma_f32_16x16x32_bf16 v[42:45], v[122:125], v[194:197], v[42:45]
	v_mfma_f32_16x16x32_bf16 v[34:37], v[114:117], v[206:209], v[34:37]
	v_mfma_f32_16x16x32_bf16 v[26:29], v[122:125], v[206:209], v[26:29]
	v_mfma_f32_16x16x32_bf16 v[18:21], v[114:117], v[214:217], v[18:21]
	v_mfma_f32_16x16x32_bf16 v[10:13], v[122:125], v[214:217], v[10:13]
	v_mfma_f32_16x16x32_bf16 v[62:65], v[118:121], v[166:169], v[62:65]
	v_mfma_f32_16x16x32_bf16 v[58:61], v[126:129], v[166:169], v[58:61]
	v_mfma_f32_16x16x32_bf16 v[50:53], v[118:121], v[198:201], v[50:53]
	v_mfma_f32_16x16x32_bf16 v[42:45], v[126:129], v[198:201], v[42:45]
	v_mfma_f32_16x16x32_bf16 v[34:37], v[118:121], v[210:213], v[34:37]
	v_mfma_f32_16x16x32_bf16 v[26:29], v[126:129], v[210:213], v[26:29]
	v_mfma_f32_16x16x32_bf16 v[18:21], v[118:121], v[218:221], v[18:21]
	v_mfma_f32_16x16x32_bf16 v[10:13], v[126:129], v[218:221], v[10:13]
	v_mfma_f32_16x16x32_bf16 v[54:57], v[146:149], v[162:165], v[54:57]
	v_mfma_f32_16x16x32_bf16 v[46:49], v[154:157], v[162:165], v[46:49]
	v_mfma_f32_16x16x32_bf16 v[38:41], v[146:149], v[194:197], v[38:41]
	v_mfma_f32_16x16x32_bf16 v[30:33], v[154:157], v[194:197], v[30:33]
	v_mfma_f32_16x16x32_bf16 v[22:25], v[146:149], v[206:209], v[22:25]
	v_mfma_f32_16x16x32_bf16 v[14:17], v[154:157], v[206:209], v[14:17]
	v_mfma_f32_16x16x32_bf16 v[6:9], v[146:149], v[214:217], v[6:9]
	v_mfma_f32_16x16x32_bf16 v[2:5], v[154:157], v[214:217], v[2:5]
	v_mfma_f32_16x16x32_bf16 v[54:57], v[150:153], v[166:169], v[54:57]
	v_mfma_f32_16x16x32_bf16 v[46:49], v[158:161], v[166:169], v[46:49]
	v_mfma_f32_16x16x32_bf16 v[38:41], v[150:153], v[198:201], v[38:41]
	v_mfma_f32_16x16x32_bf16 v[30:33], v[158:161], v[198:201], v[30:33]
	v_mfma_f32_16x16x32_bf16 v[22:25], v[150:153], v[210:213], v[22:25]
	v_mfma_f32_16x16x32_bf16 v[14:17], v[158:161], v[210:213], v[14:17]
	v_mfma_f32_16x16x32_bf16 v[6:9], v[150:153], v[218:221], v[6:9]
	v_mfma_f32_16x16x32_bf16 v[2:5], v[158:161], v[218:221], v[2:5]
	s_setprio 0
	s_barrier
	s_add_i32 s63, 0, 0x18000
	s_add_i32 s83, 0, 0x1c000
	v_add_u32_e32 v126, s63, v189
	v_add_u32_e32 v158, s83, v189
	ds_read_b128 v[114:117], v126
	ds_read_b128 v[118:121], v126 offset:1024
	ds_read_b128 v[122:125], v126 offset:2048
	ds_read_b128 v[126:129], v126 offset:3072
	ds_read_b128 v[146:149], v158
	ds_read_b128 v[150:153], v158 offset:1024
	ds_read_b128 v[154:157], v158 offset:2048
	ds_read_b128 v[158:161], v158 offset:3072
	s_add_u32 s80, s80, 0x100000
	s_addc_u32 s81, s81, 0
	s_mov_b32 m0, s89
	v_lshl_add_u64 v[226:227], s[80:81], 0, v[170:171]
	ds_read_b128 v[162:165], v192 offset:32768
	ds_read_b128 v[166:169], v192 offset:33792
	ds_read_b128 v[194:197], v192 offset:34816
	ds_read_b128 v[198:201], v192 offset:35840
	ds_read_b128 v[206:209], v192 offset:36864
	ds_read_b128 v[210:213], v192 offset:37888
	ds_read_b128 v[214:217], v192 offset:38912
	ds_read_b128 v[218:221], v192 offset:39936
	global_load_lds_dwordx4 v[226:227], off
	v_lshl_add_u64 v[226:227], s[80:81], 0, v[174:175]
	s_mov_b32 m0, s90
	s_nop 0
	global_load_lds_dwordx4 v[226:227], off
	s_waitcnt vmcnt(8)
	s_waitcnt lgkmcnt(0)
	s_setprio 1
	s_barrier
	v_mfma_f32_16x16x32_bf16 v[142:145], v[114:117], v[162:165], v[142:145]
	v_mfma_f32_16x16x32_bf16 v[138:141], v[122:125], v[162:165], v[138:141]
	v_mfma_f32_16x16x32_bf16 v[110:113], v[114:117], v[194:197], v[110:113]
	v_mfma_f32_16x16x32_bf16 v[106:109], v[122:125], v[194:197], v[106:109]
	v_mfma_f32_16x16x32_bf16 v[98:101], v[114:117], v[206:209], v[98:101]
	v_mfma_f32_16x16x32_bf16 v[90:93], v[122:125], v[206:209], v[90:93]
	v_mfma_f32_16x16x32_bf16 v[82:85], v[114:117], v[214:217], v[82:85]
	v_mfma_f32_16x16x32_bf16 v[74:77], v[122:125], v[214:217], v[74:77]
	v_mfma_f32_16x16x32_bf16 v[142:145], v[118:121], v[166:169], v[142:145]
	v_mfma_f32_16x16x32_bf16 v[138:141], v[126:129], v[166:169], v[138:141]
	v_mfma_f32_16x16x32_bf16 v[110:113], v[118:121], v[198:201], v[110:113]
	v_mfma_f32_16x16x32_bf16 v[106:109], v[126:129], v[198:201], v[106:109]
	v_mfma_f32_16x16x32_bf16 v[98:101], v[118:121], v[210:213], v[98:101]
	v_mfma_f32_16x16x32_bf16 v[90:93], v[126:129], v[210:213], v[90:93]
	v_mfma_f32_16x16x32_bf16 v[82:85], v[118:121], v[218:221], v[82:85]
	v_mfma_f32_16x16x32_bf16 v[74:77], v[126:129], v[218:221], v[74:77]
	v_mfma_f32_16x16x32_bf16 v[134:137], v[146:149], v[162:165], v[134:137]
	v_mfma_f32_16x16x32_bf16 v[130:133], v[154:157], v[162:165], v[130:133]
	v_mfma_f32_16x16x32_bf16 v[102:105], v[146:149], v[194:197], v[102:105]
	v_mfma_f32_16x16x32_bf16 v[94:97], v[154:157], v[194:197], v[94:97]
	v_mfma_f32_16x16x32_bf16 v[86:89], v[146:149], v[206:209], v[86:89]
	v_mfma_f32_16x16x32_bf16 v[78:81], v[154:157], v[206:209], v[78:81]
	v_mfma_f32_16x16x32_bf16 v[70:73], v[146:149], v[214:217], v[70:73]
	v_mfma_f32_16x16x32_bf16 v[66:69], v[154:157], v[214:217], v[66:69]
	v_mfma_f32_16x16x32_bf16 v[134:137], v[150:153], v[166:169], v[134:137]
	v_mfma_f32_16x16x32_bf16 v[130:133], v[158:161], v[166:169], v[130:133]
	v_mfma_f32_16x16x32_bf16 v[102:105], v[150:153], v[198:201], v[102:105]
	v_mfma_f32_16x16x32_bf16 v[94:97], v[158:161], v[198:201], v[94:97]
	v_mfma_f32_16x16x32_bf16 v[86:89], v[150:153], v[210:213], v[86:89]
	v_mfma_f32_16x16x32_bf16 v[78:81], v[158:161], v[210:213], v[78:81]
	v_mfma_f32_16x16x32_bf16 v[70:73], v[150:153], v[218:221], v[70:73]
	v_mfma_f32_16x16x32_bf16 v[66:69], v[158:161], v[218:221], v[66:69]
	s_setprio 0
	s_barrier
	s_add_i32 s63, s63, s86
	v_lshl_add_u64 v[186:187], v[186:187], 0, s[22:23]
	s_mov_b32 m0, s63
	ds_read_b128 v[162:165], v192 offset:49152
	ds_read_b128 v[166:169], v192 offset:50176
	ds_read_b128 v[194:197], v192 offset:51200
	ds_read_b128 v[198:201], v192 offset:52224
	ds_read_b128 v[206:209], v192 offset:53248
	ds_read_b128 v[210:213], v192 offset:54272
	ds_read_b128 v[214:217], v192 offset:55296
	ds_read_b128 v[218:221], v192 offset:56320
	global_load_lds_dwordx4 v[186:187], off
	s_add_i32 m0, s63, 0x2000
	s_add_u32 s78, s78, 0x100080
	v_lshl_add_u64 v[186:187], v[202:203], 0, s[22:23]
	s_addc_u32 s79, s79, 0
	s_add_i32 s63, s83, s86
	global_load_lds_dwordx4 v[186:187], off
	v_lshl_add_u64 v[186:187], s[78:79], 0, v[172:173]
	s_mov_b32 m0, s63
	s_nop 0
	global_load_lds_dwordx4 v[186:187], off
	v_lshl_add_u64 v[186:187], s[78:79], 0, v[176:177]
	s_add_i32 m0, s63, 0x2000
	s_nop 0
	global_load_lds_dwordx4 v[186:187], off
	v_lshl_add_u64 v[186:187], v[222:223], 0, s[22:23]
	s_mov_b32 m0, s95
	s_nop 0
	global_load_lds_dwordx4 v[186:187], off
	v_lshl_add_u64 v[186:187], v[224:225], 0, s[22:23]
	s_mov_b32 m0, s96
	s_nop 0
	global_load_lds_dwordx4 v[186:187], off
	s_waitcnt vmcnt(8)
	s_waitcnt lgkmcnt(0)
	s_setprio 1
	s_barrier
	v_mfma_f32_16x16x32_bf16 v[62:65], v[114:117], v[162:165], v[62:65]
	v_mfma_f32_16x16x32_bf16 v[58:61], v[122:125], v[162:165], v[58:61]
	v_mfma_f32_16x16x32_bf16 v[50:53], v[114:117], v[194:197], v[50:53]
	v_mfma_f32_16x16x32_bf16 v[42:45], v[122:125], v[194:197], v[42:45]
	v_mfma_f32_16x16x32_bf16 v[34:37], v[114:117], v[206:209], v[34:37]
	v_mfma_f32_16x16x32_bf16 v[26:29], v[122:125], v[206:209], v[26:29]
	v_mfma_f32_16x16x32_bf16 v[18:21], v[114:117], v[214:217], v[18:21]
	v_mfma_f32_16x16x32_bf16 v[10:13], v[122:125], v[214:217], v[10:13]
	v_mfma_f32_16x16x32_bf16 v[62:65], v[118:121], v[166:169], v[62:65]
	v_mfma_f32_16x16x32_bf16 v[58:61], v[126:129], v[166:169], v[58:61]
	v_mfma_f32_16x16x32_bf16 v[50:53], v[118:121], v[198:201], v[50:53]
	v_mfma_f32_16x16x32_bf16 v[42:45], v[126:129], v[198:201], v[42:45]
	v_mfma_f32_16x16x32_bf16 v[34:37], v[118:121], v[210:213], v[34:37]
	v_mfma_f32_16x16x32_bf16 v[26:29], v[126:129], v[210:213], v[26:29]
	v_mfma_f32_16x16x32_bf16 v[18:21], v[118:121], v[218:221], v[18:21]
	v_mfma_f32_16x16x32_bf16 v[10:13], v[126:129], v[218:221], v[10:13]
	v_mfma_f32_16x16x32_bf16 v[54:57], v[146:149], v[162:165], v[54:57]
	v_mfma_f32_16x16x32_bf16 v[46:49], v[154:157], v[162:165], v[46:49]
	v_mfma_f32_16x16x32_bf16 v[38:41], v[146:149], v[194:197], v[38:41]
	v_mfma_f32_16x16x32_bf16 v[30:33], v[154:157], v[194:197], v[30:33]
	v_mfma_f32_16x16x32_bf16 v[22:25], v[146:149], v[206:209], v[22:25]
	v_mfma_f32_16x16x32_bf16 v[14:17], v[154:157], v[206:209], v[14:17]
	v_mfma_f32_16x16x32_bf16 v[6:9], v[146:149], v[214:217], v[6:9]
	v_mfma_f32_16x16x32_bf16 v[2:5], v[154:157], v[214:217], v[2:5]
	v_mfma_f32_16x16x32_bf16 v[54:57], v[150:153], v[166:169], v[54:57]
	v_mfma_f32_16x16x32_bf16 v[46:49], v[158:161], v[166:169], v[46:49]
	v_mfma_f32_16x16x32_bf16 v[38:41], v[150:153], v[198:201], v[38:41]
	v_mfma_f32_16x16x32_bf16 v[30:33], v[158:161], v[198:201], v[30:33]
	v_mfma_f32_16x16x32_bf16 v[22:25], v[150:153], v[210:213], v[22:25]
	v_mfma_f32_16x16x32_bf16 v[14:17], v[158:161], v[210:213], v[14:17]
	v_mfma_f32_16x16x32_bf16 v[6:9], v[150:153], v[218:221], v[6:9]
	v_mfma_f32_16x16x32_bf16 v[2:5], v[158:161], v[218:221], v[2:5]
	s_setprio 0
	s_barrier
	s_add_u32 s76, s76, 0x100
	s_addc_u32 s77, s77, 0
	s_add_u32 s47, s47, 0x100
	s_addc_u32 s62, s62, 0
	s_cmp_ge_i32 s82, s7
	s_mov_b32 s63, s82
	s_cbranch_scc0 .LBB0_834
	s_and_b64 vcc, exec, s[26:27]
	s_cbranch_vccz .LBB0_837
	s_barrier

.LBB0_1012:
	s_add_u32 s48, s96, s44
	s_addc_u32 s49, s97, s45
	s_and_b64 s[14:15], s[4:5], exec
	s_cselect_b32 s6, s49, s65
	s_cselect_b32 s14, s48, s64
	s_add_u32 s50, s3, s46
	s_addc_u32 s51, s35, s47
	s_and_b64 s[18:19], s[4:5], exec
	s_cselect_b32 s15, s51, s67
	s_cselect_b32 s17, s50, s66
	s_add_u32 s64, s64, 0x40080
	s_addc_u32 s65, s65, 0
	s_add_u32 s18, s66, 0x100
	s_addc_u32 s19, s67, 0
	s_mov_b32 s24, -2
	s_waitcnt vmcnt(0)
	ds_read_b128 v[130:133], v172
	ds_read_b128 v[134:137], v172 offset:1024
	ds_read_b128 v[138:141], v172 offset:2048
	ds_read_b128 v[142:145], v172 offset:3072
	ds_read_b128 v[164:167], v173
	ds_read_b128 v[176:179], v173 offset:1024
	ds_read_b128 v[180:183], v173 offset:2048
	ds_read_b128 v[184:187], v173 offset:3072
	s_add_u32 s25, s64, 0xfffc0080
	s_addc_u32 s28, s65, -1
	s_cmp_eq_u32 s24, 12
	s_cselect_b32 s69, s6, s28
	s_cselect_b32 s68, s14, s25
	s_cselect_b32 s67, s15, s19
	s_cselect_b32 s66, s17, s18
	v_lshl_add_u64 v[168:169], s[64:65], 0, v[156:157]
	s_add_i32 m0, s73, 0xc000
	ds_read_b128 v[188:191], v174
	ds_read_b128 v[192:195], v174 offset:1024
	ds_read_b128 v[196:199], v174 offset:2048
	ds_read_b128 v[200:203], v174 offset:3072
	ds_read_b128 v[206:209], v174 offset:4096
	ds_read_b128 v[210:213], v174 offset:5120
	ds_read_b128 v[214:217], v174 offset:6144
	ds_read_b128 v[218:221], v174 offset:7168
	global_load_lds_dwordx4 v[168:169], off
	v_lshl_add_u64 v[168:169], s[64:65], 0, v[158:159]
	s_add_i32 m0, s73, 0xe000
	s_nop 0
	global_load_lds_dwordx4 v[168:169], off
	s_waitcnt vmcnt(8)
	s_waitcnt lgkmcnt(0)
	s_setprio 1
	s_barrier
	v_mfma_f32_16x16x32_bf16 v[126:129], v[130:133], v[188:191], 0
	v_mfma_f32_16x16x32_bf16 v[122:125], v[138:141], v[188:191], 0
	v_mfma_f32_16x16x32_bf16 v[110:113], v[130:133], v[196:199], 0
	v_mfma_f32_16x16x32_bf16 v[106:109], v[138:141], v[196:199], 0
	v_mfma_f32_16x16x32_bf16 v[94:97], v[130:133], v[206:209], 0
	v_mfma_f32_16x16x32_bf16 v[90:93], v[138:141], v[206:209], 0
	v_mfma_f32_16x16x32_bf16 v[78:81], v[130:133], v[214:217], 0
	v_mfma_f32_16x16x32_bf16 v[74:77], v[138:141], v[214:217], 0
	v_mfma_f32_16x16x32_bf16 v[126:129], v[134:137], v[192:195], v[126:129]
	v_mfma_f32_16x16x32_bf16 v[122:125], v[142:145], v[192:195], v[122:125]
	v_mfma_f32_16x16x32_bf16 v[110:113], v[134:137], v[200:203], v[110:113]
	v_mfma_f32_16x16x32_bf16 v[106:109], v[142:145], v[200:203], v[106:109]
	v_mfma_f32_16x16x32_bf16 v[94:97], v[134:137], v[210:213], v[94:97]
	v_mfma_f32_16x16x32_bf16 v[90:93], v[142:145], v[210:213], v[90:93]
	v_mfma_f32_16x16x32_bf16 v[78:81], v[134:137], v[218:221], v[78:81]
	v_mfma_f32_16x16x32_bf16 v[74:77], v[142:145], v[218:221], v[74:77]
	v_mfma_f32_16x16x32_bf16 v[118:121], v[164:167], v[188:191], 0
	v_mfma_f32_16x16x32_bf16 v[114:117], v[180:183], v[188:191], 0
	v_mfma_f32_16x16x32_bf16 v[102:105], v[164:167], v[196:199], 0
	v_mfma_f32_16x16x32_bf16 v[98:101], v[180:183], v[196:199], 0
	v_mfma_f32_16x16x32_bf16 v[86:89], v[164:167], v[206:209], 0
	v_mfma_f32_16x16x32_bf16 v[82:85], v[180:183], v[206:209], 0
	v_mfma_f32_16x16x32_bf16 v[70:73], v[164:167], v[214:217], 0
	v_mfma_f32_16x16x32_bf16 v[66:69], v[180:183], v[214:217], 0
	v_mfma_f32_16x16x32_bf16 v[118:121], v[176:179], v[192:195], v[118:121]
	v_mfma_f32_16x16x32_bf16 v[114:117], v[184:187], v[192:195], v[114:117]
	v_mfma_f32_16x16x32_bf16 v[102:105], v[176:179], v[200:203], v[102:105]
	v_mfma_f32_16x16x32_bf16 v[98:101], v[184:187], v[200:203], v[98:101]
	v_mfma_f32_16x16x32_bf16 v[86:89], v[176:179], v[210:213], v[86:89]
	v_mfma_f32_16x16x32_bf16 v[82:85], v[184:187], v[210:213], v[82:85]
	v_mfma_f32_16x16x32_bf16 v[70:73], v[176:179], v[218:221], v[70:73]
	v_mfma_f32_16x16x32_bf16 v[66:69], v[184:187], v[218:221], v[66:69]
	s_setprio 0
	s_barrier
	s_add_i32 s25, s82, s70
	v_lshl_add_u64 v[168:169], s[66:67], 0, v[150:151]
	s_mov_b32 m0, s25
	ds_read_b128 v[188:191], v174 offset:16384
	ds_read_b128 v[192:195], v174 offset:17408
	ds_read_b128 v[196:199], v174 offset:18432
	ds_read_b128 v[200:203], v174 offset:19456
	ds_read_b128 v[206:209], v174 offset:20480
	ds_read_b128 v[210:213], v174 offset:21504
	ds_read_b128 v[214:217], v174 offset:22528
	ds_read_b128 v[218:221], v174 offset:23552
	global_load_lds_dwordx4 v[168:169], off
	s_add_i32 m0, s25, 0x2000
	s_add_u32 s28, s66, 0x40000
	v_lshl_add_u64 v[222:223], s[66:67], 0, v[146:147]
	s_addc_u32 s29, s67, 0
	s_add_i32 s25, s83, s70
	global_load_lds_dwordx4 v[222:223], off
	v_lshl_add_u64 v[224:225], s[28:29], 0, v[150:151]
	s_mov_b32 m0, s25
	v_lshl_add_u64 v[226:227], s[68:69], 0, v[148:149]
	global_load_lds_dwordx4 v[224:225], off
	v_lshl_add_u64 v[224:225], s[28:29], 0, v[146:147]
	s_add_i32 m0, s25, 0x2000
	s_nop 0
	global_load_lds_dwordx4 v[224:225], off
	v_lshl_add_u64 v[224:225], s[68:69], 0, v[152:153]
	s_mov_b32 m0, s73
	s_nop 0
	global_load_lds_dwordx4 v[224:225], off
	s_mov_b32 m0, s74
	s_nop 0
	global_load_lds_dwordx4 v[226:227], off
	s_waitcnt vmcnt(8)
	s_waitcnt lgkmcnt(0)
	s_setprio 1
	s_barrier
	v_mfma_f32_16x16x32_bf16 v[62:65], v[130:133], v[188:191], 0
	v_mfma_f32_16x16x32_bf16 v[58:61], v[138:141], v[188:191], 0
	v_mfma_f32_16x16x32_bf16 v[46:49], v[130:133], v[196:199], 0
	v_mfma_f32_16x16x32_bf16 v[42:45], v[138:141], v[196:199], 0
	v_mfma_f32_16x16x32_bf16 v[30:33], v[130:133], v[206:209], 0
	v_mfma_f32_16x16x32_bf16 v[26:29], v[138:141], v[206:209], 0
	v_mfma_f32_16x16x32_bf16 v[14:17], v[130:133], v[214:217], 0
	v_mfma_f32_16x16x32_bf16 v[10:13], v[138:141], v[214:217], 0
	v_mfma_f32_16x16x32_bf16 v[62:65], v[134:137], v[192:195], v[62:65]
	v_mfma_f32_16x16x32_bf16 v[58:61], v[142:145], v[192:195], v[58:61]
	v_mfma_f32_16x16x32_bf16 v[46:49], v[134:137], v[200:203], v[46:49]
	v_mfma_f32_16x16x32_bf16 v[42:45], v[142:145], v[200:203], v[42:45]
	v_mfma_f32_16x16x32_bf16 v[30:33], v[134:137], v[210:213], v[30:33]
	v_mfma_f32_16x16x32_bf16 v[26:29], v[142:145], v[210:213], v[26:29]
	v_mfma_f32_16x16x32_bf16 v[14:17], v[134:137], v[218:221], v[14:17]
	v_mfma_f32_16x16x32_bf16 v[10:13], v[142:145], v[218:221], v[10:13]
	v_mfma_f32_16x16x32_bf16 v[54:57], v[164:167], v[188:191], 0
	v_mfma_f32_16x16x32_bf16 v[50:53], v[180:183], v[188:191], 0
	v_mfma_f32_16x16x32_bf16 v[38:41], v[164:167], v[196:199], 0
	v_mfma_f32_16x16x32_bf16 v[34:37], v[180:183], v[196:199], 0
	v_mfma_f32_16x16x32_bf16 v[22:25], v[164:167], v[206:209], 0
	v_mfma_f32_16x16x32_bf16 v[18:21], v[180:183], v[206:209], 0
	v_mfma_f32_16x16x32_bf16 v[6:9], v[164:167], v[214:217], 0
	v_mfma_f32_16x16x32_bf16 v[2:5], v[180:183], v[214:217], 0
	v_mfma_f32_16x16x32_bf16 v[54:57], v[176:179], v[192:195], v[54:57]
	v_mfma_f32_16x16x32_bf16 v[50:53], v[184:187], v[192:195], v[50:53]
	v_mfma_f32_16x16x32_bf16 v[38:41], v[176:179], v[200:203], v[38:41]
	v_mfma_f32_16x16x32_bf16 v[34:37], v[184:187], v[200:203], v[34:37]
	v_mfma_f32_16x16x32_bf16 v[22:25], v[176:179], v[210:213], v[22:25]
	v_mfma_f32_16x16x32_bf16 v[18:21], v[184:187], v[210:213], v[18:21]
	v_mfma_f32_16x16x32_bf16 v[6:9], v[176:179], v[218:221], v[6:9]
	v_mfma_f32_16x16x32_bf16 v[2:5], v[184:187], v[218:221], v[2:5]
	s_setprio 0
	s_barrier
	s_add_i32 s25, 0, 0x18000
	s_add_i32 s30, 0, 0x1c000
	v_add_u32_e32 v142, s25, v171
	v_add_u32_e32 v175, s30, v171
	ds_read_b128 v[130:133], v142
	ds_read_b128 v[134:137], v142 offset:1024
	ds_read_b128 v[138:141], v142 offset:2048
	ds_read_b128 v[142:145], v142 offset:3072
	ds_read_b128 v[164:167], v175
	ds_read_b128 v[176:179], v175 offset:1024
	ds_read_b128 v[180:183], v175 offset:2048
	ds_read_b128 v[184:187], v175 offset:3072
	s_add_u32 s28, s68, 0x40000
	s_addc_u32 s29, s69, 0
	s_mov_b32 m0, s75
	v_lshl_add_u64 v[228:229], s[28:29], 0, v[152:153]
	ds_read_b128 v[188:191], v174 offset:32768
	ds_read_b128 v[192:195], v174 offset:33792
	ds_read_b128 v[196:199], v174 offset:34816
	ds_read_b128 v[200:203], v174 offset:35840
	ds_read_b128 v[206:209], v174 offset:36864
	ds_read_b128 v[210:213], v174 offset:37888
	ds_read_b128 v[214:217], v174 offset:38912
	ds_read_b128 v[218:221], v174 offset:39936
	global_load_lds_dwordx4 v[228:229], off
	v_lshl_add_u64 v[228:229], s[28:29], 0, v[148:149]
	s_mov_b32 m0, s76
	s_nop 0
	global_load_lds_dwordx4 v[228:229], off
	s_waitcnt vmcnt(8)
	s_waitcnt lgkmcnt(0)
	s_setprio 1
	s_barrier
	v_mfma_f32_16x16x32_bf16 v[126:129], v[130:133], v[188:191], v[126:129]
	v_mfma_f32_16x16x32_bf16 v[122:125], v[138:141], v[188:191], v[122:125]
	v_mfma_f32_16x16x32_bf16 v[110:113], v[130:133], v[196:199], v[110:113]
	v_mfma_f32_16x16x32_bf16 v[106:109], v[138:141], v[196:199], v[106:109]
	v_mfma_f32_16x16x32_bf16 v[94:97], v[130:133], v[206:209], v[94:97]
	v_mfma_f32_16x16x32_bf16 v[90:93], v[138:141], v[206:209], v[90:93]
	v_mfma_f32_16x16x32_bf16 v[78:81], v[130:133], v[214:217], v[78:81]
	v_mfma_f32_16x16x32_bf16 v[74:77], v[138:141], v[214:217], v[74:77]
	v_mfma_f32_16x16x32_bf16 v[126:129], v[134:137], v[192:195], v[126:129]
	v_mfma_f32_16x16x32_bf16 v[122:125], v[142:145], v[192:195], v[122:125]
	v_mfma_f32_16x16x32_bf16 v[110:113], v[134:137], v[200:203], v[110:113]
	v_mfma_f32_16x16x32_bf16 v[106:109], v[142:145], v[200:203], v[106:109]
	v_mfma_f32_16x16x32_bf16 v[94:97], v[134:137], v[210:213], v[94:97]
	v_mfma_f32_16x16x32_bf16 v[90:93], v[142:145], v[210:213], v[90:93]
	v_mfma_f32_16x16x32_bf16 v[78:81], v[134:137], v[218:221], v[78:81]
	v_mfma_f32_16x16x32_bf16 v[74:77], v[142:145], v[218:221], v[74:77]
	v_mfma_f32_16x16x32_bf16 v[118:121], v[164:167], v[188:191], v[118:121]
	v_mfma_f32_16x16x32_bf16 v[114:117], v[180:183], v[188:191], v[114:117]
	v_mfma_f32_16x16x32_bf16 v[102:105], v[164:167], v[196:199], v[102:105]
	v_mfma_f32_16x16x32_bf16 v[98:101], v[180:183], v[196:199], v[98:101]
	v_mfma_f32_16x16x32_bf16 v[86:89], v[164:167], v[206:209], v[86:89]
	v_mfma_f32_16x16x32_bf16 v[82:85], v[180:183], v[206:209], v[82:85]
	v_mfma_f32_16x16x32_bf16 v[70:73], v[164:167], v[214:217], v[70:73]
	v_mfma_f32_16x16x32_bf16 v[66:69], v[180:183], v[214:217], v[66:69]
	v_mfma_f32_16x16x32_bf16 v[118:121], v[176:179], v[192:195], v[118:121]
	v_mfma_f32_16x16x32_bf16 v[114:117], v[184:187], v[192:195], v[114:117]
	v_mfma_f32_16x16x32_bf16 v[102:105], v[176:179], v[200:203], v[102:105]
	v_mfma_f32_16x16x32_bf16 v[98:101], v[184:187], v[200:203], v[98:101]
	v_mfma_f32_16x16x32_bf16 v[86:89], v[176:179], v[210:213], v[86:89]
	v_mfma_f32_16x16x32_bf16 v[82:85], v[184:187], v[210:213], v[82:85]
	v_mfma_f32_16x16x32_bf16 v[70:73], v[176:179], v[218:221], v[70:73]
	v_mfma_f32_16x16x32_bf16 v[66:69], v[184:187], v[218:221], v[66:69]
	s_setprio 0
	s_barrier
	s_add_i32 s25, s25, s70
	v_lshl_add_u64 v[168:169], v[168:169], 0, s[36:37]
	s_mov_b32 m0, s25
	ds_read_b128 v[188:191], v174 offset:49152
	ds_read_b128 v[192:195], v174 offset:50176
	ds_read_b128 v[196:199], v174 offset:51200
	ds_read_b128 v[200:203], v174 offset:52224
	ds_read_b128 v[206:209], v174 offset:53248
	ds_read_b128 v[210:213], v174 offset:54272
	ds_read_b128 v[214:217], v174 offset:55296
	ds_read_b128 v[218:221], v174 offset:56320
	global_load_lds_dwordx4 v[168:169], off
	s_add_i32 m0, s25, 0x2000
	s_add_u32 s28, s66, 0x40080
	v_lshl_add_u64 v[168:169], v[222:223], 0, s[36:37]
	s_addc_u32 s29, s67, 0
	s_add_i32 s25, s30, s70
	global_load_lds_dwordx4 v[168:169], off
	v_lshl_add_u64 v[168:169], s[28:29], 0, v[150:151]
	s_mov_b32 m0, s25
	s_nop 0
	global_load_lds_dwordx4 v[168:169], off
	v_lshl_add_u64 v[168:169], s[28:29], 0, v[146:147]
	s_add_i32 m0, s25, 0x2000
	s_nop 0
	global_load_lds_dwordx4 v[168:169], off
	v_lshl_add_u64 v[168:169], v[224:225], 0, s[36:37]
	s_mov_b32 m0, s79
	s_nop 0
	global_load_lds_dwordx4 v[168:169], off
	v_lshl_add_u64 v[168:169], v[226:227], 0, s[36:37]
	s_mov_b32 m0, s80
	s_nop 0
	global_load_lds_dwordx4 v[168:169], off
	s_waitcnt vmcnt(8)
	s_waitcnt lgkmcnt(0)
	s_setprio 1
	s_barrier
	v_mfma_f32_16x16x32_bf16 v[62:65], v[130:133], v[188:191], v[62:65]
	v_mfma_f32_16x16x32_bf16 v[58:61], v[138:141], v[188:191], v[58:61]
	v_mfma_f32_16x16x32_bf16 v[46:49], v[130:133], v[196:199], v[46:49]
	v_mfma_f32_16x16x32_bf16 v[42:45], v[138:141], v[196:199], v[42:45]
	v_mfma_f32_16x16x32_bf16 v[30:33], v[130:133], v[206:209], v[30:33]
	v_mfma_f32_16x16x32_bf16 v[26:29], v[138:141], v[206:209], v[26:29]
	v_mfma_f32_16x16x32_bf16 v[14:17], v[130:133], v[214:217], v[14:17]
	v_mfma_f32_16x16x32_bf16 v[10:13], v[138:141], v[214:217], v[10:13]
	v_mfma_f32_16x16x32_bf16 v[62:65], v[134:137], v[192:195], v[62:65]
	v_mfma_f32_16x16x32_bf16 v[58:61], v[142:145], v[192:195], v[58:61]
	v_mfma_f32_16x16x32_bf16 v[46:49], v[134:137], v[200:203], v[46:49]
	v_mfma_f32_16x16x32_bf16 v[42:45], v[142:145], v[200:203], v[42:45]
	v_mfma_f32_16x16x32_bf16 v[30:33], v[134:137], v[210:213], v[30:33]
	v_mfma_f32_16x16x32_bf16 v[26:29], v[142:145], v[210:213], v[26:29]
	v_mfma_f32_16x16x32_bf16 v[14:17], v[134:137], v[218:221], v[14:17]
	v_mfma_f32_16x16x32_bf16 v[10:13], v[142:145], v[218:221], v[10:13]
	v_mfma_f32_16x16x32_bf16 v[54:57], v[164:167], v[188:191], v[54:57]
	v_mfma_f32_16x16x32_bf16 v[50:53], v[180:183], v[188:191], v[50:53]
	v_mfma_f32_16x16x32_bf16 v[38:41], v[164:167], v[196:199], v[38:41]
	v_mfma_f32_16x16x32_bf16 v[34:37], v[180:183], v[196:199], v[34:37]
	v_mfma_f32_16x16x32_bf16 v[22:25], v[164:167], v[206:209], v[22:25]
	v_mfma_f32_16x16x32_bf16 v[18:21], v[180:183], v[206:209], v[18:21]
	v_mfma_f32_16x16x32_bf16 v[6:9], v[164:167], v[214:217], v[6:9]
	v_mfma_f32_16x16x32_bf16 v[2:5], v[180:183], v[214:217], v[2:5]
	v_mfma_f32_16x16x32_bf16 v[54:57], v[176:179], v[192:195], v[54:57]
	v_mfma_f32_16x16x32_bf16 v[50:53], v[184:187], v[192:195], v[50:53]
	v_mfma_f32_16x16x32_bf16 v[38:41], v[176:179], v[200:203], v[38:41]
	v_mfma_f32_16x16x32_bf16 v[34:37], v[184:187], v[200:203], v[34:37]
	v_mfma_f32_16x16x32_bf16 v[22:25], v[176:179], v[210:213], v[22:25]
	v_mfma_f32_16x16x32_bf16 v[18:21], v[184:187], v[210:213], v[18:21]
	v_mfma_f32_16x16x32_bf16 v[6:9], v[176:179], v[218:221], v[6:9]
	v_mfma_f32_16x16x32_bf16 v[2:5], v[184:187], v[218:221], v[2:5]
	s_setprio 0
	s_barrier
	s_add_i32 s24, s24, 2
	s_add_u32 s64, s64, 0x100
	s_addc_u32 s65, s65, 0
	s_add_u32 s18, s18, 0x100
	s_addc_u32 s19, s19, 0
	s_cmp_gt_u32 s24, 13
.LBB0_1013:
	ds_read_b128 v[130:133], v172
	ds_read_b128 v[134:137], v172 offset:1024
	ds_read_b128 v[138:141], v172 offset:2048
	ds_read_b128 v[142:145], v172 offset:3072
	ds_read_b128 v[164:167], v173
	ds_read_b128 v[176:179], v173 offset:1024
	ds_read_b128 v[180:183], v173 offset:2048
	ds_read_b128 v[184:187], v173 offset:3072
	s_add_u32 s25, s64, 0xfffc0080
	s_addc_u32 s28, s65, -1
	s_cmp_eq_u32 s24, 12
	s_cselect_b32 s69, s6, s28
	s_cselect_b32 s68, s14, s25
	s_cselect_b32 s67, s15, s19
	s_cselect_b32 s66, s17, s18
	v_lshl_add_u64 v[168:169], s[64:65], 0, v[156:157]
	s_add_i32 m0, s73, 0xc000
	ds_read_b128 v[188:191], v174
	ds_read_b128 v[192:195], v174 offset:1024
	ds_read_b128 v[196:199], v174 offset:2048
	ds_read_b128 v[200:203], v174 offset:3072
	ds_read_b128 v[206:209], v174 offset:4096
	ds_read_b128 v[210:213], v174 offset:5120
	ds_read_b128 v[214:217], v174 offset:6144
	ds_read_b128 v[218:221], v174 offset:7168
	global_load_lds_dwordx4 v[168:169], off
	v_lshl_add_u64 v[168:169], s[64:65], 0, v[158:159]
	s_add_i32 m0, s73, 0xe000
	s_nop 0
	global_load_lds_dwordx4 v[168:169], off
	s_waitcnt vmcnt(8)
	s_waitcnt lgkmcnt(0)
	s_setprio 1
	s_barrier
	v_mfma_f32_16x16x32_bf16 v[126:129], v[130:133], v[188:191], v[126:129]
	v_mfma_f32_16x16x32_bf16 v[122:125], v[138:141], v[188:191], v[122:125]
	v_mfma_f32_16x16x32_bf16 v[110:113], v[130:133], v[196:199], v[110:113]
	v_mfma_f32_16x16x32_bf16 v[106:109], v[138:141], v[196:199], v[106:109]
	v_mfma_f32_16x16x32_bf16 v[94:97], v[130:133], v[206:209], v[94:97]
	v_mfma_f32_16x16x32_bf16 v[90:93], v[138:141], v[206:209], v[90:93]
	v_mfma_f32_16x16x32_bf16 v[78:81], v[130:133], v[214:217], v[78:81]
	v_mfma_f32_16x16x32_bf16 v[74:77], v[138:141], v[214:217], v[74:77]
	v_mfma_f32_16x16x32_bf16 v[126:129], v[134:137], v[192:195], v[126:129]
	v_mfma_f32_16x16x32_bf16 v[122:125], v[142:145], v[192:195], v[122:125]
	v_mfma_f32_16x16x32_bf16 v[110:113], v[134:137], v[200:203], v[110:113]
	v_mfma_f32_16x16x32_bf16 v[106:109], v[142:145], v[200:203], v[106:109]
	v_mfma_f32_16x16x32_bf16 v[94:97], v[134:137], v[210:213], v[94:97]
	v_mfma_f32_16x16x32_bf16 v[90:93], v[142:145], v[210:213], v[90:93]
	v_mfma_f32_16x16x32_bf16 v[78:81], v[134:137], v[218:221], v[78:81]
	v_mfma_f32_16x16x32_bf16 v[74:77], v[142:145], v[218:221], v[74:77]
	v_mfma_f32_16x16x32_bf16 v[118:121], v[164:167], v[188:191], v[118:121]
	v_mfma_f32_16x16x32_bf16 v[114:117], v[180:183], v[188:191], v[114:117]
	v_mfma_f32_16x16x32_bf16 v[102:105], v[164:167], v[196:199], v[102:105]
	v_mfma_f32_16x16x32_bf16 v[98:101], v[180:183], v[196:199], v[98:101]
	v_mfma_f32_16x16x32_bf16 v[86:89], v[164:167], v[206:209], v[86:89]
	v_mfma_f32_16x16x32_bf16 v[82:85], v[180:183], v[206:209], v[82:85]
	v_mfma_f32_16x16x32_bf16 v[70:73], v[164:167], v[214:217], v[70:73]
	v_mfma_f32_16x16x32_bf16 v[66:69], v[180:183], v[214:217], v[66:69]
	v_mfma_f32_16x16x32_bf16 v[118:121], v[176:179], v[192:195], v[118:121]
	v_mfma_f32_16x16x32_bf16 v[114:117], v[184:187], v[192:195], v[114:117]
	v_mfma_f32_16x16x32_bf16 v[102:105], v[176:179], v[200:203], v[102:105]
	v_mfma_f32_16x16x32_bf16 v[98:101], v[184:187], v[200:203], v[98:101]
	v_mfma_f32_16x16x32_bf16 v[86:89], v[176:179], v[210:213], v[86:89]
	v_mfma_f32_16x16x32_bf16 v[82:85], v[184:187], v[210:213], v[82:85]
	v_mfma_f32_16x16x32_bf16 v[70:73], v[176:179], v[218:221], v[70:73]
	v_mfma_f32_16x16x32_bf16 v[66:69], v[184:187], v[218:221], v[66:69]
	s_setprio 0
	s_barrier
	s_add_i32 s25, s82, s70
	v_lshl_add_u64 v[168:169], s[66:67], 0, v[150:151]
	s_mov_b32 m0, s25
	ds_read_b128 v[188:191], v174 offset:16384
	ds_read_b128 v[192:195], v174 offset:17408
	ds_read_b128 v[196:199], v174 offset:18432
	ds_read_b128 v[200:203], v174 offset:19456
	ds_read_b128 v[206:209], v174 offset:20480
	ds_read_b128 v[210:213], v174 offset:21504
	ds_read_b128 v[214:217], v174 offset:22528
	ds_read_b128 v[218:221], v174 offset:23552
	global_load_lds_dwordx4 v[168:169], off
	s_add_i32 m0, s25, 0x2000
	s_add_u32 s28, s66, 0x40000
	v_lshl_add_u64 v[222:223], s[66:67], 0, v[146:147]
	s_addc_u32 s29, s67, 0
	s_add_i32 s25, s83, s70
	global_load_lds_dwordx4 v[222:223], off
	v_lshl_add_u64 v[224:225], s[28:29], 0, v[150:151]
	s_mov_b32 m0, s25
	v_lshl_add_u64 v[226:227], s[68:69], 0, v[148:149]
	global_load_lds_dwordx4 v[224:225], off
	v_lshl_add_u64 v[224:225], s[28:29], 0, v[146:147]
	s_add_i32 m0, s25, 0x2000
	s_nop 0
	global_load_lds_dwordx4 v[224:225], off
	v_lshl_add_u64 v[224:225], s[68:69], 0, v[152:153]
	s_mov_b32 m0, s73
	s_nop 0
	global_load_lds_dwordx4 v[224:225], off
	s_mov_b32 m0, s74
	s_nop 0
	global_load_lds_dwordx4 v[226:227], off
	s_waitcnt vmcnt(8)
	s_waitcnt lgkmcnt(0)
	s_setprio 1
	s_barrier
	v_mfma_f32_16x16x32_bf16 v[62:65], v[130:133], v[188:191], v[62:65]
	v_mfma_f32_16x16x32_bf16 v[58:61], v[138:141], v[188:191], v[58:61]
	v_mfma_f32_16x16x32_bf16 v[46:49], v[130:133], v[196:199], v[46:49]
	v_mfma_f32_16x16x32_bf16 v[42:45], v[138:141], v[196:199], v[42:45]
	v_mfma_f32_16x16x32_bf16 v[30:33], v[130:133], v[206:209], v[30:33]
	v_mfma_f32_16x16x32_bf16 v[26:29], v[138:141], v[206:209], v[26:29]
	v_mfma_f32_16x16x32_bf16 v[14:17], v[130:133], v[214:217], v[14:17]
	v_mfma_f32_16x16x32_bf16 v[10:13], v[138:141], v[214:217], v[10:13]
	v_mfma_f32_16x16x32_bf16 v[62:65], v[134:137], v[192:195], v[62:65]
	v_mfma_f32_16x16x32_bf16 v[58:61], v[142:145], v[192:195], v[58:61]
	v_mfma_f32_16x16x32_bf16 v[46:49], v[134:137], v[200:203], v[46:49]
	v_mfma_f32_16x16x32_bf16 v[42:45], v[142:145], v[200:203], v[42:45]
	v_mfma_f32_16x16x32_bf16 v[30:33], v[134:137], v[210:213], v[30:33]
	v_mfma_f32_16x16x32_bf16 v[26:29], v[142:145], v[210:213], v[26:29]
	v_mfma_f32_16x16x32_bf16 v[14:17], v[134:137], v[218:221], v[14:17]
	v_mfma_f32_16x16x32_bf16 v[10:13], v[142:145], v[218:221], v[10:13]
	v_mfma_f32_16x16x32_bf16 v[54:57], v[164:167], v[188:191], v[54:57]
	v_mfma_f32_16x16x32_bf16 v[50:53], v[180:183], v[188:191], v[50:53]
	v_mfma_f32_16x16x32_bf16 v[38:41], v[164:167], v[196:199], v[38:41]
	v_mfma_f32_16x16x32_bf16 v[34:37], v[180:183], v[196:199], v[34:37]
	v_mfma_f32_16x16x32_bf16 v[22:25], v[164:167], v[206:209], v[22:25]
	v_mfma_f32_16x16x32_bf16 v[18:21], v[180:183], v[206:209], v[18:21]
	v_mfma_f32_16x16x32_bf16 v[6:9], v[164:167], v[214:217], v[6:9]
	v_mfma_f32_16x16x32_bf16 v[2:5], v[180:183], v[214:217], v[2:5]
	v_mfma_f32_16x16x32_bf16 v[54:57], v[176:179], v[192:195], v[54:57]
	v_mfma_f32_16x16x32_bf16 v[50:53], v[184:187], v[192:195], v[50:53]
	v_mfma_f32_16x16x32_bf16 v[38:41], v[176:179], v[200:203], v[38:41]
	v_mfma_f32_16x16x32_bf16 v[34:37], v[184:187], v[200:203], v[34:37]
	v_mfma_f32_16x16x32_bf16 v[22:25], v[176:179], v[210:213], v[22:25]
	v_mfma_f32_16x16x32_bf16 v[18:21], v[184:187], v[210:213], v[18:21]
	v_mfma_f32_16x16x32_bf16 v[6:9], v[176:179], v[218:221], v[6:9]
	v_mfma_f32_16x16x32_bf16 v[2:5], v[184:187], v[218:221], v[2:5]
	s_setprio 0
	s_barrier
	s_add_i32 s25, 0, 0x18000
	s_add_i32 s30, 0, 0x1c000
	v_add_u32_e32 v142, s25, v171
	v_add_u32_e32 v175, s30, v171
	ds_read_b128 v[130:133], v142
	ds_read_b128 v[134:137], v142 offset:1024
	ds_read_b128 v[138:141], v142 offset:2048
	ds_read_b128 v[142:145], v142 offset:3072
	ds_read_b128 v[164:167], v175
	ds_read_b128 v[176:179], v175 offset:1024
	ds_read_b128 v[180:183], v175 offset:2048
	ds_read_b128 v[184:187], v175 offset:3072
	s_add_u32 s28, s68, 0x40000
	s_addc_u32 s29, s69, 0
	s_mov_b32 m0, s75
	v_lshl_add_u64 v[228:229], s[28:29], 0, v[152:153]
	ds_read_b128 v[188:191], v174 offset:32768
	ds_read_b128 v[192:195], v174 offset:33792
	ds_read_b128 v[196:199], v174 offset:34816
	ds_read_b128 v[200:203], v174 offset:35840
	ds_read_b128 v[206:209], v174 offset:36864
	ds_read_b128 v[210:213], v174 offset:37888
	ds_read_b128 v[214:217], v174 offset:38912
	ds_read_b128 v[218:221], v174 offset:39936
	global_load_lds_dwordx4 v[228:229], off
	v_lshl_add_u64 v[228:229], s[28:29], 0, v[148:149]
	s_mov_b32 m0, s76
	s_nop 0
	global_load_lds_dwordx4 v[228:229], off
	s_waitcnt vmcnt(8)
	s_waitcnt lgkmcnt(0)
	s_setprio 1
	s_barrier
	v_mfma_f32_16x16x32_bf16 v[126:129], v[130:133], v[188:191], v[126:129]
	v_mfma_f32_16x16x32_bf16 v[122:125], v[138:141], v[188:191], v[122:125]
	v_mfma_f32_16x16x32_bf16 v[110:113], v[130:133], v[196:199], v[110:113]
	v_mfma_f32_16x16x32_bf16 v[106:109], v[138:141], v[196:199], v[106:109]
	v_mfma_f32_16x16x32_bf16 v[94:97], v[130:133], v[206:209], v[94:97]
	v_mfma_f32_16x16x32_bf16 v[90:93], v[138:141], v[206:209], v[90:93]
	v_mfma_f32_16x16x32_bf16 v[78:81], v[130:133], v[214:217], v[78:81]
	v_mfma_f32_16x16x32_bf16 v[74:77], v[138:141], v[214:217], v[74:77]
	v_mfma_f32_16x16x32_bf16 v[126:129], v[134:137], v[192:195], v[126:129]
	v_mfma_f32_16x16x32_bf16 v[122:125], v[142:145], v[192:195], v[122:125]
	v_mfma_f32_16x16x32_bf16 v[110:113], v[134:137], v[200:203], v[110:113]
	v_mfma_f32_16x16x32_bf16 v[106:109], v[142:145], v[200:203], v[106:109]
	v_mfma_f32_16x16x32_bf16 v[94:97], v[134:137], v[210:213], v[94:97]
	v_mfma_f32_16x16x32_bf16 v[90:93], v[142:145], v[210:213], v[90:93]
	v_mfma_f32_16x16x32_bf16 v[78:81], v[134:137], v[218:221], v[78:81]
	v_mfma_f32_16x16x32_bf16 v[74:77], v[142:145], v[218:221], v[74:77]
	v_mfma_f32_16x16x32_bf16 v[118:121], v[164:167], v[188:191], v[118:121]
	v_mfma_f32_16x16x32_bf16 v[114:117], v[180:183], v[188:191], v[114:117]
	v_mfma_f32_16x16x32_bf16 v[102:105], v[164:167], v[196:199], v[102:105]
	v_mfma_f32_16x16x32_bf16 v[98:101], v[180:183], v[196:199], v[98:101]
	v_mfma_f32_16x16x32_bf16 v[86:89], v[164:167], v[206:209], v[86:89]
	v_mfma_f32_16x16x32_bf16 v[82:85], v[180:183], v[206:209], v[82:85]
	v_mfma_f32_16x16x32_bf16 v[70:73], v[164:167], v[214:217], v[70:73]
	v_mfma_f32_16x16x32_bf16 v[66:69], v[180:183], v[214:217], v[66:69]
	v_mfma_f32_16x16x32_bf16 v[118:121], v[176:179], v[192:195], v[118:121]
	v_mfma_f32_16x16x32_bf16 v[114:117], v[184:187], v[192:195], v[114:117]
	v_mfma_f32_16x16x32_bf16 v[102:105], v[176:179], v[200:203], v[102:105]
	v_mfma_f32_16x16x32_bf16 v[98:101], v[184:187], v[200:203], v[98:101]
	v_mfma_f32_16x16x32_bf16 v[86:89], v[176:179], v[210:213], v[86:89]
	v_mfma_f32_16x16x32_bf16 v[82:85], v[184:187], v[210:213], v[82:85]
	v_mfma_f32_16x16x32_bf16 v[70:73], v[176:179], v[218:221], v[70:73]
	v_mfma_f32_16x16x32_bf16 v[66:69], v[184:187], v[218:221], v[66:69]
	s_setprio 0
	s_barrier
	s_add_i32 s25, s25, s70
	v_lshl_add_u64 v[168:169], v[168:169], 0, s[36:37]
	s_mov_b32 m0, s25
	ds_read_b128 v[188:191], v174 offset:49152
	ds_read_b128 v[192:195], v174 offset:50176
	ds_read_b128 v[196:199], v174 offset:51200
	ds_read_b128 v[200:203], v174 offset:52224
	ds_read_b128 v[206:209], v174 offset:53248
	ds_read_b128 v[210:213], v174 offset:54272
	ds_read_b128 v[214:217], v174 offset:55296
	ds_read_b128 v[218:221], v174 offset:56320
	global_load_lds_dwordx4 v[168:169], off
	s_add_i32 m0, s25, 0x2000
	s_add_u32 s28, s66, 0x40080
	v_lshl_add_u64 v[168:169], v[222:223], 0, s[36:37]
	s_addc_u32 s29, s67, 0
	s_add_i32 s25, s30, s70
	global_load_lds_dwordx4 v[168:169], off
	v_lshl_add_u64 v[168:169], s[28:29], 0, v[150:151]
	s_mov_b32 m0, s25
	s_nop 0
	global_load_lds_dwordx4 v[168:169], off
	v_lshl_add_u64 v[168:169], s[28:29], 0, v[146:147]
	s_add_i32 m0, s25, 0x2000
	s_nop 0
	global_load_lds_dwordx4 v[168:169], off
	v_lshl_add_u64 v[168:169], v[224:225], 0, s[36:37]
	s_mov_b32 m0, s79
	s_nop 0
	global_load_lds_dwordx4 v[168:169], off
	v_lshl_add_u64 v[168:169], v[226:227], 0, s[36:37]
	s_mov_b32 m0, s80
	s_nop 0
	global_load_lds_dwordx4 v[168:169], off
	s_waitcnt vmcnt(8)
	s_waitcnt lgkmcnt(0)
	s_setprio 1
	s_barrier
	v_mfma_f32_16x16x32_bf16 v[62:65], v[130:133], v[188:191], v[62:65]
	v_mfma_f32_16x16x32_bf16 v[58:61], v[138:141], v[188:191], v[58:61]
	v_mfma_f32_16x16x32_bf16 v[46:49], v[130:133], v[196:199], v[46:49]
	v_mfma_f32_16x16x32_bf16 v[42:45], v[138:141], v[196:199], v[42:45]
	v_mfma_f32_16x16x32_bf16 v[30:33], v[130:133], v[206:209], v[30:33]
	v_mfma_f32_16x16x32_bf16 v[26:29], v[138:141], v[206:209], v[26:29]
	v_mfma_f32_16x16x32_bf16 v[14:17], v[130:133], v[214:217], v[14:17]
	v_mfma_f32_16x16x32_bf16 v[10:13], v[138:141], v[214:217], v[10:13]
	v_mfma_f32_16x16x32_bf16 v[62:65], v[134:137], v[192:195], v[62:65]
	v_mfma_f32_16x16x32_bf16 v[58:61], v[142:145], v[192:195], v[58:61]
	v_mfma_f32_16x16x32_bf16 v[46:49], v[134:137], v[200:203], v[46:49]
	v_mfma_f32_16x16x32_bf16 v[42:45], v[142:145], v[200:203], v[42:45]
	v_mfma_f32_16x16x32_bf16 v[30:33], v[134:137], v[210:213], v[30:33]
	v_mfma_f32_16x16x32_bf16 v[26:29], v[142:145], v[210:213], v[26:29]
	v_mfma_f32_16x16x32_bf16 v[14:17], v[134:137], v[218:221], v[14:17]
	v_mfma_f32_16x16x32_bf16 v[10:13], v[142:145], v[218:221], v[10:13]
	v_mfma_f32_16x16x32_bf16 v[54:57], v[164:167], v[188:191], v[54:57]
	v_mfma_f32_16x16x32_bf16 v[50:53], v[180:183], v[188:191], v[50:53]
	v_mfma_f32_16x16x32_bf16 v[38:41], v[164:167], v[196:199], v[38:41]
	v_mfma_f32_16x16x32_bf16 v[34:37], v[180:183], v[196:199], v[34:37]
	v_mfma_f32_16x16x32_bf16 v[22:25], v[164:167], v[206:209], v[22:25]
	v_mfma_f32_16x16x32_bf16 v[18:21], v[180:183], v[206:209], v[18:21]
	v_mfma_f32_16x16x32_bf16 v[6:9], v[164:167], v[214:217], v[6:9]
	v_mfma_f32_16x16x32_bf16 v[2:5], v[180:183], v[214:217], v[2:5]
	v_mfma_f32_16x16x32_bf16 v[54:57], v[176:179], v[192:195], v[54:57]
	v_mfma_f32_16x16x32_bf16 v[50:53], v[184:187], v[192:195], v[50:53]
	v_mfma_f32_16x16x32_bf16 v[38:41], v[176:179], v[200:203], v[38:41]
	v_mfma_f32_16x16x32_bf16 v[34:37], v[184:187], v[200:203], v[34:37]
	v_mfma_f32_16x16x32_bf16 v[22:25], v[176:179], v[210:213], v[22:25]
	v_mfma_f32_16x16x32_bf16 v[18:21], v[184:187], v[210:213], v[18:21]
	v_mfma_f32_16x16x32_bf16 v[6:9], v[176:179], v[218:221], v[6:9]
	v_mfma_f32_16x16x32_bf16 v[2:5], v[184:187], v[218:221], v[2:5]
	s_setprio 0
	s_barrier
	s_add_i32 s24, s24, 2
	s_add_u32 s64, s64, 0x100
	s_addc_u32 s65, s65, 0
	s_add_u32 s18, s18, 0x100
	s_addc_u32 s19, s19, 0
	s_cmp_gt_u32 s24, 13
	s_cbranch_scc0 .LBB0_1013
	s_and_b64 vcc, exec, s[38:39]
	s_cbranch_vccz .LBB0_1016
	s_barrier

.LBB0_1427:
	s_add_u32 s90, s35, s86
	s_addc_u32 s91, s64, s87
	s_and_b64 s[14:15], s[88:89], exec
	s_cselect_b32 s14, s91, s11
	s_cselect_b32 s15, s90, s10
	s_add_u32 s92, s65, s74
	s_addc_u32 s93, s68, s75
	s_and_b64 s[66:67], s[88:89], exec
	s_cselect_b32 s51, s93, s95
	s_cselect_b32 s84, s92, s94
	s_add_i32 s85, s18, -2
	s_add_u32 s10, s10, 0x40080
	s_addc_u32 s11, s11, 0
	s_add_u32 vcc_lo, s94, 0x100
	s_addc_u32 vcc_hi, s95, 0
	s_mov_b32 s94, 0
	s_waitcnt vmcnt(0)
	s_add_i32 s66, s94, 2
	s_add_u32 s67, s10, 0xfffc0080
	s_addc_u32 s72, s11, -1
	s_cmp_eq_u32 s85, s94
	s_cselect_b32 s97, s14, s72
	s_cselect_b32 s96, s15, s67
	s_cselect_b32 s95, s51, vcc_hi
	s_cselect_b32 s94, s84, vcc_lo
	s_add_i32 s67, 0, 0x10000
	s_add_i32 s62, 0, 0x14000
	v_add_u32_e32 v126, s67, v199
	v_add_u32_e32 v158, s62, v199
	ds_read_b128 v[114:117], v126
	ds_read_b128 v[118:121], v126 offset:1024
	ds_read_b128 v[122:125], v126 offset:2048
	ds_read_b128 v[126:129], v126 offset:3072
	ds_read_b128 v[146:149], v158
	ds_read_b128 v[150:153], v158 offset:1024
	ds_read_b128 v[154:157], v158 offset:2048
	ds_read_b128 v[158:161], v158 offset:3072
	v_lshl_add_u64 v[202:203], s[10:11], 0, v[196:197]
	s_add_i32 m0, s28, 0xc000
	ds_read_b128 v[162:165], v214
	ds_read_b128 v[166:169], v214 offset:1024
	ds_read_b128 v[216:219], v214 offset:2048
	ds_read_b128 v[220:223], v214 offset:3072
	ds_read_b128 v[224:227], v214 offset:4096
	ds_read_b128 v[228:231], v214 offset:5120
	ds_read_b128 v[232:235], v214 offset:6144
	ds_read_b128 v[236:239], v214 offset:7168
	global_load_lds_dwordx4 v[202:203], off
	v_lshl_add_u64 v[202:203], s[10:11], 0, v[176:177]
	s_add_i32 m0, s28, 0xe000
	s_nop 0
	global_load_lds_dwordx4 v[202:203], off
	s_waitcnt vmcnt(8)
	s_waitcnt lgkmcnt(0)
	s_setprio 1
	s_barrier
	v_mfma_f32_16x16x32_bf16 v[142:145], v[114:117], v[162:165], 0
	v_mfma_f32_16x16x32_bf16 v[138:141], v[122:125], v[162:165], 0
	v_mfma_f32_16x16x32_bf16 v[110:113], v[114:117], v[216:219], 0
	v_mfma_f32_16x16x32_bf16 v[106:109], v[122:125], v[216:219], 0
	v_mfma_f32_16x16x32_bf16 v[98:101], v[114:117], v[224:227], 0
	v_mfma_f32_16x16x32_bf16 v[90:93], v[122:125], v[224:227], 0
	v_mfma_f32_16x16x32_bf16 v[82:85], v[114:117], v[232:235], 0
	v_mfma_f32_16x16x32_bf16 v[74:77], v[122:125], v[232:235], 0
	v_mfma_f32_16x16x32_bf16 v[142:145], v[118:121], v[166:169], v[142:145]
	v_mfma_f32_16x16x32_bf16 v[138:141], v[126:129], v[166:169], v[138:141]
	v_mfma_f32_16x16x32_bf16 v[110:113], v[118:121], v[220:223], v[110:113]
	v_mfma_f32_16x16x32_bf16 v[106:109], v[126:129], v[220:223], v[106:109]
	v_mfma_f32_16x16x32_bf16 v[98:101], v[118:121], v[228:231], v[98:101]
	v_mfma_f32_16x16x32_bf16 v[90:93], v[126:129], v[228:231], v[90:93]
	v_mfma_f32_16x16x32_bf16 v[82:85], v[118:121], v[236:239], v[82:85]
	v_mfma_f32_16x16x32_bf16 v[74:77], v[126:129], v[236:239], v[74:77]
	v_mfma_f32_16x16x32_bf16 v[134:137], v[146:149], v[162:165], 0
	v_mfma_f32_16x16x32_bf16 v[130:133], v[154:157], v[162:165], 0
	v_mfma_f32_16x16x32_bf16 v[102:105], v[146:149], v[216:219], 0
	v_mfma_f32_16x16x32_bf16 v[94:97], v[154:157], v[216:219], 0
	v_mfma_f32_16x16x32_bf16 v[86:89], v[146:149], v[224:227], 0
	v_mfma_f32_16x16x32_bf16 v[78:81], v[154:157], v[224:227], 0
	v_mfma_f32_16x16x32_bf16 v[70:73], v[146:149], v[232:235], 0
	v_mfma_f32_16x16x32_bf16 v[66:69], v[154:157], v[232:235], 0
	v_mfma_f32_16x16x32_bf16 v[134:137], v[150:153], v[166:169], v[134:137]
	v_mfma_f32_16x16x32_bf16 v[130:133], v[158:161], v[166:169], v[130:133]
	v_mfma_f32_16x16x32_bf16 v[102:105], v[150:153], v[220:223], v[102:105]
	v_mfma_f32_16x16x32_bf16 v[94:97], v[158:161], v[220:223], v[94:97]
	v_mfma_f32_16x16x32_bf16 v[86:89], v[150:153], v[228:231], v[86:89]
	v_mfma_f32_16x16x32_bf16 v[78:81], v[158:161], v[228:231], v[78:81]
	v_mfma_f32_16x16x32_bf16 v[70:73], v[150:153], v[236:239], v[70:73]
	v_mfma_f32_16x16x32_bf16 v[66:69], v[158:161], v[236:239], v[66:69]
	s_setprio 0
	s_barrier
	s_add_i32 s63, s67, s17
	v_lshl_add_u64 v[202:203], s[94:95], 0, v[174:175]
	s_mov_b32 m0, s63
	ds_read_b128 v[162:165], v214 offset:16384
	ds_read_b128 v[166:169], v214 offset:17408
	ds_read_b128 v[216:219], v214 offset:18432
	ds_read_b128 v[220:223], v214 offset:19456
	ds_read_b128 v[224:227], v214 offset:20480
	ds_read_b128 v[228:231], v214 offset:21504
	ds_read_b128 v[232:235], v214 offset:22528
	ds_read_b128 v[236:239], v214 offset:23552
	global_load_lds_dwordx4 v[202:203], off
	s_add_i32 m0, s63, 0x2000
	s_add_u32 s72, s94, 0x40000
	v_lshl_add_u64 v[240:241], s[94:95], 0, v[178:179]
	s_addc_u32 s73, s95, 0
	s_add_i32 s62, s62, s17
	global_load_lds_dwordx4 v[240:241], off
	v_lshl_add_u64 v[242:243], s[72:73], 0, v[174:175]
	s_mov_b32 m0, s62
	v_lshl_add_u64 v[244:245], s[96:97], 0, v[176:177]
	global_load_lds_dwordx4 v[242:243], off
	v_lshl_add_u64 v[242:243], s[72:73], 0, v[178:179]
	s_add_i32 m0, s62, 0x2000
	s_nop 0
	global_load_lds_dwordx4 v[242:243], off
	v_lshl_add_u64 v[242:243], s[96:97], 0, v[172:173]
	s_mov_b32 m0, s28
	s_nop 0
	global_load_lds_dwordx4 v[242:243], off
	s_mov_b32 m0, s29
	s_nop 0
	global_load_lds_dwordx4 v[244:245], off
	s_waitcnt vmcnt(8)
	s_waitcnt lgkmcnt(0)
	s_setprio 1
	s_barrier
	v_mfma_f32_16x16x32_bf16 v[62:65], v[114:117], v[162:165], 0
	v_mfma_f32_16x16x32_bf16 v[58:61], v[122:125], v[162:165], 0
	v_mfma_f32_16x16x32_bf16 v[50:53], v[114:117], v[216:219], 0
	v_mfma_f32_16x16x32_bf16 v[42:45], v[122:125], v[216:219], 0
	v_mfma_f32_16x16x32_bf16 v[34:37], v[114:117], v[224:227], 0
	v_mfma_f32_16x16x32_bf16 v[26:29], v[122:125], v[224:227], 0
	v_mfma_f32_16x16x32_bf16 v[18:21], v[114:117], v[232:235], 0
	v_mfma_f32_16x16x32_bf16 v[10:13], v[122:125], v[232:235], 0
	v_mfma_f32_16x16x32_bf16 v[62:65], v[118:121], v[166:169], v[62:65]
	v_mfma_f32_16x16x32_bf16 v[58:61], v[126:129], v[166:169], v[58:61]
	v_mfma_f32_16x16x32_bf16 v[50:53], v[118:121], v[220:223], v[50:53]
	v_mfma_f32_16x16x32_bf16 v[42:45], v[126:129], v[220:223], v[42:45]
	v_mfma_f32_16x16x32_bf16 v[34:37], v[118:121], v[228:231], v[34:37]
	v_mfma_f32_16x16x32_bf16 v[26:29], v[126:129], v[228:231], v[26:29]
	v_mfma_f32_16x16x32_bf16 v[18:21], v[118:121], v[236:239], v[18:21]
	v_mfma_f32_16x16x32_bf16 v[10:13], v[126:129], v[236:239], v[10:13]
	v_mfma_f32_16x16x32_bf16 v[54:57], v[146:149], v[162:165], 0
	v_mfma_f32_16x16x32_bf16 v[46:49], v[154:157], v[162:165], 0
	v_mfma_f32_16x16x32_bf16 v[38:41], v[146:149], v[216:219], 0
	v_mfma_f32_16x16x32_bf16 v[30:33], v[154:157], v[216:219], 0
	v_mfma_f32_16x16x32_bf16 v[22:25], v[146:149], v[224:227], 0
	v_mfma_f32_16x16x32_bf16 v[14:17], v[154:157], v[224:227], 0
	v_mfma_f32_16x16x32_bf16 v[6:9], v[146:149], v[232:235], 0
	v_mfma_f32_16x16x32_bf16 v[2:5], v[154:157], v[232:235], 0
	v_mfma_f32_16x16x32_bf16 v[54:57], v[150:153], v[166:169], v[54:57]
	v_mfma_f32_16x16x32_bf16 v[46:49], v[158:161], v[166:169], v[46:49]
	v_mfma_f32_16x16x32_bf16 v[38:41], v[150:153], v[220:223], v[38:41]
	v_mfma_f32_16x16x32_bf16 v[30:33], v[158:161], v[220:223], v[30:33]
	v_mfma_f32_16x16x32_bf16 v[22:25], v[150:153], v[228:231], v[22:25]
	v_mfma_f32_16x16x32_bf16 v[14:17], v[158:161], v[228:231], v[14:17]
	v_mfma_f32_16x16x32_bf16 v[6:9], v[150:153], v[236:239], v[6:9]
	v_mfma_f32_16x16x32_bf16 v[2:5], v[158:161], v[236:239], v[2:5]
	s_setprio 0
	s_barrier
	s_add_i32 s62, 0, 0x18000
	s_add_i32 s63, 0, 0x1c000
	v_add_u32_e32 v126, s62, v199
	v_add_u32_e32 v158, s63, v199
	ds_read_b128 v[114:117], v126
	ds_read_b128 v[118:121], v126 offset:1024
	ds_read_b128 v[122:125], v126 offset:2048
	ds_read_b128 v[126:129], v126 offset:3072
	ds_read_b128 v[146:149], v158
	ds_read_b128 v[150:153], v158 offset:1024
	ds_read_b128 v[154:157], v158 offset:2048
	ds_read_b128 v[158:161], v158 offset:3072
	s_add_u32 s72, s96, 0x40000
	s_addc_u32 s73, s97, 0
	s_mov_b32 m0, s30
	v_lshl_add_u64 v[246:247], s[72:73], 0, v[172:173]
	ds_read_b128 v[162:165], v214 offset:32768
	ds_read_b128 v[166:169], v214 offset:33792
	ds_read_b128 v[216:219], v214 offset:34816
	ds_read_b128 v[220:223], v214 offset:35840
	ds_read_b128 v[224:227], v214 offset:36864
	ds_read_b128 v[228:231], v214 offset:37888
	ds_read_b128 v[232:235], v214 offset:38912
	ds_read_b128 v[236:239], v214 offset:39936
	global_load_lds_dwordx4 v[246:247], off
	v_lshl_add_u64 v[246:247], s[72:73], 0, v[176:177]
	s_mov_b32 m0, s31
	s_nop 0
	global_load_lds_dwordx4 v[246:247], off
	s_waitcnt vmcnt(8)
	s_waitcnt lgkmcnt(0)
	s_setprio 1
	s_barrier
	v_mfma_f32_16x16x32_bf16 v[142:145], v[114:117], v[162:165], v[142:145]
	v_mfma_f32_16x16x32_bf16 v[138:141], v[122:125], v[162:165], v[138:141]
	v_mfma_f32_16x16x32_bf16 v[110:113], v[114:117], v[216:219], v[110:113]
	v_mfma_f32_16x16x32_bf16 v[106:109], v[122:125], v[216:219], v[106:109]
	v_mfma_f32_16x16x32_bf16 v[98:101], v[114:117], v[224:227], v[98:101]
	v_mfma_f32_16x16x32_bf16 v[90:93], v[122:125], v[224:227], v[90:93]
	v_mfma_f32_16x16x32_bf16 v[82:85], v[114:117], v[232:235], v[82:85]
	v_mfma_f32_16x16x32_bf16 v[74:77], v[122:125], v[232:235], v[74:77]
	v_mfma_f32_16x16x32_bf16 v[142:145], v[118:121], v[166:169], v[142:145]
	v_mfma_f32_16x16x32_bf16 v[138:141], v[126:129], v[166:169], v[138:141]
	v_mfma_f32_16x16x32_bf16 v[110:113], v[118:121], v[220:223], v[110:113]
	v_mfma_f32_16x16x32_bf16 v[106:109], v[126:129], v[220:223], v[106:109]
	v_mfma_f32_16x16x32_bf16 v[98:101], v[118:121], v[228:231], v[98:101]
	v_mfma_f32_16x16x32_bf16 v[90:93], v[126:129], v[228:231], v[90:93]
	v_mfma_f32_16x16x32_bf16 v[82:85], v[118:121], v[236:239], v[82:85]
	v_mfma_f32_16x16x32_bf16 v[74:77], v[126:129], v[236:239], v[74:77]
	v_mfma_f32_16x16x32_bf16 v[134:137], v[146:149], v[162:165], v[134:137]
	v_mfma_f32_16x16x32_bf16 v[130:133], v[154:157], v[162:165], v[130:133]
	v_mfma_f32_16x16x32_bf16 v[102:105], v[146:149], v[216:219], v[102:105]
	v_mfma_f32_16x16x32_bf16 v[94:97], v[154:157], v[216:219], v[94:97]
	v_mfma_f32_16x16x32_bf16 v[86:89], v[146:149], v[224:227], v[86:89]
	v_mfma_f32_16x16x32_bf16 v[78:81], v[154:157], v[224:227], v[78:81]
	v_mfma_f32_16x16x32_bf16 v[70:73], v[146:149], v[232:235], v[70:73]
	v_mfma_f32_16x16x32_bf16 v[66:69], v[154:157], v[232:235], v[66:69]
	v_mfma_f32_16x16x32_bf16 v[134:137], v[150:153], v[166:169], v[134:137]
	v_mfma_f32_16x16x32_bf16 v[130:133], v[158:161], v[166:169], v[130:133]
	v_mfma_f32_16x16x32_bf16 v[102:105], v[150:153], v[220:223], v[102:105]
	v_mfma_f32_16x16x32_bf16 v[94:97], v[158:161], v[220:223], v[94:97]
	v_mfma_f32_16x16x32_bf16 v[86:89], v[150:153], v[228:231], v[86:89]
	v_mfma_f32_16x16x32_bf16 v[78:81], v[158:161], v[228:231], v[78:81]
	v_mfma_f32_16x16x32_bf16 v[70:73], v[150:153], v[236:239], v[70:73]
	v_mfma_f32_16x16x32_bf16 v[66:69], v[158:161], v[236:239], v[66:69]
	s_setprio 0
	s_barrier
	s_add_i32 s62, s62, s17
	v_lshl_add_u64 v[202:203], v[202:203], 0, s[76:77]
	s_mov_b32 m0, s62
	ds_read_b128 v[162:165], v214 offset:49152
	ds_read_b128 v[166:169], v214 offset:50176
	ds_read_b128 v[216:219], v214 offset:51200
	ds_read_b128 v[220:223], v214 offset:52224
	ds_read_b128 v[224:227], v214 offset:53248
	ds_read_b128 v[228:231], v214 offset:54272
	ds_read_b128 v[232:235], v214 offset:55296
	ds_read_b128 v[236:239], v214 offset:56320
	global_load_lds_dwordx4 v[202:203], off
	s_add_i32 m0, s62, 0x2000
	s_add_u32 s72, s94, 0x40080
	v_lshl_add_u64 v[202:203], v[240:241], 0, s[76:77]
	s_addc_u32 s73, s95, 0
	s_add_i32 s62, s63, s17
	global_load_lds_dwordx4 v[202:203], off
	v_lshl_add_u64 v[202:203], s[72:73], 0, v[174:175]
	s_mov_b32 m0, s62
	s_nop 0
	global_load_lds_dwordx4 v[202:203], off
	v_lshl_add_u64 v[202:203], s[72:73], 0, v[178:179]
	s_add_i32 m0, s62, 0x2000
	s_nop 0
	global_load_lds_dwordx4 v[202:203], off
	v_lshl_add_u64 v[202:203], v[242:243], 0, s[76:77]
	s_mov_b32 m0, s44
	s_nop 0
	global_load_lds_dwordx4 v[202:203], off
	v_lshl_add_u64 v[202:203], v[244:245], 0, s[76:77]
	s_mov_b32 m0, s36
	s_nop 0
	global_load_lds_dwordx4 v[202:203], off
	s_waitcnt vmcnt(8)
	s_waitcnt lgkmcnt(0)
	s_setprio 1
	s_barrier
	v_mfma_f32_16x16x32_bf16 v[62:65], v[114:117], v[162:165], v[62:65]
	v_mfma_f32_16x16x32_bf16 v[58:61], v[122:125], v[162:165], v[58:61]
	v_mfma_f32_16x16x32_bf16 v[50:53], v[114:117], v[216:219], v[50:53]
	v_mfma_f32_16x16x32_bf16 v[42:45], v[122:125], v[216:219], v[42:45]
	v_mfma_f32_16x16x32_bf16 v[34:37], v[114:117], v[224:227], v[34:37]
	v_mfma_f32_16x16x32_bf16 v[26:29], v[122:125], v[224:227], v[26:29]
	v_mfma_f32_16x16x32_bf16 v[18:21], v[114:117], v[232:235], v[18:21]
	v_mfma_f32_16x16x32_bf16 v[10:13], v[122:125], v[232:235], v[10:13]
	v_mfma_f32_16x16x32_bf16 v[62:65], v[118:121], v[166:169], v[62:65]
	v_mfma_f32_16x16x32_bf16 v[58:61], v[126:129], v[166:169], v[58:61]
	v_mfma_f32_16x16x32_bf16 v[50:53], v[118:121], v[220:223], v[50:53]
	v_mfma_f32_16x16x32_bf16 v[42:45], v[126:129], v[220:223], v[42:45]
	v_mfma_f32_16x16x32_bf16 v[34:37], v[118:121], v[228:231], v[34:37]
	v_mfma_f32_16x16x32_bf16 v[26:29], v[126:129], v[228:231], v[26:29]
	v_mfma_f32_16x16x32_bf16 v[18:21], v[118:121], v[236:239], v[18:21]
	v_mfma_f32_16x16x32_bf16 v[10:13], v[126:129], v[236:239], v[10:13]
	v_mfma_f32_16x16x32_bf16 v[54:57], v[146:149], v[162:165], v[54:57]
	v_mfma_f32_16x16x32_bf16 v[46:49], v[154:157], v[162:165], v[46:49]
	v_mfma_f32_16x16x32_bf16 v[38:41], v[146:149], v[216:219], v[38:41]
	v_mfma_f32_16x16x32_bf16 v[30:33], v[154:157], v[216:219], v[30:33]
	v_mfma_f32_16x16x32_bf16 v[22:25], v[146:149], v[224:227], v[22:25]
	v_mfma_f32_16x16x32_bf16 v[14:17], v[154:157], v[224:227], v[14:17]
	v_mfma_f32_16x16x32_bf16 v[6:9], v[146:149], v[232:235], v[6:9]
	v_mfma_f32_16x16x32_bf16 v[2:5], v[154:157], v[232:235], v[2:5]
	v_mfma_f32_16x16x32_bf16 v[54:57], v[150:153], v[166:169], v[54:57]
	v_mfma_f32_16x16x32_bf16 v[46:49], v[158:161], v[166:169], v[46:49]
	v_mfma_f32_16x16x32_bf16 v[38:41], v[150:153], v[220:223], v[38:41]
	v_mfma_f32_16x16x32_bf16 v[30:33], v[158:161], v[220:223], v[30:33]
	v_mfma_f32_16x16x32_bf16 v[22:25], v[150:153], v[228:231], v[22:25]
	v_mfma_f32_16x16x32_bf16 v[14:17], v[158:161], v[228:231], v[14:17]
	v_mfma_f32_16x16x32_bf16 v[6:9], v[150:153], v[236:239], v[6:9]
	v_mfma_f32_16x16x32_bf16 v[2:5], v[158:161], v[236:239], v[2:5]
	s_setprio 0
	s_barrier
	s_add_u32 s10, s10, 0x100
	s_addc_u32 s11, s11, 0
	s_add_u32 vcc_lo, vcc_lo, 0x100
	s_addc_u32 vcc_hi, vcc_hi, 0
	s_cmp_ge_i32 s66, s18
	s_mov_b32 s94, s66
.LBB0_1428:
	s_add_i32 s66, s94, 2
	s_add_u32 s67, s10, 0xfffc0080
	s_addc_u32 s72, s11, -1
	s_cmp_eq_u32 s85, s94
	s_cselect_b32 s97, s14, s72
	s_cselect_b32 s96, s15, s67
	s_cselect_b32 s95, s51, vcc_hi
	s_cselect_b32 s94, s84, vcc_lo
	s_add_i32 s67, 0, 0x10000
	s_add_i32 s62, 0, 0x14000
	v_add_u32_e32 v126, s67, v199
	v_add_u32_e32 v158, s62, v199
	ds_read_b128 v[114:117], v126
	ds_read_b128 v[118:121], v126 offset:1024
	ds_read_b128 v[122:125], v126 offset:2048
	ds_read_b128 v[126:129], v126 offset:3072
	ds_read_b128 v[146:149], v158
	ds_read_b128 v[150:153], v158 offset:1024
	ds_read_b128 v[154:157], v158 offset:2048
	ds_read_b128 v[158:161], v158 offset:3072
	v_lshl_add_u64 v[202:203], s[10:11], 0, v[196:197]
	s_add_i32 m0, s28, 0xc000
	ds_read_b128 v[162:165], v214
	ds_read_b128 v[166:169], v214 offset:1024
	ds_read_b128 v[216:219], v214 offset:2048
	ds_read_b128 v[220:223], v214 offset:3072
	ds_read_b128 v[224:227], v214 offset:4096
	ds_read_b128 v[228:231], v214 offset:5120
	ds_read_b128 v[232:235], v214 offset:6144
	ds_read_b128 v[236:239], v214 offset:7168
	global_load_lds_dwordx4 v[202:203], off
	v_lshl_add_u64 v[202:203], s[10:11], 0, v[176:177]
	s_add_i32 m0, s28, 0xe000
	s_nop 0
	global_load_lds_dwordx4 v[202:203], off
	s_waitcnt vmcnt(8)
	s_waitcnt lgkmcnt(0)
	s_setprio 1
	s_barrier
	v_mfma_f32_16x16x32_bf16 v[142:145], v[114:117], v[162:165], v[142:145]
	v_mfma_f32_16x16x32_bf16 v[138:141], v[122:125], v[162:165], v[138:141]
	v_mfma_f32_16x16x32_bf16 v[110:113], v[114:117], v[216:219], v[110:113]
	v_mfma_f32_16x16x32_bf16 v[106:109], v[122:125], v[216:219], v[106:109]
	v_mfma_f32_16x16x32_bf16 v[98:101], v[114:117], v[224:227], v[98:101]
	v_mfma_f32_16x16x32_bf16 v[90:93], v[122:125], v[224:227], v[90:93]
	v_mfma_f32_16x16x32_bf16 v[82:85], v[114:117], v[232:235], v[82:85]
	v_mfma_f32_16x16x32_bf16 v[74:77], v[122:125], v[232:235], v[74:77]
	v_mfma_f32_16x16x32_bf16 v[142:145], v[118:121], v[166:169], v[142:145]
	v_mfma_f32_16x16x32_bf16 v[138:141], v[126:129], v[166:169], v[138:141]
	v_mfma_f32_16x16x32_bf16 v[110:113], v[118:121], v[220:223], v[110:113]
	v_mfma_f32_16x16x32_bf16 v[106:109], v[126:129], v[220:223], v[106:109]
	v_mfma_f32_16x16x32_bf16 v[98:101], v[118:121], v[228:231], v[98:101]
	v_mfma_f32_16x16x32_bf16 v[90:93], v[126:129], v[228:231], v[90:93]
	v_mfma_f32_16x16x32_bf16 v[82:85], v[118:121], v[236:239], v[82:85]
	v_mfma_f32_16x16x32_bf16 v[74:77], v[126:129], v[236:239], v[74:77]
	v_mfma_f32_16x16x32_bf16 v[134:137], v[146:149], v[162:165], v[134:137]
	v_mfma_f32_16x16x32_bf16 v[130:133], v[154:157], v[162:165], v[130:133]
	v_mfma_f32_16x16x32_bf16 v[102:105], v[146:149], v[216:219], v[102:105]
	v_mfma_f32_16x16x32_bf16 v[94:97], v[154:157], v[216:219], v[94:97]
	v_mfma_f32_16x16x32_bf16 v[86:89], v[146:149], v[224:227], v[86:89]
	v_mfma_f32_16x16x32_bf16 v[78:81], v[154:157], v[224:227], v[78:81]
	v_mfma_f32_16x16x32_bf16 v[70:73], v[146:149], v[232:235], v[70:73]
	v_mfma_f32_16x16x32_bf16 v[66:69], v[154:157], v[232:235], v[66:69]
	v_mfma_f32_16x16x32_bf16 v[134:137], v[150:153], v[166:169], v[134:137]
	v_mfma_f32_16x16x32_bf16 v[130:133], v[158:161], v[166:169], v[130:133]
	v_mfma_f32_16x16x32_bf16 v[102:105], v[150:153], v[220:223], v[102:105]
	v_mfma_f32_16x16x32_bf16 v[94:97], v[158:161], v[220:223], v[94:97]
	v_mfma_f32_16x16x32_bf16 v[86:89], v[150:153], v[228:231], v[86:89]
	v_mfma_f32_16x16x32_bf16 v[78:81], v[158:161], v[228:231], v[78:81]
	v_mfma_f32_16x16x32_bf16 v[70:73], v[150:153], v[236:239], v[70:73]
	v_mfma_f32_16x16x32_bf16 v[66:69], v[158:161], v[236:239], v[66:69]
	s_setprio 0
	s_barrier
	s_add_i32 s63, s67, s17
	v_lshl_add_u64 v[202:203], s[94:95], 0, v[174:175]
	s_mov_b32 m0, s63
	ds_read_b128 v[162:165], v214 offset:16384
	ds_read_b128 v[166:169], v214 offset:17408
	ds_read_b128 v[216:219], v214 offset:18432
	ds_read_b128 v[220:223], v214 offset:19456
	ds_read_b128 v[224:227], v214 offset:20480
	ds_read_b128 v[228:231], v214 offset:21504
	ds_read_b128 v[232:235], v214 offset:22528
	ds_read_b128 v[236:239], v214 offset:23552
	global_load_lds_dwordx4 v[202:203], off
	s_add_i32 m0, s63, 0x2000
	s_add_u32 s72, s94, 0x40000
	v_lshl_add_u64 v[240:241], s[94:95], 0, v[178:179]
	s_addc_u32 s73, s95, 0
	s_add_i32 s62, s62, s17
	global_load_lds_dwordx4 v[240:241], off
	v_lshl_add_u64 v[242:243], s[72:73], 0, v[174:175]
	s_mov_b32 m0, s62
	v_lshl_add_u64 v[244:245], s[96:97], 0, v[176:177]
	global_load_lds_dwordx4 v[242:243], off
	v_lshl_add_u64 v[242:243], s[72:73], 0, v[178:179]
	s_add_i32 m0, s62, 0x2000
	s_nop 0
	global_load_lds_dwordx4 v[242:243], off
	v_lshl_add_u64 v[242:243], s[96:97], 0, v[172:173]
	s_mov_b32 m0, s28
	s_nop 0
	global_load_lds_dwordx4 v[242:243], off
	s_mov_b32 m0, s29
	s_nop 0
	global_load_lds_dwordx4 v[244:245], off
	s_waitcnt vmcnt(8)
	s_waitcnt lgkmcnt(0)
	s_setprio 1
	s_barrier
	v_mfma_f32_16x16x32_bf16 v[62:65], v[114:117], v[162:165], v[62:65]
	v_mfma_f32_16x16x32_bf16 v[58:61], v[122:125], v[162:165], v[58:61]
	v_mfma_f32_16x16x32_bf16 v[50:53], v[114:117], v[216:219], v[50:53]
	v_mfma_f32_16x16x32_bf16 v[42:45], v[122:125], v[216:219], v[42:45]
	v_mfma_f32_16x16x32_bf16 v[34:37], v[114:117], v[224:227], v[34:37]
	v_mfma_f32_16x16x32_bf16 v[26:29], v[122:125], v[224:227], v[26:29]
	v_mfma_f32_16x16x32_bf16 v[18:21], v[114:117], v[232:235], v[18:21]
	v_mfma_f32_16x16x32_bf16 v[10:13], v[122:125], v[232:235], v[10:13]
	v_mfma_f32_16x16x32_bf16 v[62:65], v[118:121], v[166:169], v[62:65]
	v_mfma_f32_16x16x32_bf16 v[58:61], v[126:129], v[166:169], v[58:61]
	v_mfma_f32_16x16x32_bf16 v[50:53], v[118:121], v[220:223], v[50:53]
	v_mfma_f32_16x16x32_bf16 v[42:45], v[126:129], v[220:223], v[42:45]
	v_mfma_f32_16x16x32_bf16 v[34:37], v[118:121], v[228:231], v[34:37]
	v_mfma_f32_16x16x32_bf16 v[26:29], v[126:129], v[228:231], v[26:29]
	v_mfma_f32_16x16x32_bf16 v[18:21], v[118:121], v[236:239], v[18:21]
	v_mfma_f32_16x16x32_bf16 v[10:13], v[126:129], v[236:239], v[10:13]
	v_mfma_f32_16x16x32_bf16 v[54:57], v[146:149], v[162:165], v[54:57]
	v_mfma_f32_16x16x32_bf16 v[46:49], v[154:157], v[162:165], v[46:49]
	v_mfma_f32_16x16x32_bf16 v[38:41], v[146:149], v[216:219], v[38:41]
	v_mfma_f32_16x16x32_bf16 v[30:33], v[154:157], v[216:219], v[30:33]
	v_mfma_f32_16x16x32_bf16 v[22:25], v[146:149], v[224:227], v[22:25]
	v_mfma_f32_16x16x32_bf16 v[14:17], v[154:157], v[224:227], v[14:17]
	v_mfma_f32_16x16x32_bf16 v[6:9], v[146:149], v[232:235], v[6:9]
	v_mfma_f32_16x16x32_bf16 v[2:5], v[154:157], v[232:235], v[2:5]
	v_mfma_f32_16x16x32_bf16 v[54:57], v[150:153], v[166:169], v[54:57]
	v_mfma_f32_16x16x32_bf16 v[46:49], v[158:161], v[166:169], v[46:49]
	v_mfma_f32_16x16x32_bf16 v[38:41], v[150:153], v[220:223], v[38:41]
	v_mfma_f32_16x16x32_bf16 v[30:33], v[158:161], v[220:223], v[30:33]
	v_mfma_f32_16x16x32_bf16 v[22:25], v[150:153], v[228:231], v[22:25]
	v_mfma_f32_16x16x32_bf16 v[14:17], v[158:161], v[228:231], v[14:17]
	v_mfma_f32_16x16x32_bf16 v[6:9], v[150:153], v[236:239], v[6:9]
	v_mfma_f32_16x16x32_bf16 v[2:5], v[158:161], v[236:239], v[2:5]
	s_setprio 0
	s_barrier
	s_add_i32 s62, 0, 0x18000
	s_add_i32 s63, 0, 0x1c000
	v_add_u32_e32 v126, s62, v199
	v_add_u32_e32 v158, s63, v199
	ds_read_b128 v[114:117], v126
	ds_read_b128 v[118:121], v126 offset:1024
	ds_read_b128 v[122:125], v126 offset:2048
	ds_read_b128 v[126:129], v126 offset:3072
	ds_read_b128 v[146:149], v158
	ds_read_b128 v[150:153], v158 offset:1024
	ds_read_b128 v[154:157], v158 offset:2048
	ds_read_b128 v[158:161], v158 offset:3072
	s_add_u32 s72, s96, 0x40000
	s_addc_u32 s73, s97, 0
	s_mov_b32 m0, s30
	v_lshl_add_u64 v[246:247], s[72:73], 0, v[172:173]
	ds_read_b128 v[162:165], v214 offset:32768
	ds_read_b128 v[166:169], v214 offset:33792
	ds_read_b128 v[216:219], v214 offset:34816
	ds_read_b128 v[220:223], v214 offset:35840
	ds_read_b128 v[224:227], v214 offset:36864
	ds_read_b128 v[228:231], v214 offset:37888
	ds_read_b128 v[232:235], v214 offset:38912
	ds_read_b128 v[236:239], v214 offset:39936
	global_load_lds_dwordx4 v[246:247], off
	v_lshl_add_u64 v[246:247], s[72:73], 0, v[176:177]
	s_mov_b32 m0, s31
	s_nop 0
	global_load_lds_dwordx4 v[246:247], off
	s_waitcnt vmcnt(8)
	s_waitcnt lgkmcnt(0)
	s_setprio 1
	s_barrier
	v_mfma_f32_16x16x32_bf16 v[142:145], v[114:117], v[162:165], v[142:145]
	v_mfma_f32_16x16x32_bf16 v[138:141], v[122:125], v[162:165], v[138:141]
	v_mfma_f32_16x16x32_bf16 v[110:113], v[114:117], v[216:219], v[110:113]
	v_mfma_f32_16x16x32_bf16 v[106:109], v[122:125], v[216:219], v[106:109]
	v_mfma_f32_16x16x32_bf16 v[98:101], v[114:117], v[224:227], v[98:101]
	v_mfma_f32_16x16x32_bf16 v[90:93], v[122:125], v[224:227], v[90:93]
	v_mfma_f32_16x16x32_bf16 v[82:85], v[114:117], v[232:235], v[82:85]
	v_mfma_f32_16x16x32_bf16 v[74:77], v[122:125], v[232:235], v[74:77]
	v_mfma_f32_16x16x32_bf16 v[142:145], v[118:121], v[166:169], v[142:145]
	v_mfma_f32_16x16x32_bf16 v[138:141], v[126:129], v[166:169], v[138:141]
	v_mfma_f32_16x16x32_bf16 v[110:113], v[118:121], v[220:223], v[110:113]
	v_mfma_f32_16x16x32_bf16 v[106:109], v[126:129], v[220:223], v[106:109]
	v_mfma_f32_16x16x32_bf16 v[98:101], v[118:121], v[228:231], v[98:101]
	v_mfma_f32_16x16x32_bf16 v[90:93], v[126:129], v[228:231], v[90:93]
	v_mfma_f32_16x16x32_bf16 v[82:85], v[118:121], v[236:239], v[82:85]
	v_mfma_f32_16x16x32_bf16 v[74:77], v[126:129], v[236:239], v[74:77]
	v_mfma_f32_16x16x32_bf16 v[134:137], v[146:149], v[162:165], v[134:137]
	v_mfma_f32_16x16x32_bf16 v[130:133], v[154:157], v[162:165], v[130:133]
	v_mfma_f32_16x16x32_bf16 v[102:105], v[146:149], v[216:219], v[102:105]
	v_mfma_f32_16x16x32_bf16 v[94:97], v[154:157], v[216:219], v[94:97]
	v_mfma_f32_16x16x32_bf16 v[86:89], v[146:149], v[224:227], v[86:89]
	v_mfma_f32_16x16x32_bf16 v[78:81], v[154:157], v[224:227], v[78:81]
	v_mfma_f32_16x16x32_bf16 v[70:73], v[146:149], v[232:235], v[70:73]
	v_mfma_f32_16x16x32_bf16 v[66:69], v[154:157], v[232:235], v[66:69]
	v_mfma_f32_16x16x32_bf16 v[134:137], v[150:153], v[166:169], v[134:137]
	v_mfma_f32_16x16x32_bf16 v[130:133], v[158:161], v[166:169], v[130:133]
	v_mfma_f32_16x16x32_bf16 v[102:105], v[150:153], v[220:223], v[102:105]
	v_mfma_f32_16x16x32_bf16 v[94:97], v[158:161], v[220:223], v[94:97]
	v_mfma_f32_16x16x32_bf16 v[86:89], v[150:153], v[228:231], v[86:89]
	v_mfma_f32_16x16x32_bf16 v[78:81], v[158:161], v[228:231], v[78:81]
	v_mfma_f32_16x16x32_bf16 v[70:73], v[150:153], v[236:239], v[70:73]
	v_mfma_f32_16x16x32_bf16 v[66:69], v[158:161], v[236:239], v[66:69]
	s_setprio 0
	s_barrier
	s_add_i32 s62, s62, s17
	v_lshl_add_u64 v[202:203], v[202:203], 0, s[76:77]
	s_mov_b32 m0, s62
	ds_read_b128 v[162:165], v214 offset:49152
	ds_read_b128 v[166:169], v214 offset:50176
	ds_read_b128 v[216:219], v214 offset:51200
	ds_read_b128 v[220:223], v214 offset:52224
	ds_read_b128 v[224:227], v214 offset:53248
	ds_read_b128 v[228:231], v214 offset:54272
	ds_read_b128 v[232:235], v214 offset:55296
	ds_read_b128 v[236:239], v214 offset:56320
	global_load_lds_dwordx4 v[202:203], off
	s_add_i32 m0, s62, 0x2000
	s_add_u32 s72, s94, 0x40080
	v_lshl_add_u64 v[202:203], v[240:241], 0, s[76:77]
	s_addc_u32 s73, s95, 0
	s_add_i32 s62, s63, s17
	global_load_lds_dwordx4 v[202:203], off
	v_lshl_add_u64 v[202:203], s[72:73], 0, v[174:175]
	s_mov_b32 m0, s62
	s_nop 0
	global_load_lds_dwordx4 v[202:203], off
	v_lshl_add_u64 v[202:203], s[72:73], 0, v[178:179]
	s_add_i32 m0, s62, 0x2000
	s_nop 0
	global_load_lds_dwordx4 v[202:203], off
	v_lshl_add_u64 v[202:203], v[242:243], 0, s[76:77]
	s_mov_b32 m0, s44
	s_nop 0
	global_load_lds_dwordx4 v[202:203], off
	v_lshl_add_u64 v[202:203], v[244:245], 0, s[76:77]
	s_mov_b32 m0, s36
	s_nop 0
	global_load_lds_dwordx4 v[202:203], off
	s_waitcnt vmcnt(8)
	s_waitcnt lgkmcnt(0)
	s_setprio 1
	s_barrier
	v_mfma_f32_16x16x32_bf16 v[62:65], v[114:117], v[162:165], v[62:65]
	v_mfma_f32_16x16x32_bf16 v[58:61], v[122:125], v[162:165], v[58:61]
	v_mfma_f32_16x16x32_bf16 v[50:53], v[114:117], v[216:219], v[50:53]
	v_mfma_f32_16x16x32_bf16 v[42:45], v[122:125], v[216:219], v[42:45]
	v_mfma_f32_16x16x32_bf16 v[34:37], v[114:117], v[224:227], v[34:37]
	v_mfma_f32_16x16x32_bf16 v[26:29], v[122:125], v[224:227], v[26:29]
	v_mfma_f32_16x16x32_bf16 v[18:21], v[114:117], v[232:235], v[18:21]
	v_mfma_f32_16x16x32_bf16 v[10:13], v[122:125], v[232:235], v[10:13]
	v_mfma_f32_16x16x32_bf16 v[62:65], v[118:121], v[166:169], v[62:65]
	v_mfma_f32_16x16x32_bf16 v[58:61], v[126:129], v[166:169], v[58:61]
	v_mfma_f32_16x16x32_bf16 v[50:53], v[118:121], v[220:223], v[50:53]
	v_mfma_f32_16x16x32_bf16 v[42:45], v[126:129], v[220:223], v[42:45]
	v_mfma_f32_16x16x32_bf16 v[34:37], v[118:121], v[228:231], v[34:37]
	v_mfma_f32_16x16x32_bf16 v[26:29], v[126:129], v[228:231], v[26:29]
	v_mfma_f32_16x16x32_bf16 v[18:21], v[118:121], v[236:239], v[18:21]
	v_mfma_f32_16x16x32_bf16 v[10:13], v[126:129], v[236:239], v[10:13]
	v_mfma_f32_16x16x32_bf16 v[54:57], v[146:149], v[162:165], v[54:57]
	v_mfma_f32_16x16x32_bf16 v[46:49], v[154:157], v[162:165], v[46:49]
	v_mfma_f32_16x16x32_bf16 v[38:41], v[146:149], v[216:219], v[38:41]
	v_mfma_f32_16x16x32_bf16 v[30:33], v[154:157], v[216:219], v[30:33]
	v_mfma_f32_16x16x32_bf16 v[22:25], v[146:149], v[224:227], v[22:25]
	v_mfma_f32_16x16x32_bf16 v[14:17], v[154:157], v[224:227], v[14:17]
	v_mfma_f32_16x16x32_bf16 v[6:9], v[146:149], v[232:235], v[6:9]
	v_mfma_f32_16x16x32_bf16 v[2:5], v[154:157], v[232:235], v[2:5]
	v_mfma_f32_16x16x32_bf16 v[54:57], v[150:153], v[166:169], v[54:57]
	v_mfma_f32_16x16x32_bf16 v[46:49], v[158:161], v[166:169], v[46:49]
	v_mfma_f32_16x16x32_bf16 v[38:41], v[150:153], v[220:223], v[38:41]
	v_mfma_f32_16x16x32_bf16 v[30:33], v[158:161], v[220:223], v[30:33]
	v_mfma_f32_16x16x32_bf16 v[22:25], v[150:153], v[228:231], v[22:25]
	v_mfma_f32_16x16x32_bf16 v[14:17], v[158:161], v[228:231], v[14:17]
	v_mfma_f32_16x16x32_bf16 v[6:9], v[150:153], v[236:239], v[6:9]
	v_mfma_f32_16x16x32_bf16 v[2:5], v[158:161], v[236:239], v[2:5]
	s_setprio 0
	s_barrier
	s_add_u32 s10, s10, 0x100
	s_addc_u32 s11, s11, 0
	s_add_u32 vcc_lo, vcc_lo, 0x100
	s_addc_u32 vcc_hi, vcc_hi, 0
	s_cmp_ge_i32 s66, s18
	s_mov_b32 s94, s66
	s_cbranch_scc0 .LBB0_1428
	s_and_b64 vcc, exec, s[82:83]
	s_cbranch_vccz .LBB0_1431
	s_barrier

.LBB0_1618:
	s_add_u32 s24, s96, s20
	s_addc_u32 s25, s97, s21
	s_and_b64 s[14:15], s[4:5], exec
	s_cselect_b32 s14, s25, s29
	s_cselect_b32 s15, s24, s28
	s_add_u32 s26, s2, s22
	s_addc_u32 s27, s3, s23
	s_and_b64 s[36:37], s[4:5], exec
	s_cselect_b32 s17, s27, s31
	s_cselect_b32 s49, s26, s30
	s_add_u32 s28, s28, 0x40080
	s_addc_u32 s29, s29, 0
	s_add_u32 s50, s30, 0x100
	s_addc_u32 s51, s31, 0
	s_mov_b32 s62, -2
	ds_read_b128 v[154:157], v150
	ds_read_b128 v[158:161], v150 offset:1024
	ds_read_b128 v[162:165], v150 offset:2048
	ds_read_b128 v[166:169], v150 offset:3072
	ds_read_b128 v[170:173], v151
	ds_read_b128 v[174:177], v151 offset:1024
	ds_read_b128 v[178:181], v151 offset:2048
	ds_read_b128 v[182:185], v151 offset:3072
	s_add_u32 s30, s28, 0xfffc0080
	s_addc_u32 s31, s29, -1
	s_cmp_eq_u32 s62, 12
	s_cselect_b32 s37, s14, s31
	s_cselect_b32 s36, s15, s30
	s_cselect_b32 s31, s17, s51
	s_cselect_b32 s30, s49, s50
	v_lshl_add_u64 v[146:147], s[28:29], 0, v[138:139]
	s_add_i32 m0, s19, 0xc000
	ds_read_b128 v[186:189], v152
	ds_read_b128 v[190:193], v152 offset:1024
	ds_read_b128 v[194:197], v152 offset:2048
	ds_read_b128 v[198:201], v152 offset:3072
	ds_read_b128 v[206:209], v152 offset:4096
	ds_read_b128 v[210:213], v152 offset:5120
	ds_read_b128 v[214:217], v152 offset:6144
	ds_read_b128 v[218:221], v152 offset:7168
	global_load_lds_dwordx4 v[146:147], off
	v_lshl_add_u64 v[146:147], s[28:29], 0, v[140:141]
	s_add_i32 m0, s19, 0xe000
	s_nop 0
	global_load_lds_dwordx4 v[146:147], off
	s_waitcnt vmcnt(8)
	s_waitcnt lgkmcnt(0)
	s_setprio 1
	s_barrier
	v_mfma_f32_16x16x32_bf16 v[126:129], v[154:157], v[186:189], 0
	v_mfma_f32_16x16x32_bf16 v[122:125], v[162:165], v[186:189], 0
	v_mfma_f32_16x16x32_bf16 v[110:113], v[154:157], v[194:197], 0
	v_mfma_f32_16x16x32_bf16 v[106:109], v[162:165], v[194:197], 0
	v_mfma_f32_16x16x32_bf16 v[94:97], v[154:157], v[206:209], 0
	v_mfma_f32_16x16x32_bf16 v[90:93], v[162:165], v[206:209], 0
	v_mfma_f32_16x16x32_bf16 v[78:81], v[154:157], v[214:217], 0
	v_mfma_f32_16x16x32_bf16 v[74:77], v[162:165], v[214:217], 0
	v_mfma_f32_16x16x32_bf16 v[126:129], v[158:161], v[190:193], v[126:129]
	v_mfma_f32_16x16x32_bf16 v[122:125], v[166:169], v[190:193], v[122:125]
	v_mfma_f32_16x16x32_bf16 v[110:113], v[158:161], v[198:201], v[110:113]
	v_mfma_f32_16x16x32_bf16 v[106:109], v[166:169], v[198:201], v[106:109]
	v_mfma_f32_16x16x32_bf16 v[94:97], v[158:161], v[210:213], v[94:97]
	v_mfma_f32_16x16x32_bf16 v[90:93], v[166:169], v[210:213], v[90:93]
	v_mfma_f32_16x16x32_bf16 v[78:81], v[158:161], v[218:221], v[78:81]
	v_mfma_f32_16x16x32_bf16 v[74:77], v[166:169], v[218:221], v[74:77]
	v_mfma_f32_16x16x32_bf16 v[118:121], v[170:173], v[186:189], 0
	v_mfma_f32_16x16x32_bf16 v[114:117], v[178:181], v[186:189], 0
	v_mfma_f32_16x16x32_bf16 v[102:105], v[170:173], v[194:197], 0
	v_mfma_f32_16x16x32_bf16 v[98:101], v[178:181], v[194:197], 0
	v_mfma_f32_16x16x32_bf16 v[86:89], v[170:173], v[206:209], 0
	v_mfma_f32_16x16x32_bf16 v[82:85], v[178:181], v[206:209], 0
	v_mfma_f32_16x16x32_bf16 v[70:73], v[170:173], v[214:217], 0
	v_mfma_f32_16x16x32_bf16 v[66:69], v[178:181], v[214:217], 0
	v_mfma_f32_16x16x32_bf16 v[118:121], v[174:177], v[190:193], v[118:121]
	v_mfma_f32_16x16x32_bf16 v[114:117], v[182:185], v[190:193], v[114:117]
	v_mfma_f32_16x16x32_bf16 v[102:105], v[174:177], v[198:201], v[102:105]
	v_mfma_f32_16x16x32_bf16 v[98:101], v[182:185], v[198:201], v[98:101]
	v_mfma_f32_16x16x32_bf16 v[86:89], v[174:177], v[210:213], v[86:89]
	v_mfma_f32_16x16x32_bf16 v[82:85], v[182:185], v[210:213], v[82:85]
	v_mfma_f32_16x16x32_bf16 v[70:73], v[174:177], v[218:221], v[70:73]
	v_mfma_f32_16x16x32_bf16 v[66:69], v[182:185], v[218:221], v[66:69]
	s_setprio 0
	s_barrier
	s_add_i32 s63, s45, s12
	v_lshl_add_u64 v[146:147], s[30:31], 0, v[134:135]
	s_mov_b32 m0, s63
	ds_read_b128 v[186:189], v152 offset:16384
	ds_read_b128 v[190:193], v152 offset:17408
	ds_read_b128 v[194:197], v152 offset:18432
	ds_read_b128 v[198:201], v152 offset:19456
	ds_read_b128 v[206:209], v152 offset:20480
	ds_read_b128 v[210:213], v152 offset:21504
	ds_read_b128 v[214:217], v152 offset:22528
	ds_read_b128 v[218:221], v152 offset:23552
	global_load_lds_dwordx4 v[146:147], off
	s_add_i32 m0, s63, 0x2000
	s_add_u32 s64, s30, 0x40000
	v_lshl_add_u64 v[202:203], s[30:31], 0, v[130:131]
	s_addc_u32 s65, s31, 0
	s_add_i32 s63, s46, s12
	global_load_lds_dwordx4 v[202:203], off
	v_lshl_add_u64 v[222:223], s[64:65], 0, v[134:135]
	s_mov_b32 m0, s63
	v_lshl_add_u64 v[224:225], s[36:37], 0, v[132:133]
	global_load_lds_dwordx4 v[222:223], off
	v_lshl_add_u64 v[222:223], s[64:65], 0, v[130:131]
	s_add_i32 m0, s63, 0x2000
	s_nop 0
	global_load_lds_dwordx4 v[222:223], off
	v_lshl_add_u64 v[222:223], s[36:37], 0, v[136:137]
	s_mov_b32 m0, s19
	s_nop 0
	global_load_lds_dwordx4 v[222:223], off
	s_mov_b32 m0, s33
	s_nop 0
	global_load_lds_dwordx4 v[224:225], off
	s_waitcnt vmcnt(8)
	s_waitcnt lgkmcnt(0)
	s_setprio 1
	s_barrier
	v_mfma_f32_16x16x32_bf16 v[62:65], v[154:157], v[186:189], 0
	v_mfma_f32_16x16x32_bf16 v[58:61], v[162:165], v[186:189], 0
	v_mfma_f32_16x16x32_bf16 v[46:49], v[154:157], v[194:197], 0
	v_mfma_f32_16x16x32_bf16 v[42:45], v[162:165], v[194:197], 0
	v_mfma_f32_16x16x32_bf16 v[30:33], v[154:157], v[206:209], 0
	v_mfma_f32_16x16x32_bf16 v[26:29], v[162:165], v[206:209], 0
	v_mfma_f32_16x16x32_bf16 v[14:17], v[154:157], v[214:217], 0
	v_mfma_f32_16x16x32_bf16 v[10:13], v[162:165], v[214:217], 0
	v_mfma_f32_16x16x32_bf16 v[62:65], v[158:161], v[190:193], v[62:65]
	v_mfma_f32_16x16x32_bf16 v[58:61], v[166:169], v[190:193], v[58:61]
	v_mfma_f32_16x16x32_bf16 v[46:49], v[158:161], v[198:201], v[46:49]
	v_mfma_f32_16x16x32_bf16 v[42:45], v[166:169], v[198:201], v[42:45]
	v_mfma_f32_16x16x32_bf16 v[30:33], v[158:161], v[210:213], v[30:33]
	v_mfma_f32_16x16x32_bf16 v[26:29], v[166:169], v[210:213], v[26:29]
	v_mfma_f32_16x16x32_bf16 v[14:17], v[158:161], v[218:221], v[14:17]
	v_mfma_f32_16x16x32_bf16 v[10:13], v[166:169], v[218:221], v[10:13]
	v_mfma_f32_16x16x32_bf16 v[54:57], v[170:173], v[186:189], 0
	v_mfma_f32_16x16x32_bf16 v[50:53], v[178:181], v[186:189], 0
	v_mfma_f32_16x16x32_bf16 v[38:41], v[170:173], v[194:197], 0
	v_mfma_f32_16x16x32_bf16 v[34:37], v[178:181], v[194:197], 0
	v_mfma_f32_16x16x32_bf16 v[22:25], v[170:173], v[206:209], 0
	v_mfma_f32_16x16x32_bf16 v[18:21], v[178:181], v[206:209], 0
	v_mfma_f32_16x16x32_bf16 v[6:9], v[170:173], v[214:217], 0
	v_mfma_f32_16x16x32_bf16 v[2:5], v[178:181], v[214:217], 0
	v_mfma_f32_16x16x32_bf16 v[54:57], v[174:177], v[190:193], v[54:57]
	v_mfma_f32_16x16x32_bf16 v[50:53], v[182:185], v[190:193], v[50:53]
	v_mfma_f32_16x16x32_bf16 v[38:41], v[174:177], v[198:201], v[38:41]
	v_mfma_f32_16x16x32_bf16 v[34:37], v[182:185], v[198:201], v[34:37]
	v_mfma_f32_16x16x32_bf16 v[22:25], v[174:177], v[210:213], v[22:25]
	v_mfma_f32_16x16x32_bf16 v[18:21], v[182:185], v[210:213], v[18:21]
	v_mfma_f32_16x16x32_bf16 v[6:9], v[174:177], v[218:221], v[6:9]
	v_mfma_f32_16x16x32_bf16 v[2:5], v[182:185], v[218:221], v[2:5]
	s_setprio 0
	s_barrier
	s_add_i32 s63, 0, 0x18000
	v_add_u32_e32 v153, s63, v149
	s_add_i32 s64, 0, 0x1c000
	ds_read_b128 v[154:157], v153
	ds_read_b128 v[158:161], v153 offset:1024
	ds_read_b128 v[162:165], v153 offset:2048
	ds_read_b128 v[166:169], v153 offset:3072
	v_add_u32_e32 v153, s64, v149
	ds_read_b128 v[170:173], v153
	ds_read_b128 v[174:177], v153 offset:1024
	ds_read_b128 v[178:181], v153 offset:2048
	ds_read_b128 v[182:185], v153 offset:3072
	s_add_u32 s36, s36, 0x40000
	s_addc_u32 s37, s37, 0
	s_mov_b32 m0, s35
	v_lshl_add_u64 v[226:227], s[36:37], 0, v[136:137]
	ds_read_b128 v[186:189], v152 offset:32768
	ds_read_b128 v[190:193], v152 offset:33792
	ds_read_b128 v[194:197], v152 offset:34816
	ds_read_b128 v[198:201], v152 offset:35840
	ds_read_b128 v[206:209], v152 offset:36864
	ds_read_b128 v[210:213], v152 offset:37888
	ds_read_b128 v[214:217], v152 offset:38912
	ds_read_b128 v[218:221], v152 offset:39936
	global_load_lds_dwordx4 v[226:227], off
	v_lshl_add_u64 v[226:227], s[36:37], 0, v[132:133]
	s_mov_b32 m0, s38
	s_nop 0
	global_load_lds_dwordx4 v[226:227], off
	s_waitcnt vmcnt(8)
	s_waitcnt lgkmcnt(0)
	s_setprio 1
	s_barrier
	v_mfma_f32_16x16x32_bf16 v[126:129], v[154:157], v[186:189], v[126:129]
	v_mfma_f32_16x16x32_bf16 v[122:125], v[162:165], v[186:189], v[122:125]
	v_mfma_f32_16x16x32_bf16 v[110:113], v[154:157], v[194:197], v[110:113]
	v_mfma_f32_16x16x32_bf16 v[106:109], v[162:165], v[194:197], v[106:109]
	v_mfma_f32_16x16x32_bf16 v[94:97], v[154:157], v[206:209], v[94:97]
	v_mfma_f32_16x16x32_bf16 v[90:93], v[162:165], v[206:209], v[90:93]
	v_mfma_f32_16x16x32_bf16 v[78:81], v[154:157], v[214:217], v[78:81]
	v_mfma_f32_16x16x32_bf16 v[74:77], v[162:165], v[214:217], v[74:77]
	v_mfma_f32_16x16x32_bf16 v[126:129], v[158:161], v[190:193], v[126:129]
	v_mfma_f32_16x16x32_bf16 v[122:125], v[166:169], v[190:193], v[122:125]
	v_mfma_f32_16x16x32_bf16 v[110:113], v[158:161], v[198:201], v[110:113]
	v_mfma_f32_16x16x32_bf16 v[106:109], v[166:169], v[198:201], v[106:109]
	v_mfma_f32_16x16x32_bf16 v[94:97], v[158:161], v[210:213], v[94:97]
	v_mfma_f32_16x16x32_bf16 v[90:93], v[166:169], v[210:213], v[90:93]
	v_mfma_f32_16x16x32_bf16 v[78:81], v[158:161], v[218:221], v[78:81]
	v_mfma_f32_16x16x32_bf16 v[74:77], v[166:169], v[218:221], v[74:77]
	v_mfma_f32_16x16x32_bf16 v[118:121], v[170:173], v[186:189], v[118:121]
	v_mfma_f32_16x16x32_bf16 v[114:117], v[178:181], v[186:189], v[114:117]
	v_mfma_f32_16x16x32_bf16 v[102:105], v[170:173], v[194:197], v[102:105]
	v_mfma_f32_16x16x32_bf16 v[98:101], v[178:181], v[194:197], v[98:101]
	v_mfma_f32_16x16x32_bf16 v[86:89], v[170:173], v[206:209], v[86:89]
	v_mfma_f32_16x16x32_bf16 v[82:85], v[178:181], v[206:209], v[82:85]
	v_mfma_f32_16x16x32_bf16 v[70:73], v[170:173], v[214:217], v[70:73]
	v_mfma_f32_16x16x32_bf16 v[66:69], v[178:181], v[214:217], v[66:69]
	v_mfma_f32_16x16x32_bf16 v[118:121], v[174:177], v[190:193], v[118:121]
	v_mfma_f32_16x16x32_bf16 v[114:117], v[182:185], v[190:193], v[114:117]
	v_mfma_f32_16x16x32_bf16 v[102:105], v[174:177], v[198:201], v[102:105]
	v_mfma_f32_16x16x32_bf16 v[98:101], v[182:185], v[198:201], v[98:101]
	v_mfma_f32_16x16x32_bf16 v[86:89], v[174:177], v[210:213], v[86:89]
	v_mfma_f32_16x16x32_bf16 v[82:85], v[182:185], v[210:213], v[82:85]
	v_mfma_f32_16x16x32_bf16 v[70:73], v[174:177], v[218:221], v[70:73]
	v_mfma_f32_16x16x32_bf16 v[66:69], v[182:185], v[218:221], v[66:69]
	s_setprio 0
	s_barrier
	s_add_i32 s36, s63, s12
	v_lshl_add_u64 v[146:147], v[146:147], 0, s[8:9]
	s_mov_b32 m0, s36
	ds_read_b128 v[186:189], v152 offset:49152
	ds_read_b128 v[190:193], v152 offset:50176
	ds_read_b128 v[194:197], v152 offset:51200
	ds_read_b128 v[198:201], v152 offset:52224
	ds_read_b128 v[206:209], v152 offset:53248
	ds_read_b128 v[210:213], v152 offset:54272
	ds_read_b128 v[214:217], v152 offset:55296
	ds_read_b128 v[218:221], v152 offset:56320
	global_load_lds_dwordx4 v[146:147], off
	s_add_i32 m0, s36, 0x2000
	s_add_u32 s30, s30, 0x40080
	v_lshl_add_u64 v[146:147], v[202:203], 0, s[8:9]
	s_addc_u32 s31, s31, 0
	s_add_i32 s36, s64, s12
	global_load_lds_dwordx4 v[146:147], off
	v_lshl_add_u64 v[146:147], s[30:31], 0, v[134:135]
	s_mov_b32 m0, s36
	s_nop 0
	global_load_lds_dwordx4 v[146:147], off
	v_lshl_add_u64 v[146:147], s[30:31], 0, v[130:131]
	s_add_i32 m0, s36, 0x2000
	s_nop 0
	global_load_lds_dwordx4 v[146:147], off
	v_lshl_add_u64 v[146:147], v[222:223], 0, s[8:9]
	s_mov_b32 m0, s42
	s_nop 0
	global_load_lds_dwordx4 v[146:147], off
	v_lshl_add_u64 v[146:147], v[224:225], 0, s[8:9]
	s_mov_b32 m0, s43
	s_nop 0
	global_load_lds_dwordx4 v[146:147], off
	s_waitcnt vmcnt(8)
	s_waitcnt lgkmcnt(0)
	s_setprio 1
	s_barrier
	v_mfma_f32_16x16x32_bf16 v[62:65], v[154:157], v[186:189], v[62:65]
	v_mfma_f32_16x16x32_bf16 v[58:61], v[162:165], v[186:189], v[58:61]
	v_mfma_f32_16x16x32_bf16 v[46:49], v[154:157], v[194:197], v[46:49]
	v_mfma_f32_16x16x32_bf16 v[42:45], v[162:165], v[194:197], v[42:45]
	v_mfma_f32_16x16x32_bf16 v[30:33], v[154:157], v[206:209], v[30:33]
	v_mfma_f32_16x16x32_bf16 v[26:29], v[162:165], v[206:209], v[26:29]
	v_mfma_f32_16x16x32_bf16 v[14:17], v[154:157], v[214:217], v[14:17]
	v_mfma_f32_16x16x32_bf16 v[10:13], v[162:165], v[214:217], v[10:13]
	v_mfma_f32_16x16x32_bf16 v[62:65], v[158:161], v[190:193], v[62:65]
	v_mfma_f32_16x16x32_bf16 v[58:61], v[166:169], v[190:193], v[58:61]
	v_mfma_f32_16x16x32_bf16 v[46:49], v[158:161], v[198:201], v[46:49]
	v_mfma_f32_16x16x32_bf16 v[42:45], v[166:169], v[198:201], v[42:45]
	v_mfma_f32_16x16x32_bf16 v[30:33], v[158:161], v[210:213], v[30:33]
	v_mfma_f32_16x16x32_bf16 v[26:29], v[166:169], v[210:213], v[26:29]
	v_mfma_f32_16x16x32_bf16 v[14:17], v[158:161], v[218:221], v[14:17]
	v_mfma_f32_16x16x32_bf16 v[10:13], v[166:169], v[218:221], v[10:13]
	v_mfma_f32_16x16x32_bf16 v[54:57], v[170:173], v[186:189], v[54:57]
	v_mfma_f32_16x16x32_bf16 v[50:53], v[178:181], v[186:189], v[50:53]
	v_mfma_f32_16x16x32_bf16 v[38:41], v[170:173], v[194:197], v[38:41]
	v_mfma_f32_16x16x32_bf16 v[34:37], v[178:181], v[194:197], v[34:37]
	v_mfma_f32_16x16x32_bf16 v[22:25], v[170:173], v[206:209], v[22:25]
	v_mfma_f32_16x16x32_bf16 v[18:21], v[178:181], v[206:209], v[18:21]
	v_mfma_f32_16x16x32_bf16 v[6:9], v[170:173], v[214:217], v[6:9]
	v_mfma_f32_16x16x32_bf16 v[2:5], v[178:181], v[214:217], v[2:5]
	v_mfma_f32_16x16x32_bf16 v[54:57], v[174:177], v[190:193], v[54:57]
	v_mfma_f32_16x16x32_bf16 v[50:53], v[182:185], v[190:193], v[50:53]
	v_mfma_f32_16x16x32_bf16 v[38:41], v[174:177], v[198:201], v[38:41]
	v_mfma_f32_16x16x32_bf16 v[34:37], v[182:185], v[198:201], v[34:37]
	v_mfma_f32_16x16x32_bf16 v[22:25], v[174:177], v[210:213], v[22:25]
	v_mfma_f32_16x16x32_bf16 v[18:21], v[182:185], v[210:213], v[18:21]
	v_mfma_f32_16x16x32_bf16 v[6:9], v[174:177], v[218:221], v[6:9]
	v_mfma_f32_16x16x32_bf16 v[2:5], v[182:185], v[218:221], v[2:5]
	s_setprio 0
	s_barrier
	s_add_i32 s62, s62, 2
	s_add_u32 s28, s28, 0x100
	s_addc_u32 s29, s29, 0
	s_add_u32 s50, s50, 0x100
	s_addc_u32 s51, s51, 0
	s_cmp_gt_u32 s62, 13
.LBB0_1619:
	ds_read_b128 v[154:157], v150
	ds_read_b128 v[158:161], v150 offset:1024
	ds_read_b128 v[162:165], v150 offset:2048
	ds_read_b128 v[166:169], v150 offset:3072
	ds_read_b128 v[170:173], v151
	ds_read_b128 v[174:177], v151 offset:1024
	ds_read_b128 v[178:181], v151 offset:2048
	ds_read_b128 v[182:185], v151 offset:3072
	s_add_u32 s30, s28, 0xfffc0080
	s_addc_u32 s31, s29, -1
	s_cmp_eq_u32 s62, 12
	s_cselect_b32 s37, s14, s31
	s_cselect_b32 s36, s15, s30
	s_cselect_b32 s31, s17, s51
	s_cselect_b32 s30, s49, s50
	v_lshl_add_u64 v[146:147], s[28:29], 0, v[138:139]
	s_add_i32 m0, s19, 0xc000
	ds_read_b128 v[186:189], v152
	ds_read_b128 v[190:193], v152 offset:1024
	ds_read_b128 v[194:197], v152 offset:2048
	ds_read_b128 v[198:201], v152 offset:3072
	ds_read_b128 v[206:209], v152 offset:4096
	ds_read_b128 v[210:213], v152 offset:5120
	ds_read_b128 v[214:217], v152 offset:6144
	ds_read_b128 v[218:221], v152 offset:7168
	global_load_lds_dwordx4 v[146:147], off
	v_lshl_add_u64 v[146:147], s[28:29], 0, v[140:141]
	s_add_i32 m0, s19, 0xe000
	s_nop 0
	global_load_lds_dwordx4 v[146:147], off
	s_waitcnt vmcnt(8)
	s_waitcnt lgkmcnt(0)
	s_setprio 1
	s_barrier
	v_mfma_f32_16x16x32_bf16 v[126:129], v[154:157], v[186:189], v[126:129]
	v_mfma_f32_16x16x32_bf16 v[122:125], v[162:165], v[186:189], v[122:125]
	v_mfma_f32_16x16x32_bf16 v[110:113], v[154:157], v[194:197], v[110:113]
	v_mfma_f32_16x16x32_bf16 v[106:109], v[162:165], v[194:197], v[106:109]
	v_mfma_f32_16x16x32_bf16 v[94:97], v[154:157], v[206:209], v[94:97]
	v_mfma_f32_16x16x32_bf16 v[90:93], v[162:165], v[206:209], v[90:93]
	v_mfma_f32_16x16x32_bf16 v[78:81], v[154:157], v[214:217], v[78:81]
	v_mfma_f32_16x16x32_bf16 v[74:77], v[162:165], v[214:217], v[74:77]
	v_mfma_f32_16x16x32_bf16 v[126:129], v[158:161], v[190:193], v[126:129]
	v_mfma_f32_16x16x32_bf16 v[122:125], v[166:169], v[190:193], v[122:125]
	v_mfma_f32_16x16x32_bf16 v[110:113], v[158:161], v[198:201], v[110:113]
	v_mfma_f32_16x16x32_bf16 v[106:109], v[166:169], v[198:201], v[106:109]
	v_mfma_f32_16x16x32_bf16 v[94:97], v[158:161], v[210:213], v[94:97]
	v_mfma_f32_16x16x32_bf16 v[90:93], v[166:169], v[210:213], v[90:93]
	v_mfma_f32_16x16x32_bf16 v[78:81], v[158:161], v[218:221], v[78:81]
	v_mfma_f32_16x16x32_bf16 v[74:77], v[166:169], v[218:221], v[74:77]
	v_mfma_f32_16x16x32_bf16 v[118:121], v[170:173], v[186:189], v[118:121]
	v_mfma_f32_16x16x32_bf16 v[114:117], v[178:181], v[186:189], v[114:117]
	v_mfma_f32_16x16x32_bf16 v[102:105], v[170:173], v[194:197], v[102:105]
	v_mfma_f32_16x16x32_bf16 v[98:101], v[178:181], v[194:197], v[98:101]
	v_mfma_f32_16x16x32_bf16 v[86:89], v[170:173], v[206:209], v[86:89]
	v_mfma_f32_16x16x32_bf16 v[82:85], v[178:181], v[206:209], v[82:85]
	v_mfma_f32_16x16x32_bf16 v[70:73], v[170:173], v[214:217], v[70:73]
	v_mfma_f32_16x16x32_bf16 v[66:69], v[178:181], v[214:217], v[66:69]
	v_mfma_f32_16x16x32_bf16 v[118:121], v[174:177], v[190:193], v[118:121]
	v_mfma_f32_16x16x32_bf16 v[114:117], v[182:185], v[190:193], v[114:117]
	v_mfma_f32_16x16x32_bf16 v[102:105], v[174:177], v[198:201], v[102:105]
	v_mfma_f32_16x16x32_bf16 v[98:101], v[182:185], v[198:201], v[98:101]
	v_mfma_f32_16x16x32_bf16 v[86:89], v[174:177], v[210:213], v[86:89]
	v_mfma_f32_16x16x32_bf16 v[82:85], v[182:185], v[210:213], v[82:85]
	v_mfma_f32_16x16x32_bf16 v[70:73], v[174:177], v[218:221], v[70:73]
	v_mfma_f32_16x16x32_bf16 v[66:69], v[182:185], v[218:221], v[66:69]
	s_setprio 0
	s_barrier
	s_add_i32 s63, s45, s12
	v_lshl_add_u64 v[146:147], s[30:31], 0, v[134:135]
	s_mov_b32 m0, s63
	ds_read_b128 v[186:189], v152 offset:16384
	ds_read_b128 v[190:193], v152 offset:17408
	ds_read_b128 v[194:197], v152 offset:18432
	ds_read_b128 v[198:201], v152 offset:19456
	ds_read_b128 v[206:209], v152 offset:20480
	ds_read_b128 v[210:213], v152 offset:21504
	ds_read_b128 v[214:217], v152 offset:22528
	ds_read_b128 v[218:221], v152 offset:23552
	global_load_lds_dwordx4 v[146:147], off
	s_add_i32 m0, s63, 0x2000
	s_add_u32 s64, s30, 0x40000
	v_lshl_add_u64 v[202:203], s[30:31], 0, v[130:131]
	s_addc_u32 s65, s31, 0
	s_add_i32 s63, s46, s12
	global_load_lds_dwordx4 v[202:203], off
	v_lshl_add_u64 v[222:223], s[64:65], 0, v[134:135]
	s_mov_b32 m0, s63
	v_lshl_add_u64 v[224:225], s[36:37], 0, v[132:133]
	global_load_lds_dwordx4 v[222:223], off
	v_lshl_add_u64 v[222:223], s[64:65], 0, v[130:131]
	s_add_i32 m0, s63, 0x2000
	s_nop 0
	global_load_lds_dwordx4 v[222:223], off
	v_lshl_add_u64 v[222:223], s[36:37], 0, v[136:137]
	s_mov_b32 m0, s19
	s_nop 0
	global_load_lds_dwordx4 v[222:223], off
	s_mov_b32 m0, s33
	s_nop 0
	global_load_lds_dwordx4 v[224:225], off
	s_waitcnt vmcnt(8)
	s_waitcnt lgkmcnt(0)
	s_setprio 1
	s_barrier
	v_mfma_f32_16x16x32_bf16 v[62:65], v[154:157], v[186:189], v[62:65]
	v_mfma_f32_16x16x32_bf16 v[58:61], v[162:165], v[186:189], v[58:61]
	v_mfma_f32_16x16x32_bf16 v[46:49], v[154:157], v[194:197], v[46:49]
	v_mfma_f32_16x16x32_bf16 v[42:45], v[162:165], v[194:197], v[42:45]
	v_mfma_f32_16x16x32_bf16 v[30:33], v[154:157], v[206:209], v[30:33]
	v_mfma_f32_16x16x32_bf16 v[26:29], v[162:165], v[206:209], v[26:29]
	v_mfma_f32_16x16x32_bf16 v[14:17], v[154:157], v[214:217], v[14:17]
	v_mfma_f32_16x16x32_bf16 v[10:13], v[162:165], v[214:217], v[10:13]
	v_mfma_f32_16x16x32_bf16 v[62:65], v[158:161], v[190:193], v[62:65]
	v_mfma_f32_16x16x32_bf16 v[58:61], v[166:169], v[190:193], v[58:61]
	v_mfma_f32_16x16x32_bf16 v[46:49], v[158:161], v[198:201], v[46:49]
	v_mfma_f32_16x16x32_bf16 v[42:45], v[166:169], v[198:201], v[42:45]
	v_mfma_f32_16x16x32_bf16 v[30:33], v[158:161], v[210:213], v[30:33]
	v_mfma_f32_16x16x32_bf16 v[26:29], v[166:169], v[210:213], v[26:29]
	v_mfma_f32_16x16x32_bf16 v[14:17], v[158:161], v[218:221], v[14:17]
	v_mfma_f32_16x16x32_bf16 v[10:13], v[166:169], v[218:221], v[10:13]
	v_mfma_f32_16x16x32_bf16 v[54:57], v[170:173], v[186:189], v[54:57]
	v_mfma_f32_16x16x32_bf16 v[50:53], v[178:181], v[186:189], v[50:53]
	v_mfma_f32_16x16x32_bf16 v[38:41], v[170:173], v[194:197], v[38:41]
	v_mfma_f32_16x16x32_bf16 v[34:37], v[178:181], v[194:197], v[34:37]
	v_mfma_f32_16x16x32_bf16 v[22:25], v[170:173], v[206:209], v[22:25]
	v_mfma_f32_16x16x32_bf16 v[18:21], v[178:181], v[206:209], v[18:21]
	v_mfma_f32_16x16x32_bf16 v[6:9], v[170:173], v[214:217], v[6:9]
	v_mfma_f32_16x16x32_bf16 v[2:5], v[178:181], v[214:217], v[2:5]
	v_mfma_f32_16x16x32_bf16 v[54:57], v[174:177], v[190:193], v[54:57]
	v_mfma_f32_16x16x32_bf16 v[50:53], v[182:185], v[190:193], v[50:53]
	v_mfma_f32_16x16x32_bf16 v[38:41], v[174:177], v[198:201], v[38:41]
	v_mfma_f32_16x16x32_bf16 v[34:37], v[182:185], v[198:201], v[34:37]
	v_mfma_f32_16x16x32_bf16 v[22:25], v[174:177], v[210:213], v[22:25]
	v_mfma_f32_16x16x32_bf16 v[18:21], v[182:185], v[210:213], v[18:21]
	v_mfma_f32_16x16x32_bf16 v[6:9], v[174:177], v[218:221], v[6:9]
	v_mfma_f32_16x16x32_bf16 v[2:5], v[182:185], v[218:221], v[2:5]
	s_setprio 0
	s_barrier
	s_add_i32 s63, 0, 0x18000
	v_add_u32_e32 v153, s63, v149
	s_add_i32 s64, 0, 0x1c000
	ds_read_b128 v[154:157], v153
	ds_read_b128 v[158:161], v153 offset:1024
	ds_read_b128 v[162:165], v153 offset:2048
	ds_read_b128 v[166:169], v153 offset:3072
	v_add_u32_e32 v153, s64, v149
	ds_read_b128 v[170:173], v153
	ds_read_b128 v[174:177], v153 offset:1024
	ds_read_b128 v[178:181], v153 offset:2048
	ds_read_b128 v[182:185], v153 offset:3072
	s_add_u32 s36, s36, 0x40000
	s_addc_u32 s37, s37, 0
	s_mov_b32 m0, s35
	v_lshl_add_u64 v[226:227], s[36:37], 0, v[136:137]
	ds_read_b128 v[186:189], v152 offset:32768
	ds_read_b128 v[190:193], v152 offset:33792
	ds_read_b128 v[194:197], v152 offset:34816
	ds_read_b128 v[198:201], v152 offset:35840
	ds_read_b128 v[206:209], v152 offset:36864
	ds_read_b128 v[210:213], v152 offset:37888
	ds_read_b128 v[214:217], v152 offset:38912
	ds_read_b128 v[218:221], v152 offset:39936
	global_load_lds_dwordx4 v[226:227], off
	v_lshl_add_u64 v[226:227], s[36:37], 0, v[132:133]
	s_mov_b32 m0, s38
	s_nop 0
	global_load_lds_dwordx4 v[226:227], off
	s_waitcnt vmcnt(8)
	s_waitcnt lgkmcnt(0)
	s_setprio 1
	s_barrier
	v_mfma_f32_16x16x32_bf16 v[126:129], v[154:157], v[186:189], v[126:129]
	v_mfma_f32_16x16x32_bf16 v[122:125], v[162:165], v[186:189], v[122:125]
	v_mfma_f32_16x16x32_bf16 v[110:113], v[154:157], v[194:197], v[110:113]
	v_mfma_f32_16x16x32_bf16 v[106:109], v[162:165], v[194:197], v[106:109]
	v_mfma_f32_16x16x32_bf16 v[94:97], v[154:157], v[206:209], v[94:97]
	v_mfma_f32_16x16x32_bf16 v[90:93], v[162:165], v[206:209], v[90:93]
	v_mfma_f32_16x16x32_bf16 v[78:81], v[154:157], v[214:217], v[78:81]
	v_mfma_f32_16x16x32_bf16 v[74:77], v[162:165], v[214:217], v[74:77]
	v_mfma_f32_16x16x32_bf16 v[126:129], v[158:161], v[190:193], v[126:129]
	v_mfma_f32_16x16x32_bf16 v[122:125], v[166:169], v[190:193], v[122:125]
	v_mfma_f32_16x16x32_bf16 v[110:113], v[158:161], v[198:201], v[110:113]
	v_mfma_f32_16x16x32_bf16 v[106:109], v[166:169], v[198:201], v[106:109]
	v_mfma_f32_16x16x32_bf16 v[94:97], v[158:161], v[210:213], v[94:97]
	v_mfma_f32_16x16x32_bf16 v[90:93], v[166:169], v[210:213], v[90:93]
	v_mfma_f32_16x16x32_bf16 v[78:81], v[158:161], v[218:221], v[78:81]
	v_mfma_f32_16x16x32_bf16 v[74:77], v[166:169], v[218:221], v[74:77]
	v_mfma_f32_16x16x32_bf16 v[118:121], v[170:173], v[186:189], v[118:121]
	v_mfma_f32_16x16x32_bf16 v[114:117], v[178:181], v[186:189], v[114:117]
	v_mfma_f32_16x16x32_bf16 v[102:105], v[170:173], v[194:197], v[102:105]
	v_mfma_f32_16x16x32_bf16 v[98:101], v[178:181], v[194:197], v[98:101]
	v_mfma_f32_16x16x32_bf16 v[86:89], v[170:173], v[206:209], v[86:89]
	v_mfma_f32_16x16x32_bf16 v[82:85], v[178:181], v[206:209], v[82:85]
	v_mfma_f32_16x16x32_bf16 v[70:73], v[170:173], v[214:217], v[70:73]
	v_mfma_f32_16x16x32_bf16 v[66:69], v[178:181], v[214:217], v[66:69]
	v_mfma_f32_16x16x32_bf16 v[118:121], v[174:177], v[190:193], v[118:121]
	v_mfma_f32_16x16x32_bf16 v[114:117], v[182:185], v[190:193], v[114:117]
	v_mfma_f32_16x16x32_bf16 v[102:105], v[174:177], v[198:201], v[102:105]
	v_mfma_f32_16x16x32_bf16 v[98:101], v[182:185], v[198:201], v[98:101]
	v_mfma_f32_16x16x32_bf16 v[86:89], v[174:177], v[210:213], v[86:89]
	v_mfma_f32_16x16x32_bf16 v[82:85], v[182:185], v[210:213], v[82:85]
	v_mfma_f32_16x16x32_bf16 v[70:73], v[174:177], v[218:221], v[70:73]
	v_mfma_f32_16x16x32_bf16 v[66:69], v[182:185], v[218:221], v[66:69]
	s_setprio 0
	s_barrier
	s_add_i32 s36, s63, s12
	v_lshl_add_u64 v[146:147], v[146:147], 0, s[8:9]
	s_mov_b32 m0, s36
	ds_read_b128 v[186:189], v152 offset:49152
	ds_read_b128 v[190:193], v152 offset:50176
	ds_read_b128 v[194:197], v152 offset:51200
	ds_read_b128 v[198:201], v152 offset:52224
	ds_read_b128 v[206:209], v152 offset:53248
	ds_read_b128 v[210:213], v152 offset:54272
	ds_read_b128 v[214:217], v152 offset:55296
	ds_read_b128 v[218:221], v152 offset:56320
	global_load_lds_dwordx4 v[146:147], off
	s_add_i32 m0, s36, 0x2000
	s_add_u32 s30, s30, 0x40080
	v_lshl_add_u64 v[146:147], v[202:203], 0, s[8:9]
	s_addc_u32 s31, s31, 0
	s_add_i32 s36, s64, s12
	global_load_lds_dwordx4 v[146:147], off
	v_lshl_add_u64 v[146:147], s[30:31], 0, v[134:135]
	s_mov_b32 m0, s36
	s_nop 0
	global_load_lds_dwordx4 v[146:147], off
	v_lshl_add_u64 v[146:147], s[30:31], 0, v[130:131]
	s_add_i32 m0, s36, 0x2000
	s_nop 0
	global_load_lds_dwordx4 v[146:147], off
	v_lshl_add_u64 v[146:147], v[222:223], 0, s[8:9]
	s_mov_b32 m0, s42
	s_nop 0
	global_load_lds_dwordx4 v[146:147], off
	v_lshl_add_u64 v[146:147], v[224:225], 0, s[8:9]
	s_mov_b32 m0, s43
	s_nop 0
	global_load_lds_dwordx4 v[146:147], off
	s_waitcnt vmcnt(8)
	s_waitcnt lgkmcnt(0)
	s_setprio 1
	s_barrier
	v_mfma_f32_16x16x32_bf16 v[62:65], v[154:157], v[186:189], v[62:65]
	v_mfma_f32_16x16x32_bf16 v[58:61], v[162:165], v[186:189], v[58:61]
	v_mfma_f32_16x16x32_bf16 v[46:49], v[154:157], v[194:197], v[46:49]
	v_mfma_f32_16x16x32_bf16 v[42:45], v[162:165], v[194:197], v[42:45]
	v_mfma_f32_16x16x32_bf16 v[30:33], v[154:157], v[206:209], v[30:33]
	v_mfma_f32_16x16x32_bf16 v[26:29], v[162:165], v[206:209], v[26:29]
	v_mfma_f32_16x16x32_bf16 v[14:17], v[154:157], v[214:217], v[14:17]
	v_mfma_f32_16x16x32_bf16 v[10:13], v[162:165], v[214:217], v[10:13]
	v_mfma_f32_16x16x32_bf16 v[62:65], v[158:161], v[190:193], v[62:65]
	v_mfma_f32_16x16x32_bf16 v[58:61], v[166:169], v[190:193], v[58:61]
	v_mfma_f32_16x16x32_bf16 v[46:49], v[158:161], v[198:201], v[46:49]
	v_mfma_f32_16x16x32_bf16 v[42:45], v[166:169], v[198:201], v[42:45]
	v_mfma_f32_16x16x32_bf16 v[30:33], v[158:161], v[210:213], v[30:33]
	v_mfma_f32_16x16x32_bf16 v[26:29], v[166:169], v[210:213], v[26:29]
	v_mfma_f32_16x16x32_bf16 v[14:17], v[158:161], v[218:221], v[14:17]
	v_mfma_f32_16x16x32_bf16 v[10:13], v[166:169], v[218:221], v[10:13]
	v_mfma_f32_16x16x32_bf16 v[54:57], v[170:173], v[186:189], v[54:57]
	v_mfma_f32_16x16x32_bf16 v[50:53], v[178:181], v[186:189], v[50:53]
	v_mfma_f32_16x16x32_bf16 v[38:41], v[170:173], v[194:197], v[38:41]
	v_mfma_f32_16x16x32_bf16 v[34:37], v[178:181], v[194:197], v[34:37]
	v_mfma_f32_16x16x32_bf16 v[22:25], v[170:173], v[206:209], v[22:25]
	v_mfma_f32_16x16x32_bf16 v[18:21], v[178:181], v[206:209], v[18:21]
	v_mfma_f32_16x16x32_bf16 v[6:9], v[170:173], v[214:217], v[6:9]
	v_mfma_f32_16x16x32_bf16 v[2:5], v[178:181], v[214:217], v[2:5]
	v_mfma_f32_16x16x32_bf16 v[54:57], v[174:177], v[190:193], v[54:57]
	v_mfma_f32_16x16x32_bf16 v[50:53], v[182:185], v[190:193], v[50:53]
	v_mfma_f32_16x16x32_bf16 v[38:41], v[174:177], v[198:201], v[38:41]
	v_mfma_f32_16x16x32_bf16 v[34:37], v[182:185], v[198:201], v[34:37]
	v_mfma_f32_16x16x32_bf16 v[22:25], v[174:177], v[210:213], v[22:25]
	v_mfma_f32_16x16x32_bf16 v[18:21], v[182:185], v[210:213], v[18:21]
	v_mfma_f32_16x16x32_bf16 v[6:9], v[174:177], v[218:221], v[6:9]
	v_mfma_f32_16x16x32_bf16 v[2:5], v[182:185], v[218:221], v[2:5]
	s_setprio 0
	s_barrier
	s_add_i32 s62, s62, 2
	s_add_u32 s28, s28, 0x100
	s_addc_u32 s29, s29, 0
	s_add_u32 s50, s50, 0x100
	s_addc_u32 s51, s51, 0
	s_cmp_gt_u32 s62, 13
	s_cbranch_scc0 .LBB0_1619
	s_and_b64 vcc, exec, s[10:11]
	s_cbranch_vccz .LBB0_1622
	s_barrier

.LBB0_1707:
	v_readlane_b32 s46, v249, 32
	v_readlane_b32 s47, v249, 33
	s_add_u32 s46, s46, s42
	s_addc_u32 s47, s47, s43
	s_and_b64 s[48:49], s[44:45], exec
	s_cselect_b32 s34, s47, s51
	s_cselect_b32 s66, s46, s50
	s_add_u32 s48, s35, s40
	s_addc_u32 s49, s70, s41
	s_and_b64 s[64:65], s[44:45], exec
	s_cselect_b32 s67, s49, s63
	s_cselect_b32 s68, s48, s62
	s_add_i32 s69, s7, -2
	s_add_u32 s50, s50, 0x100080
	s_addc_u32 s51, s51, 0
	s_add_u32 s91, s62, 0x100
	s_addc_u32 s92, s63, 0
	s_mov_b32 s62, 0
	s_waitcnt vmcnt(0)
	ds_read_b128 v[130:133], v168
	ds_read_b128 v[134:137], v168 offset:1024
	ds_read_b128 v[138:141], v168 offset:2048
	ds_read_b128 v[142:145], v168 offset:3072
	ds_read_b128 v[162:165], v169
	ds_read_b128 v[172:175], v169 offset:1024
	ds_read_b128 v[176:179], v169 offset:2048
	ds_read_b128 v[180:183], v169 offset:3072
	s_add_i32 s93, s62, 2
	s_add_u32 s63, s50, 0xfff00080
	s_addc_u32 s64, s51, -1
	s_cmp_eq_u32 s69, s62
	s_cselect_b32 s62, s68, s91
	s_cselect_b32 s65, s34, s64
	s_cselect_b32 s64, s66, s63
	s_cselect_b32 s63, s67, s92
	v_lshl_add_u64 v[218:219], s[50:51], 0, v[156:157]
	s_add_i32 m0, s12, 0xc000
	ds_read_b128 v[184:187], v170
	ds_read_b128 v[188:191], v170 offset:1024
	ds_read_b128 v[192:195], v170 offset:2048
	ds_read_b128 v[196:199], v170 offset:3072
	ds_read_b128 v[200:203], v170 offset:4096
	ds_read_b128 v[206:209], v170 offset:5120
	ds_read_b128 v[210:213], v170 offset:6144
	ds_read_b128 v[214:217], v170 offset:7168
	global_load_lds_dwordx4 v[218:219], off
	v_lshl_add_u64 v[218:219], s[50:51], 0, v[158:159]
	s_add_i32 m0, s12, 0xe000
	s_nop 0
	global_load_lds_dwordx4 v[218:219], off
	s_waitcnt vmcnt(8)
	s_waitcnt lgkmcnt(0)
	s_setprio 1
	s_barrier
	v_mfma_f32_16x16x32_bf16 v[126:129], v[130:133], v[184:187], 0
	v_mfma_f32_16x16x32_bf16 v[122:125], v[138:141], v[184:187], 0
	v_mfma_f32_16x16x32_bf16 v[110:113], v[130:133], v[192:195], 0
	v_mfma_f32_16x16x32_bf16 v[106:109], v[138:141], v[192:195], 0
	v_mfma_f32_16x16x32_bf16 v[98:101], v[130:133], v[200:203], 0
	v_mfma_f32_16x16x32_bf16 v[90:93], v[138:141], v[200:203], 0
	v_mfma_f32_16x16x32_bf16 v[82:85], v[130:133], v[210:213], 0
	v_mfma_f32_16x16x32_bf16 v[74:77], v[138:141], v[210:213], 0
	v_mfma_f32_16x16x32_bf16 v[126:129], v[134:137], v[188:191], v[126:129]
	v_mfma_f32_16x16x32_bf16 v[122:125], v[142:145], v[188:191], v[122:125]
	v_mfma_f32_16x16x32_bf16 v[110:113], v[134:137], v[196:199], v[110:113]
	v_mfma_f32_16x16x32_bf16 v[106:109], v[142:145], v[196:199], v[106:109]
	v_mfma_f32_16x16x32_bf16 v[98:101], v[134:137], v[206:209], v[98:101]
	v_mfma_f32_16x16x32_bf16 v[90:93], v[142:145], v[206:209], v[90:93]
	v_mfma_f32_16x16x32_bf16 v[82:85], v[134:137], v[214:217], v[82:85]
	v_mfma_f32_16x16x32_bf16 v[74:77], v[142:145], v[214:217], v[74:77]
	v_mfma_f32_16x16x32_bf16 v[118:121], v[162:165], v[184:187], 0
	v_mfma_f32_16x16x32_bf16 v[114:117], v[176:179], v[184:187], 0
	v_mfma_f32_16x16x32_bf16 v[102:105], v[162:165], v[192:195], 0
	v_mfma_f32_16x16x32_bf16 v[94:97], v[176:179], v[192:195], 0
	v_mfma_f32_16x16x32_bf16 v[86:89], v[162:165], v[200:203], 0
	v_mfma_f32_16x16x32_bf16 v[78:81], v[176:179], v[200:203], 0
	v_mfma_f32_16x16x32_bf16 v[70:73], v[162:165], v[210:213], 0
	v_mfma_f32_16x16x32_bf16 v[66:69], v[176:179], v[210:213], 0
	v_mfma_f32_16x16x32_bf16 v[118:121], v[172:175], v[188:191], v[118:121]
	v_mfma_f32_16x16x32_bf16 v[114:117], v[180:183], v[188:191], v[114:117]
	v_mfma_f32_16x16x32_bf16 v[102:105], v[172:175], v[196:199], v[102:105]
	v_mfma_f32_16x16x32_bf16 v[94:97], v[180:183], v[196:199], v[94:97]
	v_mfma_f32_16x16x32_bf16 v[86:89], v[172:175], v[206:209], v[86:89]
	v_mfma_f32_16x16x32_bf16 v[78:81], v[180:183], v[206:209], v[78:81]
	v_mfma_f32_16x16x32_bf16 v[70:73], v[172:175], v[214:217], v[70:73]
	v_mfma_f32_16x16x32_bf16 v[66:69], v[180:183], v[214:217], v[66:69]
	s_setprio 0
	s_barrier
	s_add_i32 s94, s31, s2
	v_lshl_add_u64 v[218:219], s[62:63], 0, v[148:149]
	s_mov_b32 m0, s94
	ds_read_b128 v[184:187], v170 offset:16384
	ds_read_b128 v[188:191], v170 offset:17408
	ds_read_b128 v[192:195], v170 offset:18432
	ds_read_b128 v[196:199], v170 offset:19456
	ds_read_b128 v[200:203], v170 offset:20480
	ds_read_b128 v[206:209], v170 offset:21504
	ds_read_b128 v[210:213], v170 offset:22528
	ds_read_b128 v[214:217], v170 offset:23552
	global_load_lds_dwordx4 v[218:219], off
	s_add_i32 m0, s94, 0x2000
	s_add_u32 s94, s62, 0x100000
	v_lshl_add_u64 v[220:221], s[62:63], 0, v[152:153]
	s_addc_u32 s95, s63, 0
	s_add_i32 s96, s82, s2
	global_load_lds_dwordx4 v[220:221], off
	v_lshl_add_u64 v[222:223], s[94:95], 0, v[148:149]
	s_mov_b32 m0, s96
	v_lshl_add_u64 v[224:225], s[64:65], 0, v[150:151]
	global_load_lds_dwordx4 v[222:223], off
	v_lshl_add_u64 v[222:223], s[94:95], 0, v[152:153]
	s_add_i32 m0, s96, 0x2000
	s_nop 0
	global_load_lds_dwordx4 v[222:223], off
	v_lshl_add_u64 v[222:223], s[64:65], 0, v[146:147]
	s_mov_b32 m0, s12
	s_nop 0
	global_load_lds_dwordx4 v[222:223], off
	s_mov_b32 m0, s13
	s_nop 0
	global_load_lds_dwordx4 v[224:225], off
	s_waitcnt vmcnt(8)
	s_waitcnt lgkmcnt(0)
	s_setprio 1
	s_barrier
	v_mfma_f32_16x16x32_bf16 v[62:65], v[130:133], v[184:187], 0
	v_mfma_f32_16x16x32_bf16 v[58:61], v[138:141], v[184:187], 0
	v_mfma_f32_16x16x32_bf16 v[50:53], v[130:133], v[192:195], 0
	v_mfma_f32_16x16x32_bf16 v[42:45], v[138:141], v[192:195], 0
	v_mfma_f32_16x16x32_bf16 v[34:37], v[130:133], v[200:203], 0
	v_mfma_f32_16x16x32_bf16 v[26:29], v[138:141], v[200:203], 0
	v_mfma_f32_16x16x32_bf16 v[18:21], v[130:133], v[210:213], 0
	v_mfma_f32_16x16x32_bf16 v[10:13], v[138:141], v[210:213], 0
	v_mfma_f32_16x16x32_bf16 v[62:65], v[134:137], v[188:191], v[62:65]
	v_mfma_f32_16x16x32_bf16 v[58:61], v[142:145], v[188:191], v[58:61]
	v_mfma_f32_16x16x32_bf16 v[50:53], v[134:137], v[196:199], v[50:53]
	v_mfma_f32_16x16x32_bf16 v[42:45], v[142:145], v[196:199], v[42:45]
	v_mfma_f32_16x16x32_bf16 v[34:37], v[134:137], v[206:209], v[34:37]
	v_mfma_f32_16x16x32_bf16 v[26:29], v[142:145], v[206:209], v[26:29]
	v_mfma_f32_16x16x32_bf16 v[18:21], v[134:137], v[214:217], v[18:21]
	v_mfma_f32_16x16x32_bf16 v[10:13], v[142:145], v[214:217], v[10:13]
	v_mfma_f32_16x16x32_bf16 v[54:57], v[162:165], v[184:187], 0
	v_mfma_f32_16x16x32_bf16 v[46:49], v[176:179], v[184:187], 0
	v_mfma_f32_16x16x32_bf16 v[38:41], v[162:165], v[192:195], 0
	v_mfma_f32_16x16x32_bf16 v[30:33], v[176:179], v[192:195], 0
	v_mfma_f32_16x16x32_bf16 v[22:25], v[162:165], v[200:203], 0
	v_mfma_f32_16x16x32_bf16 v[14:17], v[176:179], v[200:203], 0
	v_mfma_f32_16x16x32_bf16 v[6:9], v[162:165], v[210:213], 0
	v_mfma_f32_16x16x32_bf16 v[2:5], v[176:179], v[210:213], 0
	v_mfma_f32_16x16x32_bf16 v[54:57], v[172:175], v[188:191], v[54:57]
	v_mfma_f32_16x16x32_bf16 v[46:49], v[180:183], v[188:191], v[46:49]
	v_mfma_f32_16x16x32_bf16 v[38:41], v[172:175], v[196:199], v[38:41]
	v_mfma_f32_16x16x32_bf16 v[30:33], v[180:183], v[196:199], v[30:33]
	v_mfma_f32_16x16x32_bf16 v[22:25], v[172:175], v[206:209], v[22:25]
	v_mfma_f32_16x16x32_bf16 v[14:17], v[180:183], v[206:209], v[14:17]
	v_mfma_f32_16x16x32_bf16 v[6:9], v[172:175], v[214:217], v[6:9]
	v_mfma_f32_16x16x32_bf16 v[2:5], v[180:183], v[214:217], v[2:5]
	s_setprio 0
	s_barrier
	s_add_i32 s94, 0, 0x18000
	s_add_i32 s95, 0, 0x1c000
	v_add_u32_e32 v142, s94, v167
	v_add_u32_e32 v154, s95, v167
	ds_read_b128 v[130:133], v142
	ds_read_b128 v[134:137], v142 offset:1024
	ds_read_b128 v[138:141], v142 offset:2048
	ds_read_b128 v[142:145], v142 offset:3072
	ds_read_b128 v[162:165], v154
	ds_read_b128 v[172:175], v154 offset:1024
	ds_read_b128 v[176:179], v154 offset:2048
	ds_read_b128 v[180:183], v154 offset:3072
	s_add_u32 s64, s64, 0x100000
	s_addc_u32 s65, s65, 0
	s_mov_b32 m0, s18
	v_lshl_add_u64 v[226:227], s[64:65], 0, v[146:147]
	ds_read_b128 v[184:187], v170 offset:32768
	ds_read_b128 v[188:191], v170 offset:33792
	ds_read_b128 v[192:195], v170 offset:34816
	ds_read_b128 v[196:199], v170 offset:35840
	ds_read_b128 v[200:203], v170 offset:36864
	ds_read_b128 v[206:209], v170 offset:37888
	ds_read_b128 v[210:213], v170 offset:38912
	ds_read_b128 v[214:217], v170 offset:39936
	global_load_lds_dwordx4 v[226:227], off
	v_lshl_add_u64 v[226:227], s[64:65], 0, v[150:151]
	s_mov_b32 m0, s19
	s_nop 0
	global_load_lds_dwordx4 v[226:227], off
	s_waitcnt vmcnt(8)
	s_waitcnt lgkmcnt(0)
	s_setprio 1
	s_barrier
	v_mfma_f32_16x16x32_bf16 v[126:129], v[130:133], v[184:187], v[126:129]
	v_mfma_f32_16x16x32_bf16 v[122:125], v[138:141], v[184:187], v[122:125]
	v_mfma_f32_16x16x32_bf16 v[110:113], v[130:133], v[192:195], v[110:113]
	v_mfma_f32_16x16x32_bf16 v[106:109], v[138:141], v[192:195], v[106:109]
	v_mfma_f32_16x16x32_bf16 v[98:101], v[130:133], v[200:203], v[98:101]
	v_mfma_f32_16x16x32_bf16 v[90:93], v[138:141], v[200:203], v[90:93]
	v_mfma_f32_16x16x32_bf16 v[82:85], v[130:133], v[210:213], v[82:85]
	v_mfma_f32_16x16x32_bf16 v[74:77], v[138:141], v[210:213], v[74:77]
	v_mfma_f32_16x16x32_bf16 v[126:129], v[134:137], v[188:191], v[126:129]
	v_mfma_f32_16x16x32_bf16 v[122:125], v[142:145], v[188:191], v[122:125]
	v_mfma_f32_16x16x32_bf16 v[110:113], v[134:137], v[196:199], v[110:113]
	v_mfma_f32_16x16x32_bf16 v[106:109], v[142:145], v[196:199], v[106:109]
	v_mfma_f32_16x16x32_bf16 v[98:101], v[134:137], v[206:209], v[98:101]
	v_mfma_f32_16x16x32_bf16 v[90:93], v[142:145], v[206:209], v[90:93]
	v_mfma_f32_16x16x32_bf16 v[82:85], v[134:137], v[214:217], v[82:85]
	v_mfma_f32_16x16x32_bf16 v[74:77], v[142:145], v[214:217], v[74:77]
	v_mfma_f32_16x16x32_bf16 v[118:121], v[162:165], v[184:187], v[118:121]
	v_mfma_f32_16x16x32_bf16 v[114:117], v[176:179], v[184:187], v[114:117]
	v_mfma_f32_16x16x32_bf16 v[102:105], v[162:165], v[192:195], v[102:105]
	v_mfma_f32_16x16x32_bf16 v[94:97], v[176:179], v[192:195], v[94:97]
	v_mfma_f32_16x16x32_bf16 v[86:89], v[162:165], v[200:203], v[86:89]
	v_mfma_f32_16x16x32_bf16 v[78:81], v[176:179], v[200:203], v[78:81]
	v_mfma_f32_16x16x32_bf16 v[70:73], v[162:165], v[210:213], v[70:73]
	v_mfma_f32_16x16x32_bf16 v[66:69], v[176:179], v[210:213], v[66:69]
	v_mfma_f32_16x16x32_bf16 v[118:121], v[172:175], v[188:191], v[118:121]
	v_mfma_f32_16x16x32_bf16 v[114:117], v[180:183], v[188:191], v[114:117]
	v_mfma_f32_16x16x32_bf16 v[102:105], v[172:175], v[196:199], v[102:105]
	v_mfma_f32_16x16x32_bf16 v[94:97], v[180:183], v[196:199], v[94:97]
	v_mfma_f32_16x16x32_bf16 v[86:89], v[172:175], v[206:209], v[86:89]
	v_mfma_f32_16x16x32_bf16 v[78:81], v[180:183], v[206:209], v[78:81]
	v_mfma_f32_16x16x32_bf16 v[70:73], v[172:175], v[214:217], v[70:73]
	v_mfma_f32_16x16x32_bf16 v[66:69], v[180:183], v[214:217], v[66:69]
	s_setprio 0
	s_barrier
	s_add_i32 s64, s94, s2
	v_lshl_add_u64 v[218:219], v[218:219], 0, s[16:17]
	s_mov_b32 m0, s64
	ds_read_b128 v[184:187], v170 offset:49152
	ds_read_b128 v[188:191], v170 offset:50176
	ds_read_b128 v[192:195], v170 offset:51200
	ds_read_b128 v[196:199], v170 offset:52224
	ds_read_b128 v[200:203], v170 offset:53248
	ds_read_b128 v[206:209], v170 offset:54272
	ds_read_b128 v[210:213], v170 offset:55296
	ds_read_b128 v[214:217], v170 offset:56320
	global_load_lds_dwordx4 v[218:219], off
	s_add_i32 m0, s64, 0x2000
	s_add_u32 s62, s62, 0x100080
	v_lshl_add_u64 v[218:219], v[220:221], 0, s[16:17]
	s_addc_u32 s63, s63, 0
	s_add_i32 s64, s95, s2
	global_load_lds_dwordx4 v[218:219], off
	v_lshl_add_u64 v[218:219], s[62:63], 0, v[148:149]
	s_mov_b32 m0, s64
	s_nop 0
	global_load_lds_dwordx4 v[218:219], off
	v_lshl_add_u64 v[218:219], s[62:63], 0, v[152:153]
	s_add_i32 m0, s64, 0x2000
	s_nop 0
	global_load_lds_dwordx4 v[218:219], off
	v_lshl_add_u64 v[218:219], v[222:223], 0, s[16:17]
	s_mov_b32 m0, s74
	s_nop 0
	global_load_lds_dwordx4 v[218:219], off
	v_lshl_add_u64 v[218:219], v[224:225], 0, s[16:17]
	s_mov_b32 m0, s75
	s_nop 0
	global_load_lds_dwordx4 v[218:219], off
	s_waitcnt vmcnt(8)
	s_waitcnt lgkmcnt(0)
	s_setprio 1
	s_barrier
	v_mfma_f32_16x16x32_bf16 v[62:65], v[130:133], v[184:187], v[62:65]
	v_mfma_f32_16x16x32_bf16 v[58:61], v[138:141], v[184:187], v[58:61]
	v_mfma_f32_16x16x32_bf16 v[50:53], v[130:133], v[192:195], v[50:53]
	v_mfma_f32_16x16x32_bf16 v[42:45], v[138:141], v[192:195], v[42:45]
	v_mfma_f32_16x16x32_bf16 v[34:37], v[130:133], v[200:203], v[34:37]
	v_mfma_f32_16x16x32_bf16 v[26:29], v[138:141], v[200:203], v[26:29]
	v_mfma_f32_16x16x32_bf16 v[18:21], v[130:133], v[210:213], v[18:21]
	v_mfma_f32_16x16x32_bf16 v[10:13], v[138:141], v[210:213], v[10:13]
	v_mfma_f32_16x16x32_bf16 v[62:65], v[134:137], v[188:191], v[62:65]
	v_mfma_f32_16x16x32_bf16 v[58:61], v[142:145], v[188:191], v[58:61]
	v_mfma_f32_16x16x32_bf16 v[50:53], v[134:137], v[196:199], v[50:53]
	v_mfma_f32_16x16x32_bf16 v[42:45], v[142:145], v[196:199], v[42:45]
	v_mfma_f32_16x16x32_bf16 v[34:37], v[134:137], v[206:209], v[34:37]
	v_mfma_f32_16x16x32_bf16 v[26:29], v[142:145], v[206:209], v[26:29]
	v_mfma_f32_16x16x32_bf16 v[18:21], v[134:137], v[214:217], v[18:21]
	v_mfma_f32_16x16x32_bf16 v[10:13], v[142:145], v[214:217], v[10:13]
	v_mfma_f32_16x16x32_bf16 v[54:57], v[162:165], v[184:187], v[54:57]
	v_mfma_f32_16x16x32_bf16 v[46:49], v[176:179], v[184:187], v[46:49]
	v_mfma_f32_16x16x32_bf16 v[38:41], v[162:165], v[192:195], v[38:41]
	v_mfma_f32_16x16x32_bf16 v[30:33], v[176:179], v[192:195], v[30:33]
	v_mfma_f32_16x16x32_bf16 v[22:25], v[162:165], v[200:203], v[22:25]
	v_mfma_f32_16x16x32_bf16 v[14:17], v[176:179], v[200:203], v[14:17]
	v_mfma_f32_16x16x32_bf16 v[6:9], v[162:165], v[210:213], v[6:9]
	v_mfma_f32_16x16x32_bf16 v[2:5], v[176:179], v[210:213], v[2:5]
	v_mfma_f32_16x16x32_bf16 v[54:57], v[172:175], v[188:191], v[54:57]
	v_mfma_f32_16x16x32_bf16 v[46:49], v[180:183], v[188:191], v[46:49]
	v_mfma_f32_16x16x32_bf16 v[38:41], v[172:175], v[196:199], v[38:41]
	v_mfma_f32_16x16x32_bf16 v[30:33], v[180:183], v[196:199], v[30:33]
	v_mfma_f32_16x16x32_bf16 v[22:25], v[172:175], v[206:209], v[22:25]
	v_mfma_f32_16x16x32_bf16 v[14:17], v[180:183], v[206:209], v[14:17]
	v_mfma_f32_16x16x32_bf16 v[6:9], v[172:175], v[214:217], v[6:9]
	v_mfma_f32_16x16x32_bf16 v[2:5], v[180:183], v[214:217], v[2:5]
	s_setprio 0
	s_barrier
	s_add_u32 s50, s50, 0x100
	s_addc_u32 s51, s51, 0
	s_add_u32 s91, s91, 0x100
	s_addc_u32 s92, s92, 0
	s_cmp_ge_i32 s93, s7
	s_mov_b32 s62, s93
.LBB0_1708:
	ds_read_b128 v[130:133], v168
	ds_read_b128 v[134:137], v168 offset:1024
	ds_read_b128 v[138:141], v168 offset:2048
	ds_read_b128 v[142:145], v168 offset:3072
	ds_read_b128 v[162:165], v169
	ds_read_b128 v[172:175], v169 offset:1024
	ds_read_b128 v[176:179], v169 offset:2048
	ds_read_b128 v[180:183], v169 offset:3072
	s_add_i32 s93, s62, 2
	s_add_u32 s63, s50, 0xfff00080
	s_addc_u32 s64, s51, -1
	s_cmp_eq_u32 s69, s62
	s_cselect_b32 s62, s68, s91
	s_cselect_b32 s65, s34, s64
	s_cselect_b32 s64, s66, s63
	s_cselect_b32 s63, s67, s92
	v_lshl_add_u64 v[218:219], s[50:51], 0, v[156:157]
	s_add_i32 m0, s12, 0xc000
	ds_read_b128 v[184:187], v170
	ds_read_b128 v[188:191], v170 offset:1024
	ds_read_b128 v[192:195], v170 offset:2048
	ds_read_b128 v[196:199], v170 offset:3072
	ds_read_b128 v[200:203], v170 offset:4096
	ds_read_b128 v[206:209], v170 offset:5120
	ds_read_b128 v[210:213], v170 offset:6144
	ds_read_b128 v[214:217], v170 offset:7168
	global_load_lds_dwordx4 v[218:219], off
	v_lshl_add_u64 v[218:219], s[50:51], 0, v[158:159]
	s_add_i32 m0, s12, 0xe000
	s_nop 0
	global_load_lds_dwordx4 v[218:219], off
	s_waitcnt vmcnt(8)
	s_waitcnt lgkmcnt(0)
	s_setprio 1
	s_barrier
	v_mfma_f32_16x16x32_bf16 v[126:129], v[130:133], v[184:187], v[126:129]
	v_mfma_f32_16x16x32_bf16 v[122:125], v[138:141], v[184:187], v[122:125]
	v_mfma_f32_16x16x32_bf16 v[110:113], v[130:133], v[192:195], v[110:113]
	v_mfma_f32_16x16x32_bf16 v[106:109], v[138:141], v[192:195], v[106:109]
	v_mfma_f32_16x16x32_bf16 v[98:101], v[130:133], v[200:203], v[98:101]
	v_mfma_f32_16x16x32_bf16 v[90:93], v[138:141], v[200:203], v[90:93]
	v_mfma_f32_16x16x32_bf16 v[82:85], v[130:133], v[210:213], v[82:85]
	v_mfma_f32_16x16x32_bf16 v[74:77], v[138:141], v[210:213], v[74:77]
	v_mfma_f32_16x16x32_bf16 v[126:129], v[134:137], v[188:191], v[126:129]
	v_mfma_f32_16x16x32_bf16 v[122:125], v[142:145], v[188:191], v[122:125]
	v_mfma_f32_16x16x32_bf16 v[110:113], v[134:137], v[196:199], v[110:113]
	v_mfma_f32_16x16x32_bf16 v[106:109], v[142:145], v[196:199], v[106:109]
	v_mfma_f32_16x16x32_bf16 v[98:101], v[134:137], v[206:209], v[98:101]
	v_mfma_f32_16x16x32_bf16 v[90:93], v[142:145], v[206:209], v[90:93]
	v_mfma_f32_16x16x32_bf16 v[82:85], v[134:137], v[214:217], v[82:85]
	v_mfma_f32_16x16x32_bf16 v[74:77], v[142:145], v[214:217], v[74:77]
	v_mfma_f32_16x16x32_bf16 v[118:121], v[162:165], v[184:187], v[118:121]
	v_mfma_f32_16x16x32_bf16 v[114:117], v[176:179], v[184:187], v[114:117]
	v_mfma_f32_16x16x32_bf16 v[102:105], v[162:165], v[192:195], v[102:105]
	v_mfma_f32_16x16x32_bf16 v[94:97], v[176:179], v[192:195], v[94:97]
	v_mfma_f32_16x16x32_bf16 v[86:89], v[162:165], v[200:203], v[86:89]
	v_mfma_f32_16x16x32_bf16 v[78:81], v[176:179], v[200:203], v[78:81]
	v_mfma_f32_16x16x32_bf16 v[70:73], v[162:165], v[210:213], v[70:73]
	v_mfma_f32_16x16x32_bf16 v[66:69], v[176:179], v[210:213], v[66:69]
	v_mfma_f32_16x16x32_bf16 v[118:121], v[172:175], v[188:191], v[118:121]
	v_mfma_f32_16x16x32_bf16 v[114:117], v[180:183], v[188:191], v[114:117]
	v_mfma_f32_16x16x32_bf16 v[102:105], v[172:175], v[196:199], v[102:105]
	v_mfma_f32_16x16x32_bf16 v[94:97], v[180:183], v[196:199], v[94:97]
	v_mfma_f32_16x16x32_bf16 v[86:89], v[172:175], v[206:209], v[86:89]
	v_mfma_f32_16x16x32_bf16 v[78:81], v[180:183], v[206:209], v[78:81]
	v_mfma_f32_16x16x32_bf16 v[70:73], v[172:175], v[214:217], v[70:73]
	v_mfma_f32_16x16x32_bf16 v[66:69], v[180:183], v[214:217], v[66:69]
	s_setprio 0
	s_barrier
	s_add_i32 s94, s31, s2
	v_lshl_add_u64 v[218:219], s[62:63], 0, v[148:149]
	s_mov_b32 m0, s94
	ds_read_b128 v[184:187], v170 offset:16384
	ds_read_b128 v[188:191], v170 offset:17408
	ds_read_b128 v[192:195], v170 offset:18432
	ds_read_b128 v[196:199], v170 offset:19456
	ds_read_b128 v[200:203], v170 offset:20480
	ds_read_b128 v[206:209], v170 offset:21504
	ds_read_b128 v[210:213], v170 offset:22528
	ds_read_b128 v[214:217], v170 offset:23552
	global_load_lds_dwordx4 v[218:219], off
	s_add_i32 m0, s94, 0x2000
	s_add_u32 s94, s62, 0x100000
	v_lshl_add_u64 v[220:221], s[62:63], 0, v[152:153]
	s_addc_u32 s95, s63, 0
	s_add_i32 s96, s82, s2
	global_load_lds_dwordx4 v[220:221], off
	v_lshl_add_u64 v[222:223], s[94:95], 0, v[148:149]
	s_mov_b32 m0, s96
	v_lshl_add_u64 v[224:225], s[64:65], 0, v[150:151]
	global_load_lds_dwordx4 v[222:223], off
	v_lshl_add_u64 v[222:223], s[94:95], 0, v[152:153]
	s_add_i32 m0, s96, 0x2000
	s_nop 0
	global_load_lds_dwordx4 v[222:223], off
	v_lshl_add_u64 v[222:223], s[64:65], 0, v[146:147]
	s_mov_b32 m0, s12
	s_nop 0
	global_load_lds_dwordx4 v[222:223], off
	s_mov_b32 m0, s13
	s_nop 0
	global_load_lds_dwordx4 v[224:225], off
	s_waitcnt vmcnt(8)
	s_waitcnt lgkmcnt(0)
	s_setprio 1
	s_barrier
	v_mfma_f32_16x16x32_bf16 v[62:65], v[130:133], v[184:187], v[62:65]
	v_mfma_f32_16x16x32_bf16 v[58:61], v[138:141], v[184:187], v[58:61]
	v_mfma_f32_16x16x32_bf16 v[50:53], v[130:133], v[192:195], v[50:53]
	v_mfma_f32_16x16x32_bf16 v[42:45], v[138:141], v[192:195], v[42:45]
	v_mfma_f32_16x16x32_bf16 v[34:37], v[130:133], v[200:203], v[34:37]
	v_mfma_f32_16x16x32_bf16 v[26:29], v[138:141], v[200:203], v[26:29]
	v_mfma_f32_16x16x32_bf16 v[18:21], v[130:133], v[210:213], v[18:21]
	v_mfma_f32_16x16x32_bf16 v[10:13], v[138:141], v[210:213], v[10:13]
	v_mfma_f32_16x16x32_bf16 v[62:65], v[134:137], v[188:191], v[62:65]
	v_mfma_f32_16x16x32_bf16 v[58:61], v[142:145], v[188:191], v[58:61]
	v_mfma_f32_16x16x32_bf16 v[50:53], v[134:137], v[196:199], v[50:53]
	v_mfma_f32_16x16x32_bf16 v[42:45], v[142:145], v[196:199], v[42:45]
	v_mfma_f32_16x16x32_bf16 v[34:37], v[134:137], v[206:209], v[34:37]
	v_mfma_f32_16x16x32_bf16 v[26:29], v[142:145], v[206:209], v[26:29]
	v_mfma_f32_16x16x32_bf16 v[18:21], v[134:137], v[214:217], v[18:21]
	v_mfma_f32_16x16x32_bf16 v[10:13], v[142:145], v[214:217], v[10:13]
	v_mfma_f32_16x16x32_bf16 v[54:57], v[162:165], v[184:187], v[54:57]
	v_mfma_f32_16x16x32_bf16 v[46:49], v[176:179], v[184:187], v[46:49]
	v_mfma_f32_16x16x32_bf16 v[38:41], v[162:165], v[192:195], v[38:41]
	v_mfma_f32_16x16x32_bf16 v[30:33], v[176:179], v[192:195], v[30:33]
	v_mfma_f32_16x16x32_bf16 v[22:25], v[162:165], v[200:203], v[22:25]
	v_mfma_f32_16x16x32_bf16 v[14:17], v[176:179], v[200:203], v[14:17]
	v_mfma_f32_16x16x32_bf16 v[6:9], v[162:165], v[210:213], v[6:9]
	v_mfma_f32_16x16x32_bf16 v[2:5], v[176:179], v[210:213], v[2:5]
	v_mfma_f32_16x16x32_bf16 v[54:57], v[172:175], v[188:191], v[54:57]
	v_mfma_f32_16x16x32_bf16 v[46:49], v[180:183], v[188:191], v[46:49]
	v_mfma_f32_16x16x32_bf16 v[38:41], v[172:175], v[196:199], v[38:41]
	v_mfma_f32_16x16x32_bf16 v[30:33], v[180:183], v[196:199], v[30:33]
	v_mfma_f32_16x16x32_bf16 v[22:25], v[172:175], v[206:209], v[22:25]
	v_mfma_f32_16x16x32_bf16 v[14:17], v[180:183], v[206:209], v[14:17]
	v_mfma_f32_16x16x32_bf16 v[6:9], v[172:175], v[214:217], v[6:9]
	v_mfma_f32_16x16x32_bf16 v[2:5], v[180:183], v[214:217], v[2:5]
	s_setprio 0
	s_barrier
	s_add_i32 s94, 0, 0x18000
	s_add_i32 s95, 0, 0x1c000
	v_add_u32_e32 v142, s94, v167
	v_add_u32_e32 v154, s95, v167
	ds_read_b128 v[130:133], v142
	ds_read_b128 v[134:137], v142 offset:1024
	ds_read_b128 v[138:141], v142 offset:2048
	ds_read_b128 v[142:145], v142 offset:3072
	ds_read_b128 v[162:165], v154
	ds_read_b128 v[172:175], v154 offset:1024
	ds_read_b128 v[176:179], v154 offset:2048
	ds_read_b128 v[180:183], v154 offset:3072
	s_add_u32 s64, s64, 0x100000
	s_addc_u32 s65, s65, 0
	s_mov_b32 m0, s18
	v_lshl_add_u64 v[226:227], s[64:65], 0, v[146:147]
	ds_read_b128 v[184:187], v170 offset:32768
	ds_read_b128 v[188:191], v170 offset:33792
	ds_read_b128 v[192:195], v170 offset:34816
	ds_read_b128 v[196:199], v170 offset:35840
	ds_read_b128 v[200:203], v170 offset:36864
	ds_read_b128 v[206:209], v170 offset:37888
	ds_read_b128 v[210:213], v170 offset:38912
	ds_read_b128 v[214:217], v170 offset:39936
	global_load_lds_dwordx4 v[226:227], off
	v_lshl_add_u64 v[226:227], s[64:65], 0, v[150:151]
	s_mov_b32 m0, s19
	s_nop 0
	global_load_lds_dwordx4 v[226:227], off
	s_waitcnt vmcnt(8)
	s_waitcnt lgkmcnt(0)
	s_setprio 1
	s_barrier
	v_mfma_f32_16x16x32_bf16 v[126:129], v[130:133], v[184:187], v[126:129]
	v_mfma_f32_16x16x32_bf16 v[122:125], v[138:141], v[184:187], v[122:125]
	v_mfma_f32_16x16x32_bf16 v[110:113], v[130:133], v[192:195], v[110:113]
	v_mfma_f32_16x16x32_bf16 v[106:109], v[138:141], v[192:195], v[106:109]
	v_mfma_f32_16x16x32_bf16 v[98:101], v[130:133], v[200:203], v[98:101]
	v_mfma_f32_16x16x32_bf16 v[90:93], v[138:141], v[200:203], v[90:93]
	v_mfma_f32_16x16x32_bf16 v[82:85], v[130:133], v[210:213], v[82:85]
	v_mfma_f32_16x16x32_bf16 v[74:77], v[138:141], v[210:213], v[74:77]
	v_mfma_f32_16x16x32_bf16 v[126:129], v[134:137], v[188:191], v[126:129]
	v_mfma_f32_16x16x32_bf16 v[122:125], v[142:145], v[188:191], v[122:125]
	v_mfma_f32_16x16x32_bf16 v[110:113], v[134:137], v[196:199], v[110:113]
	v_mfma_f32_16x16x32_bf16 v[106:109], v[142:145], v[196:199], v[106:109]
	v_mfma_f32_16x16x32_bf16 v[98:101], v[134:137], v[206:209], v[98:101]
	v_mfma_f32_16x16x32_bf16 v[90:93], v[142:145], v[206:209], v[90:93]
	v_mfma_f32_16x16x32_bf16 v[82:85], v[134:137], v[214:217], v[82:85]
	v_mfma_f32_16x16x32_bf16 v[74:77], v[142:145], v[214:217], v[74:77]
	v_mfma_f32_16x16x32_bf16 v[118:121], v[162:165], v[184:187], v[118:121]
	v_mfma_f32_16x16x32_bf16 v[114:117], v[176:179], v[184:187], v[114:117]
	v_mfma_f32_16x16x32_bf16 v[102:105], v[162:165], v[192:195], v[102:105]
	v_mfma_f32_16x16x32_bf16 v[94:97], v[176:179], v[192:195], v[94:97]
	v_mfma_f32_16x16x32_bf16 v[86:89], v[162:165], v[200:203], v[86:89]
	v_mfma_f32_16x16x32_bf16 v[78:81], v[176:179], v[200:203], v[78:81]
	v_mfma_f32_16x16x32_bf16 v[70:73], v[162:165], v[210:213], v[70:73]
	v_mfma_f32_16x16x32_bf16 v[66:69], v[176:179], v[210:213], v[66:69]
	v_mfma_f32_16x16x32_bf16 v[118:121], v[172:175], v[188:191], v[118:121]
	v_mfma_f32_16x16x32_bf16 v[114:117], v[180:183], v[188:191], v[114:117]
	v_mfma_f32_16x16x32_bf16 v[102:105], v[172:175], v[196:199], v[102:105]
	v_mfma_f32_16x16x32_bf16 v[94:97], v[180:183], v[196:199], v[94:97]
	v_mfma_f32_16x16x32_bf16 v[86:89], v[172:175], v[206:209], v[86:89]
	v_mfma_f32_16x16x32_bf16 v[78:81], v[180:183], v[206:209], v[78:81]
	v_mfma_f32_16x16x32_bf16 v[70:73], v[172:175], v[214:217], v[70:73]
	v_mfma_f32_16x16x32_bf16 v[66:69], v[180:183], v[214:217], v[66:69]
	s_setprio 0
	s_barrier
	s_add_i32 s64, s94, s2
	v_lshl_add_u64 v[218:219], v[218:219], 0, s[16:17]
	s_mov_b32 m0, s64
	ds_read_b128 v[184:187], v170 offset:49152
	ds_read_b128 v[188:191], v170 offset:50176
	ds_read_b128 v[192:195], v170 offset:51200
	ds_read_b128 v[196:199], v170 offset:52224
	ds_read_b128 v[200:203], v170 offset:53248
	ds_read_b128 v[206:209], v170 offset:54272
	ds_read_b128 v[210:213], v170 offset:55296
	ds_read_b128 v[214:217], v170 offset:56320
	global_load_lds_dwordx4 v[218:219], off
	s_add_i32 m0, s64, 0x2000
	s_add_u32 s62, s62, 0x100080
	v_lshl_add_u64 v[218:219], v[220:221], 0, s[16:17]
	s_addc_u32 s63, s63, 0
	s_add_i32 s64, s95, s2
	global_load_lds_dwordx4 v[218:219], off
	v_lshl_add_u64 v[218:219], s[62:63], 0, v[148:149]
	s_mov_b32 m0, s64
	s_nop 0
	global_load_lds_dwordx4 v[218:219], off
	v_lshl_add_u64 v[218:219], s[62:63], 0, v[152:153]
	s_add_i32 m0, s64, 0x2000
	s_nop 0
	global_load_lds_dwordx4 v[218:219], off
	v_lshl_add_u64 v[218:219], v[222:223], 0, s[16:17]
	s_mov_b32 m0, s74
	s_nop 0
	global_load_lds_dwordx4 v[218:219], off
	v_lshl_add_u64 v[218:219], v[224:225], 0, s[16:17]
	s_mov_b32 m0, s75
	s_nop 0
	global_load_lds_dwordx4 v[218:219], off
	s_waitcnt vmcnt(8)
	s_waitcnt lgkmcnt(0)
	s_setprio 1
	s_barrier
	v_mfma_f32_16x16x32_bf16 v[62:65], v[130:133], v[184:187], v[62:65]
	v_mfma_f32_16x16x32_bf16 v[58:61], v[138:141], v[184:187], v[58:61]
	v_mfma_f32_16x16x32_bf16 v[50:53], v[130:133], v[192:195], v[50:53]
	v_mfma_f32_16x16x32_bf16 v[42:45], v[138:141], v[192:195], v[42:45]
	v_mfma_f32_16x16x32_bf16 v[34:37], v[130:133], v[200:203], v[34:37]
	v_mfma_f32_16x16x32_bf16 v[26:29], v[138:141], v[200:203], v[26:29]
	v_mfma_f32_16x16x32_bf16 v[18:21], v[130:133], v[210:213], v[18:21]
	v_mfma_f32_16x16x32_bf16 v[10:13], v[138:141], v[210:213], v[10:13]
	v_mfma_f32_16x16x32_bf16 v[62:65], v[134:137], v[188:191], v[62:65]
	v_mfma_f32_16x16x32_bf16 v[58:61], v[142:145], v[188:191], v[58:61]
	v_mfma_f32_16x16x32_bf16 v[50:53], v[134:137], v[196:199], v[50:53]
	v_mfma_f32_16x16x32_bf16 v[42:45], v[142:145], v[196:199], v[42:45]
	v_mfma_f32_16x16x32_bf16 v[34:37], v[134:137], v[206:209], v[34:37]
	v_mfma_f32_16x16x32_bf16 v[26:29], v[142:145], v[206:209], v[26:29]
	v_mfma_f32_16x16x32_bf16 v[18:21], v[134:137], v[214:217], v[18:21]
	v_mfma_f32_16x16x32_bf16 v[10:13], v[142:145], v[214:217], v[10:13]
	v_mfma_f32_16x16x32_bf16 v[54:57], v[162:165], v[184:187], v[54:57]
	v_mfma_f32_16x16x32_bf16 v[46:49], v[176:179], v[184:187], v[46:49]
	v_mfma_f32_16x16x32_bf16 v[38:41], v[162:165], v[192:195], v[38:41]
	v_mfma_f32_16x16x32_bf16 v[30:33], v[176:179], v[192:195], v[30:33]
	v_mfma_f32_16x16x32_bf16 v[22:25], v[162:165], v[200:203], v[22:25]
	v_mfma_f32_16x16x32_bf16 v[14:17], v[176:179], v[200:203], v[14:17]
	v_mfma_f32_16x16x32_bf16 v[6:9], v[162:165], v[210:213], v[6:9]
	v_mfma_f32_16x16x32_bf16 v[2:5], v[176:179], v[210:213], v[2:5]
	v_mfma_f32_16x16x32_bf16 v[54:57], v[172:175], v[188:191], v[54:57]
	v_mfma_f32_16x16x32_bf16 v[46:49], v[180:183], v[188:191], v[46:49]
	v_mfma_f32_16x16x32_bf16 v[38:41], v[172:175], v[196:199], v[38:41]
	v_mfma_f32_16x16x32_bf16 v[30:33], v[180:183], v[196:199], v[30:33]
	v_mfma_f32_16x16x32_bf16 v[22:25], v[172:175], v[206:209], v[22:25]
	v_mfma_f32_16x16x32_bf16 v[14:17], v[180:183], v[206:209], v[14:17]
	v_mfma_f32_16x16x32_bf16 v[6:9], v[172:175], v[214:217], v[6:9]
	v_mfma_f32_16x16x32_bf16 v[2:5], v[180:183], v[214:217], v[2:5]
	s_setprio 0
	s_barrier
	s_add_u32 s50, s50, 0x100
	s_addc_u32 s51, s51, 0
	s_add_u32 s91, s91, 0x100
	s_addc_u32 s92, s92, 0
	s_cmp_ge_i32 s93, s7
	s_mov_b32 s62, s93
	s_cbranch_scc0 .LBB0_1708
	s_and_b64 vcc, exec, s[20:21]
	s_cbranch_vccz .LBB0_1711
	s_barrier
